# nt hint on P1 f32 outputs and read-once bf16 intermediates (Q*, gates); K/V bf16 intermediates keep default cache policy
# speedup vs baseline: 1.1879x; 1.0034x over previous
.LBB0_205:
	v_mov_b32_e32 v128, v132
	s_mov_b64 s[8:9], -1
	v_ashrrev_i32_e32 v130, 1, v128
	v_and_b32_e32 v129, 0xc0, v128
	v_and_b32_e32 v130, 0xffffff80, v130
	v_and_b32_e32 v210, 63, v128
	v_add_u32_e32 v211, s78, v130
	v_or_b32_e32 v212, s94, v129
	s_and_b64 vcc, exec, s[92:93]
	s_cbranch_vccz .LBB0_263
	s_and_b64 vcc, exec, s[0:1]
	s_cbranch_vccz .LBB0_208
	s_movk_i32 s0, 0xff
	v_mov_b32_e32 v130, s29
	v_mov_b32_e32 v131, s31
	v_cmp_lt_i32_e32 vcc, s0, v212
	v_mov_b32_e32 v134, s30
	s_nop 0
	v_cndmask_b32_e32 v131, v130, v131, vcc
	v_mov_b32_e32 v130, s28
	v_cndmask_b32_e32 v130, v130, v134, vcc
	v_cndmask_b32_e32 v134, v250, v251, vcc
	v_lshl_add_u64 v[138:139], s[4:5], 0, v[134:135]
	v_lshlrev_b32_e32 v134, 2, v128
	v_and_or_b32 v129, v134, 60, v129
	v_lshlrev_b32_e32 v134, 1, v129
	v_lshrrev_b32_e32 v128, 2, v128
	v_lshl_add_u64 v[130:131], v[130:131], 0, v[134:135]
	v_lshlrev_b32_e32 v134, 2, v129
	v_and_or_b32 v136, v128, 12, v211
	v_lshl_add_u64 v[128:129], v[138:139], 0, v[134:135]
	v_ashrrev_i32_e32 v137, 31, v136
	v_lshlrev_b64 v[138:139], 9, v[136:137]
	v_lshl_add_u64 v[138:139], v[130:131], 0, v[138:139]
	v_cvt_pk_bf16_f32 v140, v124, v120
	v_cvt_pk_bf16_f32 v141, v116, v112
	global_store_dwordx2 v[138:139], v[140:141], off
	v_lshlrev_b64 v[138:139], 10, v[136:137]
	v_lshl_add_u64 v[142:143], v[128:129], 0, v[138:139]
	v_mov_b32_e32 v138, v124
	v_mov_b32_e32 v139, v120
	v_mov_b32_e32 v140, v116
	v_mov_b32_e32 v141, v112
	global_store_dwordx4 v[142:143], v[138:141], off nt
	s_nop 1
	v_or_b32_e32 v138, 1, v136
	v_ashrrev_i32_e32 v139, 31, v138
	v_lshlrev_b64 v[140:141], 9, v[138:139]
	v_lshl_add_u64 v[140:141], v[130:131], 0, v[140:141]
	v_cvt_pk_bf16_f32 v142, v125, v121
	v_cvt_pk_bf16_f32 v143, v117, v113
	v_lshlrev_b64 v[138:139], 10, v[138:139]
	global_store_dwordx2 v[140:141], v[142:143], off
	v_lshl_add_u64 v[142:143], v[128:129], 0, v[138:139]
	v_mov_b32_e32 v138, v125
	v_mov_b32_e32 v139, v121
	v_mov_b32_e32 v140, v117
	v_mov_b32_e32 v141, v113
	global_store_dwordx4 v[142:143], v[138:141], off nt
	s_nop 1
	v_or_b32_e32 v138, 2, v136
	v_ashrrev_i32_e32 v139, 31, v138
	v_lshlrev_b64 v[140:141], 9, v[138:139]
	v_lshl_add_u64 v[140:141], v[130:131], 0, v[140:141]
	v_cvt_pk_bf16_f32 v142, v126, v122
	v_cvt_pk_bf16_f32 v143, v118, v114
	v_lshlrev_b64 v[138:139], 10, v[138:139]
	global_store_dwordx2 v[140:141], v[142:143], off
	v_lshl_add_u64 v[142:143], v[128:129], 0, v[138:139]
	v_mov_b32_e32 v138, v126
	v_mov_b32_e32 v139, v122
	v_mov_b32_e32 v140, v118
	v_mov_b32_e32 v141, v114
	global_store_dwordx4 v[142:143], v[138:141], off nt
	s_nop 1
	v_or_b32_e32 v138, 3, v136
	v_ashrrev_i32_e32 v139, 31, v138
	v_lshlrev_b64 v[140:141], 9, v[138:139]
	v_lshl_add_u64 v[140:141], v[130:131], 0, v[140:141]
	v_cvt_pk_bf16_f32 v142, v127, v123
	v_cvt_pk_bf16_f32 v143, v119, v115
	v_lshlrev_b64 v[138:139], 10, v[138:139]
	global_store_dwordx2 v[140:141], v[142:143], off
	v_lshl_add_u64 v[142:143], v[128:129], 0, v[138:139]
	v_mov_b32_e32 v138, v127
	v_mov_b32_e32 v139, v123
	v_mov_b32_e32 v140, v119
	v_mov_b32_e32 v141, v115
	global_store_dwordx4 v[142:143], v[138:141], off nt
	s_nop 1
	v_or_b32_e32 v138, 16, v136
	v_ashrrev_i32_e32 v139, 31, v138
	v_lshlrev_b64 v[140:141], 9, v[138:139]
	v_lshl_add_u64 v[140:141], v[130:131], 0, v[140:141]
	v_cvt_pk_bf16_f32 v142, v108, v104
	v_cvt_pk_bf16_f32 v143, v100, v96
	v_lshlrev_b64 v[138:139], 10, v[138:139]
	global_store_dwordx2 v[140:141], v[142:143], off
	v_lshl_add_u64 v[142:143], v[128:129], 0, v[138:139]
	v_mov_b32_e32 v138, v108
	v_mov_b32_e32 v139, v104
	v_mov_b32_e32 v140, v100
	v_mov_b32_e32 v141, v96
	global_store_dwordx4 v[142:143], v[138:141], off nt
	s_nop 1
	v_or_b32_e32 v138, 17, v136
	v_ashrrev_i32_e32 v139, 31, v138
	v_lshlrev_b64 v[140:141], 9, v[138:139]
	v_lshl_add_u64 v[140:141], v[130:131], 0, v[140:141]
	v_cvt_pk_bf16_f32 v142, v109, v105
	v_cvt_pk_bf16_f32 v143, v101, v97
	v_lshlrev_b64 v[138:139], 10, v[138:139]
	global_store_dwordx2 v[140:141], v[142:143], off
	v_lshl_add_u64 v[142:143], v[128:129], 0, v[138:139]
	v_mov_b32_e32 v138, v109
	v_mov_b32_e32 v139, v105
	v_mov_b32_e32 v140, v101
	v_mov_b32_e32 v141, v97
	global_store_dwordx4 v[142:143], v[138:141], off nt
	s_nop 1
	v_or_b32_e32 v138, 18, v136
	v_ashrrev_i32_e32 v139, 31, v138
	v_lshlrev_b64 v[140:141], 9, v[138:139]
	v_lshl_add_u64 v[140:141], v[130:131], 0, v[140:141]
	v_cvt_pk_bf16_f32 v142, v110, v106
	v_cvt_pk_bf16_f32 v143, v102, v98
	v_lshlrev_b64 v[138:139], 10, v[138:139]
	global_store_dwordx2 v[140:141], v[142:143], off
	v_lshl_add_u64 v[142:143], v[128:129], 0, v[138:139]
	v_mov_b32_e32 v138, v110
	v_mov_b32_e32 v139, v106
	v_mov_b32_e32 v140, v102
	v_mov_b32_e32 v141, v98
	global_store_dwordx4 v[142:143], v[138:141], off nt
	s_nop 1
	v_or_b32_e32 v138, 19, v136
	v_ashrrev_i32_e32 v139, 31, v138
	v_lshlrev_b64 v[140:141], 9, v[138:139]
	v_lshl_add_u64 v[140:141], v[130:131], 0, v[140:141]
	v_cvt_pk_bf16_f32 v142, v111, v107
	v_cvt_pk_bf16_f32 v143, v103, v99
	v_lshlrev_b64 v[138:139], 10, v[138:139]
	global_store_dwordx2 v[140:141], v[142:143], off
	v_lshl_add_u64 v[142:143], v[128:129], 0, v[138:139]
	v_mov_b32_e32 v138, v111
	v_mov_b32_e32 v139, v107
	v_mov_b32_e32 v140, v103
	v_mov_b32_e32 v141, v99
	global_store_dwordx4 v[142:143], v[138:141], off nt
	s_nop 1
	v_or_b32_e32 v138, 32, v136
	v_ashrrev_i32_e32 v139, 31, v138
	v_lshlrev_b64 v[140:141], 9, v[138:139]
	v_lshl_add_u64 v[140:141], v[130:131], 0, v[140:141]
	v_cvt_pk_bf16_f32 v142, v92, v88
	v_cvt_pk_bf16_f32 v143, v84, v80
	v_lshlrev_b64 v[138:139], 10, v[138:139]
	global_store_dwordx2 v[140:141], v[142:143], off
	v_lshl_add_u64 v[142:143], v[128:129], 0, v[138:139]
	v_mov_b32_e32 v138, v92
	v_mov_b32_e32 v139, v88
	v_mov_b32_e32 v140, v84
	v_mov_b32_e32 v141, v80
	global_store_dwordx4 v[142:143], v[138:141], off nt
	s_nop 1
	v_or_b32_e32 v138, 33, v136
	v_ashrrev_i32_e32 v139, 31, v138
	v_lshlrev_b64 v[140:141], 9, v[138:139]
	v_lshl_add_u64 v[140:141], v[130:131], 0, v[140:141]
	v_cvt_pk_bf16_f32 v142, v93, v89
	v_cvt_pk_bf16_f32 v143, v85, v81
	v_lshlrev_b64 v[138:139], 10, v[138:139]
	global_store_dwordx2 v[140:141], v[142:143], off
	v_lshl_add_u64 v[142:143], v[128:129], 0, v[138:139]
	v_mov_b32_e32 v138, v93
	v_mov_b32_e32 v139, v89
	v_mov_b32_e32 v140, v85
	v_mov_b32_e32 v141, v81
	global_store_dwordx4 v[142:143], v[138:141], off nt
	s_nop 1
	v_or_b32_e32 v138, 34, v136
	v_ashrrev_i32_e32 v139, 31, v138
	v_lshlrev_b64 v[140:141], 9, v[138:139]
	v_lshl_add_u64 v[140:141], v[130:131], 0, v[140:141]
	v_cvt_pk_bf16_f32 v142, v94, v90
	v_cvt_pk_bf16_f32 v143, v86, v82
	v_lshlrev_b64 v[138:139], 10, v[138:139]
	global_store_dwordx2 v[140:141], v[142:143], off
	v_lshl_add_u64 v[142:143], v[128:129], 0, v[138:139]
	v_mov_b32_e32 v138, v94
	v_mov_b32_e32 v139, v90
	v_mov_b32_e32 v140, v86
	v_mov_b32_e32 v141, v82
	global_store_dwordx4 v[142:143], v[138:141], off nt
	s_nop 1
	v_or_b32_e32 v138, 35, v136
	v_ashrrev_i32_e32 v139, 31, v138
	v_lshlrev_b64 v[140:141], 9, v[138:139]
	v_lshl_add_u64 v[140:141], v[130:131], 0, v[140:141]
	v_cvt_pk_bf16_f32 v142, v95, v91
	v_cvt_pk_bf16_f32 v143, v87, v83
	v_lshlrev_b64 v[138:139], 10, v[138:139]
	global_store_dwordx2 v[140:141], v[142:143], off
	v_lshl_add_u64 v[142:143], v[128:129], 0, v[138:139]
	v_mov_b32_e32 v138, v95
	v_mov_b32_e32 v139, v91
	v_mov_b32_e32 v140, v87
	v_mov_b32_e32 v141, v83
	global_store_dwordx4 v[142:143], v[138:141], off nt
	s_nop 1
	v_or_b32_e32 v138, 48, v136
	v_ashrrev_i32_e32 v139, 31, v138
	v_lshlrev_b64 v[140:141], 9, v[138:139]
	v_lshl_add_u64 v[140:141], v[130:131], 0, v[140:141]
	v_cvt_pk_bf16_f32 v142, v76, v72
	v_cvt_pk_bf16_f32 v143, v68, v64
	v_lshlrev_b64 v[138:139], 10, v[138:139]
	global_store_dwordx2 v[140:141], v[142:143], off
	v_lshl_add_u64 v[142:143], v[128:129], 0, v[138:139]
	v_mov_b32_e32 v138, v76
	v_mov_b32_e32 v139, v72
	v_mov_b32_e32 v140, v68
	v_mov_b32_e32 v141, v64
	global_store_dwordx4 v[142:143], v[138:141], off nt
	s_nop 1
	v_or_b32_e32 v138, 49, v136
	v_ashrrev_i32_e32 v139, 31, v138
	v_lshlrev_b64 v[140:141], 9, v[138:139]
	v_lshl_add_u64 v[140:141], v[130:131], 0, v[140:141]
	v_cvt_pk_bf16_f32 v142, v77, v73
	v_cvt_pk_bf16_f32 v143, v69, v65
	v_lshlrev_b64 v[138:139], 10, v[138:139]
	global_store_dwordx2 v[140:141], v[142:143], off
	v_lshl_add_u64 v[142:143], v[128:129], 0, v[138:139]
	v_mov_b32_e32 v138, v77
	v_mov_b32_e32 v139, v73
	v_mov_b32_e32 v140, v69
	v_mov_b32_e32 v141, v65
	global_store_dwordx4 v[142:143], v[138:141], off nt
	s_nop 1
	v_or_b32_e32 v138, 50, v136
	v_ashrrev_i32_e32 v139, 31, v138
	v_lshlrev_b64 v[140:141], 9, v[138:139]
	v_lshl_add_u64 v[140:141], v[130:131], 0, v[140:141]
	v_cvt_pk_bf16_f32 v142, v78, v74
	v_cvt_pk_bf16_f32 v143, v70, v66
	v_lshlrev_b64 v[138:139], 10, v[138:139]
	global_store_dwordx2 v[140:141], v[142:143], off
	v_lshl_add_u64 v[142:143], v[128:129], 0, v[138:139]
	v_mov_b32_e32 v138, v78
	v_mov_b32_e32 v139, v74
	v_mov_b32_e32 v140, v70
	v_mov_b32_e32 v141, v66
	global_store_dwordx4 v[142:143], v[138:141], off nt
	s_nop 1
	v_or_b32_e32 v138, 51, v136
	v_ashrrev_i32_e32 v139, 31, v138
	v_lshlrev_b64 v[140:141], 9, v[138:139]
	v_lshl_add_u64 v[140:141], v[130:131], 0, v[140:141]
	v_cvt_pk_bf16_f32 v142, v79, v75
	v_cvt_pk_bf16_f32 v143, v71, v67
	v_lshlrev_b64 v[138:139], 10, v[138:139]
	global_store_dwordx2 v[140:141], v[142:143], off
	v_lshl_add_u64 v[142:143], v[128:129], 0, v[138:139]
	v_mov_b32_e32 v138, v79
	v_mov_b32_e32 v139, v75
	v_mov_b32_e32 v140, v71
	v_mov_b32_e32 v141, v67
	global_store_dwordx4 v[142:143], v[138:141], off nt
	s_nop 1
	v_or_b32_e32 v138, 64, v136
	v_ashrrev_i32_e32 v139, 31, v138
	v_lshlrev_b64 v[140:141], 9, v[138:139]
	v_lshl_add_u64 v[140:141], v[130:131], 0, v[140:141]
	v_cvt_pk_bf16_f32 v142, v60, v56
	v_cvt_pk_bf16_f32 v143, v52, v48
	v_lshlrev_b64 v[138:139], 10, v[138:139]
	global_store_dwordx2 v[140:141], v[142:143], off
	v_lshl_add_u64 v[142:143], v[128:129], 0, v[138:139]
	v_mov_b32_e32 v138, v60
	v_mov_b32_e32 v139, v56
	v_mov_b32_e32 v140, v52
	v_mov_b32_e32 v141, v48
	global_store_dwordx4 v[142:143], v[138:141], off nt
	s_nop 1
	v_or_b32_e32 v138, 0x41, v136
	v_ashrrev_i32_e32 v139, 31, v138
	v_lshlrev_b64 v[140:141], 9, v[138:139]
	v_lshl_add_u64 v[140:141], v[130:131], 0, v[140:141]
	v_cvt_pk_bf16_f32 v142, v61, v57
	v_cvt_pk_bf16_f32 v143, v53, v49
	v_lshlrev_b64 v[138:139], 10, v[138:139]
	global_store_dwordx2 v[140:141], v[142:143], off
	v_lshl_add_u64 v[142:143], v[128:129], 0, v[138:139]
	v_mov_b32_e32 v138, v61
	v_mov_b32_e32 v139, v57
	v_mov_b32_e32 v140, v53
	v_mov_b32_e32 v141, v49
	global_store_dwordx4 v[142:143], v[138:141], off nt
	s_nop 1
	v_or_b32_e32 v138, 0x42, v136
	v_ashrrev_i32_e32 v139, 31, v138
	v_lshlrev_b64 v[140:141], 9, v[138:139]
	v_lshl_add_u64 v[140:141], v[130:131], 0, v[140:141]
	v_cvt_pk_bf16_f32 v142, v62, v58
	v_cvt_pk_bf16_f32 v143, v54, v50
	v_lshlrev_b64 v[138:139], 10, v[138:139]
	global_store_dwordx2 v[140:141], v[142:143], off
	v_lshl_add_u64 v[142:143], v[128:129], 0, v[138:139]
	v_mov_b32_e32 v138, v62
	v_mov_b32_e32 v139, v58
	v_mov_b32_e32 v140, v54
	v_mov_b32_e32 v141, v50
	global_store_dwordx4 v[142:143], v[138:141], off nt
	s_nop 1
	v_or_b32_e32 v138, 0x43, v136
	v_ashrrev_i32_e32 v139, 31, v138
	v_lshlrev_b64 v[140:141], 9, v[138:139]
	v_lshl_add_u64 v[140:141], v[130:131], 0, v[140:141]
	v_cvt_pk_bf16_f32 v142, v63, v59
	v_cvt_pk_bf16_f32 v143, v55, v51
	v_lshlrev_b64 v[138:139], 10, v[138:139]
	global_store_dwordx2 v[140:141], v[142:143], off
	v_lshl_add_u64 v[142:143], v[128:129], 0, v[138:139]
	v_mov_b32_e32 v138, v63
	v_mov_b32_e32 v139, v59
	v_mov_b32_e32 v140, v55
	v_mov_b32_e32 v141, v51
	global_store_dwordx4 v[142:143], v[138:141], off nt
	s_nop 1
	v_or_b32_e32 v138, 0x50, v136
	v_ashrrev_i32_e32 v139, 31, v138
	v_lshlrev_b64 v[140:141], 9, v[138:139]
	v_lshl_add_u64 v[140:141], v[130:131], 0, v[140:141]
	v_cvt_pk_bf16_f32 v142, v44, v40
	v_cvt_pk_bf16_f32 v143, v36, v32
	v_lshlrev_b64 v[138:139], 10, v[138:139]
	global_store_dwordx2 v[140:141], v[142:143], off
	v_lshl_add_u64 v[142:143], v[128:129], 0, v[138:139]
	v_mov_b32_e32 v138, v44
	v_mov_b32_e32 v139, v40
	v_mov_b32_e32 v140, v36
	v_mov_b32_e32 v141, v32
	global_store_dwordx4 v[142:143], v[138:141], off nt
	s_nop 1
	v_or_b32_e32 v138, 0x51, v136
	v_ashrrev_i32_e32 v139, 31, v138
	v_lshlrev_b64 v[140:141], 9, v[138:139]
	v_lshl_add_u64 v[140:141], v[130:131], 0, v[140:141]
	v_cvt_pk_bf16_f32 v142, v45, v41
	v_cvt_pk_bf16_f32 v143, v37, v33
	v_lshlrev_b64 v[138:139], 10, v[138:139]
	global_store_dwordx2 v[140:141], v[142:143], off
	v_lshl_add_u64 v[142:143], v[128:129], 0, v[138:139]
	v_mov_b32_e32 v138, v45
	v_mov_b32_e32 v139, v41
	v_mov_b32_e32 v140, v37
	v_mov_b32_e32 v141, v33
	global_store_dwordx4 v[142:143], v[138:141], off nt
	s_nop 1
	v_or_b32_e32 v138, 0x52, v136
	v_ashrrev_i32_e32 v139, 31, v138
	v_lshlrev_b64 v[140:141], 9, v[138:139]
	v_lshl_add_u64 v[140:141], v[130:131], 0, v[140:141]
	v_cvt_pk_bf16_f32 v142, v46, v42
	v_cvt_pk_bf16_f32 v143, v38, v34
	v_lshlrev_b64 v[138:139], 10, v[138:139]
	global_store_dwordx2 v[140:141], v[142:143], off
	v_lshl_add_u64 v[142:143], v[128:129], 0, v[138:139]
	v_mov_b32_e32 v138, v46
	v_mov_b32_e32 v139, v42
	v_mov_b32_e32 v140, v38
	v_mov_b32_e32 v141, v34
	global_store_dwordx4 v[142:143], v[138:141], off nt
	s_nop 1
	v_or_b32_e32 v138, 0x53, v136
	v_ashrrev_i32_e32 v139, 31, v138
	v_lshlrev_b64 v[140:141], 9, v[138:139]
	v_lshl_add_u64 v[140:141], v[130:131], 0, v[140:141]
	v_cvt_pk_bf16_f32 v142, v47, v43
	v_cvt_pk_bf16_f32 v143, v39, v35
	v_lshlrev_b64 v[138:139], 10, v[138:139]
	global_store_dwordx2 v[140:141], v[142:143], off
	v_lshl_add_u64 v[142:143], v[128:129], 0, v[138:139]
	v_mov_b32_e32 v138, v47
	v_mov_b32_e32 v139, v43
	v_mov_b32_e32 v140, v39
	v_mov_b32_e32 v141, v35
	global_store_dwordx4 v[142:143], v[138:141], off nt
	s_nop 1
	v_or_b32_e32 v138, 0x60, v136
	v_ashrrev_i32_e32 v139, 31, v138
	v_lshlrev_b64 v[140:141], 9, v[138:139]
	v_lshl_add_u64 v[140:141], v[130:131], 0, v[140:141]
	v_cvt_pk_bf16_f32 v142, v28, v24
	v_cvt_pk_bf16_f32 v143, v20, v16
	v_lshlrev_b64 v[138:139], 10, v[138:139]
	global_store_dwordx2 v[140:141], v[142:143], off
	v_lshl_add_u64 v[142:143], v[128:129], 0, v[138:139]
	v_mov_b32_e32 v138, v28
	v_mov_b32_e32 v139, v24
	v_mov_b32_e32 v140, v20
	v_mov_b32_e32 v141, v16
	global_store_dwordx4 v[142:143], v[138:141], off nt
	s_nop 1
	v_or_b32_e32 v138, 0x61, v136
	v_ashrrev_i32_e32 v139, 31, v138
	v_lshlrev_b64 v[140:141], 9, v[138:139]
	v_lshl_add_u64 v[140:141], v[130:131], 0, v[140:141]
	v_cvt_pk_bf16_f32 v142, v29, v25
	v_cvt_pk_bf16_f32 v143, v21, v17
	v_lshlrev_b64 v[138:139], 10, v[138:139]
	global_store_dwordx2 v[140:141], v[142:143], off
	v_lshl_add_u64 v[142:143], v[128:129], 0, v[138:139]
	v_mov_b32_e32 v138, v29
	v_mov_b32_e32 v139, v25
	v_mov_b32_e32 v140, v21
	v_mov_b32_e32 v141, v17
	global_store_dwordx4 v[142:143], v[138:141], off nt
	s_nop 1
	v_or_b32_e32 v138, 0x62, v136
	v_ashrrev_i32_e32 v139, 31, v138
	v_lshlrev_b64 v[140:141], 9, v[138:139]
	v_lshl_add_u64 v[140:141], v[130:131], 0, v[140:141]
	v_cvt_pk_bf16_f32 v142, v30, v26
	v_cvt_pk_bf16_f32 v143, v22, v18
	v_lshlrev_b64 v[138:139], 10, v[138:139]
	global_store_dwordx2 v[140:141], v[142:143], off
	v_lshl_add_u64 v[142:143], v[128:129], 0, v[138:139]
	v_mov_b32_e32 v138, v30
	v_mov_b32_e32 v139, v26
	v_mov_b32_e32 v140, v22
	v_mov_b32_e32 v141, v18
	global_store_dwordx4 v[142:143], v[138:141], off nt
	s_nop 1
	v_or_b32_e32 v138, 0x63, v136
	v_ashrrev_i32_e32 v139, 31, v138
	v_lshlrev_b64 v[140:141], 9, v[138:139]
	v_lshl_add_u64 v[140:141], v[130:131], 0, v[140:141]
	v_cvt_pk_bf16_f32 v142, v31, v27
	v_cvt_pk_bf16_f32 v143, v23, v19
	v_lshlrev_b64 v[138:139], 10, v[138:139]
	global_store_dwordx2 v[140:141], v[142:143], off
	v_lshl_add_u64 v[142:143], v[128:129], 0, v[138:139]
	v_mov_b32_e32 v138, v31
	v_mov_b32_e32 v139, v27
	v_mov_b32_e32 v140, v23
	v_mov_b32_e32 v141, v19
	global_store_dwordx4 v[142:143], v[138:141], off nt
	s_nop 1
	v_or_b32_e32 v138, 0x70, v136
	v_ashrrev_i32_e32 v139, 31, v138
	v_lshlrev_b64 v[140:141], 9, v[138:139]
	v_lshl_add_u64 v[140:141], v[130:131], 0, v[140:141]
	v_cvt_pk_bf16_f32 v142, v12, v8
	v_cvt_pk_bf16_f32 v143, v4, v0
	v_lshlrev_b64 v[138:139], 10, v[138:139]
	global_store_dwordx2 v[140:141], v[142:143], off
	v_lshl_add_u64 v[142:143], v[128:129], 0, v[138:139]
	v_mov_b32_e32 v138, v12
	v_mov_b32_e32 v139, v8
	v_mov_b32_e32 v140, v4
	v_mov_b32_e32 v141, v0
	global_store_dwordx4 v[142:143], v[138:141], off nt
	s_nop 1
	v_or_b32_e32 v138, 0x71, v136
	v_ashrrev_i32_e32 v139, 31, v138
	v_lshlrev_b64 v[140:141], 9, v[138:139]
	v_lshl_add_u64 v[140:141], v[130:131], 0, v[140:141]
	v_cvt_pk_bf16_f32 v142, v13, v9
	v_cvt_pk_bf16_f32 v143, v5, v1
	v_lshlrev_b64 v[138:139], 10, v[138:139]
	global_store_dwordx2 v[140:141], v[142:143], off
	v_lshl_add_u64 v[142:143], v[128:129], 0, v[138:139]
	v_mov_b32_e32 v138, v13
	v_mov_b32_e32 v139, v9
	v_mov_b32_e32 v140, v5
	v_mov_b32_e32 v141, v1
	global_store_dwordx4 v[142:143], v[138:141], off nt
	s_nop 1
	v_or_b32_e32 v138, 0x72, v136
	v_ashrrev_i32_e32 v139, 31, v138
	v_lshlrev_b64 v[140:141], 9, v[138:139]
	v_lshl_add_u64 v[140:141], v[130:131], 0, v[140:141]
	v_cvt_pk_bf16_f32 v142, v14, v10
	v_cvt_pk_bf16_f32 v143, v6, v2
	v_lshlrev_b64 v[138:139], 10, v[138:139]
	global_store_dwordx2 v[140:141], v[142:143], off
	v_lshl_add_u64 v[142:143], v[128:129], 0, v[138:139]
	v_mov_b32_e32 v138, v14
	v_mov_b32_e32 v139, v10
	v_mov_b32_e32 v140, v6
	v_mov_b32_e32 v141, v2
	global_store_dwordx4 v[142:143], v[138:141], off nt
	v_or_b32_e32 v136, 0x73, v136
	v_ashrrev_i32_e32 v137, 31, v136
	v_lshlrev_b64 v[138:139], 9, v[136:137]
	v_lshl_add_u64 v[130:131], v[130:131], 0, v[138:139]
	v_cvt_pk_bf16_f32 v138, v15, v11
	v_cvt_pk_bf16_f32 v139, v7, v3
	global_store_dwordx2 v[130:131], v[138:139], off
	v_lshlrev_b64 v[130:131], 10, v[136:137]
	v_lshl_add_u64 v[136:137], v[128:129], 0, v[130:131]
	v_mov_b32_e32 v128, v15
	v_mov_b32_e32 v129, v11
	v_mov_b32_e32 v130, v7
	v_mov_b32_e32 v131, v3
	global_store_dwordx4 v[136:137], v[128:131], off nt
	s_mov_b64 s[8:9], 0

.LBB0_233:
	s_andn2_saveexec_b64 s[68:69], s[68:69]
	s_cbranch_execz .LBB0_241
	v_cmp_lt_i32_e32 vcc, 5, v177
	s_mov_b64 s[72:73], s[66:67]
	s_and_saveexec_b64 s[24:25], vcc
	s_xor_b64 s[74:75], exec, s[24:25]
	s_cbranch_execz .LBB0_238
	v_cmp_gt_i32_e32 vcc, 7, v177
	s_mov_b64 s[34:35], -1
	s_and_saveexec_b64 s[72:73], vcc
	s_cbranch_execz .LBB0_237
	v_readlane_b32 s36, v253, 26
	v_readlane_b32 s24, v253, 16
	v_lshlrev_b32_e32 v138, 2, v178
	v_ashrrev_i32_e32 v137, 31, v136
	v_readlane_b32 s40, v253, 30
	v_readlane_b32 s41, v253, 31
	v_readlane_b32 s25, v253, 17
	v_add_u32_e32 v134, v138, v211
	v_readlane_b32 s37, v253, 27
	v_readlane_b32 s38, v253, 28
	v_readlane_b32 s39, v253, 29
	v_readlane_b32 s42, v253, 32
	v_readlane_b32 s43, v253, 33
	v_readlane_b32 s44, v253, 34
	v_readlane_b32 s45, v253, 35
	v_readlane_b32 s46, v253, 36
	v_readlane_b32 s47, v253, 37
	v_readlane_b32 s48, v253, 38
	v_readlane_b32 s49, v253, 39
	v_readlane_b32 s50, v253, 40
	v_readlane_b32 s51, v253, 41
	v_lshl_add_u64 v[130:131], v[136:137], 1, s[40:41]
	v_lshl_add_u64 v[128:129], v[136:137], 2, s[24:25]
	v_lshrrev_b32_e32 v139, 5, v134
	v_and_b32_e32 v137, 28, v138
	v_mul_lo_u32 v138, v139, s12
	v_add_u32_e32 v144, 0x1000, v138
	v_or_b32_e32 v138, v144, v137
	v_mad_i64_i32 v[138:139], s[24:25], v138, s13, v[130:131]
	v_cvt_pk_bf16_f32 v140, v124, v120
	v_cvt_pk_bf16_f32 v141, v116, v112
	global_store_dwordx2 v[138:139], v[140:141], off
	v_mad_i64_i32 v[142:143], s[24:25], v134, s14, v[128:129]
	v_mov_b32_e32 v138, v124
	v_mov_b32_e32 v139, v120
	v_mov_b32_e32 v140, v116
	v_mov_b32_e32 v141, v112
	global_store_dwordx4 v[142:143], v[138:141], off nt
	v_or_b32_e32 v142, 1, v134
	s_nop 0
	v_and_or_b32 v138, v142, 29, v144
	v_mad_i64_i32 v[138:139], s[24:25], v138, s13, v[130:131]
	v_cvt_pk_bf16_f32 v140, v125, v121
	v_cvt_pk_bf16_f32 v141, v117, v113
	global_store_dwordx2 v[138:139], v[140:141], off
	v_mad_i64_i32 v[142:143], s[24:25], v142, s14, v[128:129]
	v_mov_b32_e32 v138, v125
	v_mov_b32_e32 v139, v121
	v_mov_b32_e32 v140, v117
	v_mov_b32_e32 v141, v113
	global_store_dwordx4 v[142:143], v[138:141], off nt
	v_or_b32_e32 v142, 2, v134
	s_nop 0
	v_and_or_b32 v138, v142, 30, v144
	v_mad_i64_i32 v[138:139], s[24:25], v138, s13, v[130:131]
	v_cvt_pk_bf16_f32 v140, v126, v122
	v_cvt_pk_bf16_f32 v141, v118, v114
	global_store_dwordx2 v[138:139], v[140:141], off
	v_mad_i64_i32 v[142:143], s[24:25], v142, s14, v[128:129]
	v_mov_b32_e32 v138, v126
	v_mov_b32_e32 v139, v122
	v_mov_b32_e32 v140, v118
	v_mov_b32_e32 v141, v114
	global_store_dwordx4 v[142:143], v[138:141], off nt
	v_or_b32_e32 v142, 3, v134
	s_nop 0
	v_and_or_b32 v138, v142, 31, v144
	v_mad_i64_i32 v[138:139], s[24:25], v138, s13, v[130:131]
	v_cvt_pk_bf16_f32 v140, v127, v123
	v_cvt_pk_bf16_f32 v141, v119, v115
	global_store_dwordx2 v[138:139], v[140:141], off
	v_mad_i64_i32 v[142:143], s[24:25], v142, s14, v[128:129]
	v_mov_b32_e32 v138, v127
	v_mov_b32_e32 v139, v123
	v_mov_b32_e32 v140, v119
	v_mov_b32_e32 v141, v115
	global_store_dwordx4 v[142:143], v[138:141], off nt
	v_add_u32_e32 v142, 16, v134
	s_nop 0
	v_lshrrev_b32_e32 v138, 5, v142
	v_mul_lo_u32 v138, v138, s12
	v_and_or_b32 v138, v142, 28, v138
	v_add_u32_e32 v138, 0x1000, v138
	v_mad_i64_i32 v[138:139], s[24:25], v138, s13, v[130:131]
	v_cvt_pk_bf16_f32 v140, v108, v104
	v_cvt_pk_bf16_f32 v141, v100, v96
	global_store_dwordx2 v[138:139], v[140:141], off
	v_mad_i64_i32 v[142:143], s[24:25], v142, s14, v[128:129]
	v_mov_b32_e32 v138, v108
	v_mov_b32_e32 v139, v104
	v_mov_b32_e32 v140, v100
	v_mov_b32_e32 v141, v96
	global_store_dwordx4 v[142:143], v[138:141], off nt
	v_add_u32_e32 v142, 17, v134
	s_nop 0
	v_lshrrev_b32_e32 v138, 5, v142
	v_mul_lo_u32 v138, v138, s12
	v_and_or_b32 v138, v142, 29, v138
	v_add_u32_e32 v138, 0x1000, v138
	v_mad_i64_i32 v[138:139], s[24:25], v138, s13, v[130:131]
	v_cvt_pk_bf16_f32 v140, v109, v105
	v_cvt_pk_bf16_f32 v141, v101, v97
	global_store_dwordx2 v[138:139], v[140:141], off
	v_mad_i64_i32 v[142:143], s[24:25], v142, s14, v[128:129]
	v_mov_b32_e32 v138, v109
	v_mov_b32_e32 v139, v105
	v_mov_b32_e32 v140, v101
	v_mov_b32_e32 v141, v97
	global_store_dwordx4 v[142:143], v[138:141], off nt
	v_add_u32_e32 v142, 18, v134
	s_nop 0
	v_lshrrev_b32_e32 v138, 5, v142
	v_mul_lo_u32 v138, v138, s12
	v_and_or_b32 v138, v142, 30, v138
	v_add_u32_e32 v138, 0x1000, v138
	v_mad_i64_i32 v[138:139], s[24:25], v138, s13, v[130:131]
	v_cvt_pk_bf16_f32 v140, v110, v106
	v_cvt_pk_bf16_f32 v141, v102, v98
	global_store_dwordx2 v[138:139], v[140:141], off
	v_mad_i64_i32 v[142:143], s[24:25], v142, s14, v[128:129]
	v_mov_b32_e32 v138, v110
	v_mov_b32_e32 v139, v106
	v_mov_b32_e32 v140, v102
	v_mov_b32_e32 v141, v98
	global_store_dwordx4 v[142:143], v[138:141], off nt
	v_add_u32_e32 v142, 19, v134
	s_nop 0
	v_lshrrev_b32_e32 v138, 5, v142
	v_mul_lo_u32 v138, v138, s12
	v_and_or_b32 v138, v142, 31, v138
	v_add_u32_e32 v138, 0x1000, v138
	v_mad_i64_i32 v[138:139], s[24:25], v138, s13, v[130:131]
	v_cvt_pk_bf16_f32 v140, v111, v107
	v_cvt_pk_bf16_f32 v141, v103, v99
	global_store_dwordx2 v[138:139], v[140:141], off
	v_mad_i64_i32 v[142:143], s[24:25], v142, s14, v[128:129]
	v_mov_b32_e32 v138, v111
	v_mov_b32_e32 v139, v107
	v_mov_b32_e32 v140, v103
	v_mov_b32_e32 v141, v99
	global_store_dwordx4 v[142:143], v[138:141], off nt
	v_add_u32_e32 v142, 32, v134
	s_nop 0
	v_lshrrev_b32_e32 v138, 5, v142
	v_mul_lo_u32 v138, v138, s12
	v_or_b32_e32 v138, v138, v137
	v_add_u32_e32 v138, 0x1000, v138
	v_mad_i64_i32 v[138:139], s[24:25], v138, s13, v[130:131]
	v_cvt_pk_bf16_f32 v140, v92, v88
	v_cvt_pk_bf16_f32 v141, v84, v80
	global_store_dwordx2 v[138:139], v[140:141], off
	v_mad_i64_i32 v[142:143], s[24:25], v142, s14, v[128:129]
	v_mov_b32_e32 v138, v92
	v_mov_b32_e32 v139, v88
	v_mov_b32_e32 v140, v84
	v_mov_b32_e32 v141, v80
	global_store_dwordx4 v[142:143], v[138:141], off nt
	v_add_u32_e32 v142, 33, v134
	s_nop 0
	v_lshrrev_b32_e32 v138, 5, v142
	v_mul_lo_u32 v138, v138, s12
	v_and_or_b32 v138, v142, 29, v138
	v_add_u32_e32 v138, 0x1000, v138
	v_mad_i64_i32 v[138:139], s[24:25], v138, s13, v[130:131]
	v_cvt_pk_bf16_f32 v140, v93, v89
	v_cvt_pk_bf16_f32 v141, v85, v81
	global_store_dwordx2 v[138:139], v[140:141], off
	v_mad_i64_i32 v[142:143], s[24:25], v142, s14, v[128:129]
	v_mov_b32_e32 v138, v93
	v_mov_b32_e32 v139, v89
	v_mov_b32_e32 v140, v85
	v_mov_b32_e32 v141, v81
	global_store_dwordx4 v[142:143], v[138:141], off nt
	v_add_u32_e32 v142, 34, v134
	s_nop 0
	v_lshrrev_b32_e32 v138, 5, v142
	v_mul_lo_u32 v138, v138, s12
	v_and_or_b32 v138, v142, 30, v138
	v_add_u32_e32 v138, 0x1000, v138
	v_mad_i64_i32 v[138:139], s[24:25], v138, s13, v[130:131]
	v_cvt_pk_bf16_f32 v140, v94, v90
	v_cvt_pk_bf16_f32 v141, v86, v82
	global_store_dwordx2 v[138:139], v[140:141], off
	v_mad_i64_i32 v[142:143], s[24:25], v142, s14, v[128:129]
	v_mov_b32_e32 v138, v94
	v_mov_b32_e32 v139, v90
	v_mov_b32_e32 v140, v86
	v_mov_b32_e32 v141, v82
	global_store_dwordx4 v[142:143], v[138:141], off nt
	v_add_u32_e32 v142, 35, v134
	s_nop 0
	v_lshrrev_b32_e32 v138, 5, v142
	v_mul_lo_u32 v138, v138, s12
	v_and_or_b32 v138, v142, 31, v138
	v_add_u32_e32 v138, 0x1000, v138
	v_mad_i64_i32 v[138:139], s[24:25], v138, s13, v[130:131]
	v_cvt_pk_bf16_f32 v140, v95, v91
	v_cvt_pk_bf16_f32 v141, v87, v83
	global_store_dwordx2 v[138:139], v[140:141], off
	v_mad_i64_i32 v[142:143], s[24:25], v142, s14, v[128:129]
	v_mov_b32_e32 v138, v95
	v_mov_b32_e32 v139, v91
	v_mov_b32_e32 v140, v87
	v_mov_b32_e32 v141, v83
	global_store_dwordx4 v[142:143], v[138:141], off nt
	v_add_u32_e32 v142, 48, v134
	s_nop 0
	v_lshrrev_b32_e32 v138, 5, v142
	v_mul_lo_u32 v138, v138, s12
	v_and_or_b32 v138, v142, 28, v138
	v_add_u32_e32 v138, 0x1000, v138
	v_mad_i64_i32 v[138:139], s[24:25], v138, s13, v[130:131]
	v_cvt_pk_bf16_f32 v140, v76, v72
	v_cvt_pk_bf16_f32 v141, v68, v64
	global_store_dwordx2 v[138:139], v[140:141], off
	v_mad_i64_i32 v[142:143], s[24:25], v142, s14, v[128:129]
	v_mov_b32_e32 v138, v76
	v_mov_b32_e32 v139, v72
	v_mov_b32_e32 v140, v68
	v_mov_b32_e32 v141, v64
	global_store_dwordx4 v[142:143], v[138:141], off nt
	v_add_u32_e32 v142, 49, v134
	s_nop 0
	v_lshrrev_b32_e32 v138, 5, v142
	v_mul_lo_u32 v138, v138, s12
	v_and_or_b32 v138, v142, 29, v138
	v_add_u32_e32 v138, 0x1000, v138
	v_mad_i64_i32 v[138:139], s[24:25], v138, s13, v[130:131]
	v_cvt_pk_bf16_f32 v140, v77, v73
	v_cvt_pk_bf16_f32 v141, v69, v65
	global_store_dwordx2 v[138:139], v[140:141], off
	v_mad_i64_i32 v[142:143], s[24:25], v142, s14, v[128:129]
	v_mov_b32_e32 v138, v77
	v_mov_b32_e32 v139, v73
	v_mov_b32_e32 v140, v69
	v_mov_b32_e32 v141, v65
	global_store_dwordx4 v[142:143], v[138:141], off nt
	v_add_u32_e32 v142, 50, v134
	s_nop 0
	v_lshrrev_b32_e32 v138, 5, v142
	v_mul_lo_u32 v138, v138, s12
	v_and_or_b32 v138, v142, 30, v138
	v_add_u32_e32 v138, 0x1000, v138
	v_mad_i64_i32 v[138:139], s[24:25], v138, s13, v[130:131]
	v_cvt_pk_bf16_f32 v140, v78, v74
	v_cvt_pk_bf16_f32 v141, v70, v66
	global_store_dwordx2 v[138:139], v[140:141], off
	v_mad_i64_i32 v[142:143], s[24:25], v142, s14, v[128:129]
	v_mov_b32_e32 v138, v78
	v_mov_b32_e32 v139, v74
	v_mov_b32_e32 v140, v70
	v_mov_b32_e32 v141, v66
	global_store_dwordx4 v[142:143], v[138:141], off nt
	v_add_u32_e32 v142, 51, v134
	s_nop 0
	v_lshrrev_b32_e32 v138, 5, v142
	v_mul_lo_u32 v138, v138, s12
	v_and_or_b32 v138, v142, 31, v138
	v_add_u32_e32 v138, 0x1000, v138
	v_mad_i64_i32 v[138:139], s[24:25], v138, s13, v[130:131]
	v_cvt_pk_bf16_f32 v140, v79, v75
	v_cvt_pk_bf16_f32 v141, v71, v67
	global_store_dwordx2 v[138:139], v[140:141], off
	v_mad_i64_i32 v[142:143], s[24:25], v142, s14, v[128:129]
	v_mov_b32_e32 v138, v79
	v_mov_b32_e32 v139, v75
	v_mov_b32_e32 v140, v71
	v_mov_b32_e32 v141, v67
	global_store_dwordx4 v[142:143], v[138:141], off nt
	v_add_u32_e32 v142, 64, v134
	s_nop 0
	v_lshrrev_b32_e32 v138, 5, v142
	v_mul_lo_u32 v138, v138, s12
	v_or_b32_e32 v138, v138, v137
	v_add_u32_e32 v138, 0x1000, v138
	v_mad_i64_i32 v[138:139], s[24:25], v138, s13, v[130:131]
	v_cvt_pk_bf16_f32 v140, v60, v56
	v_cvt_pk_bf16_f32 v141, v52, v48
	global_store_dwordx2 v[138:139], v[140:141], off
	v_mad_i64_i32 v[142:143], s[24:25], v142, s14, v[128:129]
	v_mov_b32_e32 v138, v60
	v_mov_b32_e32 v139, v56
	v_mov_b32_e32 v140, v52
	v_mov_b32_e32 v141, v48
	global_store_dwordx4 v[142:143], v[138:141], off nt
	v_add_u32_e32 v142, 0x41, v134
	s_nop 0
	v_lshrrev_b32_e32 v138, 5, v142
	v_mul_lo_u32 v138, v138, s12
	v_and_or_b32 v138, v142, 29, v138
	v_add_u32_e32 v138, 0x1000, v138
	v_mad_i64_i32 v[138:139], s[24:25], v138, s13, v[130:131]
	v_cvt_pk_bf16_f32 v140, v61, v57
	v_cvt_pk_bf16_f32 v141, v53, v49
	global_store_dwordx2 v[138:139], v[140:141], off
	v_mad_i64_i32 v[142:143], s[24:25], v142, s14, v[128:129]
	v_mov_b32_e32 v138, v61
	v_mov_b32_e32 v139, v57
	v_mov_b32_e32 v140, v53
	v_mov_b32_e32 v141, v49
	global_store_dwordx4 v[142:143], v[138:141], off nt
	v_add_u32_e32 v142, 0x42, v134
	s_nop 0
	v_lshrrev_b32_e32 v138, 5, v142
	v_mul_lo_u32 v138, v138, s12
	v_and_or_b32 v138, v142, 30, v138
	v_add_u32_e32 v138, 0x1000, v138
	v_mad_i64_i32 v[138:139], s[24:25], v138, s13, v[130:131]
	v_cvt_pk_bf16_f32 v140, v62, v58
	v_cvt_pk_bf16_f32 v141, v54, v50
	global_store_dwordx2 v[138:139], v[140:141], off
	v_mad_i64_i32 v[142:143], s[24:25], v142, s14, v[128:129]
	v_mov_b32_e32 v138, v62
	v_mov_b32_e32 v139, v58
	v_mov_b32_e32 v140, v54
	v_mov_b32_e32 v141, v50
	global_store_dwordx4 v[142:143], v[138:141], off nt
	v_add_u32_e32 v142, 0x43, v134
	s_nop 0
	v_lshrrev_b32_e32 v138, 5, v142
	v_mul_lo_u32 v138, v138, s12
	v_and_or_b32 v138, v142, 31, v138
	v_add_u32_e32 v138, 0x1000, v138
	v_mad_i64_i32 v[138:139], s[24:25], v138, s13, v[130:131]
	v_cvt_pk_bf16_f32 v140, v63, v59
	v_cvt_pk_bf16_f32 v141, v55, v51
	global_store_dwordx2 v[138:139], v[140:141], off
	v_mad_i64_i32 v[142:143], s[24:25], v142, s14, v[128:129]
	v_mov_b32_e32 v138, v63
	v_mov_b32_e32 v139, v59
	v_mov_b32_e32 v140, v55
	v_mov_b32_e32 v141, v51
	global_store_dwordx4 v[142:143], v[138:141], off nt
	v_add_u32_e32 v142, 0x50, v134
	s_nop 0
	v_lshrrev_b32_e32 v138, 5, v142
	v_mul_lo_u32 v138, v138, s12
	v_and_or_b32 v138, v142, 28, v138
	v_add_u32_e32 v138, 0x1000, v138
	v_mad_i64_i32 v[138:139], s[24:25], v138, s13, v[130:131]
	v_cvt_pk_bf16_f32 v140, v44, v40
	v_cvt_pk_bf16_f32 v141, v36, v32
	global_store_dwordx2 v[138:139], v[140:141], off
	v_mad_i64_i32 v[142:143], s[24:25], v142, s14, v[128:129]
	v_mov_b32_e32 v138, v44
	v_mov_b32_e32 v139, v40
	v_mov_b32_e32 v140, v36
	v_mov_b32_e32 v141, v32
	global_store_dwordx4 v[142:143], v[138:141], off nt
	v_add_u32_e32 v142, 0x51, v134
	s_nop 0
	v_lshrrev_b32_e32 v138, 5, v142
	v_mul_lo_u32 v138, v138, s12
	v_and_or_b32 v138, v142, 29, v138
	v_add_u32_e32 v138, 0x1000, v138
	v_mad_i64_i32 v[138:139], s[24:25], v138, s13, v[130:131]
	v_cvt_pk_bf16_f32 v140, v45, v41
	v_cvt_pk_bf16_f32 v141, v37, v33
	global_store_dwordx2 v[138:139], v[140:141], off
	v_mad_i64_i32 v[142:143], s[24:25], v142, s14, v[128:129]
	v_mov_b32_e32 v138, v45
	v_mov_b32_e32 v139, v41
	v_mov_b32_e32 v140, v37
	v_mov_b32_e32 v141, v33
	global_store_dwordx4 v[142:143], v[138:141], off nt
	v_add_u32_e32 v142, 0x52, v134
	s_nop 0
	v_lshrrev_b32_e32 v138, 5, v142
	v_mul_lo_u32 v138, v138, s12
	v_and_or_b32 v138, v142, 30, v138
	v_add_u32_e32 v138, 0x1000, v138
	v_mad_i64_i32 v[138:139], s[24:25], v138, s13, v[130:131]
	v_cvt_pk_bf16_f32 v140, v46, v42
	v_cvt_pk_bf16_f32 v141, v38, v34
	global_store_dwordx2 v[138:139], v[140:141], off
	v_mad_i64_i32 v[142:143], s[24:25], v142, s14, v[128:129]
	v_mov_b32_e32 v138, v46
	v_mov_b32_e32 v139, v42
	v_mov_b32_e32 v140, v38
	v_mov_b32_e32 v141, v34
	global_store_dwordx4 v[142:143], v[138:141], off nt
	v_add_u32_e32 v142, 0x53, v134
	s_nop 0
	v_lshrrev_b32_e32 v138, 5, v142
	v_mul_lo_u32 v138, v138, s12
	v_and_or_b32 v138, v142, 31, v138
	v_add_u32_e32 v138, 0x1000, v138
	v_mad_i64_i32 v[138:139], s[24:25], v138, s13, v[130:131]
	v_cvt_pk_bf16_f32 v140, v47, v43
	v_cvt_pk_bf16_f32 v141, v39, v35
	global_store_dwordx2 v[138:139], v[140:141], off
	v_mad_i64_i32 v[142:143], s[24:25], v142, s14, v[128:129]
	v_mov_b32_e32 v138, v47
	v_mov_b32_e32 v139, v43
	v_mov_b32_e32 v140, v39
	v_mov_b32_e32 v141, v35
	global_store_dwordx4 v[142:143], v[138:141], off nt
	v_add_u32_e32 v142, 0x60, v134
	s_nop 0
	v_lshrrev_b32_e32 v138, 5, v142
	v_mul_lo_u32 v138, v138, s12
	v_or_b32_e32 v137, v138, v137
	v_add_u32_e32 v137, 0x1000, v137
	v_mad_i64_i32 v[138:139], s[24:25], v137, s13, v[130:131]
	v_cvt_pk_bf16_f32 v140, v28, v24
	v_cvt_pk_bf16_f32 v141, v20, v16
	global_store_dwordx2 v[138:139], v[140:141], off
	v_mad_i64_i32 v[142:143], s[24:25], v142, s14, v[128:129]
	v_mov_b32_e32 v138, v28
	v_mov_b32_e32 v139, v24
	v_mov_b32_e32 v140, v20
	v_mov_b32_e32 v141, v16
	global_store_dwordx4 v[142:143], v[138:141], off nt
	v_add_u32_e32 v137, 0x61, v134
	s_nop 0
	v_lshrrev_b32_e32 v138, 5, v137
	v_mul_lo_u32 v138, v138, s12
	v_and_or_b32 v138, v137, 29, v138
	v_add_u32_e32 v138, 0x1000, v138
	v_mad_i64_i32 v[138:139], s[24:25], v138, s13, v[130:131]
	v_cvt_pk_bf16_f32 v140, v29, v25
	v_cvt_pk_bf16_f32 v141, v21, v17
	global_store_dwordx2 v[138:139], v[140:141], off
	v_mad_i64_i32 v[142:143], s[24:25], v137, s14, v[128:129]
	v_mov_b32_e32 v138, v29
	v_mov_b32_e32 v139, v25
	v_mov_b32_e32 v140, v21
	v_mov_b32_e32 v141, v17
	global_store_dwordx4 v[142:143], v[138:141], off nt
	v_add_u32_e32 v137, 0x62, v134
	s_nop 0
	v_lshrrev_b32_e32 v138, 5, v137
	v_mul_lo_u32 v138, v138, s12
	v_and_or_b32 v138, v137, 30, v138
	v_add_u32_e32 v138, 0x1000, v138
	v_mad_i64_i32 v[138:139], s[24:25], v138, s13, v[130:131]
	v_cvt_pk_bf16_f32 v140, v30, v26
	v_cvt_pk_bf16_f32 v141, v22, v18
	global_store_dwordx2 v[138:139], v[140:141], off
	v_mad_i64_i32 v[142:143], s[24:25], v137, s14, v[128:129]
	v_mov_b32_e32 v138, v30
	v_mov_b32_e32 v139, v26
	v_mov_b32_e32 v140, v22
	v_mov_b32_e32 v141, v18
	global_store_dwordx4 v[142:143], v[138:141], off nt
	v_add_u32_e32 v137, 0x63, v134
	s_nop 0
	v_lshrrev_b32_e32 v138, 5, v137
	v_mul_lo_u32 v138, v138, s12
	v_and_or_b32 v138, v137, 31, v138
	v_add_u32_e32 v138, 0x1000, v138
	v_mad_i64_i32 v[138:139], s[24:25], v138, s13, v[130:131]
	v_cvt_pk_bf16_f32 v140, v31, v27
	v_cvt_pk_bf16_f32 v141, v23, v19
	global_store_dwordx2 v[138:139], v[140:141], off
	v_mad_i64_i32 v[142:143], s[24:25], v137, s14, v[128:129]
	v_mov_b32_e32 v138, v31
	v_mov_b32_e32 v139, v27
	v_mov_b32_e32 v140, v23
	v_mov_b32_e32 v141, v19
	global_store_dwordx4 v[142:143], v[138:141], off nt
	v_add_u32_e32 v137, 0x70, v134
	s_nop 0
	v_lshrrev_b32_e32 v138, 5, v137
	v_mul_lo_u32 v138, v138, s12
	v_and_or_b32 v138, v137, 28, v138
	v_add_u32_e32 v138, 0x1000, v138
	v_mad_i64_i32 v[138:139], s[24:25], v138, s13, v[130:131]
	v_cvt_pk_bf16_f32 v140, v12, v8
	v_cvt_pk_bf16_f32 v141, v4, v0
	global_store_dwordx2 v[138:139], v[140:141], off
	v_mad_i64_i32 v[142:143], s[24:25], v137, s14, v[128:129]
	v_mov_b32_e32 v138, v12
	v_mov_b32_e32 v139, v8
	v_mov_b32_e32 v140, v4
	v_mov_b32_e32 v141, v0
	global_store_dwordx4 v[142:143], v[138:141], off nt
	v_add_u32_e32 v137, 0x71, v134
	s_nop 0
	v_lshrrev_b32_e32 v138, 5, v137
	v_mul_lo_u32 v138, v138, s12
	v_and_or_b32 v138, v137, 29, v138
	v_add_u32_e32 v138, 0x1000, v138
	v_mad_i64_i32 v[138:139], s[24:25], v138, s13, v[130:131]
	v_cvt_pk_bf16_f32 v140, v13, v9
	v_cvt_pk_bf16_f32 v141, v5, v1
	global_store_dwordx2 v[138:139], v[140:141], off
	v_mad_i64_i32 v[142:143], s[24:25], v137, s14, v[128:129]
	v_mov_b32_e32 v138, v13
	v_mov_b32_e32 v139, v9
	v_mov_b32_e32 v140, v5
	v_mov_b32_e32 v141, v1
	global_store_dwordx4 v[142:143], v[138:141], off nt
	v_add_u32_e32 v137, 0x72, v134
	s_nop 0
	v_lshrrev_b32_e32 v138, 5, v137
	v_mul_lo_u32 v138, v138, s12
	v_and_or_b32 v138, v137, 30, v138
	v_add_u32_e32 v138, 0x1000, v138
	v_mad_i64_i32 v[138:139], s[24:25], v138, s13, v[130:131]
	v_cvt_pk_bf16_f32 v140, v14, v10
	v_cvt_pk_bf16_f32 v141, v6, v2
	global_store_dwordx2 v[138:139], v[140:141], off
	v_mad_i64_i32 v[142:143], s[24:25], v137, s14, v[128:129]
	v_mov_b32_e32 v138, v14
	v_mov_b32_e32 v139, v10
	v_mov_b32_e32 v140, v6
	v_mov_b32_e32 v141, v2
	global_store_dwordx4 v[142:143], v[138:141], off nt
	v_add_u32_e32 v134, 0x73, v134
	v_lshrrev_b32_e32 v137, 5, v134
	v_mul_lo_u32 v137, v137, s12
	v_and_or_b32 v137, v134, 31, v137
	v_add_u32_e32 v137, 0x1000, v137
	v_mad_i64_i32 v[130:131], s[24:25], v137, s13, v[130:131]
	v_cvt_pk_bf16_f32 v138, v15, v11
	v_cvt_pk_bf16_f32 v139, v7, v3
	global_store_dwordx2 v[130:131], v[138:139], off
	v_mad_i64_i32 v[138:139], s[24:25], v134, s14, v[128:129]
	v_mov_b32_e32 v128, v15
	v_mov_b32_e32 v129, v11
	v_mov_b32_e32 v130, v7
	v_mov_b32_e32 v131, v3
	global_store_dwordx4 v[138:139], v[128:131], off nt
	s_xor_b64 s[34:35], exec, -1

.LBB0_238:
	s_andn2_saveexec_b64 s[74:75], s[74:75]
	s_cbranch_execz .LBB0_240
	v_mbcnt_hi_u32_b32 v129, -1, v204
	v_and_b32_e32 v131, 64, v129
	v_xor_b32_e32 v130, 8, v129
	v_add_u32_e32 v131, 64, v131
	v_cmp_lt_i32_e32 vcc, v130, v131
	v_readlane_b32 s36, v253, 26
	v_readlane_b32 s24, v253, 18
	v_lshlrev_b32_e32 v128, 2, v178
	v_cndmask_b32_e32 v129, v129, v130, vcc
	v_cmp_gt_u32_e32 vcc, 8, v176
	v_ashrrev_i32_e32 v137, 31, v136
	v_readlane_b32 s38, v253, 28
	v_readlane_b32 s39, v253, 29
	v_readlane_b32 s25, v253, 19
	v_add_u32_e32 v154, v128, v211
	v_lshlrev_b32_e32 v153, 2, v129
	v_cndmask_b32_e64 v152, 1.0, -1.0, vcc
	v_readlane_b32 s37, v253, 27
	v_readlane_b32 s40, v253, 30
	v_readlane_b32 s41, v253, 31
	v_readlane_b32 s42, v253, 32
	v_readlane_b32 s43, v253, 33
	v_readlane_b32 s44, v253, 34
	v_readlane_b32 s45, v253, 35
	v_readlane_b32 s46, v253, 36
	v_readlane_b32 s47, v253, 37
	v_readlane_b32 s48, v253, 38
	v_readlane_b32 s49, v253, 39
	v_readlane_b32 s50, v253, 40
	v_readlane_b32 s51, v253, 41
	v_lshl_add_u64 v[138:139], v[136:137], 1, s[38:39]
	v_lshl_add_u64 v[140:141], v[136:137], 2, s[24:25]
	v_lshrrev_b32_e32 v129, 5, v154
	v_and_b32_e32 v137, 28, v128
	v_mul_lo_u32 v128, v129, s12
	v_add_u32_e32 v155, 0x1000, v128
	v_lshlrev_b32_e32 v128, 5, v174
	v_and_b32_e32 v134, 0xe0, v128
	v_lshl_add_u64 v[142:143], s[58:59], 0, v[134:135]
	v_lshlrev_b32_e32 v134, 8, v137
	v_lshl_add_u64 v[144:145], v[142:143], 0, v[134:135]
	v_add_co_u32_e32 v146, vcc, s33, v144
	ds_bpermute_b32 v134, v153, v124
	s_nop 0
	v_addc_co_u32_e32 v147, vcc, 0, v145, vcc
	global_load_dwordx3 v[160:162], v[146:147], off offset:256
	global_load_dwordx4 v[128:131], v[146:147], off offset:268
	global_load_dword v149, v[146:147], off offset:284
	v_lshl_add_u64 v[144:145], v[144:145], 0, s[84:85]
	v_mov_b32_e32 v180, v116
	v_or_b32_e32 v148, v155, v137
	s_waitcnt lgkmcnt(0)
	v_mul_f32_e32 v170, v152, v134
	v_mov_b32_e32 v172, v124
	v_or_b32_e32 v134, 1, v154
	v_mad_i64_i32 v[182:183], s[24:25], v148, s13, v[138:139]
	v_mov_b32_e32 v171, v120
	v_and_or_b32 v148, v134, 29, v155
	v_mad_i64_i32 v[184:185], s[24:25], v154, s14, v[140:141]
	s_waitcnt vmcnt(2)
	v_mov_b32_e32 v150, v161
	v_mov_b32_e32 v151, v162
	global_load_dwordx3 v[162:164], v[146:147], off offset:20
	global_load_dwordx4 v[156:159], v[146:147], off
	global_load_dword v166, v[144:145], off offset:16
	ds_bpermute_b32 v161, v153, v112
	s_waitcnt lgkmcnt(0)
	v_mul_f32_e32 v181, v152, v161
	ds_bpermute_b32 v161, v153, v125
	s_waitcnt vmcnt(2)
	v_mov_b32_e32 v167, v164
	s_waitcnt vmcnt(1)
	v_mov_b32_e32 v168, v157
	v_mov_b32_e32 v169, v158
	ds_bpermute_b32 v157, v153, v120
	ds_bpermute_b32 v158, v153, v116
	s_waitcnt vmcnt(0)
	v_pk_mul_f32 v[164:165], v[180:181], v[166:167]
	ds_bpermute_b32 v167, v153, v113
	v_mad_i64_i32 v[180:181], s[24:25], v134, s14, v[140:141]
	s_waitcnt lgkmcnt(2)
	v_mul_f32_e32 v173, v152, v157
	s_waitcnt lgkmcnt(1)
	v_mul_f32_e32 v158, v152, v158
	v_mov_b32_e32 v157, v159
	v_mov_b32_e32 v159, v112
	v_pk_fma_f32 v[158:159], v[162:163], v[158:159], v[164:165]
	ds_bpermute_b32 v163, v153, v121
	ds_bpermute_b32 v164, v153, v117
	v_pk_mul_f32 v[156:157], v[172:173], v[156:157]
	v_mul_f32_e32 v162, v152, v161
	v_pk_fma_f32 v[156:157], v[168:169], v[170:171], v[156:157]
	s_waitcnt lgkmcnt(1)
	v_mul_f32_e32 v165, v152, v163
	s_waitcnt lgkmcnt(0)
	v_mul_f32_e32 v166, v152, v164
	v_mul_f32_e32 v171, v152, v167
	v_mad_i64_i32 v[172:173], s[24:25], v148, s13, v[138:139]
	v_mov_b32_e32 v164, v125
	v_mov_b32_e32 v161, v128
	v_mov_b32_e32 v170, v117
	v_mov_b32_e32 v148, v129
	v_cvt_pk_bf16_f32 v168, v156, v157
	v_cvt_pk_bf16_f32 v169, v158, v159
	v_mov_b32_e32 v163, v121
	v_pk_mul_f32 v[160:161], v[164:165], v[160:161]
	v_mov_b32_e32 v167, v113
	v_pk_mul_f32 v[148:149], v[170:171], v[148:149]
	v_pk_fma_f32 v[160:161], v[150:151], v[162:163], v[160:161]
	v_pk_fma_f32 v[162:163], v[130:131], v[166:167], v[148:149]
	v_cvt_pk_bf16_f32 v128, v160, v161
	global_store_dwordx2 v[182:183], v[168:169], off
	global_store_dwordx4 v[184:185], v[156:159], off nt
	v_cvt_pk_bf16_f32 v129, v162, v163
	global_store_dwordx2 v[172:173], v[128:129], off
	global_store_dwordx4 v[180:181], v[160:163], off nt
	v_bitop3_b32 v128, v154, 30, 2 bitop3:0xc8
	v_lshlrev_b32_e32 v134, 8, v128
	v_lshl_add_u64 v[150:151], v[142:143], 0, v[134:135]
	v_add_co_u32_e32 v156, vcc, s33, v150
	v_or_b32_e32 v165, v155, v128
	s_nop 0
	v_addc_co_u32_e32 v157, vcc, 0, v151, vcc
	global_load_dwordx3 v[160:162], v[156:157], off offset:256
	v_lshl_add_u64 v[150:151], v[150:151], 0, s[84:85]
	global_load_dwordx4 v[128:131], v[156:157], off offset:268
	global_load_dword v149, v[156:157], off offset:284
	ds_bpermute_b32 v134, v153, v126
	v_mov_b32_e32 v180, v118
	v_or_b32_e32 v148, 2, v154
	v_mad_i64_i32 v[184:185], s[24:25], v148, s14, v[140:141]
	s_waitcnt lgkmcnt(0)
	v_mul_f32_e32 v170, v152, v134
	v_or_b32_e32 v134, 3, v154
	v_and_or_b32 v148, v134, 31, v155
	ds_bpermute_b32 v155, v153, v119
	v_mov_b32_e32 v172, v126
	v_mov_b32_e32 v171, v122
	v_mad_i64_i32 v[182:183], s[24:25], v165, s13, v[138:139]
	v_mov_b32_e32 v165, v115
	s_waitcnt vmcnt(2)
	v_mov_b32_e32 v167, v162
	v_mov_b32_e32 v166, v161
	global_load_dwordx3 v[162:164], v[156:157], off offset:20
	s_nop 0
	global_load_dwordx4 v[156:159], v[156:157], off
	s_nop 0
	global_load_dword v150, v[150:151], off offset:16
	ds_bpermute_b32 v151, v153, v122
	ds_bpermute_b32 v161, v153, v114
	s_waitcnt lgkmcnt(1)
	v_mul_f32_e32 v173, v152, v151
	s_waitcnt lgkmcnt(0)
	v_mul_f32_e32 v181, v152, v161
	ds_bpermute_b32 v161, v153, v115
	s_waitcnt vmcnt(2)
	v_mov_b32_e32 v151, v164
	s_waitcnt vmcnt(1)
	v_mov_b32_e32 v168, v157
	ds_bpermute_b32 v157, v153, v118
	v_mov_b32_e32 v169, v158
	s_waitcnt vmcnt(0)
	v_pk_mul_f32 v[150:151], v[180:181], v[150:151]
	v_mul_f32_e32 v164, v152, v155
	v_mad_i64_i32 v[180:181], s[24:25], v134, s14, v[140:141]
	s_waitcnt lgkmcnt(0)
	v_mul_f32_e32 v158, v152, v157
	v_mov_b32_e32 v157, v159
	v_mov_b32_e32 v159, v114
	v_pk_fma_f32 v[158:159], v[162:163], v[158:159], v[150:151]
	ds_bpermute_b32 v151, v153, v123
	ds_bpermute_b32 v150, v153, v127
	v_pk_mul_f32 v[156:157], v[172:173], v[156:157]
	v_mad_i64_i32 v[172:173], s[24:25], v148, s13, v[138:139]
	v_pk_fma_f32 v[156:157], v[168:169], v[170:171], v[156:157]
	s_waitcnt lgkmcnt(1)
	v_mul_f32_e32 v163, v152, v151
	v_mul_f32_e32 v171, v152, v161
	v_mov_b32_e32 v162, v127
	v_mov_b32_e32 v161, v128
	v_mov_b32_e32 v170, v119
	v_mov_b32_e32 v148, v129
	v_cvt_pk_bf16_f32 v168, v156, v157
	v_cvt_pk_bf16_f32 v169, v158, v159
	s_waitcnt lgkmcnt(0)
	v_mul_f32_e32 v150, v152, v150
	v_mov_b32_e32 v151, v123
	v_pk_mul_f32 v[160:161], v[162:163], v[160:161]
	v_pk_mul_f32 v[148:149], v[170:171], v[148:149]
	v_pk_fma_f32 v[160:161], v[166:167], v[150:151], v[160:161]
	v_pk_fma_f32 v[162:163], v[130:131], v[164:165], v[148:149]
	v_cvt_pk_bf16_f32 v128, v160, v161
	global_store_dwordx2 v[182:183], v[168:169], off
	global_store_dwordx4 v[184:185], v[156:159], off nt
	v_cvt_pk_bf16_f32 v129, v162, v163
	global_store_dwordx2 v[172:173], v[128:129], off
	global_store_dwordx4 v[180:181], v[160:163], off nt
	v_add_u32_e32 v148, 16, v154
	v_and_b32_e32 v129, 28, v148
	v_lshlrev_b32_e32 v134, 8, v129
	v_lshl_add_u64 v[150:151], v[142:143], 0, v[134:135]
	v_add_co_u32_e32 v156, vcc, s33, v150
	v_lshrrev_b32_e32 v128, 5, v148
	s_nop 0
	v_addc_co_u32_e32 v157, vcc, 0, v151, vcc
	global_load_dwordx3 v[160:162], v[156:157], off offset:256
	v_mul_lo_u32 v128, v128, s12
	v_or_b32_e32 v128, v128, v129
	v_lshl_add_u64 v[150:151], v[150:151], 0, s[84:85]
	v_add_u32_e32 v155, 0x1000, v128
	global_load_dwordx4 v[128:131], v[156:157], off offset:268
	global_load_dword v149, v[156:157], off offset:284
	ds_bpermute_b32 v134, v153, v108
	v_mov_b32_e32 v180, v100
	v_mad_i64_i32 v[182:183], s[24:25], v155, s13, v[138:139]
	v_mad_i64_i32 v[184:185], s[24:25], v148, s14, v[140:141]
	s_waitcnt lgkmcnt(0)
	v_mul_f32_e32 v170, v152, v134
	v_add_u32_e32 v134, 17, v154
	v_lshrrev_b32_e32 v148, 5, v134
	ds_bpermute_b32 v155, v153, v101
	v_mul_lo_u32 v148, v148, s12
	v_mov_b32_e32 v172, v108
	v_and_or_b32 v148, v134, 29, v148
	v_mov_b32_e32 v171, v104
	v_add_u32_e32 v148, 0x1000, v148
	v_mov_b32_e32 v165, v97
	s_waitcnt vmcnt(2)
	v_mov_b32_e32 v167, v162
	v_mov_b32_e32 v166, v161
	global_load_dwordx3 v[162:164], v[156:157], off offset:20
	s_nop 0
	global_load_dwordx4 v[156:159], v[156:157], off
	s_nop 0
	global_load_dword v150, v[150:151], off offset:16
	ds_bpermute_b32 v151, v153, v104
	ds_bpermute_b32 v161, v153, v96
	s_waitcnt lgkmcnt(1)
	v_mul_f32_e32 v173, v152, v151
	s_waitcnt lgkmcnt(0)
	v_mul_f32_e32 v181, v152, v161
	ds_bpermute_b32 v161, v153, v97
	s_waitcnt vmcnt(2)
	v_mov_b32_e32 v151, v164
	s_waitcnt vmcnt(1)
	v_mov_b32_e32 v168, v157
	ds_bpermute_b32 v157, v153, v100
	v_mov_b32_e32 v169, v158
	s_waitcnt vmcnt(0)
	v_pk_mul_f32 v[150:151], v[180:181], v[150:151]
	v_mul_f32_e32 v164, v152, v155
	v_mad_i64_i32 v[180:181], s[24:25], v134, s14, v[140:141]
	s_waitcnt lgkmcnt(0)
	v_mul_f32_e32 v158, v152, v157
	v_mov_b32_e32 v157, v159
	v_mov_b32_e32 v159, v96
	v_pk_fma_f32 v[158:159], v[162:163], v[158:159], v[150:151]
	ds_bpermute_b32 v151, v153, v105
	ds_bpermute_b32 v150, v153, v109
	v_pk_mul_f32 v[156:157], v[172:173], v[156:157]
	v_mad_i64_i32 v[172:173], s[24:25], v148, s13, v[138:139]
	v_pk_fma_f32 v[156:157], v[168:169], v[170:171], v[156:157]
	s_waitcnt lgkmcnt(1)
	v_mul_f32_e32 v163, v152, v151
	v_mul_f32_e32 v171, v152, v161
	v_mov_b32_e32 v162, v109
	v_mov_b32_e32 v161, v128
	v_mov_b32_e32 v170, v101
	v_mov_b32_e32 v148, v129
	v_cvt_pk_bf16_f32 v168, v156, v157
	v_cvt_pk_bf16_f32 v169, v158, v159
	s_waitcnt lgkmcnt(0)
	v_mul_f32_e32 v150, v152, v150
	v_mov_b32_e32 v151, v105
	v_pk_mul_f32 v[160:161], v[162:163], v[160:161]
	v_pk_mul_f32 v[148:149], v[170:171], v[148:149]
	v_pk_fma_f32 v[160:161], v[166:167], v[150:151], v[160:161]
	v_pk_fma_f32 v[162:163], v[130:131], v[164:165], v[148:149]
	v_cvt_pk_bf16_f32 v128, v160, v161
	global_store_dwordx2 v[182:183], v[168:169], off
	global_store_dwordx4 v[184:185], v[156:159], off nt
	v_cvt_pk_bf16_f32 v129, v162, v163
	global_store_dwordx2 v[172:173], v[128:129], off
	global_store_dwordx4 v[180:181], v[160:163], off nt
	v_add_u32_e32 v148, 18, v154
	v_and_b32_e32 v129, 30, v148
	v_lshlrev_b32_e32 v134, 8, v129
	v_lshl_add_u64 v[150:151], v[142:143], 0, v[134:135]
	v_add_co_u32_e32 v156, vcc, s33, v150
	v_lshrrev_b32_e32 v128, 5, v148
	s_nop 0
	v_addc_co_u32_e32 v157, vcc, 0, v151, vcc
	global_load_dwordx3 v[160:162], v[156:157], off offset:256
	v_mul_lo_u32 v128, v128, s12
	v_or_b32_e32 v128, v128, v129
	v_add_u32_e32 v155, 0x1000, v128
	global_load_dwordx4 v[128:131], v[156:157], off offset:268
	global_load_dword v149, v[156:157], off offset:284
	v_lshl_add_u64 v[150:151], v[150:151], 0, s[84:85]
	ds_bpermute_b32 v134, v153, v110
	v_mov_b32_e32 v182, v102
	v_mad_i64_i32 v[184:185], s[24:25], v155, s13, v[138:139]
	ds_bpermute_b32 v155, v153, v111
	s_waitcnt lgkmcnt(1)
	v_mul_f32_e32 v172, v152, v134
	v_add_u32_e32 v134, 19, v154
	v_mov_b32_e32 v180, v110
	v_mov_b32_e32 v173, v106
	s_waitcnt vmcnt(2)
	v_mov_b32_e32 v167, v162
	v_mov_b32_e32 v166, v161
	global_load_dwordx3 v[162:164], v[156:157], off offset:20
	s_nop 0
	global_load_dwordx4 v[156:159], v[156:157], off
	s_nop 0
	global_load_dword v168, v[150:151], off offset:16
	ds_bpermute_b32 v151, v153, v102
	ds_bpermute_b32 v150, v153, v106
	ds_bpermute_b32 v161, v153, v107
	s_waitcnt lgkmcnt(1)
	v_mul_f32_e32 v181, v152, v150
	s_waitcnt vmcnt(2)
	v_mov_b32_e32 v169, v164
	s_waitcnt vmcnt(1)
	v_mov_b32_e32 v170, v157
	ds_bpermute_b32 v157, v153, v98
	v_mov_b32_e32 v171, v158
	v_mul_f32_e32 v158, v152, v151
	v_mad_i64_i32 v[150:151], s[24:25], v148, s14, v[140:141]
	s_waitcnt lgkmcnt(0)
	v_mul_f32_e32 v183, v152, v157
	v_mov_b32_e32 v157, v159
	v_mov_b32_e32 v159, v98
	s_waitcnt vmcnt(0)
	v_pk_mul_f32 v[164:165], v[182:183], v[168:169]
	v_lshrrev_b32_e32 v148, 5, v134
	v_pk_fma_f32 v[158:159], v[162:163], v[158:159], v[164:165]
	ds_bpermute_b32 v164, v153, v99
	ds_bpermute_b32 v163, v153, v103
	v_mul_lo_u32 v148, v148, s12
	v_and_or_b32 v148, v134, 31, v148
	v_pk_mul_f32 v[156:157], v[180:181], v[156:157]
	v_add_u32_e32 v148, 0x1000, v148
	v_pk_fma_f32 v[156:157], v[170:171], v[172:173], v[156:157]
	v_mul_f32_e32 v165, v152, v161
	s_waitcnt lgkmcnt(1)
	v_mul_f32_e32 v173, v152, v164
	v_mad_i64_i32 v[180:181], s[24:25], v148, s13, v[138:139]
	v_mov_b32_e32 v164, v111
	v_mov_b32_e32 v161, v128
	v_mov_b32_e32 v172, v103
	v_mov_b32_e32 v148, v129
	v_cvt_pk_bf16_f32 v170, v156, v157
	v_cvt_pk_bf16_f32 v171, v158, v159
	v_mul_f32_e32 v162, v152, v155
	s_waitcnt lgkmcnt(0)
	v_mul_f32_e32 v168, v152, v163
	v_mov_b32_e32 v163, v107
	v_pk_mul_f32 v[160:161], v[164:165], v[160:161]
	v_mov_b32_e32 v169, v99
	v_pk_mul_f32 v[148:149], v[172:173], v[148:149]
	v_mad_i64_i32 v[182:183], s[24:25], v134, s14, v[140:141]
	v_pk_fma_f32 v[160:161], v[166:167], v[162:163], v[160:161]
	v_pk_fma_f32 v[162:163], v[130:131], v[168:169], v[148:149]
	v_cvt_pk_bf16_f32 v128, v160, v161
	global_store_dwordx2 v[184:185], v[170:171], off
	global_store_dwordx4 v[150:151], v[156:159], off nt
	v_cvt_pk_bf16_f32 v129, v162, v163
	global_store_dwordx2 v[180:181], v[128:129], off
	global_store_dwordx4 v[182:183], v[160:163], off nt
	v_add_u32_e32 v134, 32, v154
	global_load_dwordx3 v[160:162], v[146:147], off offset:256
	v_lshrrev_b32_e32 v128, 5, v134
	v_mul_lo_u32 v128, v128, s12
	v_or_b32_e32 v128, v128, v137
	v_add_u32_e32 v148, 0x1000, v128
	ds_bpermute_b32 v155, v153, v92
	v_mov_b32_e32 v180, v84
	v_mad_i64_i32 v[184:185], s[24:25], v134, s14, v[140:141]
	v_add_u32_e32 v134, 33, v154
	s_waitcnt lgkmcnt(0)
	v_mul_f32_e32 v170, v152, v155
	v_mad_i64_i32 v[182:183], s[24:25], v148, s13, v[138:139]
	v_lshrrev_b32_e32 v148, 5, v134
	ds_bpermute_b32 v155, v153, v93
	v_mul_lo_u32 v148, v148, s12
	v_mov_b32_e32 v172, v92
	v_and_or_b32 v148, v134, 29, v148
	v_mov_b32_e32 v171, v88
	v_add_u32_e32 v148, 0x1000, v148
	s_waitcnt vmcnt(0)
	v_mov_b32_e32 v150, v161
	v_mov_b32_e32 v151, v162
	global_load_dwordx4 v[128:131], v[146:147], off offset:268
	global_load_dword v149, v[146:147], off offset:284
	global_load_dwordx3 v[162:164], v[146:147], off offset:20
	global_load_dwordx4 v[156:159], v[146:147], off
	global_load_dword v166, v[144:145], off offset:16
	ds_bpermute_b32 v161, v153, v80
	s_waitcnt lgkmcnt(0)
	v_mul_f32_e32 v181, v152, v161
	ds_bpermute_b32 v161, v153, v89
	s_waitcnt vmcnt(2)
	v_mov_b32_e32 v167, v164
	s_waitcnt vmcnt(1)
	v_mov_b32_e32 v168, v157
	v_mov_b32_e32 v169, v158
	ds_bpermute_b32 v157, v153, v88
	ds_bpermute_b32 v158, v153, v84
	s_waitcnt vmcnt(0)
	v_pk_mul_f32 v[164:165], v[180:181], v[166:167]
	v_mov_b32_e32 v167, v81
	v_mad_i64_i32 v[180:181], s[24:25], v134, s14, v[140:141]
	s_waitcnt lgkmcnt(1)
	v_mul_f32_e32 v173, v152, v157
	s_waitcnt lgkmcnt(0)
	v_mul_f32_e32 v158, v152, v158
	v_mov_b32_e32 v157, v159
	v_mov_b32_e32 v159, v80
	v_pk_fma_f32 v[158:159], v[162:163], v[158:159], v[164:165]
	ds_bpermute_b32 v164, v153, v81
	ds_bpermute_b32 v163, v153, v85
	v_pk_mul_f32 v[156:157], v[172:173], v[156:157]
	v_mul_f32_e32 v165, v152, v161
	v_pk_fma_f32 v[156:157], v[168:169], v[170:171], v[156:157]
	s_waitcnt lgkmcnt(1)
	v_mul_f32_e32 v171, v152, v164
	v_mad_i64_i32 v[172:173], s[24:25], v148, s13, v[138:139]
	v_mov_b32_e32 v164, v93
	v_mov_b32_e32 v161, v128
	v_mov_b32_e32 v170, v85
	v_mov_b32_e32 v148, v129
	v_cvt_pk_bf16_f32 v168, v156, v157
	v_cvt_pk_bf16_f32 v169, v158, v159
	v_mul_f32_e32 v162, v152, v155
	s_waitcnt lgkmcnt(0)
	v_mul_f32_e32 v166, v152, v163
	v_mov_b32_e32 v163, v89
	v_pk_mul_f32 v[160:161], v[164:165], v[160:161]
	v_pk_mul_f32 v[148:149], v[170:171], v[148:149]
	v_pk_fma_f32 v[160:161], v[150:151], v[162:163], v[160:161]
	v_pk_fma_f32 v[162:163], v[130:131], v[166:167], v[148:149]
	v_cvt_pk_bf16_f32 v128, v160, v161
	global_store_dwordx2 v[182:183], v[168:169], off
	global_store_dwordx4 v[184:185], v[156:159], off nt
	v_cvt_pk_bf16_f32 v129, v162, v163
	global_store_dwordx2 v[172:173], v[128:129], off
	global_store_dwordx4 v[180:181], v[160:163], off nt
	v_add_u32_e32 v148, 34, v154
	v_and_b32_e32 v129, 30, v148
	v_lshlrev_b32_e32 v134, 8, v129
	v_lshl_add_u64 v[150:151], v[142:143], 0, v[134:135]
	v_add_co_u32_e32 v156, vcc, s33, v150
	v_lshrrev_b32_e32 v128, 5, v148
	s_nop 0
	v_addc_co_u32_e32 v157, vcc, 0, v151, vcc
	global_load_dwordx3 v[160:162], v[156:157], off offset:256
	v_mul_lo_u32 v128, v128, s12
	v_or_b32_e32 v128, v128, v129
	v_add_u32_e32 v155, 0x1000, v128
	global_load_dwordx4 v[128:131], v[156:157], off offset:268
	global_load_dword v149, v[156:157], off offset:284
	v_lshl_add_u64 v[150:151], v[150:151], 0, s[84:85]
	ds_bpermute_b32 v134, v153, v94
	v_mov_b32_e32 v182, v86
	v_mad_i64_i32 v[184:185], s[24:25], v155, s13, v[138:139]
	ds_bpermute_b32 v155, v153, v95
	s_waitcnt lgkmcnt(1)
	v_mul_f32_e32 v172, v152, v134
	v_add_u32_e32 v134, 35, v154
	v_mov_b32_e32 v180, v94
	v_mov_b32_e32 v173, v90
	s_waitcnt vmcnt(2)
	v_mov_b32_e32 v167, v162
	v_mov_b32_e32 v166, v161
	global_load_dwordx3 v[162:164], v[156:157], off offset:20
	s_nop 0
	global_load_dwordx4 v[156:159], v[156:157], off
	s_nop 0
	global_load_dword v168, v[150:151], off offset:16
	ds_bpermute_b32 v151, v153, v86
	ds_bpermute_b32 v150, v153, v90
	ds_bpermute_b32 v161, v153, v91
	s_waitcnt lgkmcnt(1)
	v_mul_f32_e32 v181, v152, v150
	s_waitcnt vmcnt(2)
	v_mov_b32_e32 v169, v164
	s_waitcnt vmcnt(1)
	v_mov_b32_e32 v170, v157
	ds_bpermute_b32 v157, v153, v82
	v_mov_b32_e32 v171, v158
	v_mul_f32_e32 v158, v152, v151
	v_mad_i64_i32 v[150:151], s[24:25], v148, s14, v[140:141]
	s_waitcnt lgkmcnt(0)
	v_mul_f32_e32 v183, v152, v157
	v_mov_b32_e32 v157, v159
	v_mov_b32_e32 v159, v82
	s_waitcnt vmcnt(0)
	v_pk_mul_f32 v[164:165], v[182:183], v[168:169]
	v_lshrrev_b32_e32 v148, 5, v134
	v_pk_fma_f32 v[158:159], v[162:163], v[158:159], v[164:165]
	ds_bpermute_b32 v164, v153, v83
	ds_bpermute_b32 v163, v153, v87
	v_mul_lo_u32 v148, v148, s12
	v_and_or_b32 v148, v134, 31, v148
	v_pk_mul_f32 v[156:157], v[180:181], v[156:157]
	v_add_u32_e32 v148, 0x1000, v148
	v_pk_fma_f32 v[156:157], v[170:171], v[172:173], v[156:157]
	v_mul_f32_e32 v165, v152, v161
	s_waitcnt lgkmcnt(1)
	v_mul_f32_e32 v173, v152, v164
	v_mad_i64_i32 v[180:181], s[24:25], v148, s13, v[138:139]
	v_mov_b32_e32 v164, v95
	v_mov_b32_e32 v161, v128
	v_mov_b32_e32 v172, v87
	v_mov_b32_e32 v148, v129
	v_cvt_pk_bf16_f32 v170, v156, v157
	v_cvt_pk_bf16_f32 v171, v158, v159
	v_mul_f32_e32 v162, v152, v155
	s_waitcnt lgkmcnt(0)
	v_mul_f32_e32 v168, v152, v163
	v_mov_b32_e32 v163, v91
	v_pk_mul_f32 v[160:161], v[164:165], v[160:161]
	v_mov_b32_e32 v169, v83
	v_pk_mul_f32 v[148:149], v[172:173], v[148:149]
	v_mad_i64_i32 v[182:183], s[24:25], v134, s14, v[140:141]
	v_pk_fma_f32 v[160:161], v[166:167], v[162:163], v[160:161]
	v_pk_fma_f32 v[162:163], v[130:131], v[168:169], v[148:149]
	v_cvt_pk_bf16_f32 v128, v160, v161
	global_store_dwordx2 v[184:185], v[170:171], off
	global_store_dwordx4 v[150:151], v[156:159], off nt
	v_cvt_pk_bf16_f32 v129, v162, v163
	global_store_dwordx2 v[180:181], v[128:129], off
	global_store_dwordx4 v[182:183], v[160:163], off nt
	v_add_u32_e32 v148, 48, v154
	v_and_b32_e32 v129, 28, v148
	v_lshlrev_b32_e32 v134, 8, v129
	v_lshl_add_u64 v[150:151], v[142:143], 0, v[134:135]
	v_add_co_u32_e32 v156, vcc, s33, v150
	v_lshrrev_b32_e32 v128, 5, v148
	s_nop 0
	v_addc_co_u32_e32 v157, vcc, 0, v151, vcc
	global_load_dwordx3 v[160:162], v[156:157], off offset:256
	v_mul_lo_u32 v128, v128, s12
	v_or_b32_e32 v128, v128, v129
	v_lshl_add_u64 v[150:151], v[150:151], 0, s[84:85]
	v_add_u32_e32 v155, 0x1000, v128
	global_load_dwordx4 v[128:131], v[156:157], off offset:268
	global_load_dword v149, v[156:157], off offset:284
	ds_bpermute_b32 v134, v153, v76
	v_mov_b32_e32 v180, v68
	v_mad_i64_i32 v[182:183], s[24:25], v155, s13, v[138:139]
	v_mad_i64_i32 v[184:185], s[24:25], v148, s14, v[140:141]
	s_waitcnt lgkmcnt(0)
	v_mul_f32_e32 v170, v152, v134
	v_add_u32_e32 v134, 49, v154
	v_lshrrev_b32_e32 v148, 5, v134
	ds_bpermute_b32 v155, v153, v69
	v_mul_lo_u32 v148, v148, s12
	v_mov_b32_e32 v172, v76
	v_and_or_b32 v148, v134, 29, v148
	v_mov_b32_e32 v171, v72
	v_add_u32_e32 v148, 0x1000, v148
	v_mov_b32_e32 v165, v65
	s_waitcnt vmcnt(2)
	v_mov_b32_e32 v167, v162
	v_mov_b32_e32 v166, v161
	global_load_dwordx3 v[162:164], v[156:157], off offset:20
	s_nop 0
	global_load_dwordx4 v[156:159], v[156:157], off
	s_nop 0
	global_load_dword v150, v[150:151], off offset:16
	ds_bpermute_b32 v151, v153, v72
	ds_bpermute_b32 v161, v153, v64
	s_waitcnt lgkmcnt(1)
	v_mul_f32_e32 v173, v152, v151
	s_waitcnt lgkmcnt(0)
	v_mul_f32_e32 v181, v152, v161
	ds_bpermute_b32 v161, v153, v65
	s_waitcnt vmcnt(2)
	v_mov_b32_e32 v151, v164
	s_waitcnt vmcnt(1)
	v_mov_b32_e32 v168, v157
	ds_bpermute_b32 v157, v153, v68
	v_mov_b32_e32 v169, v158
	s_waitcnt vmcnt(0)
	v_pk_mul_f32 v[150:151], v[180:181], v[150:151]
	v_mul_f32_e32 v164, v152, v155
	v_mad_i64_i32 v[180:181], s[24:25], v134, s14, v[140:141]
	s_waitcnt lgkmcnt(0)
	v_mul_f32_e32 v158, v152, v157
	v_mov_b32_e32 v157, v159
	v_mov_b32_e32 v159, v64
	v_pk_fma_f32 v[158:159], v[162:163], v[158:159], v[150:151]
	ds_bpermute_b32 v151, v153, v73
	ds_bpermute_b32 v150, v153, v77
	v_pk_mul_f32 v[156:157], v[172:173], v[156:157]
	v_mad_i64_i32 v[172:173], s[24:25], v148, s13, v[138:139]
	v_pk_fma_f32 v[156:157], v[168:169], v[170:171], v[156:157]
	s_waitcnt lgkmcnt(1)
	v_mul_f32_e32 v163, v152, v151
	v_mul_f32_e32 v171, v152, v161
	v_mov_b32_e32 v162, v77
	v_mov_b32_e32 v161, v128
	v_mov_b32_e32 v170, v69
	v_mov_b32_e32 v148, v129
	v_cvt_pk_bf16_f32 v168, v156, v157
	v_cvt_pk_bf16_f32 v169, v158, v159
	s_waitcnt lgkmcnt(0)
	v_mul_f32_e32 v150, v152, v150
	v_mov_b32_e32 v151, v73
	v_pk_mul_f32 v[160:161], v[162:163], v[160:161]
	v_pk_mul_f32 v[148:149], v[170:171], v[148:149]
	v_pk_fma_f32 v[160:161], v[166:167], v[150:151], v[160:161]
	v_pk_fma_f32 v[162:163], v[130:131], v[164:165], v[148:149]
	v_cvt_pk_bf16_f32 v128, v160, v161
	global_store_dwordx2 v[182:183], v[168:169], off
	global_store_dwordx4 v[184:185], v[156:159], off nt
	v_cvt_pk_bf16_f32 v129, v162, v163
	global_store_dwordx2 v[172:173], v[128:129], off
	global_store_dwordx4 v[180:181], v[160:163], off nt
	v_add_u32_e32 v148, 50, v154
	v_and_b32_e32 v129, 30, v148
	v_lshlrev_b32_e32 v134, 8, v129
	v_lshl_add_u64 v[150:151], v[142:143], 0, v[134:135]
	v_add_co_u32_e32 v156, vcc, s33, v150
	v_lshrrev_b32_e32 v128, 5, v148
	s_nop 0
	v_addc_co_u32_e32 v157, vcc, 0, v151, vcc
	global_load_dwordx3 v[160:162], v[156:157], off offset:256
	v_mul_lo_u32 v128, v128, s12
	v_or_b32_e32 v128, v128, v129
	v_add_u32_e32 v155, 0x1000, v128
	global_load_dwordx4 v[128:131], v[156:157], off offset:268
	global_load_dword v149, v[156:157], off offset:284
	v_lshl_add_u64 v[150:151], v[150:151], 0, s[84:85]
	ds_bpermute_b32 v134, v153, v78
	v_mov_b32_e32 v182, v70
	v_mad_i64_i32 v[184:185], s[24:25], v155, s13, v[138:139]
	ds_bpermute_b32 v155, v153, v79
	s_waitcnt lgkmcnt(1)
	v_mul_f32_e32 v172, v152, v134
	v_add_u32_e32 v134, 51, v154
	v_mov_b32_e32 v180, v78
	v_mov_b32_e32 v173, v74
	s_waitcnt vmcnt(2)
	v_mov_b32_e32 v167, v162
	v_mov_b32_e32 v166, v161
	global_load_dwordx3 v[162:164], v[156:157], off offset:20
	s_nop 0
	global_load_dwordx4 v[156:159], v[156:157], off
	s_nop 0
	global_load_dword v168, v[150:151], off offset:16
	ds_bpermute_b32 v151, v153, v70
	ds_bpermute_b32 v150, v153, v74
	ds_bpermute_b32 v161, v153, v75
	s_waitcnt lgkmcnt(1)
	v_mul_f32_e32 v181, v152, v150
	s_waitcnt vmcnt(2)
	v_mov_b32_e32 v169, v164
	s_waitcnt vmcnt(1)
	v_mov_b32_e32 v170, v157
	ds_bpermute_b32 v157, v153, v66
	v_mov_b32_e32 v171, v158
	v_mul_f32_e32 v158, v152, v151
	v_mad_i64_i32 v[150:151], s[24:25], v148, s14, v[140:141]
	s_waitcnt lgkmcnt(0)
	v_mul_f32_e32 v183, v152, v157
	v_mov_b32_e32 v157, v159
	v_mov_b32_e32 v159, v66
	s_waitcnt vmcnt(0)
	v_pk_mul_f32 v[164:165], v[182:183], v[168:169]
	v_lshrrev_b32_e32 v148, 5, v134
	v_pk_fma_f32 v[158:159], v[162:163], v[158:159], v[164:165]
	ds_bpermute_b32 v164, v153, v67
	ds_bpermute_b32 v163, v153, v71
	v_mul_lo_u32 v148, v148, s12
	v_and_or_b32 v148, v134, 31, v148
	v_pk_mul_f32 v[156:157], v[180:181], v[156:157]
	v_add_u32_e32 v148, 0x1000, v148
	v_pk_fma_f32 v[156:157], v[170:171], v[172:173], v[156:157]
	v_mul_f32_e32 v165, v152, v161
	s_waitcnt lgkmcnt(1)
	v_mul_f32_e32 v173, v152, v164
	v_mad_i64_i32 v[180:181], s[24:25], v148, s13, v[138:139]
	v_mov_b32_e32 v164, v79
	v_mov_b32_e32 v161, v128
	v_mov_b32_e32 v172, v71
	v_mov_b32_e32 v148, v129
	v_cvt_pk_bf16_f32 v170, v156, v157
	v_cvt_pk_bf16_f32 v171, v158, v159
	v_mul_f32_e32 v162, v152, v155
	s_waitcnt lgkmcnt(0)
	v_mul_f32_e32 v168, v152, v163
	v_mov_b32_e32 v163, v75
	v_pk_mul_f32 v[160:161], v[164:165], v[160:161]
	v_mov_b32_e32 v169, v67
	v_pk_mul_f32 v[148:149], v[172:173], v[148:149]
	v_mad_i64_i32 v[182:183], s[24:25], v134, s14, v[140:141]
	v_pk_fma_f32 v[160:161], v[166:167], v[162:163], v[160:161]
	v_pk_fma_f32 v[162:163], v[130:131], v[168:169], v[148:149]
	v_cvt_pk_bf16_f32 v128, v160, v161
	global_store_dwordx2 v[184:185], v[170:171], off
	global_store_dwordx4 v[150:151], v[156:159], off nt
	v_cvt_pk_bf16_f32 v129, v162, v163
	global_store_dwordx2 v[180:181], v[128:129], off
	global_store_dwordx4 v[182:183], v[160:163], off nt
	v_add_u32_e32 v134, 64, v154
	global_load_dwordx3 v[160:162], v[146:147], off offset:256
	v_lshrrev_b32_e32 v128, 5, v134
	v_mul_lo_u32 v128, v128, s12
	v_or_b32_e32 v128, v128, v137
	v_add_u32_e32 v148, 0x1000, v128
	ds_bpermute_b32 v155, v153, v60
	v_mov_b32_e32 v180, v52
	v_mad_i64_i32 v[184:185], s[24:25], v134, s14, v[140:141]
	v_add_u32_e32 v134, 0x41, v154
	s_waitcnt lgkmcnt(0)
	v_mul_f32_e32 v170, v152, v155
	v_mad_i64_i32 v[182:183], s[24:25], v148, s13, v[138:139]
	v_lshrrev_b32_e32 v148, 5, v134
	ds_bpermute_b32 v155, v153, v61
	v_mul_lo_u32 v148, v148, s12
	v_mov_b32_e32 v172, v60
	v_and_or_b32 v148, v134, 29, v148
	v_mov_b32_e32 v171, v56
	v_add_u32_e32 v148, 0x1000, v148
	s_waitcnt vmcnt(0)
	v_mov_b32_e32 v150, v161
	v_mov_b32_e32 v151, v162
	global_load_dwordx4 v[128:131], v[146:147], off offset:268
	global_load_dword v149, v[146:147], off offset:284
	global_load_dwordx3 v[162:164], v[146:147], off offset:20
	global_load_dwordx4 v[156:159], v[146:147], off
	global_load_dword v166, v[144:145], off offset:16
	ds_bpermute_b32 v161, v153, v48
	s_waitcnt lgkmcnt(0)
	v_mul_f32_e32 v181, v152, v161
	ds_bpermute_b32 v161, v153, v57
	s_waitcnt vmcnt(2)
	v_mov_b32_e32 v167, v164
	s_waitcnt vmcnt(1)
	v_mov_b32_e32 v168, v157
	v_mov_b32_e32 v169, v158
	ds_bpermute_b32 v157, v153, v56
	ds_bpermute_b32 v158, v153, v52
	s_waitcnt vmcnt(0)
	v_pk_mul_f32 v[164:165], v[180:181], v[166:167]
	v_mov_b32_e32 v167, v49
	v_mad_i64_i32 v[180:181], s[24:25], v134, s14, v[140:141]
	s_waitcnt lgkmcnt(1)
	v_mul_f32_e32 v173, v152, v157
	s_waitcnt lgkmcnt(0)
	v_mul_f32_e32 v158, v152, v158
	v_mov_b32_e32 v157, v159
	v_mov_b32_e32 v159, v48
	v_pk_fma_f32 v[158:159], v[162:163], v[158:159], v[164:165]
	ds_bpermute_b32 v164, v153, v49
	ds_bpermute_b32 v163, v153, v53
	v_pk_mul_f32 v[156:157], v[172:173], v[156:157]
	v_mul_f32_e32 v165, v152, v161
	v_pk_fma_f32 v[156:157], v[168:169], v[170:171], v[156:157]
	s_waitcnt lgkmcnt(1)
	v_mul_f32_e32 v171, v152, v164
	v_mad_i64_i32 v[172:173], s[24:25], v148, s13, v[138:139]
	v_mov_b32_e32 v164, v61
	v_mov_b32_e32 v161, v128
	v_mov_b32_e32 v170, v53
	v_mov_b32_e32 v148, v129
	v_cvt_pk_bf16_f32 v168, v156, v157
	v_cvt_pk_bf16_f32 v169, v158, v159
	v_mul_f32_e32 v162, v152, v155
	s_waitcnt lgkmcnt(0)
	v_mul_f32_e32 v166, v152, v163
	v_mov_b32_e32 v163, v57
	v_pk_mul_f32 v[160:161], v[164:165], v[160:161]
	v_pk_mul_f32 v[148:149], v[170:171], v[148:149]
	v_pk_fma_f32 v[160:161], v[150:151], v[162:163], v[160:161]
	v_pk_fma_f32 v[162:163], v[130:131], v[166:167], v[148:149]
	v_cvt_pk_bf16_f32 v128, v160, v161
	global_store_dwordx2 v[182:183], v[168:169], off
	global_store_dwordx4 v[184:185], v[156:159], off nt
	v_cvt_pk_bf16_f32 v129, v162, v163
	global_store_dwordx2 v[172:173], v[128:129], off
	global_store_dwordx4 v[180:181], v[160:163], off nt
	v_add_u32_e32 v148, 0x42, v154
	v_and_b32_e32 v129, 30, v148
	v_lshlrev_b32_e32 v134, 8, v129
	v_lshl_add_u64 v[150:151], v[142:143], 0, v[134:135]
	v_add_co_u32_e32 v156, vcc, s33, v150
	v_lshrrev_b32_e32 v128, 5, v148
	s_nop 0
	v_addc_co_u32_e32 v157, vcc, 0, v151, vcc
	global_load_dwordx3 v[160:162], v[156:157], off offset:256
	v_mul_lo_u32 v128, v128, s12
	v_or_b32_e32 v128, v128, v129
	v_add_u32_e32 v155, 0x1000, v128
	global_load_dwordx4 v[128:131], v[156:157], off offset:268
	global_load_dword v149, v[156:157], off offset:284
	v_lshl_add_u64 v[150:151], v[150:151], 0, s[84:85]
	ds_bpermute_b32 v134, v153, v62
	v_mov_b32_e32 v182, v54
	v_mad_i64_i32 v[184:185], s[24:25], v155, s13, v[138:139]
	ds_bpermute_b32 v155, v153, v63
	s_waitcnt lgkmcnt(1)
	v_mul_f32_e32 v172, v152, v134
	v_add_u32_e32 v134, 0x43, v154
	v_mov_b32_e32 v180, v62
	v_mov_b32_e32 v173, v58
	s_waitcnt vmcnt(2)
	v_mov_b32_e32 v167, v162
	v_mov_b32_e32 v166, v161
	global_load_dwordx3 v[162:164], v[156:157], off offset:20
	s_nop 0
	global_load_dwordx4 v[156:159], v[156:157], off
	s_nop 0
	global_load_dword v168, v[150:151], off offset:16
	ds_bpermute_b32 v151, v153, v54
	ds_bpermute_b32 v150, v153, v58
	ds_bpermute_b32 v161, v153, v59
	s_waitcnt lgkmcnt(1)
	v_mul_f32_e32 v181, v152, v150
	s_waitcnt vmcnt(2)
	v_mov_b32_e32 v169, v164
	s_waitcnt vmcnt(1)
	v_mov_b32_e32 v170, v157
	ds_bpermute_b32 v157, v153, v50
	v_mov_b32_e32 v171, v158
	v_mul_f32_e32 v158, v152, v151
	v_mad_i64_i32 v[150:151], s[24:25], v148, s14, v[140:141]
	s_waitcnt lgkmcnt(0)
	v_mul_f32_e32 v183, v152, v157
	v_mov_b32_e32 v157, v159
	v_mov_b32_e32 v159, v50
	s_waitcnt vmcnt(0)
	v_pk_mul_f32 v[164:165], v[182:183], v[168:169]
	v_lshrrev_b32_e32 v148, 5, v134
	v_pk_fma_f32 v[158:159], v[162:163], v[158:159], v[164:165]
	ds_bpermute_b32 v164, v153, v51
	ds_bpermute_b32 v163, v153, v55
	v_mul_lo_u32 v148, v148, s12
	v_and_or_b32 v148, v134, 31, v148
	v_pk_mul_f32 v[156:157], v[180:181], v[156:157]
	v_add_u32_e32 v148, 0x1000, v148
	v_pk_fma_f32 v[156:157], v[170:171], v[172:173], v[156:157]
	v_mul_f32_e32 v165, v152, v161
	s_waitcnt lgkmcnt(1)
	v_mul_f32_e32 v173, v152, v164
	v_mad_i64_i32 v[180:181], s[24:25], v148, s13, v[138:139]
	v_mov_b32_e32 v164, v63
	v_mov_b32_e32 v161, v128
	v_mov_b32_e32 v172, v55
	v_mov_b32_e32 v148, v129
	v_cvt_pk_bf16_f32 v170, v156, v157
	v_cvt_pk_bf16_f32 v171, v158, v159
	v_mul_f32_e32 v162, v152, v155
	s_waitcnt lgkmcnt(0)
	v_mul_f32_e32 v168, v152, v163
	v_mov_b32_e32 v163, v59
	v_pk_mul_f32 v[160:161], v[164:165], v[160:161]
	v_mov_b32_e32 v169, v51
	v_pk_mul_f32 v[148:149], v[172:173], v[148:149]
	v_mad_i64_i32 v[182:183], s[24:25], v134, s14, v[140:141]
	v_pk_fma_f32 v[160:161], v[166:167], v[162:163], v[160:161]
	v_pk_fma_f32 v[162:163], v[130:131], v[168:169], v[148:149]
	v_cvt_pk_bf16_f32 v128, v160, v161
	global_store_dwordx2 v[184:185], v[170:171], off
	global_store_dwordx4 v[150:151], v[156:159], off nt
	v_cvt_pk_bf16_f32 v129, v162, v163
	global_store_dwordx2 v[180:181], v[128:129], off
	global_store_dwordx4 v[182:183], v[160:163], off nt
	v_add_u32_e32 v148, 0x50, v154
	v_and_b32_e32 v129, 28, v148
	v_lshlrev_b32_e32 v134, 8, v129
	v_lshl_add_u64 v[150:151], v[142:143], 0, v[134:135]
	v_add_co_u32_e32 v156, vcc, s33, v150
	v_lshrrev_b32_e32 v128, 5, v148
	s_nop 0
	v_addc_co_u32_e32 v157, vcc, 0, v151, vcc
	global_load_dwordx3 v[160:162], v[156:157], off offset:256
	v_mul_lo_u32 v128, v128, s12
	v_or_b32_e32 v128, v128, v129
	v_lshl_add_u64 v[150:151], v[150:151], 0, s[84:85]
	v_add_u32_e32 v155, 0x1000, v128
	global_load_dwordx4 v[128:131], v[156:157], off offset:268
	global_load_dword v149, v[156:157], off offset:284
	ds_bpermute_b32 v134, v153, v44
	v_mov_b32_e32 v180, v36
	v_mad_i64_i32 v[182:183], s[24:25], v155, s13, v[138:139]
	v_mad_i64_i32 v[184:185], s[24:25], v148, s14, v[140:141]
	s_waitcnt lgkmcnt(0)
	v_mul_f32_e32 v170, v152, v134
	v_add_u32_e32 v134, 0x51, v154
	v_lshrrev_b32_e32 v148, 5, v134
	ds_bpermute_b32 v155, v153, v37
	v_mul_lo_u32 v148, v148, s12
	v_mov_b32_e32 v172, v44
	v_and_or_b32 v148, v134, 29, v148
	v_mov_b32_e32 v171, v40
	v_add_u32_e32 v148, 0x1000, v148
	v_mov_b32_e32 v165, v33
	s_waitcnt vmcnt(2)
	v_mov_b32_e32 v167, v162
	v_mov_b32_e32 v166, v161
	global_load_dwordx3 v[162:164], v[156:157], off offset:20
	s_nop 0
	global_load_dwordx4 v[156:159], v[156:157], off
	s_nop 0
	global_load_dword v150, v[150:151], off offset:16
	ds_bpermute_b32 v151, v153, v40
	ds_bpermute_b32 v161, v153, v32
	s_waitcnt lgkmcnt(1)
	v_mul_f32_e32 v173, v152, v151
	s_waitcnt lgkmcnt(0)
	v_mul_f32_e32 v181, v152, v161
	ds_bpermute_b32 v161, v153, v33
	s_waitcnt vmcnt(2)
	v_mov_b32_e32 v151, v164
	s_waitcnt vmcnt(1)
	v_mov_b32_e32 v168, v157
	ds_bpermute_b32 v157, v153, v36
	v_mov_b32_e32 v169, v158
	s_waitcnt vmcnt(0)
	v_pk_mul_f32 v[150:151], v[180:181], v[150:151]
	v_mul_f32_e32 v164, v152, v155
	v_mad_i64_i32 v[180:181], s[24:25], v134, s14, v[140:141]
	s_waitcnt lgkmcnt(0)
	v_mul_f32_e32 v158, v152, v157
	v_mov_b32_e32 v157, v159
	v_mov_b32_e32 v159, v32
	v_pk_fma_f32 v[158:159], v[162:163], v[158:159], v[150:151]
	ds_bpermute_b32 v151, v153, v41
	ds_bpermute_b32 v150, v153, v45
	v_pk_mul_f32 v[156:157], v[172:173], v[156:157]
	v_mad_i64_i32 v[172:173], s[24:25], v148, s13, v[138:139]
	v_pk_fma_f32 v[156:157], v[168:169], v[170:171], v[156:157]
	s_waitcnt lgkmcnt(1)
	v_mul_f32_e32 v163, v152, v151
	v_mul_f32_e32 v171, v152, v161
	v_mov_b32_e32 v162, v45
	v_mov_b32_e32 v161, v128
	v_mov_b32_e32 v170, v37
	v_mov_b32_e32 v148, v129
	v_cvt_pk_bf16_f32 v168, v156, v157
	v_cvt_pk_bf16_f32 v169, v158, v159
	s_waitcnt lgkmcnt(0)
	v_mul_f32_e32 v150, v152, v150
	v_mov_b32_e32 v151, v41
	v_pk_mul_f32 v[160:161], v[162:163], v[160:161]
	v_pk_mul_f32 v[148:149], v[170:171], v[148:149]
	v_pk_fma_f32 v[160:161], v[166:167], v[150:151], v[160:161]
	v_pk_fma_f32 v[162:163], v[130:131], v[164:165], v[148:149]
	v_cvt_pk_bf16_f32 v128, v160, v161
	global_store_dwordx2 v[182:183], v[168:169], off
	global_store_dwordx4 v[184:185], v[156:159], off nt
	v_cvt_pk_bf16_f32 v129, v162, v163
	global_store_dwordx2 v[172:173], v[128:129], off
	global_store_dwordx4 v[180:181], v[160:163], off nt
	v_add_u32_e32 v148, 0x52, v154
	v_and_b32_e32 v129, 30, v148
	v_lshlrev_b32_e32 v134, 8, v129
	v_lshl_add_u64 v[150:151], v[142:143], 0, v[134:135]
	v_add_co_u32_e32 v156, vcc, s33, v150
	v_lshrrev_b32_e32 v128, 5, v148
	s_nop 0
	v_addc_co_u32_e32 v157, vcc, 0, v151, vcc
	global_load_dwordx3 v[160:162], v[156:157], off offset:256
	v_mul_lo_u32 v128, v128, s12
	v_or_b32_e32 v128, v128, v129
	v_add_u32_e32 v155, 0x1000, v128
	global_load_dwordx4 v[128:131], v[156:157], off offset:268
	global_load_dword v149, v[156:157], off offset:284
	v_lshl_add_u64 v[150:151], v[150:151], 0, s[84:85]
	ds_bpermute_b32 v134, v153, v46
	v_mov_b32_e32 v182, v38
	v_mad_i64_i32 v[184:185], s[24:25], v155, s13, v[138:139]
	ds_bpermute_b32 v155, v153, v47
	s_waitcnt lgkmcnt(1)
	v_mul_f32_e32 v172, v152, v134
	v_add_u32_e32 v134, 0x53, v154
	v_mov_b32_e32 v180, v46
	v_mov_b32_e32 v173, v42
	s_waitcnt vmcnt(2)
	v_mov_b32_e32 v167, v162
	v_mov_b32_e32 v166, v161
	global_load_dwordx3 v[162:164], v[156:157], off offset:20
	s_nop 0
	global_load_dwordx4 v[156:159], v[156:157], off
	s_nop 0
	global_load_dword v168, v[150:151], off offset:16
	ds_bpermute_b32 v151, v153, v38
	ds_bpermute_b32 v150, v153, v42
	ds_bpermute_b32 v161, v153, v43
	s_waitcnt lgkmcnt(1)
	v_mul_f32_e32 v181, v152, v150
	s_waitcnt vmcnt(2)
	v_mov_b32_e32 v169, v164
	s_waitcnt vmcnt(1)
	v_mov_b32_e32 v170, v157
	ds_bpermute_b32 v157, v153, v34
	v_mov_b32_e32 v171, v158
	v_mul_f32_e32 v158, v152, v151
	v_mad_i64_i32 v[150:151], s[24:25], v148, s14, v[140:141]
	s_waitcnt lgkmcnt(0)
	v_mul_f32_e32 v183, v152, v157
	v_mov_b32_e32 v157, v159
	v_mov_b32_e32 v159, v34
	s_waitcnt vmcnt(0)
	v_pk_mul_f32 v[164:165], v[182:183], v[168:169]
	v_lshrrev_b32_e32 v148, 5, v134
	v_pk_fma_f32 v[158:159], v[162:163], v[158:159], v[164:165]
	ds_bpermute_b32 v164, v153, v35
	ds_bpermute_b32 v163, v153, v39
	v_mul_lo_u32 v148, v148, s12
	v_and_or_b32 v148, v134, 31, v148
	v_pk_mul_f32 v[156:157], v[180:181], v[156:157]
	v_add_u32_e32 v148, 0x1000, v148
	v_pk_fma_f32 v[156:157], v[170:171], v[172:173], v[156:157]
	v_mul_f32_e32 v165, v152, v161
	s_waitcnt lgkmcnt(1)
	v_mul_f32_e32 v173, v152, v164
	v_mad_i64_i32 v[180:181], s[24:25], v148, s13, v[138:139]
	v_mov_b32_e32 v164, v47
	v_mov_b32_e32 v161, v128
	v_mov_b32_e32 v172, v39
	v_mov_b32_e32 v148, v129
	v_cvt_pk_bf16_f32 v170, v156, v157
	v_cvt_pk_bf16_f32 v171, v158, v159
	v_mul_f32_e32 v162, v152, v155
	s_waitcnt lgkmcnt(0)
	v_mul_f32_e32 v168, v152, v163
	v_mov_b32_e32 v163, v43
	v_pk_mul_f32 v[160:161], v[164:165], v[160:161]
	v_mov_b32_e32 v169, v35
	v_pk_mul_f32 v[148:149], v[172:173], v[148:149]
	v_mad_i64_i32 v[182:183], s[24:25], v134, s14, v[140:141]
	v_pk_fma_f32 v[160:161], v[166:167], v[162:163], v[160:161]
	v_pk_fma_f32 v[162:163], v[130:131], v[168:169], v[148:149]
	v_cvt_pk_bf16_f32 v128, v160, v161
	global_store_dwordx2 v[184:185], v[170:171], off
	global_store_dwordx4 v[150:151], v[156:159], off nt
	v_cvt_pk_bf16_f32 v129, v162, v163
	global_store_dwordx2 v[180:181], v[128:129], off
	global_store_dwordx4 v[182:183], v[160:163], off nt
	v_add_u32_e32 v134, 0x60, v154
	global_load_dwordx3 v[160:162], v[146:147], off offset:256
	v_lshrrev_b32_e32 v128, 5, v134
	v_mul_lo_u32 v128, v128, s12
	v_or_b32_e32 v128, v128, v137
	v_add_u32_e32 v137, 0x1000, v128
	ds_bpermute_b32 v148, v153, v24
	ds_bpermute_b32 v155, v153, v20
	v_mov_b32_e32 v170, v20
	v_mov_b32_e32 v168, v28
	v_mov_b32_e32 v167, v24
	s_waitcnt lgkmcnt(1)
	v_mul_f32_e32 v169, v152, v148
	ds_bpermute_b32 v148, v153, v29
	v_mad_i64_i32 v[180:181], s[24:25], v134, s14, v[140:141]
	v_add_u32_e32 v134, 0x61, v154
	v_mad_i64_i32 v[172:173], s[24:25], v137, s13, v[138:139]
	v_lshrrev_b32_e32 v137, 5, v134
	v_mul_lo_u32 v137, v137, s12
	v_and_or_b32 v137, v134, 29, v137
	v_add_u32_e32 v137, 0x1000, v137
	s_waitcnt vmcnt(0)
	v_mov_b32_e32 v150, v161
	v_mov_b32_e32 v151, v162
	global_load_dwordx4 v[128:131], v[146:147], off offset:268
	global_load_dword v149, v[146:147], off offset:284
	global_load_dwordx3 v[162:164], v[146:147], off offset:20
	global_load_dwordx4 v[156:159], v[146:147], off
	s_nop 0
	global_load_dword v146, v[144:145], off offset:16
	ds_bpermute_b32 v147, v153, v28
	s_waitcnt lgkmcnt(0)
	v_mul_f32_e32 v166, v152, v147
	s_waitcnt vmcnt(4)
	v_mov_b32_e32 v161, v128
	s_waitcnt vmcnt(2)
	v_mov_b32_e32 v147, v164
	s_waitcnt vmcnt(1)
	v_mov_b32_e32 v144, v157
	ds_bpermute_b32 v157, v153, v16
	v_mov_b32_e32 v145, v158
	v_mul_f32_e32 v158, v152, v155
	ds_bpermute_b32 v155, v153, v25
	v_mov_b32_e32 v164, v21
	s_waitcnt lgkmcnt(1)
	v_mul_f32_e32 v171, v152, v157
	v_mov_b32_e32 v157, v159
	v_mov_b32_e32 v159, v16
	s_waitcnt vmcnt(0)
	v_pk_mul_f32 v[146:147], v[170:171], v[146:147]
	v_pk_mul_f32 v[156:157], v[168:169], v[156:157]
	v_pk_fma_f32 v[146:147], v[162:163], v[158:159], v[146:147]
	ds_bpermute_b32 v158, v153, v17
	v_pk_fma_f32 v[144:145], v[144:145], v[166:167], v[156:157]
	ds_bpermute_b32 v157, v153, v21
	v_mul_f32_e32 v156, v152, v148
	s_waitcnt lgkmcnt(2)
	v_mul_f32_e32 v159, v152, v155
	s_waitcnt lgkmcnt(1)
	v_mul_f32_e32 v165, v152, v158
	v_mov_b32_e32 v158, v29
	v_mov_b32_e32 v148, v129
	v_cvt_pk_bf16_f32 v166, v144, v145
	v_cvt_pk_bf16_f32 v167, v146, v147
	s_waitcnt lgkmcnt(0)
	v_mul_f32_e32 v162, v152, v157
	v_mov_b32_e32 v157, v25
	v_pk_mul_f32 v[158:159], v[158:159], v[160:161]
	v_mov_b32_e32 v163, v17
	v_pk_mul_f32 v[148:149], v[164:165], v[148:149]
	v_mad_i64_i32 v[168:169], s[24:25], v137, s13, v[138:139]
	v_mad_i64_i32 v[170:171], s[24:25], v134, s14, v[140:141]
	v_pk_fma_f32 v[156:157], v[150:151], v[156:157], v[158:159]
	v_pk_fma_f32 v[158:159], v[130:131], v[162:163], v[148:149]
	v_cvt_pk_bf16_f32 v128, v156, v157
	global_store_dwordx2 v[172:173], v[166:167], off
	global_store_dwordx4 v[180:181], v[144:147], off nt
	v_cvt_pk_bf16_f32 v129, v158, v159
	global_store_dwordx2 v[168:169], v[128:129], off
	global_store_dwordx4 v[170:171], v[156:159], off nt
	v_add_u32_e32 v137, 0x62, v154
	v_and_b32_e32 v129, 30, v137
	v_lshlrev_b32_e32 v134, 8, v129
	v_lshl_add_u64 v[146:147], v[142:143], 0, v[134:135]
	v_add_co_u32_e32 v148, vcc, s33, v146
	v_lshrrev_b32_e32 v128, 5, v137
	s_nop 0
	v_addc_co_u32_e32 v149, vcc, 0, v147, vcc
	global_load_dwordx3 v[156:158], v[148:149], off offset:256
	v_mul_lo_u32 v128, v128, s12
	v_or_b32_e32 v128, v128, v129
	v_add_u32_e32 v144, 0x1000, v128
	global_load_dwordx4 v[128:131], v[148:149], off offset:268
	global_load_dword v145, v[148:149], off offset:284
	v_lshl_add_u64 v[146:147], v[146:147], 0, s[84:85]
	ds_bpermute_b32 v134, v153, v30
	v_mov_b32_e32 v172, v22
	v_mad_i64_i32 v[180:181], s[24:25], v144, s13, v[138:139]
	ds_bpermute_b32 v144, v153, v31
	ds_bpermute_b32 v155, v153, v27
	s_waitcnt lgkmcnt(2)
	v_mul_f32_e32 v168, v152, v134
	v_add_u32_e32 v134, 0x63, v154
	v_mov_b32_e32 v170, v30
	v_mov_b32_e32 v169, v26
	s_waitcnt vmcnt(2)
	v_mov_b32_e32 v163, v158
	v_mov_b32_e32 v162, v157
	global_load_dwordx3 v[158:160], v[148:149], off offset:20
	s_nop 0
	global_load_dwordx4 v[148:151], v[148:149], off
	s_nop 0
	global_load_dword v164, v[146:147], off offset:16
	ds_bpermute_b32 v147, v153, v22
	ds_bpermute_b32 v146, v153, v26
	ds_bpermute_b32 v157, v153, v23
	s_waitcnt lgkmcnt(1)
	v_mul_f32_e32 v171, v152, v146
	s_waitcnt vmcnt(2)
	v_mov_b32_e32 v165, v160
	s_waitcnt vmcnt(1)
	v_mov_b32_e32 v166, v149
	ds_bpermute_b32 v149, v153, v18
	v_mov_b32_e32 v167, v150
	v_mul_f32_e32 v150, v152, v147
	v_mad_i64_i32 v[146:147], s[24:25], v137, s14, v[140:141]
	s_waitcnt lgkmcnt(0)
	v_mul_f32_e32 v173, v152, v149
	v_mov_b32_e32 v149, v151
	v_mov_b32_e32 v151, v18
	s_waitcnt vmcnt(0)
	v_pk_mul_f32 v[160:161], v[172:173], v[164:165]
	v_lshrrev_b32_e32 v137, 5, v134
	v_pk_fma_f32 v[150:151], v[158:159], v[150:151], v[160:161]
	ds_bpermute_b32 v159, v153, v19
	v_pk_mul_f32 v[148:149], v[170:171], v[148:149]
	v_mul_lo_u32 v137, v137, s12
	v_pk_fma_f32 v[148:149], v[166:167], v[168:169], v[148:149]
	v_and_or_b32 v137, v134, 31, v137
	v_mul_f32_e32 v158, v152, v144
	v_mul_f32_e32 v161, v152, v155
	v_mul_f32_e32 v164, v152, v157
	s_waitcnt lgkmcnt(0)
	v_mul_f32_e32 v169, v152, v159
	v_mov_b32_e32 v160, v31
	v_mov_b32_e32 v157, v128
	v_mov_b32_e32 v168, v23
	v_mov_b32_e32 v144, v129
	v_cvt_pk_bf16_f32 v166, v148, v149
	v_cvt_pk_bf16_f32 v167, v150, v151
	v_add_u32_e32 v137, 0x1000, v137
	v_mov_b32_e32 v159, v27
	v_pk_mul_f32 v[156:157], v[160:161], v[156:157]
	v_mov_b32_e32 v165, v19
	v_pk_mul_f32 v[144:145], v[168:169], v[144:145]
	v_mad_i64_i32 v[170:171], s[24:25], v137, s13, v[138:139]
	v_mad_i64_i32 v[172:173], s[24:25], v134, s14, v[140:141]
	v_pk_fma_f32 v[156:157], v[162:163], v[158:159], v[156:157]
	v_pk_fma_f32 v[158:159], v[130:131], v[164:165], v[144:145]
	v_cvt_pk_bf16_f32 v128, v156, v157
	global_store_dwordx2 v[180:181], v[166:167], off
	global_store_dwordx4 v[146:147], v[148:151], off nt
	v_cvt_pk_bf16_f32 v129, v158, v159
	global_store_dwordx2 v[170:171], v[128:129], off
	global_store_dwordx4 v[172:173], v[156:159], off nt
	v_add_u32_e32 v137, 0x70, v154
	v_and_b32_e32 v129, 28, v137
	v_lshlrev_b32_e32 v134, 8, v129
	v_lshl_add_u64 v[146:147], v[142:143], 0, v[134:135]
	v_add_co_u32_e32 v148, vcc, s33, v146
	v_lshrrev_b32_e32 v128, 5, v137
	s_nop 0
	v_addc_co_u32_e32 v149, vcc, 0, v147, vcc
	global_load_dwordx3 v[156:158], v[148:149], off offset:256
	v_mul_lo_u32 v128, v128, s12
	v_or_b32_e32 v128, v128, v129
	v_lshl_add_u64 v[162:163], v[146:147], 0, s[84:85]
	v_add_u32_e32 v144, 0x1000, v128
	global_load_dwordx4 v[128:131], v[148:149], off offset:268
	global_load_dword v145, v[148:149], off offset:284
	ds_bpermute_b32 v155, v153, v0
	ds_bpermute_b32 v134, v153, v12
	v_mov_b32_e32 v170, v4
	v_mad_i64_i32 v[172:173], s[24:25], v144, s13, v[138:139]
	s_waitcnt lgkmcnt(1)
	v_mul_f32_e32 v171, v152, v155
	ds_bpermute_b32 v144, v153, v13
	ds_bpermute_b32 v155, v153, v9
	s_waitcnt lgkmcnt(2)
	v_mul_f32_e32 v166, v152, v134
	v_add_u32_e32 v134, 0x71, v154
	v_mad_i64_i32 v[180:181], s[24:25], v137, s14, v[140:141]
	v_mov_b32_e32 v168, v12
	v_lshrrev_b32_e32 v137, 5, v134
	v_mov_b32_e32 v167, v8
	v_mul_lo_u32 v137, v137, s12
	v_and_or_b32 v137, v134, 29, v137
	v_add_u32_e32 v137, 0x1000, v137
	s_waitcnt vmcnt(2)
	v_mov_b32_e32 v150, v157
	v_mov_b32_e32 v151, v158
	global_load_dwordx3 v[158:160], v[148:149], off offset:20
	s_nop 0
	global_load_dwordx4 v[146:149], v[148:149], off
	s_nop 0
	global_load_dword v162, v[162:163], off offset:16
	ds_bpermute_b32 v157, v153, v5
	s_waitcnt vmcnt(2)
	v_mov_b32_e32 v163, v160
	s_waitcnt vmcnt(1)
	v_mov_b32_e32 v164, v147
	v_mov_b32_e32 v165, v148
	ds_bpermute_b32 v147, v153, v8
	ds_bpermute_b32 v148, v153, v4
	s_waitcnt vmcnt(0)
	v_pk_mul_f32 v[160:161], v[170:171], v[162:163]
	s_waitcnt lgkmcnt(2)
	v_mul_f32_e32 v162, v152, v157
	v_mov_b32_e32 v157, v128
	s_waitcnt lgkmcnt(1)
	v_mul_f32_e32 v169, v152, v147
	s_waitcnt lgkmcnt(0)
	v_mul_f32_e32 v148, v152, v148
	v_mov_b32_e32 v147, v149
	v_mov_b32_e32 v149, v0
	v_pk_fma_f32 v[148:149], v[158:159], v[148:149], v[160:161]
	ds_bpermute_b32 v159, v153, v1
	v_pk_mul_f32 v[146:147], v[168:169], v[146:147]
	v_mul_f32_e32 v158, v152, v144
	v_pk_fma_f32 v[146:147], v[164:165], v[166:167], v[146:147]
	v_mul_f32_e32 v161, v152, v155
	s_waitcnt lgkmcnt(0)
	v_mul_f32_e32 v167, v152, v159
	v_mov_b32_e32 v160, v13
	v_mov_b32_e32 v166, v5
	v_mov_b32_e32 v144, v129
	v_cvt_pk_bf16_f32 v164, v146, v147
	v_cvt_pk_bf16_f32 v165, v148, v149
	v_mov_b32_e32 v159, v9
	v_pk_mul_f32 v[156:157], v[160:161], v[156:157]
	v_mov_b32_e32 v163, v1
	v_pk_mul_f32 v[144:145], v[166:167], v[144:145]
	v_mad_i64_i32 v[168:169], s[24:25], v137, s13, v[138:139]
	v_mad_i64_i32 v[170:171], s[24:25], v134, s14, v[140:141]
	v_pk_fma_f32 v[156:157], v[150:151], v[158:159], v[156:157]
	v_pk_fma_f32 v[158:159], v[130:131], v[162:163], v[144:145]
	v_cvt_pk_bf16_f32 v128, v156, v157
	global_store_dwordx2 v[172:173], v[164:165], off
	global_store_dwordx4 v[180:181], v[146:149], off nt
	v_cvt_pk_bf16_f32 v129, v158, v159
	global_store_dwordx2 v[168:169], v[128:129], off
	global_store_dwordx4 v[170:171], v[156:159], off nt
	v_add_u32_e32 v137, 0x72, v154
	v_and_b32_e32 v129, 30, v137
	v_lshlrev_b32_e32 v134, 8, v129
	v_lshl_add_u64 v[144:145], v[142:143], 0, v[134:135]
	v_add_co_u32_e32 v146, vcc, s33, v144
	v_lshrrev_b32_e32 v128, 5, v137
	s_nop 0
	v_addc_co_u32_e32 v147, vcc, 0, v145, vcc
	global_load_dwordx3 v[156:158], v[146:147], off offset:256
	v_mul_lo_u32 v128, v128, s12
	v_or_b32_e32 v128, v128, v129
	v_add_u32_e32 v155, 0x1000, v128
	global_load_dwordx4 v[128:131], v[146:147], off offset:268
	global_load_dword v143, v[146:147], off offset:284
	v_lshl_add_u64 v[144:145], v[144:145], 0, s[84:85]
	ds_bpermute_b32 v142, v153, v10
	ds_bpermute_b32 v134, v153, v14
	v_mov_b32_e32 v170, v6
	v_mad_i64_i32 v[172:173], s[24:25], v155, s13, v[138:139]
	s_waitcnt lgkmcnt(1)
	v_mul_f32_e32 v169, v152, v142
	ds_bpermute_b32 v142, v153, v15
	ds_bpermute_b32 v155, v153, v11
	s_waitcnt lgkmcnt(2)
	v_mul_f32_e32 v166, v152, v134
	v_add_u32_e32 v134, 0x73, v154
	v_mov_b32_e32 v168, v14
	v_mov_b32_e32 v167, v10
	s_waitcnt lgkmcnt(1)
	v_mul_f32_e32 v154, v152, v142
	s_waitcnt vmcnt(2)
	v_mov_b32_e32 v150, v157
	v_mov_b32_e32 v151, v158
	global_load_dwordx3 v[158:160], v[146:147], off offset:20
	s_nop 0
	global_load_dwordx4 v[146:149], v[146:147], off
	s_nop 0
	global_load_dword v162, v[144:145], off offset:16
	ds_bpermute_b32 v145, v153, v2
	ds_bpermute_b32 v144, v153, v6
	ds_bpermute_b32 v157, v153, v7
	s_waitcnt vmcnt(4)
	v_mov_b32_e32 v142, v129
	s_waitcnt lgkmcnt(2)
	v_mul_f32_e32 v171, v152, v145
	s_waitcnt vmcnt(2)
	v_mov_b32_e32 v163, v160
	s_waitcnt vmcnt(1)
	v_mov_b32_e32 v164, v147
	v_mov_b32_e32 v165, v148
	s_waitcnt lgkmcnt(1)
	v_mul_f32_e32 v148, v152, v144
	v_mov_b32_e32 v147, v149
	v_mov_b32_e32 v149, v2
	s_waitcnt vmcnt(0)
	v_pk_mul_f32 v[160:161], v[170:171], v[162:163]
	v_mad_i64_i32 v[144:145], s[24:25], v137, s14, v[140:141]
	v_pk_fma_f32 v[148:149], v[158:159], v[148:149], v[160:161]
	ds_bpermute_b32 v159, v153, v3
	v_lshrrev_b32_e32 v137, 5, v134
	v_mul_lo_u32 v137, v137, s12
	v_and_or_b32 v137, v134, 31, v137
	v_pk_mul_f32 v[146:147], v[168:169], v[146:147]
	v_add_u32_e32 v137, 0x1000, v137
	v_mul_f32_e32 v153, v152, v155
	s_waitcnt lgkmcnt(1)
	v_mul_f32_e32 v158, v152, v157
	s_waitcnt lgkmcnt(0)
	v_mul_f32_e32 v161, v152, v159
	v_mov_b32_e32 v152, v15
	v_mov_b32_e32 v157, v128
	v_mov_b32_e32 v160, v7
	v_pk_fma_f32 v[146:147], v[164:165], v[166:167], v[146:147]
	v_cvt_pk_bf16_f32 v165, v148, v149
	v_mad_i64_i32 v[162:163], s[24:25], v137, s13, v[138:139]
	v_cvt_pk_bf16_f32 v164, v146, v147
	v_mad_i64_i32 v[166:167], s[24:25], v134, s14, v[140:141]
	v_mov_b32_e32 v155, v11
	v_pk_mul_f32 v[138:139], v[152:153], v[156:157]
	v_mov_b32_e32 v159, v3
	v_pk_mul_f32 v[140:141], v[160:161], v[142:143]
	v_pk_fma_f32 v[138:139], v[150:151], v[154:155], v[138:139]
	v_pk_fma_f32 v[140:141], v[130:131], v[158:159], v[140:141]
	v_cvt_pk_bf16_f32 v128, v138, v139
	global_store_dwordx2 v[172:173], v[164:165], off
	global_store_dwordx4 v[144:145], v[146:149], off nt
	v_cvt_pk_bf16_f32 v129, v140, v141
	global_store_dwordx2 v[162:163], v[128:129], off
	global_store_dwordx4 v[166:167], v[138:141], off nt

.LBB0_269:
	global_load_dwordx2 v[172:173], v[172:173], off
	v_lshlrev_b32_e32 v134, 2, v170
	v_lshl_add_u64 v[170:171], s[4:5], 0, v[134:135]
	v_lshl_add_u64 v[170:171], v[136:137], 2, v[170:171]
	s_waitcnt vmcnt(0)
	v_lshl_add_u64 v[172:173], v[136:137], 1, v[172:173]
	v_lshrrev_b32_e32 v129, 5, v168
	v_mul_lo_u32 v129, v129, s16
	v_add_u32_e32 v129, 0x200, v129
	v_or_b32_e32 v131, v129, v139
	v_mad_i64_i32 v[178:179], s[24:25], v131, s13, v[172:173]
	v_cvt_pk_bf16_f32 v180, v124, v120
	v_cvt_pk_bf16_f32 v181, v116, v112
	global_store_dwordx2 v[178:179], v[180:181], off
	v_mad_i64_i32 v[182:183], s[24:25], v168, s14, v[170:171]
	v_mov_b32_e32 v178, v124
	v_mov_b32_e32 v179, v120
	v_mov_b32_e32 v180, v116
	v_mov_b32_e32 v181, v112
	global_store_dwordx4 v[182:183], v[178:181], off nt
	v_or_b32_e32 v131, 1, v168
	v_and_or_b32 v134, v131, 29, v129
	v_mad_i64_i32 v[178:179], s[24:25], v134, s13, v[172:173]
	v_cvt_pk_bf16_f32 v180, v125, v121
	v_cvt_pk_bf16_f32 v181, v117, v113
	global_store_dwordx2 v[178:179], v[180:181], off
	v_mad_i64_i32 v[182:183], s[24:25], v131, s14, v[170:171]
	v_mov_b32_e32 v178, v125
	v_mov_b32_e32 v179, v121
	v_mov_b32_e32 v180, v117
	v_mov_b32_e32 v181, v113
	global_store_dwordx4 v[182:183], v[178:181], off nt
	v_or_b32_e32 v131, 2, v168
	v_and_or_b32 v134, v131, 30, v129
	v_mad_i64_i32 v[178:179], s[24:25], v134, s13, v[172:173]
	v_cvt_pk_bf16_f32 v180, v126, v122
	v_cvt_pk_bf16_f32 v181, v118, v114
	global_store_dwordx2 v[178:179], v[180:181], off
	v_mad_i64_i32 v[182:183], s[24:25], v131, s14, v[170:171]
	v_mov_b32_e32 v178, v126
	v_mov_b32_e32 v179, v122
	v_mov_b32_e32 v180, v118
	v_mov_b32_e32 v181, v114
	global_store_dwordx4 v[182:183], v[178:181], off nt
	v_or_b32_e32 v131, 3, v168
	v_and_or_b32 v129, v131, 31, v129
	v_mad_i64_i32 v[178:179], s[24:25], v129, s13, v[172:173]
	v_cvt_pk_bf16_f32 v180, v127, v123
	v_cvt_pk_bf16_f32 v181, v119, v115
	global_store_dwordx2 v[178:179], v[180:181], off
	v_mad_i64_i32 v[182:183], s[24:25], v131, s14, v[170:171]
	v_mov_b32_e32 v178, v127
	v_mov_b32_e32 v179, v123
	v_mov_b32_e32 v180, v119
	v_mov_b32_e32 v181, v115
	global_store_dwordx4 v[182:183], v[178:181], off nt
	v_add_u32_e32 v129, 16, v168
	v_lshrrev_b32_e32 v131, 5, v129
	v_mul_lo_u32 v131, v131, s16
	v_and_or_b32 v131, v129, 28, v131
	v_add_u32_e32 v131, 0x200, v131
	v_mad_i64_i32 v[178:179], s[24:25], v131, s13, v[172:173]
	v_cvt_pk_bf16_f32 v180, v108, v104
	v_cvt_pk_bf16_f32 v181, v100, v96
	global_store_dwordx2 v[178:179], v[180:181], off
	v_mad_i64_i32 v[182:183], s[24:25], v129, s14, v[170:171]
	v_mov_b32_e32 v178, v108
	v_mov_b32_e32 v179, v104
	v_mov_b32_e32 v180, v100
	v_mov_b32_e32 v181, v96
	global_store_dwordx4 v[182:183], v[178:181], off nt
	v_add_u32_e32 v129, 17, v168
	v_lshrrev_b32_e32 v131, 5, v129
	v_mul_lo_u32 v131, v131, s16
	v_and_or_b32 v131, v129, 29, v131
	v_add_u32_e32 v131, 0x200, v131
	v_mad_i64_i32 v[178:179], s[24:25], v131, s13, v[172:173]
	v_cvt_pk_bf16_f32 v180, v109, v105
	v_cvt_pk_bf16_f32 v181, v101, v97
	global_store_dwordx2 v[178:179], v[180:181], off
	v_mad_i64_i32 v[182:183], s[24:25], v129, s14, v[170:171]
	v_mov_b32_e32 v178, v109
	v_mov_b32_e32 v179, v105
	v_mov_b32_e32 v180, v101
	v_mov_b32_e32 v181, v97
	global_store_dwordx4 v[182:183], v[178:181], off nt
	v_add_u32_e32 v129, 18, v168
	v_lshrrev_b32_e32 v131, 5, v129
	v_mul_lo_u32 v131, v131, s16
	v_and_or_b32 v131, v129, 30, v131
	v_add_u32_e32 v131, 0x200, v131
	v_mad_i64_i32 v[178:179], s[24:25], v131, s13, v[172:173]
	v_cvt_pk_bf16_f32 v180, v110, v106
	v_cvt_pk_bf16_f32 v181, v102, v98
	global_store_dwordx2 v[178:179], v[180:181], off
	v_mad_i64_i32 v[182:183], s[24:25], v129, s14, v[170:171]
	v_mov_b32_e32 v178, v110
	v_mov_b32_e32 v179, v106
	v_mov_b32_e32 v180, v102
	v_mov_b32_e32 v181, v98
	global_store_dwordx4 v[182:183], v[178:181], off nt
	v_add_u32_e32 v129, 19, v168
	v_lshrrev_b32_e32 v131, 5, v129
	v_mul_lo_u32 v131, v131, s16
	v_and_or_b32 v131, v129, 31, v131
	v_add_u32_e32 v131, 0x200, v131
	v_mad_i64_i32 v[178:179], s[24:25], v131, s13, v[172:173]
	v_cvt_pk_bf16_f32 v180, v111, v107
	v_cvt_pk_bf16_f32 v181, v103, v99
	global_store_dwordx2 v[178:179], v[180:181], off
	v_mad_i64_i32 v[182:183], s[24:25], v129, s14, v[170:171]
	v_mov_b32_e32 v178, v111
	v_mov_b32_e32 v179, v107
	v_mov_b32_e32 v180, v103
	v_mov_b32_e32 v181, v99
	global_store_dwordx4 v[182:183], v[178:181], off nt
	v_add_u32_e32 v129, 32, v168
	v_lshrrev_b32_e32 v131, 5, v129
	v_mul_lo_u32 v131, v131, s16
	v_or_b32_e32 v131, v131, v139
	v_add_u32_e32 v131, 0x200, v131
	v_mad_i64_i32 v[178:179], s[24:25], v131, s13, v[172:173]
	v_cvt_pk_bf16_f32 v180, v92, v88
	v_cvt_pk_bf16_f32 v181, v84, v80
	global_store_dwordx2 v[178:179], v[180:181], off
	v_mad_i64_i32 v[182:183], s[24:25], v129, s14, v[170:171]
	v_mov_b32_e32 v178, v92
	v_mov_b32_e32 v179, v88
	v_mov_b32_e32 v180, v84
	v_mov_b32_e32 v181, v80
	global_store_dwordx4 v[182:183], v[178:181], off nt
	v_add_u32_e32 v129, 33, v168
	v_lshrrev_b32_e32 v131, 5, v129
	v_mul_lo_u32 v131, v131, s16
	v_and_or_b32 v131, v129, 29, v131
	v_add_u32_e32 v131, 0x200, v131
	v_mad_i64_i32 v[178:179], s[24:25], v131, s13, v[172:173]
	v_cvt_pk_bf16_f32 v180, v93, v89
	v_cvt_pk_bf16_f32 v181, v85, v81
	global_store_dwordx2 v[178:179], v[180:181], off
	v_mad_i64_i32 v[182:183], s[24:25], v129, s14, v[170:171]
	v_mov_b32_e32 v178, v93
	v_mov_b32_e32 v179, v89
	v_mov_b32_e32 v180, v85
	v_mov_b32_e32 v181, v81
	global_store_dwordx4 v[182:183], v[178:181], off nt
	v_add_u32_e32 v129, 34, v168
	v_lshrrev_b32_e32 v131, 5, v129
	v_mul_lo_u32 v131, v131, s16
	v_and_or_b32 v131, v129, 30, v131
	v_add_u32_e32 v131, 0x200, v131
	v_mad_i64_i32 v[178:179], s[24:25], v131, s13, v[172:173]
	v_cvt_pk_bf16_f32 v180, v94, v90
	v_cvt_pk_bf16_f32 v181, v86, v82
	global_store_dwordx2 v[178:179], v[180:181], off
	v_mad_i64_i32 v[182:183], s[24:25], v129, s14, v[170:171]
	v_mov_b32_e32 v178, v94
	v_mov_b32_e32 v179, v90
	v_mov_b32_e32 v180, v86
	v_mov_b32_e32 v181, v82
	global_store_dwordx4 v[182:183], v[178:181], off nt
	v_add_u32_e32 v129, 35, v168
	v_lshrrev_b32_e32 v131, 5, v129
	v_mul_lo_u32 v131, v131, s16
	v_and_or_b32 v131, v129, 31, v131
	v_add_u32_e32 v131, 0x200, v131
	v_mad_i64_i32 v[178:179], s[24:25], v131, s13, v[172:173]
	v_cvt_pk_bf16_f32 v180, v95, v91
	v_cvt_pk_bf16_f32 v181, v87, v83
	global_store_dwordx2 v[178:179], v[180:181], off
	v_mad_i64_i32 v[182:183], s[24:25], v129, s14, v[170:171]
	v_mov_b32_e32 v178, v95
	v_mov_b32_e32 v179, v91
	v_mov_b32_e32 v180, v87
	v_mov_b32_e32 v181, v83
	global_store_dwordx4 v[182:183], v[178:181], off nt
	v_add_u32_e32 v129, 48, v168
	v_lshrrev_b32_e32 v131, 5, v129
	v_mul_lo_u32 v131, v131, s16
	v_and_or_b32 v131, v129, 28, v131
	v_add_u32_e32 v131, 0x200, v131
	v_mad_i64_i32 v[178:179], s[24:25], v131, s13, v[172:173]
	v_cvt_pk_bf16_f32 v180, v76, v72
	v_cvt_pk_bf16_f32 v181, v68, v64
	global_store_dwordx2 v[178:179], v[180:181], off
	v_mad_i64_i32 v[182:183], s[24:25], v129, s14, v[170:171]
	v_mov_b32_e32 v178, v76
	v_mov_b32_e32 v179, v72
	v_mov_b32_e32 v180, v68
	v_mov_b32_e32 v181, v64
	global_store_dwordx4 v[182:183], v[178:181], off nt
	v_add_u32_e32 v129, 49, v168
	v_lshrrev_b32_e32 v131, 5, v129
	v_mul_lo_u32 v131, v131, s16
	v_and_or_b32 v131, v129, 29, v131
	v_add_u32_e32 v131, 0x200, v131
	v_mad_i64_i32 v[178:179], s[24:25], v131, s13, v[172:173]
	v_cvt_pk_bf16_f32 v180, v77, v73
	v_cvt_pk_bf16_f32 v181, v69, v65
	global_store_dwordx2 v[178:179], v[180:181], off
	v_mad_i64_i32 v[182:183], s[24:25], v129, s14, v[170:171]
	v_mov_b32_e32 v178, v77
	v_mov_b32_e32 v179, v73
	v_mov_b32_e32 v180, v69
	v_mov_b32_e32 v181, v65
	global_store_dwordx4 v[182:183], v[178:181], off nt
	v_add_u32_e32 v129, 50, v168
	v_lshrrev_b32_e32 v131, 5, v129
	v_mul_lo_u32 v131, v131, s16
	v_and_or_b32 v131, v129, 30, v131
	v_add_u32_e32 v131, 0x200, v131
	v_mad_i64_i32 v[178:179], s[24:25], v131, s13, v[172:173]
	v_cvt_pk_bf16_f32 v180, v78, v74
	v_cvt_pk_bf16_f32 v181, v70, v66
	global_store_dwordx2 v[178:179], v[180:181], off
	v_mad_i64_i32 v[182:183], s[24:25], v129, s14, v[170:171]
	v_mov_b32_e32 v178, v78
	v_mov_b32_e32 v179, v74
	v_mov_b32_e32 v180, v70
	v_mov_b32_e32 v181, v66
	global_store_dwordx4 v[182:183], v[178:181], off nt
	v_add_u32_e32 v129, 51, v168
	v_lshrrev_b32_e32 v131, 5, v129
	v_mul_lo_u32 v131, v131, s16
	v_and_or_b32 v131, v129, 31, v131
	v_add_u32_e32 v131, 0x200, v131
	v_mad_i64_i32 v[178:179], s[24:25], v131, s13, v[172:173]
	v_cvt_pk_bf16_f32 v180, v79, v75
	v_cvt_pk_bf16_f32 v181, v71, v67
	global_store_dwordx2 v[178:179], v[180:181], off
	v_mad_i64_i32 v[182:183], s[24:25], v129, s14, v[170:171]
	v_mov_b32_e32 v178, v79
	v_mov_b32_e32 v179, v75
	v_mov_b32_e32 v180, v71
	v_mov_b32_e32 v181, v67
	global_store_dwordx4 v[182:183], v[178:181], off nt
	v_add_u32_e32 v129, 64, v168
	v_lshrrev_b32_e32 v131, 5, v129
	v_mul_lo_u32 v131, v131, s16
	v_or_b32_e32 v131, v131, v139
	v_add_u32_e32 v131, 0x200, v131
	v_mad_i64_i32 v[178:179], s[24:25], v131, s13, v[172:173]
	v_cvt_pk_bf16_f32 v180, v60, v56
	v_cvt_pk_bf16_f32 v181, v52, v48
	global_store_dwordx2 v[178:179], v[180:181], off
	v_mad_i64_i32 v[182:183], s[24:25], v129, s14, v[170:171]
	v_mov_b32_e32 v178, v60
	v_mov_b32_e32 v179, v56
	v_mov_b32_e32 v180, v52
	v_mov_b32_e32 v181, v48
	global_store_dwordx4 v[182:183], v[178:181], off nt
	v_add_u32_e32 v129, 0x41, v168
	v_lshrrev_b32_e32 v131, 5, v129
	v_mul_lo_u32 v131, v131, s16
	v_and_or_b32 v131, v129, 29, v131
	v_add_u32_e32 v131, 0x200, v131
	v_mad_i64_i32 v[178:179], s[24:25], v131, s13, v[172:173]
	v_cvt_pk_bf16_f32 v180, v61, v57
	v_cvt_pk_bf16_f32 v181, v53, v49
	global_store_dwordx2 v[178:179], v[180:181], off
	v_mad_i64_i32 v[182:183], s[24:25], v129, s14, v[170:171]
	v_mov_b32_e32 v178, v61
	v_mov_b32_e32 v179, v57
	v_mov_b32_e32 v180, v53
	v_mov_b32_e32 v181, v49
	global_store_dwordx4 v[182:183], v[178:181], off nt
	v_add_u32_e32 v129, 0x42, v168
	v_lshrrev_b32_e32 v131, 5, v129
	v_mul_lo_u32 v131, v131, s16
	v_and_or_b32 v131, v129, 30, v131
	v_add_u32_e32 v131, 0x200, v131
	v_mad_i64_i32 v[178:179], s[24:25], v131, s13, v[172:173]
	v_cvt_pk_bf16_f32 v180, v62, v58
	v_cvt_pk_bf16_f32 v181, v54, v50
	global_store_dwordx2 v[178:179], v[180:181], off
	v_mad_i64_i32 v[182:183], s[24:25], v129, s14, v[170:171]
	v_mov_b32_e32 v178, v62
	v_mov_b32_e32 v179, v58
	v_mov_b32_e32 v180, v54
	v_mov_b32_e32 v181, v50
	global_store_dwordx4 v[182:183], v[178:181], off nt
	v_add_u32_e32 v129, 0x43, v168
	v_lshrrev_b32_e32 v131, 5, v129
	v_mul_lo_u32 v131, v131, s16
	v_and_or_b32 v131, v129, 31, v131
	v_add_u32_e32 v131, 0x200, v131
	v_mad_i64_i32 v[178:179], s[24:25], v131, s13, v[172:173]
	v_cvt_pk_bf16_f32 v180, v63, v59
	v_cvt_pk_bf16_f32 v181, v55, v51
	global_store_dwordx2 v[178:179], v[180:181], off
	v_mad_i64_i32 v[182:183], s[24:25], v129, s14, v[170:171]
	v_mov_b32_e32 v178, v63
	v_mov_b32_e32 v179, v59
	v_mov_b32_e32 v180, v55
	v_mov_b32_e32 v181, v51
	global_store_dwordx4 v[182:183], v[178:181], off nt
	v_add_u32_e32 v129, 0x50, v168
	v_lshrrev_b32_e32 v131, 5, v129
	v_mul_lo_u32 v131, v131, s16
	v_and_or_b32 v131, v129, 28, v131
	v_add_u32_e32 v131, 0x200, v131
	v_mad_i64_i32 v[178:179], s[24:25], v131, s13, v[172:173]
	v_cvt_pk_bf16_f32 v180, v44, v40
	v_cvt_pk_bf16_f32 v181, v36, v32
	global_store_dwordx2 v[178:179], v[180:181], off
	v_mad_i64_i32 v[182:183], s[24:25], v129, s14, v[170:171]
	v_mov_b32_e32 v178, v44
	v_mov_b32_e32 v179, v40
	v_mov_b32_e32 v180, v36
	v_mov_b32_e32 v181, v32
	global_store_dwordx4 v[182:183], v[178:181], off nt
	v_add_u32_e32 v129, 0x51, v168
	v_lshrrev_b32_e32 v131, 5, v129
	v_mul_lo_u32 v131, v131, s16
	v_and_or_b32 v131, v129, 29, v131
	v_add_u32_e32 v131, 0x200, v131
	v_mad_i64_i32 v[178:179], s[24:25], v131, s13, v[172:173]
	v_cvt_pk_bf16_f32 v180, v45, v41
	v_cvt_pk_bf16_f32 v181, v37, v33
	global_store_dwordx2 v[178:179], v[180:181], off
	v_mad_i64_i32 v[182:183], s[24:25], v129, s14, v[170:171]
	v_mov_b32_e32 v178, v45
	v_mov_b32_e32 v179, v41
	v_mov_b32_e32 v180, v37
	v_mov_b32_e32 v181, v33
	global_store_dwordx4 v[182:183], v[178:181], off nt
	v_add_u32_e32 v129, 0x52, v168
	v_lshrrev_b32_e32 v131, 5, v129
	v_mul_lo_u32 v131, v131, s16
	v_and_or_b32 v131, v129, 30, v131
	v_add_u32_e32 v131, 0x200, v131
	v_mad_i64_i32 v[178:179], s[24:25], v131, s13, v[172:173]
	v_cvt_pk_bf16_f32 v180, v46, v42
	v_cvt_pk_bf16_f32 v181, v38, v34
	global_store_dwordx2 v[178:179], v[180:181], off
	v_mad_i64_i32 v[182:183], s[24:25], v129, s14, v[170:171]
	v_mov_b32_e32 v178, v46
	v_mov_b32_e32 v179, v42
	v_mov_b32_e32 v180, v38
	v_mov_b32_e32 v181, v34
	global_store_dwordx4 v[182:183], v[178:181], off nt
	v_add_u32_e32 v129, 0x53, v168
	v_lshrrev_b32_e32 v131, 5, v129
	v_mul_lo_u32 v131, v131, s16
	v_and_or_b32 v131, v129, 31, v131
	v_add_u32_e32 v131, 0x200, v131
	v_mad_i64_i32 v[178:179], s[24:25], v131, s13, v[172:173]
	v_cvt_pk_bf16_f32 v180, v47, v43
	v_cvt_pk_bf16_f32 v181, v39, v35
	global_store_dwordx2 v[178:179], v[180:181], off
	v_mad_i64_i32 v[182:183], s[24:25], v129, s14, v[170:171]
	v_mov_b32_e32 v178, v47
	v_mov_b32_e32 v179, v43
	v_mov_b32_e32 v180, v39
	v_mov_b32_e32 v181, v35
	global_store_dwordx4 v[182:183], v[178:181], off nt
	v_add_u32_e32 v129, 0x60, v168
	v_lshrrev_b32_e32 v131, 5, v129
	v_mul_lo_u32 v131, v131, s16
	v_or_b32_e32 v131, v131, v139
	v_add_u32_e32 v131, 0x200, v131
	v_mad_i64_i32 v[178:179], s[24:25], v131, s13, v[172:173]
	v_cvt_pk_bf16_f32 v180, v28, v24
	v_cvt_pk_bf16_f32 v181, v20, v16
	global_store_dwordx2 v[178:179], v[180:181], off
	v_mad_i64_i32 v[182:183], s[24:25], v129, s14, v[170:171]
	v_mov_b32_e32 v178, v28
	v_mov_b32_e32 v179, v24
	v_mov_b32_e32 v180, v20
	v_mov_b32_e32 v181, v16
	global_store_dwordx4 v[182:183], v[178:181], off nt
	v_add_u32_e32 v129, 0x61, v168
	v_lshrrev_b32_e32 v131, 5, v129
	v_mul_lo_u32 v131, v131, s16
	v_and_or_b32 v131, v129, 29, v131
	v_add_u32_e32 v131, 0x200, v131
	v_mad_i64_i32 v[178:179], s[24:25], v131, s13, v[172:173]
	v_cvt_pk_bf16_f32 v180, v29, v25
	v_cvt_pk_bf16_f32 v181, v21, v17
	global_store_dwordx2 v[178:179], v[180:181], off
	v_mad_i64_i32 v[182:183], s[24:25], v129, s14, v[170:171]
	v_mov_b32_e32 v178, v29
	v_mov_b32_e32 v179, v25
	v_mov_b32_e32 v180, v21
	v_mov_b32_e32 v181, v17
	global_store_dwordx4 v[182:183], v[178:181], off nt
	v_add_u32_e32 v129, 0x62, v168
	v_lshrrev_b32_e32 v131, 5, v129
	v_mul_lo_u32 v131, v131, s16
	v_and_or_b32 v131, v129, 30, v131
	v_add_u32_e32 v131, 0x200, v131
	v_mad_i64_i32 v[178:179], s[24:25], v131, s13, v[172:173]
	v_cvt_pk_bf16_f32 v180, v30, v26
	v_cvt_pk_bf16_f32 v181, v22, v18
	global_store_dwordx2 v[178:179], v[180:181], off
	v_mad_i64_i32 v[182:183], s[24:25], v129, s14, v[170:171]
	v_mov_b32_e32 v178, v30
	v_mov_b32_e32 v179, v26
	v_mov_b32_e32 v180, v22
	v_mov_b32_e32 v181, v18
	global_store_dwordx4 v[182:183], v[178:181], off nt
	v_add_u32_e32 v129, 0x63, v168
	v_lshrrev_b32_e32 v131, 5, v129
	v_mul_lo_u32 v131, v131, s16
	v_and_or_b32 v131, v129, 31, v131
	v_add_u32_e32 v131, 0x200, v131
	v_mad_i64_i32 v[178:179], s[24:25], v131, s13, v[172:173]
	v_cvt_pk_bf16_f32 v180, v31, v27
	v_cvt_pk_bf16_f32 v181, v23, v19
	global_store_dwordx2 v[178:179], v[180:181], off
	v_mad_i64_i32 v[182:183], s[24:25], v129, s14, v[170:171]
	v_mov_b32_e32 v178, v31
	v_mov_b32_e32 v179, v27
	v_mov_b32_e32 v180, v23
	v_mov_b32_e32 v181, v19
	global_store_dwordx4 v[182:183], v[178:181], off nt
	v_add_u32_e32 v129, 0x70, v168
	v_lshrrev_b32_e32 v131, 5, v129
	v_mul_lo_u32 v131, v131, s16
	v_and_or_b32 v131, v129, 28, v131
	v_add_u32_e32 v131, 0x200, v131
	v_mad_i64_i32 v[178:179], s[24:25], v131, s13, v[172:173]
	v_cvt_pk_bf16_f32 v180, v12, v8
	v_cvt_pk_bf16_f32 v181, v4, v0
	global_store_dwordx2 v[178:179], v[180:181], off
	v_mad_i64_i32 v[182:183], s[24:25], v129, s14, v[170:171]
	v_mov_b32_e32 v178, v12
	v_mov_b32_e32 v179, v8
	v_mov_b32_e32 v180, v4
	v_mov_b32_e32 v181, v0
	global_store_dwordx4 v[182:183], v[178:181], off nt
	v_add_u32_e32 v129, 0x71, v168
	v_lshrrev_b32_e32 v131, 5, v129
	v_mul_lo_u32 v131, v131, s16
	v_and_or_b32 v131, v129, 29, v131
	v_add_u32_e32 v131, 0x200, v131
	v_mad_i64_i32 v[178:179], s[24:25], v131, s13, v[172:173]
	v_cvt_pk_bf16_f32 v180, v13, v9
	v_cvt_pk_bf16_f32 v181, v5, v1
	global_store_dwordx2 v[178:179], v[180:181], off
	v_mad_i64_i32 v[182:183], s[24:25], v129, s14, v[170:171]
	v_mov_b32_e32 v178, v13
	v_mov_b32_e32 v179, v9
	v_mov_b32_e32 v180, v5
	v_mov_b32_e32 v181, v1
	global_store_dwordx4 v[182:183], v[178:181], off nt
	v_add_u32_e32 v129, 0x72, v168
	v_lshrrev_b32_e32 v131, 5, v129
	v_mul_lo_u32 v131, v131, s16
	v_and_or_b32 v131, v129, 30, v131
	v_add_u32_e32 v131, 0x200, v131
	v_mad_i64_i32 v[178:179], s[24:25], v131, s13, v[172:173]
	v_cvt_pk_bf16_f32 v180, v14, v10
	v_cvt_pk_bf16_f32 v181, v6, v2
	global_store_dwordx2 v[178:179], v[180:181], off
	v_mad_i64_i32 v[182:183], s[24:25], v129, s14, v[170:171]
	v_mov_b32_e32 v178, v14
	v_mov_b32_e32 v179, v10
	v_mov_b32_e32 v180, v6
	v_mov_b32_e32 v181, v2
	global_store_dwordx4 v[182:183], v[178:181], off nt
	v_add_u32_e32 v129, 0x73, v168
	v_lshrrev_b32_e32 v131, 5, v129
	v_mul_lo_u32 v131, v131, s16
	v_and_or_b32 v131, v129, 31, v131
	v_add_u32_e32 v131, 0x200, v131
	v_mad_i64_i32 v[172:173], s[24:25], v131, s13, v[172:173]
	v_cvt_pk_bf16_f32 v178, v15, v11
	v_cvt_pk_bf16_f32 v179, v7, v3
	global_store_dwordx2 v[172:173], v[178:179], off
	v_mad_i64_i32 v[178:179], s[24:25], v129, s14, v[170:171]
	v_mov_b32_e32 v170, v15
	v_mov_b32_e32 v171, v11
	v_mov_b32_e32 v172, v7
	v_mov_b32_e32 v173, v3
	global_store_dwordx4 v[178:179], v[170:173], off nt
	s_andn2_b64 s[8:9], s[8:9], exec
	s_or_b64 exec, exec, s[0:1]
	s_mov_b64 s[66:67], 0
	s_and_saveexec_b64 s[0:1], s[8:9]
	s_cbranch_execz .LBB0_258

.LBB0_275:
	s_or_saveexec_b64 s[72:73], s[72:73]
	v_cndmask_b32_e64 v172, 1.0, -1.0, s[0:1]
	v_readlane_b32 s36, v253, 26
	v_readlane_b32 s0, v253, 20
	v_lshlrev_b32_e32 v174, 1, v175
	v_mov_b32_e32 v175, v135
	v_readlane_b32 s48, v253, 38
	v_readlane_b32 s49, v253, 39
	v_readlane_b32 s1, v253, 21
	v_readlane_b32 s37, v253, 27
	v_lshl_add_u64 v[176:177], s[48:49], 0, v[174:175]
	v_lshl_add_u64 v[174:175], s[0:1], 0, v[134:135]
	v_lshrrev_b32_e32 v134, 5, v168
	v_mul_lo_u32 v141, v134, s12
	v_readlane_b32 s38, v253, 28
	v_readlane_b32 s39, v253, 29
	v_readlane_b32 s40, v253, 30
	v_readlane_b32 s41, v253, 31
	v_readlane_b32 s42, v253, 32
	v_readlane_b32 s43, v253, 33
	v_readlane_b32 s44, v253, 34
	v_readlane_b32 s45, v253, 35
	v_readlane_b32 s46, v253, 36
	v_readlane_b32 s47, v253, 37
	v_readlane_b32 s50, v253, 40
	v_readlane_b32 s51, v253, 41
	s_xor_b64 exec, exec, s[72:73]
	s_cbranch_execz .LBB0_277
	v_or_b32_e32 v134, v141, v139
	v_add_u32_e32 v192, 0x1000, v134
	v_ashrrev_i32_e32 v193, 31, v192
	v_lshlrev_b64 v[192:193], 6, v[192:193]
	v_ashrrev_i32_e32 v169, 31, v168
	v_lshl_add_u64 v[194:195], v[176:177], 0, v[192:193]
	v_lshlrev_b64 v[192:193], 7, v[168:169]
	v_lshl_add_u64 v[196:197], v[174:175], 0, v[192:193]
	v_add_co_u32_e32 v192, vcc, 0x80000, v178
	v_mov_b32_e32 v202, v124
	s_nop 0
	v_addc_co_u32_e32 v193, vcc, 0, v179, vcc
	global_load_dwordx2 v[198:199], v[192:193], off offset:16
	global_load_dwordx2 v[200:201], v[192:193], off
	v_mov_b32_e32 v203, v120
	s_waitcnt lgkmcnt(2)
	v_pk_mul_f32 v[190:191], v[172:173], v[190:191] op_sel_hi:[0,1]
	s_waitcnt lgkmcnt(0)
	v_pk_mul_f32 v[188:189], v[172:173], v[188:189] op_sel_hi:[0,1]
	s_waitcnt vmcnt(1)
	v_mov_b32_e32 v207, v198
	s_waitcnt vmcnt(0)
	v_mov_b32_e32 v206, v200
	v_mov_b32_e32 v198, v201
	global_load_dwordx2 v[200:201], v[192:193], off offset:48
	s_nop 0
	global_load_dwordx2 v[192:193], v[192:193], off offset:32
	v_pk_mul_f32 v[202:203], v[202:203], v[206:207]
	s_waitcnt vmcnt(1)
	v_mov_b32_e32 v207, v200
	v_pk_fma_f32 v[190:191], v[190:191], v[198:199], v[202:203]
	v_mov_b32_e32 v202, v116
	v_mov_b32_e32 v203, v112
	s_waitcnt vmcnt(0)
	v_mov_b32_e32 v206, v192
	v_pk_mul_f32 v[202:203], v[202:203], v[206:207]
	v_mov_b32_e32 v200, v193
	v_cvt_pk_bf16_f32 v198, v190, v191
	v_pk_fma_f32 v[192:193], v[188:189], v[200:201], v[202:203]
	s_nop 0
	v_cvt_pk_bf16_f32 v199, v192, v193
	global_store_dwordx2 v[194:195], v[198:199], off
	global_store_dwordx4 v[196:197], v[190:193], off nt

.LBB0_281:
	s_andn2_saveexec_b64 s[0:1], s[0:1]
	s_cbranch_execz .LBB0_283
	v_and_or_b32 v134, v190, 29, v141
	v_add_u32_e32 v194, 0x1000, v134
	v_ashrrev_i32_e32 v195, 31, v194
	s_waitcnt vmcnt(0)
	v_mov_b32_e32 v199, v180
	v_mov_b32_e32 v202, v186
	v_mov_b32_e32 v203, v184
	s_waitcnt lgkmcnt(2)
	v_pk_mul_f32 v[192:193], v[172:173], v[192:193] op_sel_hi:[0,1]
	v_mov_b32_e32 v184, v187
	s_waitcnt lgkmcnt(0)
	v_pk_mul_f32 v[186:187], v[172:173], v[188:189] op_sel_hi:[0,1]
	v_mov_b32_e32 v180, v183
	v_mov_b32_e32 v196, v117
	v_mov_b32_e32 v197, v113
	v_mov_b32_e32 v198, v182
	v_mov_b32_e32 v200, v125
	v_mov_b32_e32 v201, v121
	v_lshlrev_b64 v[194:195], 6, v[194:195]
	v_ashrrev_i32_e32 v191, 31, v190
	v_pk_mul_f32 v[184:185], v[184:185], v[192:193]
	v_pk_mul_f32 v[180:181], v[180:181], v[186:187]
	v_lshl_add_u64 v[194:195], v[176:177], 0, v[194:195]
	v_lshlrev_b64 v[190:191], 7, v[190:191]
	v_pk_fma_f32 v[184:185], v[200:201], v[202:203], v[184:185]
	v_pk_fma_f32 v[186:187], v[196:197], v[198:199], v[180:181]
	v_cvt_pk_bf16_f32 v182, v184, v185
	v_lshl_add_u64 v[190:191], v[174:175], 0, v[190:191]
	v_cvt_pk_bf16_f32 v183, v186, v187
	global_store_dwordx2 v[194:195], v[182:183], off
	global_store_dwordx4 v[190:191], v[184:187], off nt

.LBB0_287:
	s_andn2_saveexec_b64 s[0:1], s[0:1]
	s_cbranch_execz .LBB0_289
	v_add_co_u32_e32 v192, vcc, 0x80000, v192
	v_or_b32_e32 v134, v141, v143
	s_nop 0
	v_addc_co_u32_e32 v193, vcc, 0, v193, vcc
	global_load_dwordx2 v[198:199], v[192:193], off offset:16
	global_load_dwordx2 v[200:201], v[192:193], off
	v_mov_b32_e32 v202, v126
	v_mov_b32_e32 v203, v122
	v_add_u32_e32 v196, 0x1000, v134
	s_waitcnt lgkmcnt(2)
	v_pk_mul_f32 v[190:191], v[172:173], v[190:191] op_sel_hi:[0,1]
	v_ashrrev_i32_e32 v197, 31, v196
	v_lshlrev_b64 v[196:197], 6, v[196:197]
	v_ashrrev_i32_e32 v195, 31, v194
	s_waitcnt lgkmcnt(0)
	v_pk_mul_f32 v[188:189], v[172:173], v[188:189] op_sel_hi:[0,1]
	v_lshl_add_u64 v[196:197], v[176:177], 0, v[196:197]
	v_lshlrev_b64 v[194:195], 7, v[194:195]
	v_lshl_add_u64 v[194:195], v[174:175], 0, v[194:195]
	s_waitcnt vmcnt(1)
	v_mov_b32_e32 v207, v198
	s_waitcnt vmcnt(0)
	v_mov_b32_e32 v206, v200
	v_mov_b32_e32 v198, v201
	global_load_dwordx2 v[200:201], v[192:193], off offset:48
	s_nop 0
	global_load_dwordx2 v[192:193], v[192:193], off offset:32
	v_pk_mul_f32 v[202:203], v[202:203], v[206:207]
	s_waitcnt vmcnt(1)
	v_mov_b32_e32 v207, v200
	v_pk_fma_f32 v[190:191], v[190:191], v[198:199], v[202:203]
	v_mov_b32_e32 v202, v118
	v_mov_b32_e32 v203, v114
	s_waitcnt vmcnt(0)
	v_mov_b32_e32 v206, v192
	v_pk_mul_f32 v[202:203], v[202:203], v[206:207]
	v_mov_b32_e32 v200, v193
	v_cvt_pk_bf16_f32 v198, v190, v191
	v_pk_fma_f32 v[192:193], v[188:189], v[200:201], v[202:203]
	s_nop 0
	v_cvt_pk_bf16_f32 v199, v192, v193
	global_store_dwordx2 v[196:197], v[198:199], off
	global_store_dwordx4 v[194:195], v[190:193], off nt

.LBB0_293:
	s_andn2_saveexec_b64 s[0:1], s[0:1]
	s_cbranch_execz .LBB0_295
	v_and_or_b32 v134, v190, 31, v141
	v_add_u32_e32 v194, 0x1000, v134
	v_ashrrev_i32_e32 v195, 31, v194
	s_waitcnt vmcnt(0)
	v_mov_b32_e32 v199, v180
	v_mov_b32_e32 v202, v186
	v_mov_b32_e32 v203, v184
	s_waitcnt lgkmcnt(2)
	v_pk_mul_f32 v[192:193], v[172:173], v[192:193] op_sel_hi:[0,1]
	v_mov_b32_e32 v184, v187
	s_waitcnt lgkmcnt(0)
	v_pk_mul_f32 v[186:187], v[172:173], v[188:189] op_sel_hi:[0,1]
	v_mov_b32_e32 v180, v183
	v_mov_b32_e32 v196, v119
	v_mov_b32_e32 v197, v115
	v_mov_b32_e32 v198, v182
	v_mov_b32_e32 v200, v127
	v_mov_b32_e32 v201, v123
	v_lshlrev_b64 v[194:195], 6, v[194:195]
	v_ashrrev_i32_e32 v191, 31, v190
	v_pk_mul_f32 v[184:185], v[184:185], v[192:193]
	v_pk_mul_f32 v[180:181], v[180:181], v[186:187]
	v_lshl_add_u64 v[194:195], v[176:177], 0, v[194:195]
	v_lshlrev_b64 v[190:191], 7, v[190:191]
	v_pk_fma_f32 v[184:185], v[200:201], v[202:203], v[184:185]
	v_pk_fma_f32 v[186:187], v[196:197], v[198:199], v[180:181]
	v_cvt_pk_bf16_f32 v182, v184, v185
	v_lshl_add_u64 v[190:191], v[174:175], 0, v[190:191]
	v_cvt_pk_bf16_f32 v183, v186, v187
	global_store_dwordx2 v[194:195], v[182:183], off
	global_store_dwordx4 v[190:191], v[184:187], off nt

.LBB0_299:
	s_andn2_saveexec_b64 s[0:1], s[0:1]
	s_cbranch_execz .LBB0_301
	v_add_co_u32_e32 v192, vcc, 0x80000, v192
	v_lshrrev_b32_e32 v134, 5, v194
	s_nop 0
	v_addc_co_u32_e32 v193, vcc, 0, v193, vcc
	global_load_dwordx2 v[198:199], v[192:193], off offset:16
	global_load_dwordx2 v[200:201], v[192:193], off
	v_mul_lo_u32 v134, v134, s12
	v_or_b32_e32 v134, v134, v141
	v_mov_b32_e32 v202, v108
	v_mov_b32_e32 v203, v104
	v_add_u32_e32 v196, 0x1000, v134
	s_waitcnt lgkmcnt(2)
	v_pk_mul_f32 v[190:191], v[172:173], v[190:191] op_sel_hi:[0,1]
	v_ashrrev_i32_e32 v197, 31, v196
	v_lshlrev_b64 v[196:197], 6, v[196:197]
	v_ashrrev_i32_e32 v195, 31, v194
	s_waitcnt lgkmcnt(0)
	v_pk_mul_f32 v[188:189], v[172:173], v[188:189] op_sel_hi:[0,1]
	v_lshl_add_u64 v[196:197], v[176:177], 0, v[196:197]
	v_lshlrev_b64 v[194:195], 7, v[194:195]
	v_lshl_add_u64 v[194:195], v[174:175], 0, v[194:195]
	s_waitcnt vmcnt(1)
	v_mov_b32_e32 v207, v198
	s_waitcnt vmcnt(0)
	v_mov_b32_e32 v206, v200
	v_mov_b32_e32 v198, v201
	global_load_dwordx2 v[200:201], v[192:193], off offset:48
	s_nop 0
	global_load_dwordx2 v[192:193], v[192:193], off offset:32
	v_pk_mul_f32 v[202:203], v[202:203], v[206:207]
	s_waitcnt vmcnt(1)
	v_mov_b32_e32 v207, v200
	v_pk_fma_f32 v[190:191], v[190:191], v[198:199], v[202:203]
	v_mov_b32_e32 v202, v100
	v_mov_b32_e32 v203, v96
	s_waitcnt vmcnt(0)
	v_mov_b32_e32 v206, v192
	v_pk_mul_f32 v[202:203], v[202:203], v[206:207]
	v_mov_b32_e32 v200, v193
	v_cvt_pk_bf16_f32 v198, v190, v191
	v_pk_fma_f32 v[192:193], v[188:189], v[200:201], v[202:203]
	s_nop 0
	v_cvt_pk_bf16_f32 v199, v192, v193
	global_store_dwordx2 v[196:197], v[198:199], off
	global_store_dwordx4 v[194:195], v[190:193], off nt

.LBB0_305:
	s_andn2_saveexec_b64 s[0:1], s[0:1]
	s_cbranch_execz .LBB0_307
	v_lshrrev_b32_e32 v134, 5, v190
	v_mul_lo_u32 v134, v134, s12
	v_and_or_b32 v134, v190, 29, v134
	v_add_u32_e32 v194, 0x1000, v134
	v_ashrrev_i32_e32 v195, 31, v194
	s_waitcnt vmcnt(0)
	v_mov_b32_e32 v199, v180
	v_mov_b32_e32 v202, v186
	v_mov_b32_e32 v203, v184
	s_waitcnt lgkmcnt(2)
	v_pk_mul_f32 v[192:193], v[172:173], v[192:193] op_sel_hi:[0,1]
	v_mov_b32_e32 v184, v187
	s_waitcnt lgkmcnt(0)
	v_pk_mul_f32 v[186:187], v[172:173], v[188:189] op_sel_hi:[0,1]
	v_mov_b32_e32 v180, v183
	v_mov_b32_e32 v196, v101
	v_mov_b32_e32 v197, v97
	v_mov_b32_e32 v198, v182
	v_mov_b32_e32 v200, v109
	v_mov_b32_e32 v201, v105
	v_lshlrev_b64 v[194:195], 6, v[194:195]
	v_ashrrev_i32_e32 v191, 31, v190
	v_pk_mul_f32 v[184:185], v[184:185], v[192:193]
	v_pk_mul_f32 v[180:181], v[180:181], v[186:187]
	v_lshl_add_u64 v[194:195], v[176:177], 0, v[194:195]
	v_lshlrev_b64 v[190:191], 7, v[190:191]
	v_pk_fma_f32 v[184:185], v[200:201], v[202:203], v[184:185]
	v_pk_fma_f32 v[186:187], v[196:197], v[198:199], v[180:181]
	v_cvt_pk_bf16_f32 v182, v184, v185
	v_lshl_add_u64 v[190:191], v[174:175], 0, v[190:191]
	v_cvt_pk_bf16_f32 v183, v186, v187
	global_store_dwordx2 v[194:195], v[182:183], off
	global_store_dwordx4 v[190:191], v[184:187], off nt

.LBB0_311:
	s_andn2_saveexec_b64 s[0:1], s[0:1]
	s_cbranch_execz .LBB0_313
	v_add_co_u32_e32 v192, vcc, 0x80000, v192
	v_lshrrev_b32_e32 v134, 5, v194
	s_nop 0
	v_addc_co_u32_e32 v193, vcc, 0, v193, vcc
	global_load_dwordx2 v[198:199], v[192:193], off offset:16
	global_load_dwordx2 v[200:201], v[192:193], off
	v_mul_lo_u32 v134, v134, s12
	v_or_b32_e32 v134, v134, v141
	v_mov_b32_e32 v202, v110
	v_mov_b32_e32 v203, v106
	v_add_u32_e32 v196, 0x1000, v134
	s_waitcnt lgkmcnt(2)
	v_pk_mul_f32 v[190:191], v[172:173], v[190:191] op_sel_hi:[0,1]
	v_ashrrev_i32_e32 v197, 31, v196
	v_lshlrev_b64 v[196:197], 6, v[196:197]
	v_ashrrev_i32_e32 v195, 31, v194
	s_waitcnt lgkmcnt(0)
	v_pk_mul_f32 v[188:189], v[172:173], v[188:189] op_sel_hi:[0,1]
	v_lshl_add_u64 v[196:197], v[176:177], 0, v[196:197]
	v_lshlrev_b64 v[194:195], 7, v[194:195]
	v_lshl_add_u64 v[194:195], v[174:175], 0, v[194:195]
	s_waitcnt vmcnt(1)
	v_mov_b32_e32 v207, v198
	s_waitcnt vmcnt(0)
	v_mov_b32_e32 v206, v200
	v_mov_b32_e32 v198, v201
	global_load_dwordx2 v[200:201], v[192:193], off offset:48
	s_nop 0
	global_load_dwordx2 v[192:193], v[192:193], off offset:32
	v_pk_mul_f32 v[202:203], v[202:203], v[206:207]
	s_waitcnt vmcnt(1)
	v_mov_b32_e32 v207, v200
	v_pk_fma_f32 v[190:191], v[190:191], v[198:199], v[202:203]
	v_mov_b32_e32 v202, v102
	v_mov_b32_e32 v203, v98
	s_waitcnt vmcnt(0)
	v_mov_b32_e32 v206, v192
	v_pk_mul_f32 v[202:203], v[202:203], v[206:207]
	v_mov_b32_e32 v200, v193
	v_cvt_pk_bf16_f32 v198, v190, v191
	v_pk_fma_f32 v[192:193], v[188:189], v[200:201], v[202:203]
	s_nop 0
	v_cvt_pk_bf16_f32 v199, v192, v193
	global_store_dwordx2 v[196:197], v[198:199], off
	global_store_dwordx4 v[194:195], v[190:193], off nt

.LBB0_317:
	s_andn2_saveexec_b64 s[0:1], s[0:1]
	s_cbranch_execz .LBB0_319
	v_lshrrev_b32_e32 v134, 5, v190
	v_mul_lo_u32 v134, v134, s12
	v_and_or_b32 v134, v190, 31, v134
	v_add_u32_e32 v194, 0x1000, v134
	v_ashrrev_i32_e32 v195, 31, v194
	s_waitcnt vmcnt(0)
	v_mov_b32_e32 v199, v180
	v_mov_b32_e32 v202, v186
	v_mov_b32_e32 v203, v184
	s_waitcnt lgkmcnt(2)
	v_pk_mul_f32 v[192:193], v[172:173], v[192:193] op_sel_hi:[0,1]
	v_mov_b32_e32 v184, v187
	s_waitcnt lgkmcnt(0)
	v_pk_mul_f32 v[186:187], v[172:173], v[188:189] op_sel_hi:[0,1]
	v_mov_b32_e32 v180, v183
	v_mov_b32_e32 v196, v103
	v_mov_b32_e32 v197, v99
	v_mov_b32_e32 v198, v182
	v_mov_b32_e32 v200, v111
	v_mov_b32_e32 v201, v107
	v_lshlrev_b64 v[194:195], 6, v[194:195]
	v_ashrrev_i32_e32 v191, 31, v190
	v_pk_mul_f32 v[184:185], v[184:185], v[192:193]
	v_pk_mul_f32 v[180:181], v[180:181], v[186:187]
	v_lshl_add_u64 v[194:195], v[176:177], 0, v[194:195]
	v_lshlrev_b64 v[190:191], 7, v[190:191]
	v_pk_fma_f32 v[184:185], v[200:201], v[202:203], v[184:185]
	v_pk_fma_f32 v[186:187], v[196:197], v[198:199], v[180:181]
	v_cvt_pk_bf16_f32 v182, v184, v185
	v_lshl_add_u64 v[190:191], v[174:175], 0, v[190:191]
	v_cvt_pk_bf16_f32 v183, v186, v187
	global_store_dwordx2 v[194:195], v[182:183], off
	global_store_dwordx4 v[190:191], v[184:187], off nt

.LBB0_323:
	s_andn2_saveexec_b64 s[0:1], s[0:1]
	s_cbranch_execz .LBB0_325
	v_ashrrev_i32_e32 v201, 31, v200
	v_lshrrev_b32_e32 v134, 5, v200
	v_lshlrev_b64 v[200:201], 7, v[200:201]
	v_lshl_add_u64 v[206:207], v[174:175], 0, v[200:201]
	v_add_co_u32_e32 v200, vcc, 0x80000, v178
	v_mul_lo_u32 v134, v134, s12
	s_nop 0
	v_addc_co_u32_e32 v201, vcc, 0, v179, vcc
	global_load_dwordx2 v[208:209], v[200:201], off offset:16
	global_load_dwordx2 v[214:215], v[200:201], off
	v_or_b32_e32 v134, v134, v139
	v_mov_b32_e32 v216, v92
	v_mov_b32_e32 v217, v88
	v_add_u32_e32 v202, 0x1000, v134
	s_waitcnt lgkmcnt(2)
	v_pk_mul_f32 v[198:199], v[172:173], v[198:199] op_sel_hi:[0,1]
	v_ashrrev_i32_e32 v203, 31, v202
	v_lshlrev_b64 v[202:203], 6, v[202:203]
	s_waitcnt lgkmcnt(0)
	v_pk_mul_f32 v[196:197], v[172:173], v[196:197] op_sel_hi:[0,1]
	v_lshl_add_u64 v[202:203], v[176:177], 0, v[202:203]
	s_waitcnt vmcnt(1)
	v_mov_b32_e32 v219, v208
	s_waitcnt vmcnt(0)
	v_mov_b32_e32 v218, v214
	v_mov_b32_e32 v208, v215
	global_load_dwordx2 v[214:215], v[200:201], off offset:48
	s_nop 0
	global_load_dwordx2 v[200:201], v[200:201], off offset:32
	v_pk_mul_f32 v[216:217], v[216:217], v[218:219]
	s_waitcnt vmcnt(1)
	v_mov_b32_e32 v219, v214
	v_pk_fma_f32 v[198:199], v[198:199], v[208:209], v[216:217]
	v_mov_b32_e32 v216, v84
	v_mov_b32_e32 v217, v80
	s_waitcnt vmcnt(0)
	v_mov_b32_e32 v218, v200
	v_pk_mul_f32 v[216:217], v[216:217], v[218:219]
	v_mov_b32_e32 v214, v201
	v_cvt_pk_bf16_f32 v208, v198, v199
	v_pk_fma_f32 v[200:201], v[196:197], v[214:215], v[216:217]
	s_nop 0
	v_cvt_pk_bf16_f32 v209, v200, v201
	global_store_dwordx2 v[202:203], v[208:209], off
	global_store_dwordx4 v[206:207], v[198:201], off nt

.LBB0_329:
	s_andn2_saveexec_b64 s[0:1], s[0:1]
	s_cbranch_execz .LBB0_331
	v_lshrrev_b32_e32 v134, 5, v198
	v_mul_lo_u32 v134, v134, s12
	v_and_or_b32 v134, v198, 29, v134
	v_add_u32_e32 v202, 0x1000, v134
	v_ashrrev_i32_e32 v203, 31, v202
	s_waitcnt vmcnt(0)
	v_mov_b32_e32 v209, v188
	v_mov_b32_e32 v216, v194
	v_mov_b32_e32 v217, v192
	s_waitcnt lgkmcnt(2)
	v_pk_mul_f32 v[200:201], v[172:173], v[200:201] op_sel_hi:[0,1]
	v_mov_b32_e32 v192, v195
	s_waitcnt lgkmcnt(0)
	v_pk_mul_f32 v[194:195], v[172:173], v[196:197] op_sel_hi:[0,1]
	v_mov_b32_e32 v188, v191
	v_mov_b32_e32 v206, v85
	v_mov_b32_e32 v207, v81
	v_mov_b32_e32 v208, v190
	v_mov_b32_e32 v214, v93
	v_mov_b32_e32 v215, v89
	v_lshlrev_b64 v[202:203], 6, v[202:203]
	v_ashrrev_i32_e32 v199, 31, v198
	v_pk_mul_f32 v[192:193], v[192:193], v[200:201]
	v_pk_mul_f32 v[188:189], v[188:189], v[194:195]
	v_lshl_add_u64 v[202:203], v[176:177], 0, v[202:203]
	v_lshlrev_b64 v[198:199], 7, v[198:199]
	v_pk_fma_f32 v[192:193], v[214:215], v[216:217], v[192:193]
	v_pk_fma_f32 v[194:195], v[206:207], v[208:209], v[188:189]
	v_cvt_pk_bf16_f32 v190, v192, v193
	v_lshl_add_u64 v[198:199], v[174:175], 0, v[198:199]
	v_cvt_pk_bf16_f32 v191, v194, v195
	global_store_dwordx2 v[202:203], v[190:191], off
	global_store_dwordx4 v[198:199], v[192:195], off nt

.LBB0_335:
	s_andn2_saveexec_b64 s[0:1], s[0:1]
	s_cbranch_execz .LBB0_337
	v_add_co_u32_e32 v200, vcc, 0x80000, v200
	v_lshrrev_b32_e32 v134, 5, v202
	s_nop 0
	v_addc_co_u32_e32 v201, vcc, 0, v201, vcc
	global_load_dwordx2 v[208:209], v[200:201], off offset:16
	global_load_dwordx2 v[214:215], v[200:201], off
	v_mul_lo_u32 v134, v134, s12
	v_or_b32_e32 v134, v134, v141
	v_mov_b32_e32 v216, v94
	v_mov_b32_e32 v217, v90
	v_add_u32_e32 v206, 0x1000, v134
	s_waitcnt lgkmcnt(2)
	v_pk_mul_f32 v[198:199], v[172:173], v[198:199] op_sel_hi:[0,1]
	v_ashrrev_i32_e32 v207, 31, v206
	v_lshlrev_b64 v[206:207], 6, v[206:207]
	v_ashrrev_i32_e32 v203, 31, v202
	s_waitcnt lgkmcnt(0)
	v_pk_mul_f32 v[196:197], v[172:173], v[196:197] op_sel_hi:[0,1]
	v_lshl_add_u64 v[206:207], v[176:177], 0, v[206:207]
	v_lshlrev_b64 v[202:203], 7, v[202:203]
	v_lshl_add_u64 v[202:203], v[174:175], 0, v[202:203]
	s_waitcnt vmcnt(1)
	v_mov_b32_e32 v219, v208
	s_waitcnt vmcnt(0)
	v_mov_b32_e32 v218, v214
	v_mov_b32_e32 v208, v215
	global_load_dwordx2 v[214:215], v[200:201], off offset:48
	s_nop 0
	global_load_dwordx2 v[200:201], v[200:201], off offset:32
	v_pk_mul_f32 v[216:217], v[216:217], v[218:219]
	s_waitcnt vmcnt(1)
	v_mov_b32_e32 v219, v214
	v_pk_fma_f32 v[198:199], v[198:199], v[208:209], v[216:217]
	v_mov_b32_e32 v216, v86
	v_mov_b32_e32 v217, v82
	s_waitcnt vmcnt(0)
	v_mov_b32_e32 v218, v200
	v_pk_mul_f32 v[216:217], v[216:217], v[218:219]
	v_mov_b32_e32 v214, v201
	v_cvt_pk_bf16_f32 v208, v198, v199
	v_pk_fma_f32 v[200:201], v[196:197], v[214:215], v[216:217]
	s_nop 0
	v_cvt_pk_bf16_f32 v209, v200, v201
	global_store_dwordx2 v[206:207], v[208:209], off
	global_store_dwordx4 v[202:203], v[198:201], off nt

.LBB0_341:
	s_andn2_saveexec_b64 s[0:1], s[0:1]
	s_cbranch_execz .LBB0_343
	v_lshrrev_b32_e32 v134, 5, v198
	v_mul_lo_u32 v134, v134, s12
	v_and_or_b32 v134, v198, 31, v134
	v_add_u32_e32 v202, 0x1000, v134
	v_ashrrev_i32_e32 v203, 31, v202
	s_waitcnt vmcnt(0)
	v_mov_b32_e32 v209, v188
	v_mov_b32_e32 v216, v194
	v_mov_b32_e32 v217, v192
	s_waitcnt lgkmcnt(2)
	v_pk_mul_f32 v[200:201], v[172:173], v[200:201] op_sel_hi:[0,1]
	v_mov_b32_e32 v192, v195
	s_waitcnt lgkmcnt(0)
	v_pk_mul_f32 v[194:195], v[172:173], v[196:197] op_sel_hi:[0,1]
	v_mov_b32_e32 v188, v191
	v_mov_b32_e32 v206, v87
	v_mov_b32_e32 v207, v83
	v_mov_b32_e32 v208, v190
	v_mov_b32_e32 v214, v95
	v_mov_b32_e32 v215, v91
	v_lshlrev_b64 v[202:203], 6, v[202:203]
	v_ashrrev_i32_e32 v199, 31, v198
	v_pk_mul_f32 v[192:193], v[192:193], v[200:201]
	v_pk_mul_f32 v[188:189], v[188:189], v[194:195]
	v_lshl_add_u64 v[202:203], v[176:177], 0, v[202:203]
	v_lshlrev_b64 v[198:199], 7, v[198:199]
	v_pk_fma_f32 v[192:193], v[214:215], v[216:217], v[192:193]
	v_pk_fma_f32 v[194:195], v[206:207], v[208:209], v[188:189]
	v_cvt_pk_bf16_f32 v190, v192, v193
	v_lshl_add_u64 v[198:199], v[174:175], 0, v[198:199]
	v_cvt_pk_bf16_f32 v191, v194, v195
	global_store_dwordx2 v[202:203], v[190:191], off
	global_store_dwordx4 v[198:199], v[192:195], off nt

.LBB0_347:
	s_andn2_saveexec_b64 s[0:1], s[0:1]
	s_cbranch_execz .LBB0_349
	v_add_co_u32_e32 v200, vcc, 0x80000, v200
	v_lshrrev_b32_e32 v134, 5, v202
	s_nop 0
	v_addc_co_u32_e32 v201, vcc, 0, v201, vcc
	global_load_dwordx2 v[208:209], v[200:201], off offset:16
	global_load_dwordx2 v[214:215], v[200:201], off
	v_mul_lo_u32 v134, v134, s12
	v_or_b32_e32 v134, v134, v141
	v_mov_b32_e32 v216, v76
	v_mov_b32_e32 v217, v72
	v_add_u32_e32 v206, 0x1000, v134
	s_waitcnt lgkmcnt(2)
	v_pk_mul_f32 v[198:199], v[172:173], v[198:199] op_sel_hi:[0,1]
	v_ashrrev_i32_e32 v207, 31, v206
	v_lshlrev_b64 v[206:207], 6, v[206:207]
	v_ashrrev_i32_e32 v203, 31, v202
	s_waitcnt lgkmcnt(0)
	v_pk_mul_f32 v[196:197], v[172:173], v[196:197] op_sel_hi:[0,1]
	v_lshl_add_u64 v[206:207], v[176:177], 0, v[206:207]
	v_lshlrev_b64 v[202:203], 7, v[202:203]
	v_lshl_add_u64 v[202:203], v[174:175], 0, v[202:203]
	s_waitcnt vmcnt(1)
	v_mov_b32_e32 v219, v208
	s_waitcnt vmcnt(0)
	v_mov_b32_e32 v218, v214
	v_mov_b32_e32 v208, v215
	global_load_dwordx2 v[214:215], v[200:201], off offset:48
	s_nop 0
	global_load_dwordx2 v[200:201], v[200:201], off offset:32
	v_pk_mul_f32 v[216:217], v[216:217], v[218:219]
	s_waitcnt vmcnt(1)
	v_mov_b32_e32 v219, v214
	v_pk_fma_f32 v[198:199], v[198:199], v[208:209], v[216:217]
	v_mov_b32_e32 v216, v68
	v_mov_b32_e32 v217, v64
	s_waitcnt vmcnt(0)
	v_mov_b32_e32 v218, v200
	v_pk_mul_f32 v[216:217], v[216:217], v[218:219]
	v_mov_b32_e32 v214, v201
	v_cvt_pk_bf16_f32 v208, v198, v199
	v_pk_fma_f32 v[200:201], v[196:197], v[214:215], v[216:217]
	s_nop 0
	v_cvt_pk_bf16_f32 v209, v200, v201
	global_store_dwordx2 v[206:207], v[208:209], off
	global_store_dwordx4 v[202:203], v[198:201], off nt

.LBB0_353:
	s_andn2_saveexec_b64 s[0:1], s[0:1]
	s_cbranch_execz .LBB0_355
	v_lshrrev_b32_e32 v134, 5, v198
	v_mul_lo_u32 v134, v134, s12
	v_and_or_b32 v134, v198, 29, v134
	v_add_u32_e32 v202, 0x1000, v134
	v_ashrrev_i32_e32 v203, 31, v202
	s_waitcnt vmcnt(0)
	v_mov_b32_e32 v209, v188
	v_mov_b32_e32 v216, v194
	v_mov_b32_e32 v217, v192
	s_waitcnt lgkmcnt(2)
	v_pk_mul_f32 v[200:201], v[172:173], v[200:201] op_sel_hi:[0,1]
	v_mov_b32_e32 v192, v195
	s_waitcnt lgkmcnt(0)
	v_pk_mul_f32 v[194:195], v[172:173], v[196:197] op_sel_hi:[0,1]
	v_mov_b32_e32 v188, v191
	v_mov_b32_e32 v206, v69
	v_mov_b32_e32 v207, v65
	v_mov_b32_e32 v208, v190
	v_mov_b32_e32 v214, v77
	v_mov_b32_e32 v215, v73
	v_lshlrev_b64 v[202:203], 6, v[202:203]
	v_ashrrev_i32_e32 v199, 31, v198
	v_pk_mul_f32 v[192:193], v[192:193], v[200:201]
	v_pk_mul_f32 v[188:189], v[188:189], v[194:195]
	v_lshl_add_u64 v[202:203], v[176:177], 0, v[202:203]
	v_lshlrev_b64 v[198:199], 7, v[198:199]
	v_pk_fma_f32 v[192:193], v[214:215], v[216:217], v[192:193]
	v_pk_fma_f32 v[194:195], v[206:207], v[208:209], v[188:189]
	v_cvt_pk_bf16_f32 v190, v192, v193
	v_lshl_add_u64 v[198:199], v[174:175], 0, v[198:199]
	v_cvt_pk_bf16_f32 v191, v194, v195
	global_store_dwordx2 v[202:203], v[190:191], off
	global_store_dwordx4 v[198:199], v[192:195], off nt

.LBB0_359:
	s_andn2_saveexec_b64 s[0:1], s[0:1]
	s_cbranch_execz .LBB0_361
	v_add_co_u32_e32 v200, vcc, 0x80000, v200
	v_lshrrev_b32_e32 v134, 5, v202
	s_nop 0
	v_addc_co_u32_e32 v201, vcc, 0, v201, vcc
	global_load_dwordx2 v[208:209], v[200:201], off offset:16
	global_load_dwordx2 v[214:215], v[200:201], off
	v_mul_lo_u32 v134, v134, s12
	v_or_b32_e32 v134, v134, v141
	v_mov_b32_e32 v216, v78
	v_mov_b32_e32 v217, v74
	v_add_u32_e32 v206, 0x1000, v134
	s_waitcnt lgkmcnt(2)
	v_pk_mul_f32 v[198:199], v[172:173], v[198:199] op_sel_hi:[0,1]
	v_ashrrev_i32_e32 v207, 31, v206
	v_lshlrev_b64 v[206:207], 6, v[206:207]
	v_ashrrev_i32_e32 v203, 31, v202
	s_waitcnt lgkmcnt(0)
	v_pk_mul_f32 v[196:197], v[172:173], v[196:197] op_sel_hi:[0,1]
	v_lshl_add_u64 v[206:207], v[176:177], 0, v[206:207]
	v_lshlrev_b64 v[202:203], 7, v[202:203]
	v_lshl_add_u64 v[202:203], v[174:175], 0, v[202:203]
	s_waitcnt vmcnt(1)
	v_mov_b32_e32 v219, v208
	s_waitcnt vmcnt(0)
	v_mov_b32_e32 v218, v214
	v_mov_b32_e32 v208, v215
	global_load_dwordx2 v[214:215], v[200:201], off offset:48
	s_nop 0
	global_load_dwordx2 v[200:201], v[200:201], off offset:32
	v_pk_mul_f32 v[216:217], v[216:217], v[218:219]
	s_waitcnt vmcnt(1)
	v_mov_b32_e32 v219, v214
	v_pk_fma_f32 v[198:199], v[198:199], v[208:209], v[216:217]
	v_mov_b32_e32 v216, v70
	v_mov_b32_e32 v217, v66
	s_waitcnt vmcnt(0)
	v_mov_b32_e32 v218, v200
	v_pk_mul_f32 v[216:217], v[216:217], v[218:219]
	v_mov_b32_e32 v214, v201
	v_cvt_pk_bf16_f32 v208, v198, v199
	v_pk_fma_f32 v[200:201], v[196:197], v[214:215], v[216:217]
	s_nop 0
	v_cvt_pk_bf16_f32 v209, v200, v201
	global_store_dwordx2 v[206:207], v[208:209], off
	global_store_dwordx4 v[202:203], v[198:201], off nt

.LBB0_365:
	s_andn2_saveexec_b64 s[0:1], s[0:1]
	s_cbranch_execz .LBB0_367
	v_lshrrev_b32_e32 v134, 5, v198
	v_mul_lo_u32 v134, v134, s12
	v_and_or_b32 v134, v198, 31, v134
	v_add_u32_e32 v202, 0x1000, v134
	v_ashrrev_i32_e32 v203, 31, v202
	s_waitcnt vmcnt(0)
	v_mov_b32_e32 v209, v188
	v_mov_b32_e32 v216, v194
	v_mov_b32_e32 v217, v192
	s_waitcnt lgkmcnt(2)
	v_pk_mul_f32 v[200:201], v[172:173], v[200:201] op_sel_hi:[0,1]
	v_mov_b32_e32 v192, v195
	s_waitcnt lgkmcnt(0)
	v_pk_mul_f32 v[194:195], v[172:173], v[196:197] op_sel_hi:[0,1]
	v_mov_b32_e32 v188, v191
	v_mov_b32_e32 v206, v71
	v_mov_b32_e32 v207, v67
	v_mov_b32_e32 v208, v190
	v_mov_b32_e32 v214, v79
	v_mov_b32_e32 v215, v75
	v_lshlrev_b64 v[202:203], 6, v[202:203]
	v_ashrrev_i32_e32 v199, 31, v198
	v_pk_mul_f32 v[192:193], v[192:193], v[200:201]
	v_pk_mul_f32 v[188:189], v[188:189], v[194:195]
	v_lshl_add_u64 v[202:203], v[176:177], 0, v[202:203]
	v_lshlrev_b64 v[198:199], 7, v[198:199]
	v_pk_fma_f32 v[192:193], v[214:215], v[216:217], v[192:193]
	v_pk_fma_f32 v[194:195], v[206:207], v[208:209], v[188:189]
	v_cvt_pk_bf16_f32 v190, v192, v193
	v_lshl_add_u64 v[198:199], v[174:175], 0, v[198:199]
	v_cvt_pk_bf16_f32 v191, v194, v195
	global_store_dwordx2 v[202:203], v[190:191], off
	global_store_dwordx4 v[198:199], v[192:195], off nt

.LBB0_371:
	s_andn2_saveexec_b64 s[0:1], s[0:1]
	s_cbranch_execz .LBB0_373
	v_ashrrev_i32_e32 v201, 31, v200
	v_lshrrev_b32_e32 v134, 5, v200
	v_lshlrev_b64 v[200:201], 7, v[200:201]
	v_lshl_add_u64 v[206:207], v[174:175], 0, v[200:201]
	v_add_co_u32_e32 v200, vcc, 0x80000, v178
	v_mul_lo_u32 v134, v134, s12
	s_nop 0
	v_addc_co_u32_e32 v201, vcc, 0, v179, vcc
	global_load_dwordx2 v[208:209], v[200:201], off offset:16
	global_load_dwordx2 v[214:215], v[200:201], off
	v_or_b32_e32 v134, v134, v139
	v_mov_b32_e32 v216, v60
	v_mov_b32_e32 v217, v56
	v_add_u32_e32 v202, 0x1000, v134
	s_waitcnt lgkmcnt(2)
	v_pk_mul_f32 v[198:199], v[172:173], v[198:199] op_sel_hi:[0,1]
	v_ashrrev_i32_e32 v203, 31, v202
	v_lshlrev_b64 v[202:203], 6, v[202:203]
	s_waitcnt lgkmcnt(0)
	v_pk_mul_f32 v[196:197], v[172:173], v[196:197] op_sel_hi:[0,1]
	v_lshl_add_u64 v[202:203], v[176:177], 0, v[202:203]
	s_waitcnt vmcnt(1)
	v_mov_b32_e32 v219, v208
	s_waitcnt vmcnt(0)
	v_mov_b32_e32 v218, v214
	v_mov_b32_e32 v208, v215
	global_load_dwordx2 v[214:215], v[200:201], off offset:48
	s_nop 0
	global_load_dwordx2 v[200:201], v[200:201], off offset:32
	v_pk_mul_f32 v[216:217], v[216:217], v[218:219]
	s_waitcnt vmcnt(1)
	v_mov_b32_e32 v219, v214
	v_pk_fma_f32 v[198:199], v[198:199], v[208:209], v[216:217]
	v_mov_b32_e32 v216, v52
	v_mov_b32_e32 v217, v48
	s_waitcnt vmcnt(0)
	v_mov_b32_e32 v218, v200
	v_pk_mul_f32 v[216:217], v[216:217], v[218:219]
	v_mov_b32_e32 v214, v201
	v_cvt_pk_bf16_f32 v208, v198, v199
	v_pk_fma_f32 v[200:201], v[196:197], v[214:215], v[216:217]
	s_nop 0
	v_cvt_pk_bf16_f32 v209, v200, v201
	global_store_dwordx2 v[202:203], v[208:209], off
	global_store_dwordx4 v[206:207], v[198:201], off nt

.LBB0_377:
	s_andn2_saveexec_b64 s[0:1], s[0:1]
	s_cbranch_execz .LBB0_379
	v_lshrrev_b32_e32 v134, 5, v198
	v_mul_lo_u32 v134, v134, s12
	v_and_or_b32 v134, v198, 29, v134
	v_add_u32_e32 v202, 0x1000, v134
	v_ashrrev_i32_e32 v203, 31, v202
	s_waitcnt vmcnt(0)
	v_mov_b32_e32 v209, v188
	v_mov_b32_e32 v216, v194
	v_mov_b32_e32 v217, v192
	s_waitcnt lgkmcnt(2)
	v_pk_mul_f32 v[200:201], v[172:173], v[200:201] op_sel_hi:[0,1]
	v_mov_b32_e32 v192, v195
	s_waitcnt lgkmcnt(0)
	v_pk_mul_f32 v[194:195], v[172:173], v[196:197] op_sel_hi:[0,1]
	v_mov_b32_e32 v188, v191
	v_mov_b32_e32 v206, v53
	v_mov_b32_e32 v207, v49
	v_mov_b32_e32 v208, v190
	v_mov_b32_e32 v214, v61
	v_mov_b32_e32 v215, v57
	v_lshlrev_b64 v[202:203], 6, v[202:203]
	v_ashrrev_i32_e32 v199, 31, v198
	v_pk_mul_f32 v[192:193], v[192:193], v[200:201]
	v_pk_mul_f32 v[188:189], v[188:189], v[194:195]
	v_lshl_add_u64 v[202:203], v[176:177], 0, v[202:203]
	v_lshlrev_b64 v[198:199], 7, v[198:199]
	v_pk_fma_f32 v[192:193], v[214:215], v[216:217], v[192:193]
	v_pk_fma_f32 v[194:195], v[206:207], v[208:209], v[188:189]
	v_cvt_pk_bf16_f32 v190, v192, v193
	v_lshl_add_u64 v[198:199], v[174:175], 0, v[198:199]
	v_cvt_pk_bf16_f32 v191, v194, v195
	global_store_dwordx2 v[202:203], v[190:191], off
	global_store_dwordx4 v[198:199], v[192:195], off nt

.LBB0_383:
	s_andn2_saveexec_b64 s[0:1], s[0:1]
	s_cbranch_execz .LBB0_385
	v_add_co_u32_e32 v200, vcc, 0x80000, v200
	v_lshrrev_b32_e32 v134, 5, v202
	s_nop 0
	v_addc_co_u32_e32 v201, vcc, 0, v201, vcc
	global_load_dwordx2 v[208:209], v[200:201], off offset:16
	global_load_dwordx2 v[214:215], v[200:201], off
	v_mul_lo_u32 v134, v134, s12
	v_or_b32_e32 v134, v134, v141
	v_mov_b32_e32 v216, v62
	v_mov_b32_e32 v217, v58
	v_add_u32_e32 v206, 0x1000, v134
	s_waitcnt lgkmcnt(2)
	v_pk_mul_f32 v[198:199], v[172:173], v[198:199] op_sel_hi:[0,1]
	v_ashrrev_i32_e32 v207, 31, v206
	v_lshlrev_b64 v[206:207], 6, v[206:207]
	v_ashrrev_i32_e32 v203, 31, v202
	s_waitcnt lgkmcnt(0)
	v_pk_mul_f32 v[196:197], v[172:173], v[196:197] op_sel_hi:[0,1]
	v_lshl_add_u64 v[206:207], v[176:177], 0, v[206:207]
	v_lshlrev_b64 v[202:203], 7, v[202:203]
	v_lshl_add_u64 v[202:203], v[174:175], 0, v[202:203]
	s_waitcnt vmcnt(1)
	v_mov_b32_e32 v219, v208
	s_waitcnt vmcnt(0)
	v_mov_b32_e32 v218, v214
	v_mov_b32_e32 v208, v215
	global_load_dwordx2 v[214:215], v[200:201], off offset:48
	s_nop 0
	global_load_dwordx2 v[200:201], v[200:201], off offset:32
	v_pk_mul_f32 v[216:217], v[216:217], v[218:219]
	s_waitcnt vmcnt(1)
	v_mov_b32_e32 v219, v214
	v_pk_fma_f32 v[198:199], v[198:199], v[208:209], v[216:217]
	v_mov_b32_e32 v216, v54
	v_mov_b32_e32 v217, v50
	s_waitcnt vmcnt(0)
	v_mov_b32_e32 v218, v200
	v_pk_mul_f32 v[216:217], v[216:217], v[218:219]
	v_mov_b32_e32 v214, v201
	v_cvt_pk_bf16_f32 v208, v198, v199
	v_pk_fma_f32 v[200:201], v[196:197], v[214:215], v[216:217]
	s_nop 0
	v_cvt_pk_bf16_f32 v209, v200, v201
	global_store_dwordx2 v[206:207], v[208:209], off
	global_store_dwordx4 v[202:203], v[198:201], off nt

.LBB0_389:
	s_andn2_saveexec_b64 s[0:1], s[0:1]
	s_cbranch_execz .LBB0_391
	v_lshrrev_b32_e32 v134, 5, v198
	v_mul_lo_u32 v134, v134, s12
	v_and_or_b32 v134, v198, 31, v134
	v_add_u32_e32 v202, 0x1000, v134
	v_ashrrev_i32_e32 v203, 31, v202
	s_waitcnt vmcnt(0)
	v_mov_b32_e32 v209, v188
	v_mov_b32_e32 v216, v194
	v_mov_b32_e32 v217, v192
	s_waitcnt lgkmcnt(2)
	v_pk_mul_f32 v[200:201], v[172:173], v[200:201] op_sel_hi:[0,1]
	v_mov_b32_e32 v192, v195
	s_waitcnt lgkmcnt(0)
	v_pk_mul_f32 v[194:195], v[172:173], v[196:197] op_sel_hi:[0,1]
	v_mov_b32_e32 v188, v191
	v_mov_b32_e32 v206, v55
	v_mov_b32_e32 v207, v51
	v_mov_b32_e32 v208, v190
	v_mov_b32_e32 v214, v63
	v_mov_b32_e32 v215, v59
	v_lshlrev_b64 v[202:203], 6, v[202:203]
	v_ashrrev_i32_e32 v199, 31, v198
	v_pk_mul_f32 v[192:193], v[192:193], v[200:201]
	v_pk_mul_f32 v[188:189], v[188:189], v[194:195]
	v_lshl_add_u64 v[202:203], v[176:177], 0, v[202:203]
	v_lshlrev_b64 v[198:199], 7, v[198:199]
	v_pk_fma_f32 v[192:193], v[214:215], v[216:217], v[192:193]
	v_pk_fma_f32 v[194:195], v[206:207], v[208:209], v[188:189]
	v_cvt_pk_bf16_f32 v190, v192, v193
	v_lshl_add_u64 v[198:199], v[174:175], 0, v[198:199]
	v_cvt_pk_bf16_f32 v191, v194, v195
	global_store_dwordx2 v[202:203], v[190:191], off
	global_store_dwordx4 v[198:199], v[192:195], off nt

.LBB0_395:
	s_andn2_saveexec_b64 s[0:1], s[0:1]
	s_cbranch_execz .LBB0_397
	v_add_co_u32_e32 v200, vcc, 0x80000, v200
	v_lshrrev_b32_e32 v134, 5, v202
	s_nop 0
	v_addc_co_u32_e32 v201, vcc, 0, v201, vcc
	global_load_dwordx2 v[208:209], v[200:201], off offset:16
	global_load_dwordx2 v[214:215], v[200:201], off
	v_mul_lo_u32 v134, v134, s12
	v_or_b32_e32 v134, v134, v141
	v_mov_b32_e32 v216, v44
	v_mov_b32_e32 v217, v40
	v_add_u32_e32 v206, 0x1000, v134
	s_waitcnt lgkmcnt(2)
	v_pk_mul_f32 v[198:199], v[172:173], v[198:199] op_sel_hi:[0,1]
	v_ashrrev_i32_e32 v207, 31, v206
	v_lshlrev_b64 v[206:207], 6, v[206:207]
	v_ashrrev_i32_e32 v203, 31, v202
	s_waitcnt lgkmcnt(0)
	v_pk_mul_f32 v[196:197], v[172:173], v[196:197] op_sel_hi:[0,1]
	v_lshl_add_u64 v[206:207], v[176:177], 0, v[206:207]
	v_lshlrev_b64 v[202:203], 7, v[202:203]
	v_lshl_add_u64 v[202:203], v[174:175], 0, v[202:203]
	s_waitcnt vmcnt(1)
	v_mov_b32_e32 v219, v208
	s_waitcnt vmcnt(0)
	v_mov_b32_e32 v218, v214
	v_mov_b32_e32 v208, v215
	global_load_dwordx2 v[214:215], v[200:201], off offset:48
	s_nop 0
	global_load_dwordx2 v[200:201], v[200:201], off offset:32
	v_pk_mul_f32 v[216:217], v[216:217], v[218:219]
	s_waitcnt vmcnt(1)
	v_mov_b32_e32 v219, v214
	v_pk_fma_f32 v[198:199], v[198:199], v[208:209], v[216:217]
	v_mov_b32_e32 v216, v36
	v_mov_b32_e32 v217, v32
	s_waitcnt vmcnt(0)
	v_mov_b32_e32 v218, v200
	v_pk_mul_f32 v[216:217], v[216:217], v[218:219]
	v_mov_b32_e32 v214, v201
	v_cvt_pk_bf16_f32 v208, v198, v199
	v_pk_fma_f32 v[200:201], v[196:197], v[214:215], v[216:217]
	s_nop 0
	v_cvt_pk_bf16_f32 v209, v200, v201
	global_store_dwordx2 v[206:207], v[208:209], off
	global_store_dwordx4 v[202:203], v[198:201], off nt

.LBB0_401:
	s_andn2_saveexec_b64 s[0:1], s[0:1]
	s_cbranch_execz .LBB0_403
	v_lshrrev_b32_e32 v134, 5, v198
	v_mul_lo_u32 v134, v134, s12
	v_and_or_b32 v134, v198, 29, v134
	v_add_u32_e32 v202, 0x1000, v134
	v_ashrrev_i32_e32 v203, 31, v202
	s_waitcnt vmcnt(0)
	v_mov_b32_e32 v209, v188
	v_mov_b32_e32 v216, v194
	v_mov_b32_e32 v217, v192
	s_waitcnt lgkmcnt(2)
	v_pk_mul_f32 v[200:201], v[172:173], v[200:201] op_sel_hi:[0,1]
	v_mov_b32_e32 v192, v195
	s_waitcnt lgkmcnt(0)
	v_pk_mul_f32 v[194:195], v[172:173], v[196:197] op_sel_hi:[0,1]
	v_mov_b32_e32 v188, v191
	v_mov_b32_e32 v206, v37
	v_mov_b32_e32 v207, v33
	v_mov_b32_e32 v208, v190
	v_mov_b32_e32 v214, v45
	v_mov_b32_e32 v215, v41
	v_lshlrev_b64 v[202:203], 6, v[202:203]
	v_ashrrev_i32_e32 v199, 31, v198
	v_pk_mul_f32 v[192:193], v[192:193], v[200:201]
	v_pk_mul_f32 v[188:189], v[188:189], v[194:195]
	v_lshl_add_u64 v[202:203], v[176:177], 0, v[202:203]
	v_lshlrev_b64 v[198:199], 7, v[198:199]
	v_pk_fma_f32 v[192:193], v[214:215], v[216:217], v[192:193]
	v_pk_fma_f32 v[194:195], v[206:207], v[208:209], v[188:189]
	v_cvt_pk_bf16_f32 v190, v192, v193
	v_lshl_add_u64 v[198:199], v[174:175], 0, v[198:199]
	v_cvt_pk_bf16_f32 v191, v194, v195
	global_store_dwordx2 v[202:203], v[190:191], off
	global_store_dwordx4 v[198:199], v[192:195], off nt

.LBB0_407:
	s_andn2_saveexec_b64 s[0:1], s[0:1]
	s_cbranch_execz .LBB0_409
	v_add_co_u32_e32 v200, vcc, 0x80000, v200
	v_lshrrev_b32_e32 v134, 5, v202
	s_nop 0
	v_addc_co_u32_e32 v201, vcc, 0, v201, vcc
	global_load_dwordx2 v[208:209], v[200:201], off offset:16
	global_load_dwordx2 v[214:215], v[200:201], off
	v_mul_lo_u32 v134, v134, s12
	v_or_b32_e32 v134, v134, v141
	v_mov_b32_e32 v216, v46
	v_mov_b32_e32 v217, v42
	v_add_u32_e32 v206, 0x1000, v134
	s_waitcnt lgkmcnt(2)
	v_pk_mul_f32 v[198:199], v[172:173], v[198:199] op_sel_hi:[0,1]
	v_ashrrev_i32_e32 v207, 31, v206
	v_lshlrev_b64 v[206:207], 6, v[206:207]
	v_ashrrev_i32_e32 v203, 31, v202
	s_waitcnt lgkmcnt(0)
	v_pk_mul_f32 v[196:197], v[172:173], v[196:197] op_sel_hi:[0,1]
	v_lshl_add_u64 v[206:207], v[176:177], 0, v[206:207]
	v_lshlrev_b64 v[202:203], 7, v[202:203]
	v_lshl_add_u64 v[202:203], v[174:175], 0, v[202:203]
	s_waitcnt vmcnt(1)
	v_mov_b32_e32 v219, v208
	s_waitcnt vmcnt(0)
	v_mov_b32_e32 v218, v214
	v_mov_b32_e32 v208, v215
	global_load_dwordx2 v[214:215], v[200:201], off offset:48
	s_nop 0
	global_load_dwordx2 v[200:201], v[200:201], off offset:32
	v_pk_mul_f32 v[216:217], v[216:217], v[218:219]
	s_waitcnt vmcnt(1)
	v_mov_b32_e32 v219, v214
	v_pk_fma_f32 v[198:199], v[198:199], v[208:209], v[216:217]
	v_mov_b32_e32 v216, v38
	v_mov_b32_e32 v217, v34
	s_waitcnt vmcnt(0)
	v_mov_b32_e32 v218, v200
	v_pk_mul_f32 v[216:217], v[216:217], v[218:219]
	v_mov_b32_e32 v214, v201
	v_cvt_pk_bf16_f32 v208, v198, v199
	v_pk_fma_f32 v[200:201], v[196:197], v[214:215], v[216:217]
	s_nop 0
	v_cvt_pk_bf16_f32 v209, v200, v201
	global_store_dwordx2 v[206:207], v[208:209], off
	global_store_dwordx4 v[202:203], v[198:201], off nt

.LBB0_413:
	s_andn2_saveexec_b64 s[0:1], s[0:1]
	s_cbranch_execz .LBB0_415
	v_lshrrev_b32_e32 v134, 5, v198
	v_mul_lo_u32 v134, v134, s12
	v_and_or_b32 v134, v198, 31, v134
	v_add_u32_e32 v202, 0x1000, v134
	v_ashrrev_i32_e32 v203, 31, v202
	s_waitcnt vmcnt(0)
	v_mov_b32_e32 v209, v188
	v_mov_b32_e32 v216, v194
	v_mov_b32_e32 v217, v192
	s_waitcnt lgkmcnt(2)
	v_pk_mul_f32 v[200:201], v[172:173], v[200:201] op_sel_hi:[0,1]
	v_mov_b32_e32 v192, v195
	s_waitcnt lgkmcnt(0)
	v_pk_mul_f32 v[194:195], v[172:173], v[196:197] op_sel_hi:[0,1]
	v_mov_b32_e32 v188, v191
	v_mov_b32_e32 v206, v39
	v_mov_b32_e32 v207, v35
	v_mov_b32_e32 v208, v190
	v_mov_b32_e32 v214, v47
	v_mov_b32_e32 v215, v43
	v_lshlrev_b64 v[202:203], 6, v[202:203]
	v_ashrrev_i32_e32 v199, 31, v198
	v_pk_mul_f32 v[192:193], v[192:193], v[200:201]
	v_pk_mul_f32 v[188:189], v[188:189], v[194:195]
	v_lshl_add_u64 v[202:203], v[176:177], 0, v[202:203]
	v_lshlrev_b64 v[198:199], 7, v[198:199]
	v_pk_fma_f32 v[192:193], v[214:215], v[216:217], v[192:193]
	v_pk_fma_f32 v[194:195], v[206:207], v[208:209], v[188:189]
	v_cvt_pk_bf16_f32 v190, v192, v193
	v_lshl_add_u64 v[198:199], v[174:175], 0, v[198:199]
	v_cvt_pk_bf16_f32 v191, v194, v195
	global_store_dwordx2 v[202:203], v[190:191], off
	global_store_dwordx4 v[198:199], v[192:195], off nt

.LBB0_419:
	s_andn2_saveexec_b64 s[0:1], s[0:1]
	s_cbranch_execz .LBB0_421
	v_lshrrev_b32_e32 v134, 5, v192
	v_mul_lo_u32 v134, v134, s12
	v_or_b32_e32 v134, v134, v139
	v_add_u32_e32 v194, 0x1000, v134
	v_ashrrev_i32_e32 v195, 31, v194
	v_ashrrev_i32_e32 v193, 31, v192
	v_add_co_u32_e32 v178, vcc, 0x80000, v178
	v_lshlrev_b64 v[194:195], 6, v[194:195]
	v_lshlrev_b64 v[192:193], 7, v[192:193]
	v_addc_co_u32_e32 v179, vcc, 0, v179, vcc
	s_waitcnt lgkmcnt(4)
	v_lshl_add_u64 v[196:197], v[176:177], 0, v[194:195]
	v_lshl_add_u64 v[198:199], v[174:175], 0, v[192:193]
	global_load_dwordx2 v[192:193], v[178:179], off offset:16
	global_load_dwordx2 v[194:195], v[178:179], off
	v_mov_b32_e32 v200, v28
	v_mov_b32_e32 v201, v24
	s_waitcnt lgkmcnt(2)
	v_pk_mul_f32 v[186:187], v[172:173], v[186:187] op_sel_hi:[0,1]
	s_waitcnt lgkmcnt(0)
	v_pk_mul_f32 v[184:185], v[172:173], v[184:185] op_sel_hi:[0,1]
	s_waitcnt vmcnt(1)
	v_mov_b32_e32 v203, v192
	s_waitcnt vmcnt(0)
	v_mov_b32_e32 v202, v194
	v_mov_b32_e32 v192, v195
	global_load_dwordx2 v[194:195], v[178:179], off offset:48
	s_nop 0
	global_load_dwordx2 v[178:179], v[178:179], off offset:32
	v_pk_mul_f32 v[200:201], v[200:201], v[202:203]
	s_waitcnt vmcnt(1)
	v_mov_b32_e32 v203, v194
	v_pk_fma_f32 v[192:193], v[186:187], v[192:193], v[200:201]
	v_mov_b32_e32 v200, v20
	v_mov_b32_e32 v201, v16
	s_waitcnt vmcnt(0)
	v_mov_b32_e32 v202, v178
	v_pk_mul_f32 v[200:201], v[200:201], v[202:203]
	v_mov_b32_e32 v194, v179
	v_cvt_pk_bf16_f32 v186, v192, v193
	v_pk_fma_f32 v[194:195], v[184:185], v[194:195], v[200:201]
	s_nop 0
	v_cvt_pk_bf16_f32 v187, v194, v195
	global_store_dwordx2 v[196:197], v[186:187], off
	global_store_dwordx4 v[198:199], v[192:195], off nt

.LBB0_425:
	s_andn2_saveexec_b64 s[0:1], s[0:1]
	s_cbranch_execz .LBB0_427
	v_lshrrev_b32_e32 v134, 5, v184
	v_mul_lo_u32 v134, v134, s12
	v_and_or_b32 v134, v184, 29, v134
	s_waitcnt lgkmcnt(4)
	v_ashrrev_i32_e32 v185, 31, v184
	v_add_u32_e32 v192, 0x1000, v134
	v_lshlrev_b64 v[184:185], 7, v[184:185]
	v_ashrrev_i32_e32 v193, 31, v192
	s_waitcnt vmcnt(0)
	v_mov_b32_e32 v197, v180
	v_mov_b32_e32 v201, v188
	v_lshl_add_u64 v[202:203], v[174:175], 0, v[184:185]
	s_waitcnt lgkmcnt(2)
	v_pk_mul_f32 v[184:185], v[172:173], v[186:187] op_sel_hi:[0,1]
	v_mov_b32_e32 v188, v191
	s_waitcnt lgkmcnt(0)
	v_pk_mul_f32 v[178:179], v[172:173], v[178:179] op_sel_hi:[0,1]
	v_mov_b32_e32 v180, v183
	v_mov_b32_e32 v194, v21
	v_mov_b32_e32 v195, v17
	v_mov_b32_e32 v196, v182
	v_mov_b32_e32 v198, v29
	v_mov_b32_e32 v199, v25
	v_mov_b32_e32 v200, v190
	v_lshlrev_b64 v[192:193], 6, v[192:193]
	v_pk_mul_f32 v[184:185], v[188:189], v[184:185]
	v_pk_mul_f32 v[178:179], v[180:181], v[178:179]
	v_lshl_add_u64 v[192:193], v[176:177], 0, v[192:193]
	v_pk_fma_f32 v[184:185], v[198:199], v[200:201], v[184:185]
	v_pk_fma_f32 v[186:187], v[194:195], v[196:197], v[178:179]
	v_cvt_pk_bf16_f32 v182, v184, v185
	s_nop 0
	v_cvt_pk_bf16_f32 v183, v186, v187
	global_store_dwordx2 v[192:193], v[182:183], off
	global_store_dwordx4 v[202:203], v[184:187], off nt

.LBB0_431:
	s_andn2_saveexec_b64 s[0:1], s[0:1]
	s_cbranch_execz .LBB0_433
	v_add_co_u32_e32 v190, vcc, 0x80000, v190
	v_lshrrev_b32_e32 v134, 5, v192
	s_nop 0
	v_addc_co_u32_e32 v191, vcc, 0, v191, vcc
	global_load_dwordx2 v[196:197], v[190:191], off offset:16
	global_load_dwordx2 v[198:199], v[190:191], off
	v_mul_lo_u32 v134, v134, s12
	v_or_b32_e32 v134, v134, v139
	v_mov_b32_e32 v200, v30
	v_mov_b32_e32 v201, v26
	v_add_u32_e32 v194, 0x1000, v134
	s_waitcnt lgkmcnt(2)
	v_pk_mul_f32 v[188:189], v[172:173], v[188:189] op_sel_hi:[0,1]
	v_ashrrev_i32_e32 v195, 31, v194
	v_lshlrev_b64 v[194:195], 6, v[194:195]
	v_ashrrev_i32_e32 v193, 31, v192
	s_waitcnt lgkmcnt(0)
	v_pk_mul_f32 v[186:187], v[172:173], v[186:187] op_sel_hi:[0,1]
	v_lshl_add_u64 v[194:195], v[176:177], 0, v[194:195]
	v_lshlrev_b64 v[192:193], 7, v[192:193]
	v_lshl_add_u64 v[192:193], v[174:175], 0, v[192:193]
	s_waitcnt vmcnt(1)
	v_mov_b32_e32 v203, v196
	s_waitcnt vmcnt(0)
	v_mov_b32_e32 v202, v198
	v_mov_b32_e32 v196, v199
	global_load_dwordx2 v[198:199], v[190:191], off offset:48
	s_nop 0
	global_load_dwordx2 v[190:191], v[190:191], off offset:32
	v_pk_mul_f32 v[200:201], v[200:201], v[202:203]
	s_waitcnt vmcnt(1)
	v_mov_b32_e32 v203, v198
	v_pk_fma_f32 v[188:189], v[188:189], v[196:197], v[200:201]
	v_mov_b32_e32 v200, v22
	v_mov_b32_e32 v201, v18
	s_waitcnt vmcnt(0)
	v_mov_b32_e32 v202, v190
	v_pk_mul_f32 v[200:201], v[200:201], v[202:203]
	v_mov_b32_e32 v198, v191
	v_cvt_pk_bf16_f32 v196, v188, v189
	v_pk_fma_f32 v[190:191], v[186:187], v[198:199], v[200:201]
	s_nop 0
	v_cvt_pk_bf16_f32 v197, v190, v191
	global_store_dwordx2 v[194:195], v[196:197], off
	global_store_dwordx4 v[192:193], v[188:191], off nt

.LBB0_437:
	s_andn2_saveexec_b64 s[0:1], s[0:1]
	s_cbranch_execz .LBB0_439
	v_lshrrev_b32_e32 v134, 5, v188
	v_mul_lo_u32 v134, v134, s12
	v_and_or_b32 v134, v188, 31, v134
	v_add_u32_e32 v192, 0x1000, v134
	v_ashrrev_i32_e32 v193, 31, v192
	s_waitcnt vmcnt(0)
	v_mov_b32_e32 v197, v178
	v_mov_b32_e32 v200, v184
	v_mov_b32_e32 v201, v182
	s_waitcnt lgkmcnt(2)
	v_pk_mul_f32 v[190:191], v[172:173], v[190:191] op_sel_hi:[0,1]
	v_mov_b32_e32 v182, v185
	s_waitcnt lgkmcnt(0)
	v_pk_mul_f32 v[184:185], v[172:173], v[186:187] op_sel_hi:[0,1]
	v_mov_b32_e32 v178, v181
	v_mov_b32_e32 v194, v23
	v_mov_b32_e32 v195, v19
	v_mov_b32_e32 v196, v180
	v_mov_b32_e32 v198, v31
	v_mov_b32_e32 v199, v27
	v_lshlrev_b64 v[192:193], 6, v[192:193]
	v_ashrrev_i32_e32 v189, 31, v188
	v_pk_mul_f32 v[182:183], v[182:183], v[190:191]
	v_pk_mul_f32 v[178:179], v[178:179], v[184:185]
	v_lshl_add_u64 v[192:193], v[176:177], 0, v[192:193]
	v_lshlrev_b64 v[188:189], 7, v[188:189]
	v_pk_fma_f32 v[182:183], v[198:199], v[200:201], v[182:183]
	v_pk_fma_f32 v[184:185], v[194:195], v[196:197], v[178:179]
	v_cvt_pk_bf16_f32 v180, v182, v183
	v_lshl_add_u64 v[188:189], v[174:175], 0, v[188:189]
	v_cvt_pk_bf16_f32 v181, v184, v185
	global_store_dwordx2 v[192:193], v[180:181], off
	global_store_dwordx4 v[188:189], v[182:185], off nt

.LBB0_443:
	s_andn2_saveexec_b64 s[0:1], s[0:1]
	s_cbranch_execz .LBB0_445
	v_add_co_u32_e32 v190, vcc, 0x80000, v190
	v_lshrrev_b32_e32 v134, 5, v192
	s_nop 0
	v_addc_co_u32_e32 v191, vcc, 0, v191, vcc
	global_load_dwordx2 v[196:197], v[190:191], off offset:16
	global_load_dwordx2 v[198:199], v[190:191], off
	v_mul_lo_u32 v134, v134, s12
	v_or_b32_e32 v134, v134, v139
	v_mov_b32_e32 v200, v12
	v_mov_b32_e32 v201, v8
	v_add_u32_e32 v194, 0x1000, v134
	s_waitcnt lgkmcnt(2)
	v_pk_mul_f32 v[188:189], v[172:173], v[188:189] op_sel_hi:[0,1]
	v_ashrrev_i32_e32 v195, 31, v194
	v_lshlrev_b64 v[194:195], 6, v[194:195]
	v_ashrrev_i32_e32 v193, 31, v192
	s_waitcnt lgkmcnt(0)
	v_pk_mul_f32 v[186:187], v[172:173], v[186:187] op_sel_hi:[0,1]
	v_lshl_add_u64 v[194:195], v[176:177], 0, v[194:195]
	v_lshlrev_b64 v[192:193], 7, v[192:193]
	v_lshl_add_u64 v[192:193], v[174:175], 0, v[192:193]
	s_waitcnt vmcnt(1)
	v_mov_b32_e32 v203, v196
	s_waitcnt vmcnt(0)
	v_mov_b32_e32 v202, v198
	v_mov_b32_e32 v196, v199
	global_load_dwordx2 v[198:199], v[190:191], off offset:48
	s_nop 0
	global_load_dwordx2 v[190:191], v[190:191], off offset:32
	v_pk_mul_f32 v[200:201], v[200:201], v[202:203]
	s_waitcnt vmcnt(1)
	v_mov_b32_e32 v203, v198
	v_pk_fma_f32 v[188:189], v[188:189], v[196:197], v[200:201]
	v_mov_b32_e32 v200, v4
	v_mov_b32_e32 v201, v0
	s_waitcnt vmcnt(0)
	v_mov_b32_e32 v202, v190
	v_pk_mul_f32 v[200:201], v[200:201], v[202:203]
	v_mov_b32_e32 v198, v191
	v_cvt_pk_bf16_f32 v196, v188, v189
	v_pk_fma_f32 v[190:191], v[186:187], v[198:199], v[200:201]
	s_nop 0
	v_cvt_pk_bf16_f32 v197, v190, v191
	global_store_dwordx2 v[194:195], v[196:197], off
	global_store_dwordx4 v[192:193], v[188:191], off nt

.LBB0_449:
	s_andn2_saveexec_b64 s[0:1], s[0:1]
	s_cbranch_execz .LBB0_451
	v_lshrrev_b32_e32 v134, 5, v188
	v_mul_lo_u32 v134, v134, s12
	v_and_or_b32 v134, v188, 29, v134
	v_add_u32_e32 v192, 0x1000, v134
	v_ashrrev_i32_e32 v193, 31, v192
	s_waitcnt vmcnt(0)
	v_mov_b32_e32 v197, v178
	v_mov_b32_e32 v200, v184
	v_mov_b32_e32 v201, v182
	s_waitcnt lgkmcnt(2)
	v_pk_mul_f32 v[190:191], v[172:173], v[190:191] op_sel_hi:[0,1]
	v_mov_b32_e32 v182, v185
	s_waitcnt lgkmcnt(0)
	v_pk_mul_f32 v[184:185], v[172:173], v[186:187] op_sel_hi:[0,1]
	v_mov_b32_e32 v178, v181
	v_mov_b32_e32 v194, v5
	v_mov_b32_e32 v195, v1
	v_mov_b32_e32 v196, v180
	v_mov_b32_e32 v198, v13
	v_mov_b32_e32 v199, v9
	v_lshlrev_b64 v[192:193], 6, v[192:193]
	v_ashrrev_i32_e32 v189, 31, v188
	v_pk_mul_f32 v[182:183], v[182:183], v[190:191]
	v_pk_mul_f32 v[178:179], v[178:179], v[184:185]
	v_lshl_add_u64 v[192:193], v[176:177], 0, v[192:193]
	v_lshlrev_b64 v[188:189], 7, v[188:189]
	v_pk_fma_f32 v[182:183], v[198:199], v[200:201], v[182:183]
	v_pk_fma_f32 v[184:185], v[194:195], v[196:197], v[178:179]
	v_cvt_pk_bf16_f32 v180, v182, v183
	v_lshl_add_u64 v[188:189], v[174:175], 0, v[188:189]
	v_cvt_pk_bf16_f32 v181, v184, v185
	global_store_dwordx2 v[192:193], v[180:181], off
	global_store_dwordx4 v[188:189], v[182:185], off nt

.LBB0_455:
	s_andn2_saveexec_b64 s[0:1], s[0:1]
	s_cbranch_execz .LBB0_457
	v_add_co_u32_e32 v190, vcc, 0x80000, v190
	v_lshrrev_b32_e32 v131, 5, v192
	s_nop 0
	v_addc_co_u32_e32 v191, vcc, 0, v191, vcc
	global_load_dwordx2 v[196:197], v[190:191], off offset:16
	global_load_dwordx2 v[198:199], v[190:191], off
	v_mul_lo_u32 v131, v131, s12
	v_or_b32_e32 v131, v131, v139
	v_mov_b32_e32 v200, v14
	v_mov_b32_e32 v201, v10
	v_add_u32_e32 v194, 0x1000, v131
	s_waitcnt lgkmcnt(2)
	v_pk_mul_f32 v[188:189], v[172:173], v[188:189] op_sel_hi:[0,1]
	v_ashrrev_i32_e32 v195, 31, v194
	v_lshlrev_b64 v[194:195], 6, v[194:195]
	v_ashrrev_i32_e32 v193, 31, v192
	s_waitcnt lgkmcnt(0)
	v_pk_mul_f32 v[186:187], v[172:173], v[186:187] op_sel_hi:[0,1]
	v_lshl_add_u64 v[194:195], v[176:177], 0, v[194:195]
	v_lshlrev_b64 v[192:193], 7, v[192:193]
	v_lshl_add_u64 v[192:193], v[174:175], 0, v[192:193]
	s_waitcnt vmcnt(1)
	v_mov_b32_e32 v203, v196
	s_waitcnt vmcnt(0)
	v_mov_b32_e32 v202, v198
	v_mov_b32_e32 v196, v199
	global_load_dwordx2 v[198:199], v[190:191], off offset:48
	s_nop 0
	global_load_dwordx2 v[190:191], v[190:191], off offset:32
	v_pk_mul_f32 v[200:201], v[200:201], v[202:203]
	s_waitcnt vmcnt(1)
	v_mov_b32_e32 v203, v198
	v_pk_fma_f32 v[188:189], v[188:189], v[196:197], v[200:201]
	v_mov_b32_e32 v200, v6
	v_mov_b32_e32 v201, v2
	s_waitcnt vmcnt(0)
	v_mov_b32_e32 v202, v190
	v_pk_mul_f32 v[200:201], v[200:201], v[202:203]
	v_mov_b32_e32 v198, v191
	v_cvt_pk_bf16_f32 v196, v188, v189
	v_pk_fma_f32 v[190:191], v[186:187], v[198:199], v[200:201]
	s_nop 0
	v_cvt_pk_bf16_f32 v197, v190, v191
	global_store_dwordx2 v[194:195], v[196:197], off
	global_store_dwordx4 v[192:193], v[188:191], off nt

.LBB0_461:
	s_andn2_saveexec_b64 s[0:1], s[0:1]
	s_cbranch_execz .LBB0_463
	v_lshrrev_b32_e32 v129, 5, v168
	v_mul_lo_u32 v129, v129, s12
	v_and_or_b32 v129, v168, 31, v129
	v_add_u32_e32 v170, 0x1000, v129
	v_ashrrev_i32_e32 v171, 31, v170
	v_ashrrev_i32_e32 v169, 31, v168
	v_lshlrev_b64 v[170:171], 6, v[170:171]
	v_lshlrev_b64 v[168:169], 7, v[168:169]
	s_waitcnt vmcnt(0)
	v_mov_b32_e32 v193, v178
	v_mov_b32_e32 v197, v182
	v_lshl_add_u64 v[176:177], v[176:177], 0, v[170:171]
	v_lshl_add_u64 v[174:175], v[174:175], 0, v[168:169]
	s_waitcnt lgkmcnt(2)
	v_pk_mul_f32 v[168:169], v[172:173], v[188:189] op_sel_hi:[0,1]
	v_mov_b32_e32 v182, v185
	s_waitcnt lgkmcnt(0)
	v_pk_mul_f32 v[170:171], v[172:173], v[186:187] op_sel_hi:[0,1]
	v_mov_b32_e32 v178, v181
	v_mov_b32_e32 v190, v7
	v_mov_b32_e32 v191, v3
	v_mov_b32_e32 v192, v180
	v_mov_b32_e32 v194, v15
	v_mov_b32_e32 v195, v11
	v_mov_b32_e32 v196, v184
	v_pk_mul_f32 v[168:169], v[182:183], v[168:169]
	v_pk_mul_f32 v[170:171], v[178:179], v[170:171]
	v_pk_fma_f32 v[168:169], v[194:195], v[196:197], v[168:169]
	v_pk_fma_f32 v[170:171], v[190:191], v[192:193], v[170:171]
	v_cvt_pk_bf16_f32 v180, v168, v169
	s_nop 0
	v_cvt_pk_bf16_f32 v181, v170, v171
	global_store_dwordx2 v[176:177], v[180:181], off
	global_store_dwordx4 v[174:175], v[168:171], off nt

.LBB0_483:
	s_andn2_saveexec_b64 s[66:67], s[66:67]
	s_cbranch_execz .LBB0_491
	v_cmp_lt_i32_e32 vcc, 5, v176
	s_mov_b64 s[72:73], s[96:97]
	s_and_saveexec_b64 s[24:25], vcc
	s_xor_b64 s[74:75], exec, s[24:25]
	s_cbranch_execz .LBB0_488
	v_cmp_gt_i32_e32 vcc, 7, v176
	s_mov_b64 s[94:95], -1
	s_and_saveexec_b64 s[72:73], vcc
	s_cbranch_execz .LBB0_487
	v_readlane_b32 s36, v253, 44
	v_readlane_b32 s24, v253, 22
	v_ashrrev_i32_e32 v137, 31, v136
	v_readlane_b32 s40, v253, 48
	v_readlane_b32 s41, v253, 49
	v_readlane_b32 s25, v253, 23
	v_lshl_add_u32 v134, v146, 2, v211
	v_readlane_b32 s37, v253, 45
	v_readlane_b32 s38, v253, 46
	v_readlane_b32 s39, v253, 47
	v_readlane_b32 s42, v253, 50
	v_readlane_b32 s43, v253, 51
	v_readlane_b32 s44, v253, 52
	v_readlane_b32 s45, v253, 53
	v_readlane_b32 s46, v253, 54
	v_readlane_b32 s47, v253, 55
	v_readlane_b32 s48, v253, 56
	v_readlane_b32 s49, v253, 57
	v_readlane_b32 s50, v253, 58
	v_readlane_b32 s51, v253, 59
	v_lshl_add_u64 v[130:131], v[136:137], 1, s[40:41]
	v_lshl_add_u64 v[128:129], v[136:137], 2, s[24:25]
	v_mad_i64_i32 v[138:139], s[24:25], v134, s15, 0
	v_lshl_add_u64 v[140:141], v[138:139], 1, v[130:131]
	v_cvt_pk_bf16_f32 v142, v124, v120
	v_cvt_pk_bf16_f32 v143, v116, v112
	global_store_dwordx2 v[140:141], v[142:143], off
	v_lshl_add_u64 v[142:143], v[138:139], 2, v[128:129]
	v_mov_b32_e32 v138, v124
	v_mov_b32_e32 v139, v120
	v_mov_b32_e32 v140, v116
	v_mov_b32_e32 v141, v112
	global_store_dwordx4 v[142:143], v[138:141], off nt
	v_or_b32_e32 v137, 1, v134
	s_nop 0
	v_mad_i64_i32 v[138:139], s[24:25], v137, s15, 0
	v_lshl_add_u64 v[140:141], v[138:139], 1, v[130:131]
	v_cvt_pk_bf16_f32 v142, v125, v121
	v_cvt_pk_bf16_f32 v143, v117, v113
	global_store_dwordx2 v[140:141], v[142:143], off
	v_lshl_add_u64 v[142:143], v[138:139], 2, v[128:129]
	v_mov_b32_e32 v138, v125
	v_mov_b32_e32 v139, v121
	v_mov_b32_e32 v140, v117
	v_mov_b32_e32 v141, v113
	global_store_dwordx4 v[142:143], v[138:141], off nt
	v_or_b32_e32 v137, 2, v134
	s_nop 0
	v_mad_i64_i32 v[138:139], s[24:25], v137, s15, 0
	v_lshl_add_u64 v[140:141], v[138:139], 1, v[130:131]
	v_cvt_pk_bf16_f32 v142, v126, v122
	v_cvt_pk_bf16_f32 v143, v118, v114
	global_store_dwordx2 v[140:141], v[142:143], off
	v_lshl_add_u64 v[142:143], v[138:139], 2, v[128:129]
	v_mov_b32_e32 v138, v126
	v_mov_b32_e32 v139, v122
	v_mov_b32_e32 v140, v118
	v_mov_b32_e32 v141, v114
	global_store_dwordx4 v[142:143], v[138:141], off nt
	v_or_b32_e32 v137, 3, v134
	s_nop 0
	v_mad_i64_i32 v[138:139], s[24:25], v137, s15, 0
	v_lshl_add_u64 v[140:141], v[138:139], 1, v[130:131]
	v_cvt_pk_bf16_f32 v142, v127, v123
	v_cvt_pk_bf16_f32 v143, v119, v115
	global_store_dwordx2 v[140:141], v[142:143], off
	v_lshl_add_u64 v[142:143], v[138:139], 2, v[128:129]
	v_mov_b32_e32 v138, v127
	v_mov_b32_e32 v139, v123
	v_mov_b32_e32 v140, v119
	v_mov_b32_e32 v141, v115
	global_store_dwordx4 v[142:143], v[138:141], off nt
	v_add_u32_e32 v137, 16, v134
	s_nop 0
	v_mad_i64_i32 v[138:139], s[24:25], v137, s15, 0
	v_lshl_add_u64 v[140:141], v[138:139], 1, v[130:131]
	v_cvt_pk_bf16_f32 v142, v108, v104
	v_cvt_pk_bf16_f32 v143, v100, v96
	global_store_dwordx2 v[140:141], v[142:143], off
	v_lshl_add_u64 v[142:143], v[138:139], 2, v[128:129]
	v_mov_b32_e32 v138, v108
	v_mov_b32_e32 v139, v104
	v_mov_b32_e32 v140, v100
	v_mov_b32_e32 v141, v96
	global_store_dwordx4 v[142:143], v[138:141], off nt
	v_add_u32_e32 v137, 17, v134
	s_nop 0
	v_mad_i64_i32 v[138:139], s[24:25], v137, s15, 0
	v_lshl_add_u64 v[140:141], v[138:139], 1, v[130:131]
	v_cvt_pk_bf16_f32 v142, v109, v105
	v_cvt_pk_bf16_f32 v143, v101, v97
	global_store_dwordx2 v[140:141], v[142:143], off
	v_lshl_add_u64 v[142:143], v[138:139], 2, v[128:129]
	v_mov_b32_e32 v138, v109
	v_mov_b32_e32 v139, v105
	v_mov_b32_e32 v140, v101
	v_mov_b32_e32 v141, v97
	global_store_dwordx4 v[142:143], v[138:141], off nt
	v_add_u32_e32 v137, 18, v134
	s_nop 0
	v_mad_i64_i32 v[138:139], s[24:25], v137, s15, 0
	v_lshl_add_u64 v[140:141], v[138:139], 1, v[130:131]
	v_cvt_pk_bf16_f32 v142, v110, v106
	v_cvt_pk_bf16_f32 v143, v102, v98
	global_store_dwordx2 v[140:141], v[142:143], off
	v_lshl_add_u64 v[142:143], v[138:139], 2, v[128:129]
	v_mov_b32_e32 v138, v110
	v_mov_b32_e32 v139, v106
	v_mov_b32_e32 v140, v102
	v_mov_b32_e32 v141, v98
	global_store_dwordx4 v[142:143], v[138:141], off nt
	v_add_u32_e32 v137, 19, v134
	s_nop 0
	v_mad_i64_i32 v[138:139], s[24:25], v137, s15, 0
	v_lshl_add_u64 v[140:141], v[138:139], 1, v[130:131]
	v_cvt_pk_bf16_f32 v142, v111, v107
	v_cvt_pk_bf16_f32 v143, v103, v99
	global_store_dwordx2 v[140:141], v[142:143], off
	v_lshl_add_u64 v[142:143], v[138:139], 2, v[128:129]
	v_mov_b32_e32 v138, v111
	v_mov_b32_e32 v139, v107
	v_mov_b32_e32 v140, v103
	v_mov_b32_e32 v141, v99
	global_store_dwordx4 v[142:143], v[138:141], off nt
	v_add_u32_e32 v137, 32, v134
	s_nop 0
	v_mad_i64_i32 v[138:139], s[24:25], v137, s15, 0
	v_lshl_add_u64 v[140:141], v[138:139], 1, v[130:131]
	v_cvt_pk_bf16_f32 v142, v92, v88
	v_cvt_pk_bf16_f32 v143, v84, v80
	global_store_dwordx2 v[140:141], v[142:143], off
	v_lshl_add_u64 v[142:143], v[138:139], 2, v[128:129]
	v_mov_b32_e32 v138, v92
	v_mov_b32_e32 v139, v88
	v_mov_b32_e32 v140, v84
	v_mov_b32_e32 v141, v80
	global_store_dwordx4 v[142:143], v[138:141], off nt
	v_add_u32_e32 v137, 33, v134
	s_nop 0
	v_mad_i64_i32 v[138:139], s[24:25], v137, s15, 0
	v_lshl_add_u64 v[140:141], v[138:139], 1, v[130:131]
	v_cvt_pk_bf16_f32 v142, v93, v89
	v_cvt_pk_bf16_f32 v143, v85, v81
	global_store_dwordx2 v[140:141], v[142:143], off
	v_lshl_add_u64 v[142:143], v[138:139], 2, v[128:129]
	v_mov_b32_e32 v138, v93
	v_mov_b32_e32 v139, v89
	v_mov_b32_e32 v140, v85
	v_mov_b32_e32 v141, v81
	global_store_dwordx4 v[142:143], v[138:141], off nt
	v_add_u32_e32 v137, 34, v134
	s_nop 0
	v_mad_i64_i32 v[138:139], s[24:25], v137, s15, 0
	v_lshl_add_u64 v[140:141], v[138:139], 1, v[130:131]
	v_cvt_pk_bf16_f32 v142, v94, v90
	v_cvt_pk_bf16_f32 v143, v86, v82
	global_store_dwordx2 v[140:141], v[142:143], off
	v_lshl_add_u64 v[142:143], v[138:139], 2, v[128:129]
	v_mov_b32_e32 v138, v94
	v_mov_b32_e32 v139, v90
	v_mov_b32_e32 v140, v86
	v_mov_b32_e32 v141, v82
	global_store_dwordx4 v[142:143], v[138:141], off nt
	v_add_u32_e32 v137, 35, v134
	s_nop 0
	v_mad_i64_i32 v[138:139], s[24:25], v137, s15, 0
	v_lshl_add_u64 v[140:141], v[138:139], 1, v[130:131]
	v_cvt_pk_bf16_f32 v142, v95, v91
	v_cvt_pk_bf16_f32 v143, v87, v83
	global_store_dwordx2 v[140:141], v[142:143], off
	v_lshl_add_u64 v[142:143], v[138:139], 2, v[128:129]
	v_mov_b32_e32 v138, v95
	v_mov_b32_e32 v139, v91
	v_mov_b32_e32 v140, v87
	v_mov_b32_e32 v141, v83
	global_store_dwordx4 v[142:143], v[138:141], off nt
	v_add_u32_e32 v137, 48, v134
	s_nop 0
	v_mad_i64_i32 v[138:139], s[24:25], v137, s15, 0
	v_lshl_add_u64 v[140:141], v[138:139], 1, v[130:131]
	v_cvt_pk_bf16_f32 v142, v76, v72
	v_cvt_pk_bf16_f32 v143, v68, v64
	global_store_dwordx2 v[140:141], v[142:143], off
	v_lshl_add_u64 v[142:143], v[138:139], 2, v[128:129]
	v_mov_b32_e32 v138, v76
	v_mov_b32_e32 v139, v72
	v_mov_b32_e32 v140, v68
	v_mov_b32_e32 v141, v64
	global_store_dwordx4 v[142:143], v[138:141], off nt
	v_add_u32_e32 v137, 49, v134
	s_nop 0
	v_mad_i64_i32 v[138:139], s[24:25], v137, s15, 0
	v_lshl_add_u64 v[140:141], v[138:139], 1, v[130:131]
	v_cvt_pk_bf16_f32 v142, v77, v73
	v_cvt_pk_bf16_f32 v143, v69, v65
	global_store_dwordx2 v[140:141], v[142:143], off
	v_lshl_add_u64 v[142:143], v[138:139], 2, v[128:129]
	v_mov_b32_e32 v138, v77
	v_mov_b32_e32 v139, v73
	v_mov_b32_e32 v140, v69
	v_mov_b32_e32 v141, v65
	global_store_dwordx4 v[142:143], v[138:141], off nt
	v_add_u32_e32 v137, 50, v134
	s_nop 0
	v_mad_i64_i32 v[138:139], s[24:25], v137, s15, 0
	v_lshl_add_u64 v[140:141], v[138:139], 1, v[130:131]
	v_cvt_pk_bf16_f32 v142, v78, v74
	v_cvt_pk_bf16_f32 v143, v70, v66
	global_store_dwordx2 v[140:141], v[142:143], off
	v_lshl_add_u64 v[142:143], v[138:139], 2, v[128:129]
	v_mov_b32_e32 v138, v78
	v_mov_b32_e32 v139, v74
	v_mov_b32_e32 v140, v70
	v_mov_b32_e32 v141, v66
	global_store_dwordx4 v[142:143], v[138:141], off nt
	v_add_u32_e32 v137, 51, v134
	s_nop 0
	v_mad_i64_i32 v[138:139], s[24:25], v137, s15, 0
	v_lshl_add_u64 v[140:141], v[138:139], 1, v[130:131]
	v_cvt_pk_bf16_f32 v142, v79, v75
	v_cvt_pk_bf16_f32 v143, v71, v67
	global_store_dwordx2 v[140:141], v[142:143], off
	v_lshl_add_u64 v[142:143], v[138:139], 2, v[128:129]
	v_mov_b32_e32 v138, v79
	v_mov_b32_e32 v139, v75
	v_mov_b32_e32 v140, v71
	v_mov_b32_e32 v141, v67
	global_store_dwordx4 v[142:143], v[138:141], off nt
	v_add_u32_e32 v137, 64, v134
	s_nop 0
	v_mad_i64_i32 v[138:139], s[24:25], v137, s15, 0
	v_lshl_add_u64 v[140:141], v[138:139], 1, v[130:131]
	v_cvt_pk_bf16_f32 v142, v60, v56
	v_cvt_pk_bf16_f32 v143, v52, v48
	global_store_dwordx2 v[140:141], v[142:143], off
	v_lshl_add_u64 v[142:143], v[138:139], 2, v[128:129]
	v_mov_b32_e32 v138, v60
	v_mov_b32_e32 v139, v56
	v_mov_b32_e32 v140, v52
	v_mov_b32_e32 v141, v48
	global_store_dwordx4 v[142:143], v[138:141], off nt
	v_add_u32_e32 v137, 0x41, v134
	s_nop 0
	v_mad_i64_i32 v[138:139], s[24:25], v137, s15, 0
	v_lshl_add_u64 v[140:141], v[138:139], 1, v[130:131]
	v_cvt_pk_bf16_f32 v142, v61, v57
	v_cvt_pk_bf16_f32 v143, v53, v49
	global_store_dwordx2 v[140:141], v[142:143], off
	v_lshl_add_u64 v[142:143], v[138:139], 2, v[128:129]
	v_mov_b32_e32 v138, v61
	v_mov_b32_e32 v139, v57
	v_mov_b32_e32 v140, v53
	v_mov_b32_e32 v141, v49
	global_store_dwordx4 v[142:143], v[138:141], off nt
	v_add_u32_e32 v137, 0x42, v134
	s_nop 0
	v_mad_i64_i32 v[138:139], s[24:25], v137, s15, 0
	v_lshl_add_u64 v[140:141], v[138:139], 1, v[130:131]
	v_cvt_pk_bf16_f32 v142, v62, v58
	v_cvt_pk_bf16_f32 v143, v54, v50
	global_store_dwordx2 v[140:141], v[142:143], off
	v_lshl_add_u64 v[142:143], v[138:139], 2, v[128:129]
	v_mov_b32_e32 v138, v62
	v_mov_b32_e32 v139, v58
	v_mov_b32_e32 v140, v54
	v_mov_b32_e32 v141, v50
	global_store_dwordx4 v[142:143], v[138:141], off nt
	v_add_u32_e32 v137, 0x43, v134
	s_nop 0
	v_mad_i64_i32 v[138:139], s[24:25], v137, s15, 0
	v_lshl_add_u64 v[140:141], v[138:139], 1, v[130:131]
	v_cvt_pk_bf16_f32 v142, v63, v59
	v_cvt_pk_bf16_f32 v143, v55, v51
	global_store_dwordx2 v[140:141], v[142:143], off
	v_lshl_add_u64 v[142:143], v[138:139], 2, v[128:129]
	v_mov_b32_e32 v138, v63
	v_mov_b32_e32 v139, v59
	v_mov_b32_e32 v140, v55
	v_mov_b32_e32 v141, v51
	global_store_dwordx4 v[142:143], v[138:141], off nt
	v_add_u32_e32 v137, 0x50, v134
	s_nop 0
	v_mad_i64_i32 v[138:139], s[24:25], v137, s15, 0
	v_lshl_add_u64 v[140:141], v[138:139], 1, v[130:131]
	v_cvt_pk_bf16_f32 v142, v44, v40
	v_cvt_pk_bf16_f32 v143, v36, v32
	global_store_dwordx2 v[140:141], v[142:143], off
	v_lshl_add_u64 v[142:143], v[138:139], 2, v[128:129]
	v_mov_b32_e32 v138, v44
	v_mov_b32_e32 v139, v40
	v_mov_b32_e32 v140, v36
	v_mov_b32_e32 v141, v32
	global_store_dwordx4 v[142:143], v[138:141], off nt
	v_add_u32_e32 v137, 0x51, v134
	s_nop 0
	v_mad_i64_i32 v[138:139], s[24:25], v137, s15, 0
	v_lshl_add_u64 v[140:141], v[138:139], 1, v[130:131]
	v_cvt_pk_bf16_f32 v142, v45, v41
	v_cvt_pk_bf16_f32 v143, v37, v33
	global_store_dwordx2 v[140:141], v[142:143], off
	v_lshl_add_u64 v[142:143], v[138:139], 2, v[128:129]
	v_mov_b32_e32 v138, v45
	v_mov_b32_e32 v139, v41
	v_mov_b32_e32 v140, v37
	v_mov_b32_e32 v141, v33
	global_store_dwordx4 v[142:143], v[138:141], off nt
	v_add_u32_e32 v137, 0x52, v134
	s_nop 0
	v_mad_i64_i32 v[138:139], s[24:25], v137, s15, 0
	v_lshl_add_u64 v[140:141], v[138:139], 1, v[130:131]
	v_cvt_pk_bf16_f32 v142, v46, v42
	v_cvt_pk_bf16_f32 v143, v38, v34
	global_store_dwordx2 v[140:141], v[142:143], off
	v_lshl_add_u64 v[142:143], v[138:139], 2, v[128:129]
	v_mov_b32_e32 v138, v46
	v_mov_b32_e32 v139, v42
	v_mov_b32_e32 v140, v38
	v_mov_b32_e32 v141, v34
	global_store_dwordx4 v[142:143], v[138:141], off nt
	v_add_u32_e32 v137, 0x53, v134
	s_nop 0
	v_mad_i64_i32 v[138:139], s[24:25], v137, s15, 0
	v_lshl_add_u64 v[140:141], v[138:139], 1, v[130:131]
	v_cvt_pk_bf16_f32 v142, v47, v43
	v_cvt_pk_bf16_f32 v143, v39, v35
	global_store_dwordx2 v[140:141], v[142:143], off
	v_lshl_add_u64 v[142:143], v[138:139], 2, v[128:129]
	v_mov_b32_e32 v138, v47
	v_mov_b32_e32 v139, v43
	v_mov_b32_e32 v140, v39
	v_mov_b32_e32 v141, v35
	global_store_dwordx4 v[142:143], v[138:141], off nt
	v_add_u32_e32 v137, 0x60, v134
	s_nop 0
	v_mad_i64_i32 v[138:139], s[24:25], v137, s15, 0
	v_lshl_add_u64 v[140:141], v[138:139], 1, v[130:131]
	v_cvt_pk_bf16_f32 v142, v28, v24
	v_cvt_pk_bf16_f32 v143, v20, v16
	global_store_dwordx2 v[140:141], v[142:143], off
	v_lshl_add_u64 v[142:143], v[138:139], 2, v[128:129]
	v_mov_b32_e32 v138, v28
	v_mov_b32_e32 v139, v24
	v_mov_b32_e32 v140, v20
	v_mov_b32_e32 v141, v16
	global_store_dwordx4 v[142:143], v[138:141], off nt
	v_add_u32_e32 v137, 0x61, v134
	s_nop 0
	v_mad_i64_i32 v[138:139], s[24:25], v137, s15, 0
	v_lshl_add_u64 v[140:141], v[138:139], 1, v[130:131]
	v_cvt_pk_bf16_f32 v142, v29, v25
	v_cvt_pk_bf16_f32 v143, v21, v17
	global_store_dwordx2 v[140:141], v[142:143], off
	v_lshl_add_u64 v[142:143], v[138:139], 2, v[128:129]
	v_mov_b32_e32 v138, v29
	v_mov_b32_e32 v139, v25
	v_mov_b32_e32 v140, v21
	v_mov_b32_e32 v141, v17
	global_store_dwordx4 v[142:143], v[138:141], off nt
	v_add_u32_e32 v137, 0x62, v134
	s_nop 0
	v_mad_i64_i32 v[138:139], s[24:25], v137, s15, 0
	v_lshl_add_u64 v[140:141], v[138:139], 1, v[130:131]
	v_cvt_pk_bf16_f32 v142, v30, v26
	v_cvt_pk_bf16_f32 v143, v22, v18
	global_store_dwordx2 v[140:141], v[142:143], off
	v_lshl_add_u64 v[142:143], v[138:139], 2, v[128:129]
	v_mov_b32_e32 v138, v30
	v_mov_b32_e32 v139, v26
	v_mov_b32_e32 v140, v22
	v_mov_b32_e32 v141, v18
	global_store_dwordx4 v[142:143], v[138:141], off nt
	v_add_u32_e32 v137, 0x63, v134
	s_nop 0
	v_mad_i64_i32 v[138:139], s[24:25], v137, s15, 0
	v_lshl_add_u64 v[140:141], v[138:139], 1, v[130:131]
	v_cvt_pk_bf16_f32 v142, v31, v27
	v_cvt_pk_bf16_f32 v143, v23, v19
	global_store_dwordx2 v[140:141], v[142:143], off
	v_lshl_add_u64 v[142:143], v[138:139], 2, v[128:129]
	v_mov_b32_e32 v138, v31
	v_mov_b32_e32 v139, v27
	v_mov_b32_e32 v140, v23
	v_mov_b32_e32 v141, v19
	global_store_dwordx4 v[142:143], v[138:141], off nt
	v_add_u32_e32 v137, 0x70, v134
	s_nop 0
	v_mad_i64_i32 v[138:139], s[24:25], v137, s15, 0
	v_lshl_add_u64 v[140:141], v[138:139], 1, v[130:131]
	v_cvt_pk_bf16_f32 v142, v12, v8
	v_cvt_pk_bf16_f32 v143, v4, v0
	global_store_dwordx2 v[140:141], v[142:143], off
	v_lshl_add_u64 v[142:143], v[138:139], 2, v[128:129]
	v_mov_b32_e32 v138, v12
	v_mov_b32_e32 v139, v8
	v_mov_b32_e32 v140, v4
	v_mov_b32_e32 v141, v0
	global_store_dwordx4 v[142:143], v[138:141], off nt
	v_add_u32_e32 v137, 0x71, v134
	s_nop 0
	v_mad_i64_i32 v[138:139], s[24:25], v137, s15, 0
	v_lshl_add_u64 v[140:141], v[138:139], 1, v[130:131]
	v_cvt_pk_bf16_f32 v142, v13, v9
	v_cvt_pk_bf16_f32 v143, v5, v1
	global_store_dwordx2 v[140:141], v[142:143], off
	v_lshl_add_u64 v[142:143], v[138:139], 2, v[128:129]
	v_mov_b32_e32 v138, v13
	v_mov_b32_e32 v139, v9
	v_mov_b32_e32 v140, v5
	v_mov_b32_e32 v141, v1
	global_store_dwordx4 v[142:143], v[138:141], off nt
	v_add_u32_e32 v137, 0x72, v134
	s_nop 0
	v_mad_i64_i32 v[138:139], s[24:25], v137, s15, 0
	v_lshl_add_u64 v[140:141], v[138:139], 1, v[130:131]
	v_cvt_pk_bf16_f32 v142, v14, v10
	v_cvt_pk_bf16_f32 v143, v6, v2
	global_store_dwordx2 v[140:141], v[142:143], off
	v_lshl_add_u64 v[142:143], v[138:139], 2, v[128:129]
	v_mov_b32_e32 v138, v14
	v_mov_b32_e32 v139, v10
	v_mov_b32_e32 v140, v6
	v_mov_b32_e32 v141, v2
	global_store_dwordx4 v[142:143], v[138:141], off nt
	v_add_u32_e32 v134, 0x73, v134
	s_nop 0
	v_mad_i64_i32 v[138:139], s[24:25], v134, s15, 0
	v_lshl_add_u64 v[130:131], v[138:139], 1, v[130:131]
	v_cvt_pk_bf16_f32 v140, v15, v11
	v_cvt_pk_bf16_f32 v141, v7, v3
	global_store_dwordx2 v[130:131], v[140:141], off
	v_lshl_add_u64 v[138:139], v[138:139], 2, v[128:129]
	v_mov_b32_e32 v128, v15
	v_mov_b32_e32 v129, v11
	v_mov_b32_e32 v130, v7
	v_mov_b32_e32 v131, v3
	global_store_dwordx4 v[138:139], v[128:131], off nt
	s_xor_b64 s[94:95], exec, -1

.LBB0_488:
	s_andn2_saveexec_b64 s[74:75], s[74:75]
	s_cbranch_execz .LBB0_490
	v_mbcnt_hi_u32_b32 v128, -1, v204
	v_and_b32_e32 v130, 64, v128
	v_xor_b32_e32 v129, 8, v128
	v_add_u32_e32 v130, 64, v130
	v_cmp_lt_i32_e32 vcc, v129, v130
	v_readlane_b32 s36, v253, 44
	v_readlane_b32 s24, v253, 24
	v_cndmask_b32_e32 v128, v128, v129, vcc
	v_cmp_gt_u32_e32 vcc, 8, v175
	v_ashrrev_i32_e32 v137, 31, v136
	v_readlane_b32 s38, v253, 46
	v_readlane_b32 s39, v253, 47
	v_readlane_b32 s25, v253, 25
	v_lshl_add_u32 v147, v146, 2, v211
	v_lshlrev_b32_e32 v149, 2, v128
	v_cndmask_b32_e64 v148, 1.0, -1.0, vcc
	v_readlane_b32 s37, v253, 45
	v_readlane_b32 s40, v253, 48
	v_readlane_b32 s41, v253, 49
	v_readlane_b32 s42, v253, 50
	v_readlane_b32 s43, v253, 51
	v_readlane_b32 s44, v253, 52
	v_readlane_b32 s45, v253, 53
	v_readlane_b32 s46, v253, 54
	v_readlane_b32 s47, v253, 55
	v_readlane_b32 s48, v253, 56
	v_readlane_b32 s49, v253, 57
	v_readlane_b32 s50, v253, 58
	v_readlane_b32 s51, v253, 59
	v_lshl_add_u64 v[138:139], v[136:137], 1, s[38:39]
	v_lshl_add_u64 v[140:141], v[136:137], 2, s[24:25]
	v_lshlrev_b32_e32 v128, 5, v210
	v_and_b32_e32 v134, 0xe0, v128
	v_lshlrev_b32_e32 v128, 8, v147
	v_lshl_add_u64 v[142:143], s[58:59], 0, v[134:135]
	v_and_b32_e32 v134, 0x7fc00, v128
	v_lshl_add_u64 v[154:155], v[142:143], 0, v[134:135]
	global_load_dwordx3 v[158:160], v[154:155], off offset:256
	global_load_dwordx4 v[128:131], v[154:155], off offset:268
	global_load_dword v145, v[154:155], off offset:284
	global_load_dwordx4 v[150:153], v[154:155], off offset:16
	ds_bpermute_b32 v144, v149, v116
	global_load_dwordx4 v[154:157], v[154:155], off
	ds_bpermute_b32 v137, v149, v120
	ds_bpermute_b32 v134, v149, v124
	v_mov_b32_e32 v170, v116
	v_mov_b32_e32 v168, v124
	v_mov_b32_e32 v167, v120
	s_waitcnt lgkmcnt(1)
	v_mul_f32_e32 v169, v148, v137
	ds_bpermute_b32 v137, v149, v125
	s_waitcnt lgkmcnt(1)
	v_mul_f32_e32 v166, v148, v134
	v_mad_i64_i32 v[172:173], s[24:25], v147, s15, 0
	v_or_b32_e32 v134, 1, v147
	s_waitcnt vmcnt(5)
	v_lshl_add_u64 v[178:179], v[172:173], 1, v[138:139]
	v_lshl_add_u64 v[172:173], v[172:173], 2, v[140:141]
	s_waitcnt vmcnt(4)
	v_mov_b32_e32 v161, v160
	s_waitcnt vmcnt(1)
	v_mov_b32_e32 v163, v152
	v_mov_b32_e32 v162, v151
	ds_bpermute_b32 v151, v149, v112
	s_waitcnt vmcnt(0)
	v_mov_b32_e32 v164, v155
	v_mov_b32_e32 v165, v156
	v_mul_f32_e32 v156, v148, v144
	v_mov_b32_e32 v155, v157
	s_waitcnt lgkmcnt(0)
	v_mul_f32_e32 v171, v148, v151
	v_mov_b32_e32 v151, v153
	v_mov_b32_e32 v157, v112
	v_pk_mul_f32 v[150:151], v[170:171], v[150:151]
	ds_bpermute_b32 v144, v149, v121
	ds_bpermute_b32 v152, v149, v113
	v_pk_fma_f32 v[156:157], v[162:163], v[156:157], v[150:151]
	ds_bpermute_b32 v151, v149, v117
	v_pk_mul_f32 v[154:155], v[168:169], v[154:155]
	v_mov_b32_e32 v160, v159
	v_pk_fma_f32 v[154:155], v[164:165], v[166:167], v[154:155]
	s_waitcnt lgkmcnt(2)
	v_mul_f32_e32 v153, v148, v144
	s_waitcnt lgkmcnt(1)
	v_mul_f32_e32 v167, v148, v152
	v_mov_b32_e32 v152, v125
	v_mov_b32_e32 v159, v128
	v_mov_b32_e32 v166, v117
	v_mov_b32_e32 v144, v129
	v_cvt_pk_bf16_f32 v164, v154, v155
	v_cvt_pk_bf16_f32 v165, v156, v157
	v_mul_f32_e32 v150, v148, v137
	s_waitcnt lgkmcnt(0)
	v_mul_f32_e32 v162, v148, v151
	v_mad_i64_i32 v[168:169], s[24:25], v134, s15, 0
	v_mov_b32_e32 v151, v121
	v_pk_mul_f32 v[152:153], v[152:153], v[158:159]
	v_mov_b32_e32 v163, v113
	v_pk_mul_f32 v[144:145], v[166:167], v[144:145]
	v_lshl_add_u64 v[170:171], v[168:169], 1, v[138:139]
	v_lshl_add_u64 v[168:169], v[168:169], 2, v[140:141]
	v_pk_fma_f32 v[150:151], v[160:161], v[150:151], v[152:153]
	v_pk_fma_f32 v[152:153], v[130:131], v[162:163], v[144:145]
	v_cvt_pk_bf16_f32 v128, v150, v151
	global_store_dwordx2 v[178:179], v[164:165], off
	global_store_dwordx4 v[172:173], v[154:157], off nt
	v_cvt_pk_bf16_f32 v129, v152, v153
	global_store_dwordx2 v[170:171], v[128:129], off
	global_store_dwordx4 v[168:169], v[150:153], off nt
	v_or_b32_e32 v137, 2, v147
	v_lshlrev_b32_e32 v128, 8, v137
	v_and_b32_e32 v134, 0x7fe00, v128
	v_lshl_add_u64 v[154:155], v[142:143], 0, v[134:135]
	global_load_dwordx3 v[158:160], v[154:155], off offset:256
	global_load_dwordx4 v[128:131], v[154:155], off offset:268
	global_load_dword v145, v[154:155], off offset:284
	global_load_dwordx4 v[150:153], v[154:155], off offset:16
	ds_bpermute_b32 v144, v149, v122
	global_load_dwordx4 v[154:157], v[154:155], off
	ds_bpermute_b32 v134, v149, v126
	v_mov_b32_e32 v170, v118
	v_mad_i64_i32 v[172:173], s[24:25], v137, s15, 0
	s_waitcnt lgkmcnt(1)
	v_mul_f32_e32 v169, v148, v144
	ds_bpermute_b32 v144, v149, v123
	ds_bpermute_b32 v137, v149, v127
	v_mov_b32_e32 v168, v126
	s_waitcnt lgkmcnt(2)
	v_mul_f32_e32 v166, v148, v134
	v_mov_b32_e32 v167, v122
	v_or_b32_e32 v134, 3, v147
	v_lshl_add_u64 v[178:179], v[172:173], 1, v[138:139]
	v_lshl_add_u64 v[172:173], v[172:173], 2, v[140:141]
	s_waitcnt vmcnt(4)
	v_mov_b32_e32 v161, v160
	s_waitcnt vmcnt(1)
	v_mov_b32_e32 v163, v152
	v_mov_b32_e32 v162, v151
	ds_bpermute_b32 v151, v149, v118
	ds_bpermute_b32 v152, v149, v114
	s_waitcnt vmcnt(0)
	v_mov_b32_e32 v165, v156
	v_mov_b32_e32 v164, v155
	v_mov_b32_e32 v155, v157
	s_waitcnt lgkmcnt(1)
	v_mul_f32_e32 v156, v148, v151
	s_waitcnt lgkmcnt(0)
	v_mul_f32_e32 v171, v148, v152
	v_mov_b32_e32 v151, v153
	v_mov_b32_e32 v157, v114
	v_pk_mul_f32 v[150:151], v[170:171], v[150:151]
	ds_bpermute_b32 v152, v149, v115
	v_pk_fma_f32 v[156:157], v[162:163], v[156:157], v[150:151]
	ds_bpermute_b32 v151, v149, v119
	v_pk_mul_f32 v[154:155], v[168:169], v[154:155]
	v_mov_b32_e32 v160, v159
	v_pk_fma_f32 v[154:155], v[164:165], v[166:167], v[154:155]
	v_mul_f32_e32 v153, v148, v144
	s_waitcnt lgkmcnt(1)
	v_mul_f32_e32 v167, v148, v152
	v_mov_b32_e32 v152, v127
	v_mov_b32_e32 v159, v128
	v_mov_b32_e32 v166, v119
	v_mov_b32_e32 v144, v129
	v_cvt_pk_bf16_f32 v164, v154, v155
	v_cvt_pk_bf16_f32 v165, v156, v157
	v_mul_f32_e32 v150, v148, v137
	s_waitcnt lgkmcnt(0)
	v_mul_f32_e32 v162, v148, v151
	v_mad_i64_i32 v[168:169], s[24:25], v134, s15, 0
	v_mov_b32_e32 v151, v123
	v_pk_mul_f32 v[152:153], v[152:153], v[158:159]
	v_mov_b32_e32 v163, v115
	v_pk_mul_f32 v[144:145], v[166:167], v[144:145]
	v_lshl_add_u64 v[170:171], v[168:169], 1, v[138:139]
	v_lshl_add_u64 v[168:169], v[168:169], 2, v[140:141]
	v_pk_fma_f32 v[150:151], v[160:161], v[150:151], v[152:153]
	v_pk_fma_f32 v[152:153], v[130:131], v[162:163], v[144:145]
	v_cvt_pk_bf16_f32 v128, v150, v151
	global_store_dwordx2 v[178:179], v[164:165], off
	global_store_dwordx4 v[172:173], v[154:157], off nt
	v_cvt_pk_bf16_f32 v129, v152, v153
	global_store_dwordx2 v[170:171], v[128:129], off
	global_store_dwordx4 v[168:169], v[150:153], off nt
	v_add_u32_e32 v137, 16, v147
	v_lshlrev_b32_e32 v128, 8, v137
	v_and_b32_e32 v134, 0x7fc00, v128
	v_lshl_add_u64 v[154:155], v[142:143], 0, v[134:135]
	global_load_dwordx3 v[158:160], v[154:155], off offset:256
	global_load_dwordx4 v[128:131], v[154:155], off offset:268
	global_load_dword v145, v[154:155], off offset:284
	global_load_dwordx4 v[150:153], v[154:155], off offset:16
	ds_bpermute_b32 v144, v149, v104
	global_load_dwordx4 v[154:157], v[154:155], off
	ds_bpermute_b32 v134, v149, v108
	v_mov_b32_e32 v170, v100
	v_mad_i64_i32 v[172:173], s[24:25], v137, s15, 0
	s_waitcnt lgkmcnt(1)
	v_mul_f32_e32 v169, v148, v144
	ds_bpermute_b32 v144, v149, v105
	ds_bpermute_b32 v137, v149, v109
	v_mov_b32_e32 v168, v108
	s_waitcnt lgkmcnt(2)
	v_mul_f32_e32 v166, v148, v134
	v_mov_b32_e32 v167, v104
	v_add_u32_e32 v134, 17, v147
	v_lshl_add_u64 v[178:179], v[172:173], 1, v[138:139]
	v_lshl_add_u64 v[172:173], v[172:173], 2, v[140:141]
	s_waitcnt vmcnt(4)
	v_mov_b32_e32 v161, v160
	s_waitcnt vmcnt(1)
	v_mov_b32_e32 v163, v152
	v_mov_b32_e32 v162, v151
	ds_bpermute_b32 v151, v149, v100
	ds_bpermute_b32 v152, v149, v96
	s_waitcnt vmcnt(0)
	v_mov_b32_e32 v165, v156
	v_mov_b32_e32 v164, v155
	v_mov_b32_e32 v155, v157
	s_waitcnt lgkmcnt(1)
	v_mul_f32_e32 v156, v148, v151
	s_waitcnt lgkmcnt(0)
	v_mul_f32_e32 v171, v148, v152
	v_mov_b32_e32 v151, v153
	v_mov_b32_e32 v157, v96
	v_pk_mul_f32 v[150:151], v[170:171], v[150:151]
	ds_bpermute_b32 v152, v149, v97
	v_pk_fma_f32 v[156:157], v[162:163], v[156:157], v[150:151]
	ds_bpermute_b32 v151, v149, v101
	v_pk_mul_f32 v[154:155], v[168:169], v[154:155]
	v_mov_b32_e32 v160, v159
	v_pk_fma_f32 v[154:155], v[164:165], v[166:167], v[154:155]
	v_mul_f32_e32 v153, v148, v144
	s_waitcnt lgkmcnt(1)
	v_mul_f32_e32 v167, v148, v152
	v_mov_b32_e32 v152, v109
	v_mov_b32_e32 v159, v128
	v_mov_b32_e32 v166, v101
	v_mov_b32_e32 v144, v129
	v_cvt_pk_bf16_f32 v164, v154, v155
	v_cvt_pk_bf16_f32 v165, v156, v157
	v_mul_f32_e32 v150, v148, v137
	s_waitcnt lgkmcnt(0)
	v_mul_f32_e32 v162, v148, v151
	v_mad_i64_i32 v[168:169], s[24:25], v134, s15, 0
	v_mov_b32_e32 v151, v105
	v_pk_mul_f32 v[152:153], v[152:153], v[158:159]
	v_mov_b32_e32 v163, v97
	v_pk_mul_f32 v[144:145], v[166:167], v[144:145]
	v_lshl_add_u64 v[170:171], v[168:169], 1, v[138:139]
	v_lshl_add_u64 v[168:169], v[168:169], 2, v[140:141]
	v_pk_fma_f32 v[150:151], v[160:161], v[150:151], v[152:153]
	v_pk_fma_f32 v[152:153], v[130:131], v[162:163], v[144:145]
	v_cvt_pk_bf16_f32 v128, v150, v151
	global_store_dwordx2 v[178:179], v[164:165], off
	global_store_dwordx4 v[172:173], v[154:157], off nt
	v_cvt_pk_bf16_f32 v129, v152, v153
	global_store_dwordx2 v[170:171], v[128:129], off
	global_store_dwordx4 v[168:169], v[150:153], off nt
	v_add_u32_e32 v137, 18, v147
	v_lshlrev_b32_e32 v128, 8, v137
	v_and_b32_e32 v134, 0x7fe00, v128
	v_lshl_add_u64 v[154:155], v[142:143], 0, v[134:135]
	global_load_dwordx3 v[158:160], v[154:155], off offset:256
	global_load_dwordx4 v[128:131], v[154:155], off offset:268
	global_load_dword v145, v[154:155], off offset:284
	global_load_dwordx4 v[150:153], v[154:155], off offset:16
	ds_bpermute_b32 v144, v149, v106
	global_load_dwordx4 v[154:157], v[154:155], off
	ds_bpermute_b32 v134, v149, v110
	v_mov_b32_e32 v170, v102
	v_mad_i64_i32 v[172:173], s[24:25], v137, s15, 0
	s_waitcnt lgkmcnt(1)
	v_mul_f32_e32 v169, v148, v144
	ds_bpermute_b32 v144, v149, v107
	ds_bpermute_b32 v137, v149, v111
	v_mov_b32_e32 v168, v110
	s_waitcnt lgkmcnt(2)
	v_mul_f32_e32 v166, v148, v134
	v_mov_b32_e32 v167, v106
	v_add_u32_e32 v134, 19, v147
	v_lshl_add_u64 v[178:179], v[172:173], 1, v[138:139]
	v_lshl_add_u64 v[172:173], v[172:173], 2, v[140:141]
	s_waitcnt vmcnt(4)
	v_mov_b32_e32 v161, v160
	s_waitcnt vmcnt(1)
	v_mov_b32_e32 v163, v152
	v_mov_b32_e32 v162, v151
	ds_bpermute_b32 v151, v149, v102
	ds_bpermute_b32 v152, v149, v98
	s_waitcnt vmcnt(0)
	v_mov_b32_e32 v165, v156
	v_mov_b32_e32 v164, v155
	v_mov_b32_e32 v155, v157
	s_waitcnt lgkmcnt(1)
	v_mul_f32_e32 v156, v148, v151
	s_waitcnt lgkmcnt(0)
	v_mul_f32_e32 v171, v148, v152
	v_mov_b32_e32 v151, v153
	v_mov_b32_e32 v157, v98
	v_pk_mul_f32 v[150:151], v[170:171], v[150:151]
	ds_bpermute_b32 v152, v149, v99
	v_pk_fma_f32 v[156:157], v[162:163], v[156:157], v[150:151]
	ds_bpermute_b32 v151, v149, v103
	v_pk_mul_f32 v[154:155], v[168:169], v[154:155]
	v_mov_b32_e32 v160, v159
	v_pk_fma_f32 v[154:155], v[164:165], v[166:167], v[154:155]
	v_mul_f32_e32 v153, v148, v144
	s_waitcnt lgkmcnt(1)
	v_mul_f32_e32 v167, v148, v152
	v_mov_b32_e32 v152, v111
	v_mov_b32_e32 v159, v128
	v_mov_b32_e32 v166, v103
	v_mov_b32_e32 v144, v129
	v_cvt_pk_bf16_f32 v164, v154, v155
	v_cvt_pk_bf16_f32 v165, v156, v157
	v_mul_f32_e32 v150, v148, v137
	s_waitcnt lgkmcnt(0)
	v_mul_f32_e32 v162, v148, v151
	v_mad_i64_i32 v[168:169], s[24:25], v134, s15, 0
	v_mov_b32_e32 v151, v107
	v_pk_mul_f32 v[152:153], v[152:153], v[158:159]
	v_mov_b32_e32 v163, v99
	v_pk_mul_f32 v[144:145], v[166:167], v[144:145]
	v_lshl_add_u64 v[170:171], v[168:169], 1, v[138:139]
	v_lshl_add_u64 v[168:169], v[168:169], 2, v[140:141]
	v_pk_fma_f32 v[150:151], v[160:161], v[150:151], v[152:153]
	v_pk_fma_f32 v[152:153], v[130:131], v[162:163], v[144:145]
	v_cvt_pk_bf16_f32 v128, v150, v151
	global_store_dwordx2 v[178:179], v[164:165], off
	global_store_dwordx4 v[172:173], v[154:157], off nt
	v_cvt_pk_bf16_f32 v129, v152, v153
	global_store_dwordx2 v[170:171], v[128:129], off
	global_store_dwordx4 v[168:169], v[150:153], off nt
	v_add_u32_e32 v137, 32, v147
	v_lshlrev_b32_e32 v128, 8, v137
	v_and_b32_e32 v134, 0x7fc00, v128
	v_lshl_add_u64 v[154:155], v[142:143], 0, v[134:135]
	global_load_dwordx3 v[158:160], v[154:155], off offset:256
	global_load_dwordx4 v[128:131], v[154:155], off offset:268
	global_load_dword v145, v[154:155], off offset:284
	global_load_dwordx4 v[150:153], v[154:155], off offset:16
	ds_bpermute_b32 v144, v149, v88
	global_load_dwordx4 v[154:157], v[154:155], off
	ds_bpermute_b32 v134, v149, v92
	v_mov_b32_e32 v170, v84
	v_mad_i64_i32 v[172:173], s[24:25], v137, s15, 0
	s_waitcnt lgkmcnt(1)
	v_mul_f32_e32 v169, v148, v144
	ds_bpermute_b32 v144, v149, v89
	ds_bpermute_b32 v137, v149, v93
	v_mov_b32_e32 v168, v92
	s_waitcnt lgkmcnt(2)
	v_mul_f32_e32 v166, v148, v134
	v_mov_b32_e32 v167, v88
	v_add_u32_e32 v134, 33, v147
	v_lshl_add_u64 v[178:179], v[172:173], 1, v[138:139]
	v_lshl_add_u64 v[172:173], v[172:173], 2, v[140:141]
	s_waitcnt vmcnt(4)
	v_mov_b32_e32 v161, v160
	s_waitcnt vmcnt(1)
	v_mov_b32_e32 v163, v152
	v_mov_b32_e32 v162, v151
	ds_bpermute_b32 v151, v149, v84
	ds_bpermute_b32 v152, v149, v80
	s_waitcnt vmcnt(0)
	v_mov_b32_e32 v165, v156
	v_mov_b32_e32 v164, v155
	v_mov_b32_e32 v155, v157
	s_waitcnt lgkmcnt(1)
	v_mul_f32_e32 v156, v148, v151
	s_waitcnt lgkmcnt(0)
	v_mul_f32_e32 v171, v148, v152
	v_mov_b32_e32 v151, v153
	v_mov_b32_e32 v157, v80
	v_pk_mul_f32 v[150:151], v[170:171], v[150:151]
	ds_bpermute_b32 v152, v149, v81
	v_pk_fma_f32 v[156:157], v[162:163], v[156:157], v[150:151]
	ds_bpermute_b32 v151, v149, v85
	v_pk_mul_f32 v[154:155], v[168:169], v[154:155]
	v_mov_b32_e32 v160, v159
	v_pk_fma_f32 v[154:155], v[164:165], v[166:167], v[154:155]
	v_mul_f32_e32 v153, v148, v144
	s_waitcnt lgkmcnt(1)
	v_mul_f32_e32 v167, v148, v152
	v_mov_b32_e32 v152, v93
	v_mov_b32_e32 v159, v128
	v_mov_b32_e32 v166, v85
	v_mov_b32_e32 v144, v129
	v_cvt_pk_bf16_f32 v164, v154, v155
	v_cvt_pk_bf16_f32 v165, v156, v157
	v_mul_f32_e32 v150, v148, v137
	s_waitcnt lgkmcnt(0)
	v_mul_f32_e32 v162, v148, v151
	v_mad_i64_i32 v[168:169], s[24:25], v134, s15, 0
	v_mov_b32_e32 v151, v89
	v_pk_mul_f32 v[152:153], v[152:153], v[158:159]
	v_mov_b32_e32 v163, v81
	v_pk_mul_f32 v[144:145], v[166:167], v[144:145]
	v_lshl_add_u64 v[170:171], v[168:169], 1, v[138:139]
	v_lshl_add_u64 v[168:169], v[168:169], 2, v[140:141]
	v_pk_fma_f32 v[150:151], v[160:161], v[150:151], v[152:153]
	v_pk_fma_f32 v[152:153], v[130:131], v[162:163], v[144:145]
	v_cvt_pk_bf16_f32 v128, v150, v151
	global_store_dwordx2 v[178:179], v[164:165], off
	global_store_dwordx4 v[172:173], v[154:157], off nt
	v_cvt_pk_bf16_f32 v129, v152, v153
	global_store_dwordx2 v[170:171], v[128:129], off
	global_store_dwordx4 v[168:169], v[150:153], off nt
	v_add_u32_e32 v137, 34, v147
	v_lshlrev_b32_e32 v128, 8, v137
	v_and_b32_e32 v134, 0x7fe00, v128
	v_lshl_add_u64 v[154:155], v[142:143], 0, v[134:135]
	global_load_dwordx3 v[158:160], v[154:155], off offset:256
	global_load_dwordx4 v[128:131], v[154:155], off offset:268
	global_load_dword v145, v[154:155], off offset:284
	global_load_dwordx4 v[150:153], v[154:155], off offset:16
	ds_bpermute_b32 v144, v149, v90
	global_load_dwordx4 v[154:157], v[154:155], off
	ds_bpermute_b32 v134, v149, v94
	v_mov_b32_e32 v170, v86
	v_mad_i64_i32 v[172:173], s[24:25], v137, s15, 0
	s_waitcnt lgkmcnt(1)
	v_mul_f32_e32 v169, v148, v144
	ds_bpermute_b32 v144, v149, v91
	ds_bpermute_b32 v137, v149, v95
	v_mov_b32_e32 v168, v94
	s_waitcnt lgkmcnt(2)
	v_mul_f32_e32 v166, v148, v134
	v_mov_b32_e32 v167, v90
	v_add_u32_e32 v134, 35, v147
	v_lshl_add_u64 v[178:179], v[172:173], 1, v[138:139]
	v_lshl_add_u64 v[172:173], v[172:173], 2, v[140:141]
	s_waitcnt vmcnt(4)
	v_mov_b32_e32 v161, v160
	s_waitcnt vmcnt(1)
	v_mov_b32_e32 v163, v152
	v_mov_b32_e32 v162, v151
	ds_bpermute_b32 v151, v149, v86
	ds_bpermute_b32 v152, v149, v82
	s_waitcnt vmcnt(0)
	v_mov_b32_e32 v165, v156
	v_mov_b32_e32 v164, v155
	v_mov_b32_e32 v155, v157
	s_waitcnt lgkmcnt(1)
	v_mul_f32_e32 v156, v148, v151
	s_waitcnt lgkmcnt(0)
	v_mul_f32_e32 v171, v148, v152
	v_mov_b32_e32 v151, v153
	v_mov_b32_e32 v157, v82
	v_pk_mul_f32 v[150:151], v[170:171], v[150:151]
	ds_bpermute_b32 v152, v149, v83
	v_pk_fma_f32 v[156:157], v[162:163], v[156:157], v[150:151]
	ds_bpermute_b32 v151, v149, v87
	v_pk_mul_f32 v[154:155], v[168:169], v[154:155]
	v_mov_b32_e32 v160, v159
	v_pk_fma_f32 v[154:155], v[164:165], v[166:167], v[154:155]
	v_mul_f32_e32 v153, v148, v144
	s_waitcnt lgkmcnt(1)
	v_mul_f32_e32 v167, v148, v152
	v_mov_b32_e32 v152, v95
	v_mov_b32_e32 v159, v128
	v_mov_b32_e32 v166, v87
	v_mov_b32_e32 v144, v129
	v_cvt_pk_bf16_f32 v164, v154, v155
	v_cvt_pk_bf16_f32 v165, v156, v157
	v_mul_f32_e32 v150, v148, v137
	s_waitcnt lgkmcnt(0)
	v_mul_f32_e32 v162, v148, v151
	v_mad_i64_i32 v[168:169], s[24:25], v134, s15, 0
	v_mov_b32_e32 v151, v91
	v_pk_mul_f32 v[152:153], v[152:153], v[158:159]
	v_mov_b32_e32 v163, v83
	v_pk_mul_f32 v[144:145], v[166:167], v[144:145]
	v_lshl_add_u64 v[170:171], v[168:169], 1, v[138:139]
	v_lshl_add_u64 v[168:169], v[168:169], 2, v[140:141]
	v_pk_fma_f32 v[150:151], v[160:161], v[150:151], v[152:153]
	v_pk_fma_f32 v[152:153], v[130:131], v[162:163], v[144:145]
	v_cvt_pk_bf16_f32 v128, v150, v151
	global_store_dwordx2 v[178:179], v[164:165], off
	global_store_dwordx4 v[172:173], v[154:157], off nt
	v_cvt_pk_bf16_f32 v129, v152, v153
	global_store_dwordx2 v[170:171], v[128:129], off
	global_store_dwordx4 v[168:169], v[150:153], off nt
	v_add_u32_e32 v137, 48, v147
	v_lshlrev_b32_e32 v128, 8, v137
	v_and_b32_e32 v134, 0x7fc00, v128
	v_lshl_add_u64 v[154:155], v[142:143], 0, v[134:135]
	global_load_dwordx3 v[158:160], v[154:155], off offset:256
	global_load_dwordx4 v[128:131], v[154:155], off offset:268
	global_load_dword v145, v[154:155], off offset:284
	global_load_dwordx4 v[150:153], v[154:155], off offset:16
	ds_bpermute_b32 v144, v149, v72
	global_load_dwordx4 v[154:157], v[154:155], off
	ds_bpermute_b32 v134, v149, v76
	v_mov_b32_e32 v170, v68
	v_mad_i64_i32 v[172:173], s[24:25], v137, s15, 0
	s_waitcnt lgkmcnt(1)
	v_mul_f32_e32 v169, v148, v144
	ds_bpermute_b32 v144, v149, v73
	ds_bpermute_b32 v137, v149, v77
	v_mov_b32_e32 v168, v76
	s_waitcnt lgkmcnt(2)
	v_mul_f32_e32 v166, v148, v134
	v_mov_b32_e32 v167, v72
	v_add_u32_e32 v134, 49, v147
	v_lshl_add_u64 v[178:179], v[172:173], 1, v[138:139]
	v_lshl_add_u64 v[172:173], v[172:173], 2, v[140:141]
	s_waitcnt vmcnt(4)
	v_mov_b32_e32 v161, v160
	s_waitcnt vmcnt(1)
	v_mov_b32_e32 v163, v152
	v_mov_b32_e32 v162, v151
	ds_bpermute_b32 v151, v149, v68
	ds_bpermute_b32 v152, v149, v64
	s_waitcnt vmcnt(0)
	v_mov_b32_e32 v165, v156
	v_mov_b32_e32 v164, v155
	v_mov_b32_e32 v155, v157
	s_waitcnt lgkmcnt(1)
	v_mul_f32_e32 v156, v148, v151
	s_waitcnt lgkmcnt(0)
	v_mul_f32_e32 v171, v148, v152
	v_mov_b32_e32 v151, v153
	v_mov_b32_e32 v157, v64
	v_pk_mul_f32 v[150:151], v[170:171], v[150:151]
	ds_bpermute_b32 v152, v149, v65
	v_pk_fma_f32 v[156:157], v[162:163], v[156:157], v[150:151]
	ds_bpermute_b32 v151, v149, v69
	v_pk_mul_f32 v[154:155], v[168:169], v[154:155]
	v_mov_b32_e32 v160, v159
	v_pk_fma_f32 v[154:155], v[164:165], v[166:167], v[154:155]
	v_mul_f32_e32 v153, v148, v144
	s_waitcnt lgkmcnt(1)
	v_mul_f32_e32 v167, v148, v152
	v_mov_b32_e32 v152, v77
	v_mov_b32_e32 v159, v128
	v_mov_b32_e32 v166, v69
	v_mov_b32_e32 v144, v129
	v_cvt_pk_bf16_f32 v164, v154, v155
	v_cvt_pk_bf16_f32 v165, v156, v157
	v_mul_f32_e32 v150, v148, v137
	s_waitcnt lgkmcnt(0)
	v_mul_f32_e32 v162, v148, v151
	v_mad_i64_i32 v[168:169], s[24:25], v134, s15, 0
	v_mov_b32_e32 v151, v73
	v_pk_mul_f32 v[152:153], v[152:153], v[158:159]
	v_mov_b32_e32 v163, v65
	v_pk_mul_f32 v[144:145], v[166:167], v[144:145]
	v_lshl_add_u64 v[170:171], v[168:169], 1, v[138:139]
	v_lshl_add_u64 v[168:169], v[168:169], 2, v[140:141]
	v_pk_fma_f32 v[150:151], v[160:161], v[150:151], v[152:153]
	v_pk_fma_f32 v[152:153], v[130:131], v[162:163], v[144:145]
	v_cvt_pk_bf16_f32 v128, v150, v151
	global_store_dwordx2 v[178:179], v[164:165], off
	global_store_dwordx4 v[172:173], v[154:157], off nt
	v_cvt_pk_bf16_f32 v129, v152, v153
	global_store_dwordx2 v[170:171], v[128:129], off
	global_store_dwordx4 v[168:169], v[150:153], off nt
	v_add_u32_e32 v137, 50, v147
	v_lshlrev_b32_e32 v128, 8, v137
	v_and_b32_e32 v134, 0x7fe00, v128
	v_lshl_add_u64 v[154:155], v[142:143], 0, v[134:135]
	global_load_dwordx3 v[158:160], v[154:155], off offset:256
	global_load_dwordx4 v[128:131], v[154:155], off offset:268
	global_load_dword v145, v[154:155], off offset:284
	global_load_dwordx4 v[150:153], v[154:155], off offset:16
	ds_bpermute_b32 v144, v149, v74
	global_load_dwordx4 v[154:157], v[154:155], off
	ds_bpermute_b32 v134, v149, v78
	v_mov_b32_e32 v170, v70
	v_mad_i64_i32 v[172:173], s[24:25], v137, s15, 0
	s_waitcnt lgkmcnt(1)
	v_mul_f32_e32 v169, v148, v144
	ds_bpermute_b32 v144, v149, v75
	ds_bpermute_b32 v137, v149, v79
	v_mov_b32_e32 v168, v78
	s_waitcnt lgkmcnt(2)
	v_mul_f32_e32 v166, v148, v134
	v_mov_b32_e32 v167, v74
	v_add_u32_e32 v134, 51, v147
	v_lshl_add_u64 v[178:179], v[172:173], 1, v[138:139]
	v_lshl_add_u64 v[172:173], v[172:173], 2, v[140:141]
	s_waitcnt vmcnt(4)
	v_mov_b32_e32 v161, v160
	s_waitcnt vmcnt(1)
	v_mov_b32_e32 v163, v152
	v_mov_b32_e32 v162, v151
	ds_bpermute_b32 v151, v149, v70
	ds_bpermute_b32 v152, v149, v66
	s_waitcnt vmcnt(0)
	v_mov_b32_e32 v165, v156
	v_mov_b32_e32 v164, v155
	v_mov_b32_e32 v155, v157
	s_waitcnt lgkmcnt(1)
	v_mul_f32_e32 v156, v148, v151
	s_waitcnt lgkmcnt(0)
	v_mul_f32_e32 v171, v148, v152
	v_mov_b32_e32 v151, v153
	v_mov_b32_e32 v157, v66
	v_pk_mul_f32 v[150:151], v[170:171], v[150:151]
	ds_bpermute_b32 v152, v149, v67
	v_pk_fma_f32 v[156:157], v[162:163], v[156:157], v[150:151]
	ds_bpermute_b32 v151, v149, v71
	v_pk_mul_f32 v[154:155], v[168:169], v[154:155]
	v_mov_b32_e32 v160, v159
	v_pk_fma_f32 v[154:155], v[164:165], v[166:167], v[154:155]
	v_mul_f32_e32 v153, v148, v144
	s_waitcnt lgkmcnt(1)
	v_mul_f32_e32 v167, v148, v152
	v_mov_b32_e32 v152, v79
	v_mov_b32_e32 v159, v128
	v_mov_b32_e32 v166, v71
	v_mov_b32_e32 v144, v129
	v_cvt_pk_bf16_f32 v164, v154, v155
	v_cvt_pk_bf16_f32 v165, v156, v157
	v_mul_f32_e32 v150, v148, v137
	s_waitcnt lgkmcnt(0)
	v_mul_f32_e32 v162, v148, v151
	v_mad_i64_i32 v[168:169], s[24:25], v134, s15, 0
	v_mov_b32_e32 v151, v75
	v_pk_mul_f32 v[152:153], v[152:153], v[158:159]
	v_mov_b32_e32 v163, v67
	v_pk_mul_f32 v[144:145], v[166:167], v[144:145]
	v_lshl_add_u64 v[170:171], v[168:169], 1, v[138:139]
	v_lshl_add_u64 v[168:169], v[168:169], 2, v[140:141]
	v_pk_fma_f32 v[150:151], v[160:161], v[150:151], v[152:153]
	v_pk_fma_f32 v[152:153], v[130:131], v[162:163], v[144:145]
	v_cvt_pk_bf16_f32 v128, v150, v151
	global_store_dwordx2 v[178:179], v[164:165], off
	global_store_dwordx4 v[172:173], v[154:157], off nt
	v_cvt_pk_bf16_f32 v129, v152, v153
	global_store_dwordx2 v[170:171], v[128:129], off
	global_store_dwordx4 v[168:169], v[150:153], off nt
	v_add_u32_e32 v137, 64, v147
	v_lshlrev_b32_e32 v128, 8, v137
	v_and_b32_e32 v134, 0x7fc00, v128
	v_lshl_add_u64 v[154:155], v[142:143], 0, v[134:135]
	global_load_dwordx3 v[158:160], v[154:155], off offset:256
	global_load_dwordx4 v[128:131], v[154:155], off offset:268
	global_load_dword v145, v[154:155], off offset:284
	global_load_dwordx4 v[150:153], v[154:155], off offset:16
	ds_bpermute_b32 v144, v149, v56
	global_load_dwordx4 v[154:157], v[154:155], off
	ds_bpermute_b32 v134, v149, v60
	v_mov_b32_e32 v170, v52
	v_mad_i64_i32 v[172:173], s[24:25], v137, s15, 0
	s_waitcnt lgkmcnt(1)
	v_mul_f32_e32 v169, v148, v144
	ds_bpermute_b32 v144, v149, v57
	ds_bpermute_b32 v137, v149, v61
	v_mov_b32_e32 v168, v60
	s_waitcnt lgkmcnt(2)
	v_mul_f32_e32 v166, v148, v134
	v_mov_b32_e32 v167, v56
	v_add_u32_e32 v134, 0x41, v147
	v_lshl_add_u64 v[178:179], v[172:173], 1, v[138:139]
	v_lshl_add_u64 v[172:173], v[172:173], 2, v[140:141]
	s_waitcnt vmcnt(4)
	v_mov_b32_e32 v161, v160
	s_waitcnt vmcnt(1)
	v_mov_b32_e32 v163, v152
	v_mov_b32_e32 v162, v151
	ds_bpermute_b32 v151, v149, v52
	ds_bpermute_b32 v152, v149, v48
	s_waitcnt vmcnt(0)
	v_mov_b32_e32 v165, v156
	v_mov_b32_e32 v164, v155
	v_mov_b32_e32 v155, v157
	s_waitcnt lgkmcnt(1)
	v_mul_f32_e32 v156, v148, v151
	s_waitcnt lgkmcnt(0)
	v_mul_f32_e32 v171, v148, v152
	v_mov_b32_e32 v151, v153
	v_mov_b32_e32 v157, v48
	v_pk_mul_f32 v[150:151], v[170:171], v[150:151]
	ds_bpermute_b32 v152, v149, v49
	v_pk_fma_f32 v[156:157], v[162:163], v[156:157], v[150:151]
	ds_bpermute_b32 v151, v149, v53
	v_pk_mul_f32 v[154:155], v[168:169], v[154:155]
	v_mov_b32_e32 v160, v159
	v_pk_fma_f32 v[154:155], v[164:165], v[166:167], v[154:155]
	v_mul_f32_e32 v153, v148, v144
	s_waitcnt lgkmcnt(1)
	v_mul_f32_e32 v167, v148, v152
	v_mov_b32_e32 v152, v61
	v_mov_b32_e32 v159, v128
	v_mov_b32_e32 v166, v53
	v_mov_b32_e32 v144, v129
	v_cvt_pk_bf16_f32 v164, v154, v155
	v_cvt_pk_bf16_f32 v165, v156, v157
	v_mul_f32_e32 v150, v148, v137
	s_waitcnt lgkmcnt(0)
	v_mul_f32_e32 v162, v148, v151
	v_mad_i64_i32 v[168:169], s[24:25], v134, s15, 0
	v_mov_b32_e32 v151, v57
	v_pk_mul_f32 v[152:153], v[152:153], v[158:159]
	v_mov_b32_e32 v163, v49
	v_pk_mul_f32 v[144:145], v[166:167], v[144:145]
	v_lshl_add_u64 v[170:171], v[168:169], 1, v[138:139]
	v_lshl_add_u64 v[168:169], v[168:169], 2, v[140:141]
	v_pk_fma_f32 v[150:151], v[160:161], v[150:151], v[152:153]
	v_pk_fma_f32 v[152:153], v[130:131], v[162:163], v[144:145]
	v_cvt_pk_bf16_f32 v128, v150, v151
	global_store_dwordx2 v[178:179], v[164:165], off
	global_store_dwordx4 v[172:173], v[154:157], off nt
	v_cvt_pk_bf16_f32 v129, v152, v153
	global_store_dwordx2 v[170:171], v[128:129], off
	global_store_dwordx4 v[168:169], v[150:153], off nt
	v_add_u32_e32 v137, 0x42, v147
	v_lshlrev_b32_e32 v128, 8, v137
	v_and_b32_e32 v134, 0x7fe00, v128
	v_lshl_add_u64 v[154:155], v[142:143], 0, v[134:135]
	global_load_dwordx3 v[158:160], v[154:155], off offset:256
	global_load_dwordx4 v[128:131], v[154:155], off offset:268
	global_load_dword v145, v[154:155], off offset:284
	global_load_dwordx4 v[150:153], v[154:155], off offset:16
	ds_bpermute_b32 v144, v149, v58
	global_load_dwordx4 v[154:157], v[154:155], off
	ds_bpermute_b32 v134, v149, v62
	v_mov_b32_e32 v170, v54
	v_mad_i64_i32 v[172:173], s[24:25], v137, s15, 0
	s_waitcnt lgkmcnt(1)
	v_mul_f32_e32 v169, v148, v144
	ds_bpermute_b32 v144, v149, v59
	ds_bpermute_b32 v137, v149, v63
	v_mov_b32_e32 v168, v62
	s_waitcnt lgkmcnt(2)
	v_mul_f32_e32 v166, v148, v134
	v_mov_b32_e32 v167, v58
	v_add_u32_e32 v134, 0x43, v147
	v_lshl_add_u64 v[178:179], v[172:173], 1, v[138:139]
	v_lshl_add_u64 v[172:173], v[172:173], 2, v[140:141]
	s_waitcnt vmcnt(4)
	v_mov_b32_e32 v161, v160
	s_waitcnt vmcnt(1)
	v_mov_b32_e32 v163, v152
	v_mov_b32_e32 v162, v151
	ds_bpermute_b32 v151, v149, v54
	ds_bpermute_b32 v152, v149, v50
	s_waitcnt vmcnt(0)
	v_mov_b32_e32 v165, v156
	v_mov_b32_e32 v164, v155
	v_mov_b32_e32 v155, v157
	s_waitcnt lgkmcnt(1)
	v_mul_f32_e32 v156, v148, v151
	s_waitcnt lgkmcnt(0)
	v_mul_f32_e32 v171, v148, v152
	v_mov_b32_e32 v151, v153
	v_mov_b32_e32 v157, v50
	v_pk_mul_f32 v[150:151], v[170:171], v[150:151]
	ds_bpermute_b32 v152, v149, v51
	v_pk_fma_f32 v[156:157], v[162:163], v[156:157], v[150:151]
	ds_bpermute_b32 v151, v149, v55
	v_pk_mul_f32 v[154:155], v[168:169], v[154:155]
	v_mov_b32_e32 v160, v159
	v_pk_fma_f32 v[154:155], v[164:165], v[166:167], v[154:155]
	v_mul_f32_e32 v153, v148, v144
	s_waitcnt lgkmcnt(1)
	v_mul_f32_e32 v167, v148, v152
	v_mov_b32_e32 v152, v63
	v_mov_b32_e32 v159, v128
	v_mov_b32_e32 v166, v55
	v_mov_b32_e32 v144, v129
	v_cvt_pk_bf16_f32 v164, v154, v155
	v_cvt_pk_bf16_f32 v165, v156, v157
	v_mul_f32_e32 v150, v148, v137
	s_waitcnt lgkmcnt(0)
	v_mul_f32_e32 v162, v148, v151
	v_mad_i64_i32 v[168:169], s[24:25], v134, s15, 0
	v_mov_b32_e32 v151, v59
	v_pk_mul_f32 v[152:153], v[152:153], v[158:159]
	v_mov_b32_e32 v163, v51
	v_pk_mul_f32 v[144:145], v[166:167], v[144:145]
	v_lshl_add_u64 v[170:171], v[168:169], 1, v[138:139]
	v_lshl_add_u64 v[168:169], v[168:169], 2, v[140:141]
	v_pk_fma_f32 v[150:151], v[160:161], v[150:151], v[152:153]
	v_pk_fma_f32 v[152:153], v[130:131], v[162:163], v[144:145]
	v_cvt_pk_bf16_f32 v128, v150, v151
	global_store_dwordx2 v[178:179], v[164:165], off
	global_store_dwordx4 v[172:173], v[154:157], off nt
	v_cvt_pk_bf16_f32 v129, v152, v153
	global_store_dwordx2 v[170:171], v[128:129], off
	global_store_dwordx4 v[168:169], v[150:153], off nt
	v_add_u32_e32 v137, 0x50, v147
	v_lshlrev_b32_e32 v128, 8, v137
	v_and_b32_e32 v134, 0x7fc00, v128
	v_lshl_add_u64 v[154:155], v[142:143], 0, v[134:135]
	global_load_dwordx3 v[158:160], v[154:155], off offset:256
	global_load_dwordx4 v[128:131], v[154:155], off offset:268
	global_load_dword v145, v[154:155], off offset:284
	global_load_dwordx4 v[150:153], v[154:155], off offset:16
	ds_bpermute_b32 v144, v149, v40
	global_load_dwordx4 v[154:157], v[154:155], off
	ds_bpermute_b32 v134, v149, v44
	v_mov_b32_e32 v170, v36
	v_mad_i64_i32 v[172:173], s[24:25], v137, s15, 0
	s_waitcnt lgkmcnt(1)
	v_mul_f32_e32 v169, v148, v144
	ds_bpermute_b32 v144, v149, v41
	ds_bpermute_b32 v137, v149, v45
	v_mov_b32_e32 v168, v44
	s_waitcnt lgkmcnt(2)
	v_mul_f32_e32 v166, v148, v134
	v_mov_b32_e32 v167, v40
	v_add_u32_e32 v134, 0x51, v147
	v_lshl_add_u64 v[178:179], v[172:173], 1, v[138:139]
	v_lshl_add_u64 v[172:173], v[172:173], 2, v[140:141]
	s_waitcnt vmcnt(4)
	v_mov_b32_e32 v161, v160
	s_waitcnt vmcnt(1)
	v_mov_b32_e32 v163, v152
	v_mov_b32_e32 v162, v151
	ds_bpermute_b32 v151, v149, v36
	ds_bpermute_b32 v152, v149, v32
	s_waitcnt vmcnt(0)
	v_mov_b32_e32 v165, v156
	v_mov_b32_e32 v164, v155
	v_mov_b32_e32 v155, v157
	s_waitcnt lgkmcnt(1)
	v_mul_f32_e32 v156, v148, v151
	s_waitcnt lgkmcnt(0)
	v_mul_f32_e32 v171, v148, v152
	v_mov_b32_e32 v151, v153
	v_mov_b32_e32 v157, v32
	v_pk_mul_f32 v[150:151], v[170:171], v[150:151]
	ds_bpermute_b32 v152, v149, v33
	v_pk_fma_f32 v[156:157], v[162:163], v[156:157], v[150:151]
	ds_bpermute_b32 v151, v149, v37
	v_pk_mul_f32 v[154:155], v[168:169], v[154:155]
	v_mov_b32_e32 v160, v159
	v_pk_fma_f32 v[154:155], v[164:165], v[166:167], v[154:155]
	v_mul_f32_e32 v153, v148, v144
	s_waitcnt lgkmcnt(1)
	v_mul_f32_e32 v167, v148, v152
	v_mov_b32_e32 v152, v45
	v_mov_b32_e32 v159, v128
	v_mov_b32_e32 v166, v37
	v_mov_b32_e32 v144, v129
	v_cvt_pk_bf16_f32 v164, v154, v155
	v_cvt_pk_bf16_f32 v165, v156, v157
	v_mul_f32_e32 v150, v148, v137
	s_waitcnt lgkmcnt(0)
	v_mul_f32_e32 v162, v148, v151
	v_mad_i64_i32 v[168:169], s[24:25], v134, s15, 0
	v_mov_b32_e32 v151, v41
	v_pk_mul_f32 v[152:153], v[152:153], v[158:159]
	v_mov_b32_e32 v163, v33
	v_pk_mul_f32 v[144:145], v[166:167], v[144:145]
	v_lshl_add_u64 v[170:171], v[168:169], 1, v[138:139]
	v_lshl_add_u64 v[168:169], v[168:169], 2, v[140:141]
	v_pk_fma_f32 v[150:151], v[160:161], v[150:151], v[152:153]
	v_pk_fma_f32 v[152:153], v[130:131], v[162:163], v[144:145]
	v_cvt_pk_bf16_f32 v128, v150, v151
	global_store_dwordx2 v[178:179], v[164:165], off
	global_store_dwordx4 v[172:173], v[154:157], off nt
	v_cvt_pk_bf16_f32 v129, v152, v153
	global_store_dwordx2 v[170:171], v[128:129], off
	global_store_dwordx4 v[168:169], v[150:153], off nt
	v_add_u32_e32 v137, 0x52, v147
	v_lshlrev_b32_e32 v128, 8, v137
	v_and_b32_e32 v134, 0x7fe00, v128
	v_lshl_add_u64 v[154:155], v[142:143], 0, v[134:135]
	global_load_dwordx3 v[158:160], v[154:155], off offset:256
	global_load_dwordx4 v[128:131], v[154:155], off offset:268
	global_load_dword v145, v[154:155], off offset:284
	global_load_dwordx4 v[150:153], v[154:155], off offset:16
	ds_bpermute_b32 v144, v149, v42
	global_load_dwordx4 v[154:157], v[154:155], off
	ds_bpermute_b32 v134, v149, v46
	v_mov_b32_e32 v170, v38
	v_mad_i64_i32 v[172:173], s[24:25], v137, s15, 0
	s_waitcnt lgkmcnt(1)
	v_mul_f32_e32 v169, v148, v144
	ds_bpermute_b32 v144, v149, v43
	ds_bpermute_b32 v137, v149, v47
	v_mov_b32_e32 v168, v46
	s_waitcnt lgkmcnt(2)
	v_mul_f32_e32 v166, v148, v134
	v_mov_b32_e32 v167, v42
	v_add_u32_e32 v134, 0x53, v147
	v_lshl_add_u64 v[178:179], v[172:173], 1, v[138:139]
	v_lshl_add_u64 v[172:173], v[172:173], 2, v[140:141]
	s_waitcnt vmcnt(4)
	v_mov_b32_e32 v161, v160
	s_waitcnt vmcnt(1)
	v_mov_b32_e32 v163, v152
	v_mov_b32_e32 v162, v151
	ds_bpermute_b32 v151, v149, v38
	ds_bpermute_b32 v152, v149, v34
	s_waitcnt vmcnt(0)
	v_mov_b32_e32 v165, v156
	v_mov_b32_e32 v164, v155
	v_mov_b32_e32 v155, v157
	s_waitcnt lgkmcnt(1)
	v_mul_f32_e32 v156, v148, v151
	s_waitcnt lgkmcnt(0)
	v_mul_f32_e32 v171, v148, v152
	v_mov_b32_e32 v151, v153
	v_mov_b32_e32 v157, v34
	v_pk_mul_f32 v[150:151], v[170:171], v[150:151]
	ds_bpermute_b32 v152, v149, v35
	v_pk_fma_f32 v[156:157], v[162:163], v[156:157], v[150:151]
	ds_bpermute_b32 v151, v149, v39
	v_pk_mul_f32 v[154:155], v[168:169], v[154:155]
	v_mov_b32_e32 v160, v159
	v_pk_fma_f32 v[154:155], v[164:165], v[166:167], v[154:155]
	v_mul_f32_e32 v153, v148, v144
	s_waitcnt lgkmcnt(1)
	v_mul_f32_e32 v167, v148, v152
	v_mov_b32_e32 v152, v47
	v_mov_b32_e32 v159, v128
	v_mov_b32_e32 v166, v39
	v_mov_b32_e32 v144, v129
	v_cvt_pk_bf16_f32 v164, v154, v155
	v_cvt_pk_bf16_f32 v165, v156, v157
	v_mul_f32_e32 v150, v148, v137
	s_waitcnt lgkmcnt(0)
	v_mul_f32_e32 v162, v148, v151
	v_mad_i64_i32 v[168:169], s[24:25], v134, s15, 0
	v_mov_b32_e32 v151, v43
	v_pk_mul_f32 v[152:153], v[152:153], v[158:159]
	v_mov_b32_e32 v163, v35
	v_pk_mul_f32 v[144:145], v[166:167], v[144:145]
	v_lshl_add_u64 v[170:171], v[168:169], 1, v[138:139]
	v_lshl_add_u64 v[168:169], v[168:169], 2, v[140:141]
	v_pk_fma_f32 v[150:151], v[160:161], v[150:151], v[152:153]
	v_pk_fma_f32 v[152:153], v[130:131], v[162:163], v[144:145]
	v_cvt_pk_bf16_f32 v128, v150, v151
	global_store_dwordx2 v[178:179], v[164:165], off
	global_store_dwordx4 v[172:173], v[154:157], off nt
	v_cvt_pk_bf16_f32 v129, v152, v153
	global_store_dwordx2 v[170:171], v[128:129], off
	global_store_dwordx4 v[168:169], v[150:153], off nt
	v_add_u32_e32 v137, 0x60, v147
	v_lshlrev_b32_e32 v128, 8, v137
	v_and_b32_e32 v134, 0x7fc00, v128
	v_lshl_add_u64 v[154:155], v[142:143], 0, v[134:135]
	global_load_dwordx3 v[158:160], v[154:155], off offset:256
	global_load_dwordx4 v[128:131], v[154:155], off offset:268
	global_load_dword v145, v[154:155], off offset:284
	global_load_dwordx4 v[150:153], v[154:155], off offset:16
	ds_bpermute_b32 v144, v149, v24
	global_load_dwordx4 v[154:157], v[154:155], off
	ds_bpermute_b32 v134, v149, v28
	v_mov_b32_e32 v170, v20
	v_mad_i64_i32 v[172:173], s[24:25], v137, s15, 0
	s_waitcnt lgkmcnt(1)
	v_mul_f32_e32 v169, v148, v144
	ds_bpermute_b32 v144, v149, v25
	ds_bpermute_b32 v137, v149, v29
	v_mov_b32_e32 v168, v28
	s_waitcnt lgkmcnt(2)
	v_mul_f32_e32 v166, v148, v134
	v_mov_b32_e32 v167, v24
	v_add_u32_e32 v134, 0x61, v147
	v_lshl_add_u64 v[178:179], v[172:173], 1, v[138:139]
	v_lshl_add_u64 v[172:173], v[172:173], 2, v[140:141]
	s_waitcnt vmcnt(4)
	v_mov_b32_e32 v161, v160
	s_waitcnt vmcnt(1)
	v_mov_b32_e32 v163, v152
	v_mov_b32_e32 v162, v151
	ds_bpermute_b32 v151, v149, v20
	ds_bpermute_b32 v152, v149, v16
	s_waitcnt vmcnt(0)
	v_mov_b32_e32 v165, v156
	v_mov_b32_e32 v164, v155
	v_mov_b32_e32 v155, v157
	s_waitcnt lgkmcnt(1)
	v_mul_f32_e32 v156, v148, v151
	s_waitcnt lgkmcnt(0)
	v_mul_f32_e32 v171, v148, v152
	v_mov_b32_e32 v151, v153
	v_mov_b32_e32 v157, v16
	v_pk_mul_f32 v[150:151], v[170:171], v[150:151]
	ds_bpermute_b32 v152, v149, v17
	v_pk_fma_f32 v[156:157], v[162:163], v[156:157], v[150:151]
	ds_bpermute_b32 v151, v149, v21
	v_pk_mul_f32 v[154:155], v[168:169], v[154:155]
	v_mov_b32_e32 v160, v159
	v_pk_fma_f32 v[154:155], v[164:165], v[166:167], v[154:155]
	v_mul_f32_e32 v153, v148, v144
	s_waitcnt lgkmcnt(1)
	v_mul_f32_e32 v167, v148, v152
	v_mov_b32_e32 v152, v29
	v_mov_b32_e32 v159, v128
	v_mov_b32_e32 v166, v21
	v_mov_b32_e32 v144, v129
	v_cvt_pk_bf16_f32 v164, v154, v155
	v_cvt_pk_bf16_f32 v165, v156, v157
	v_mul_f32_e32 v150, v148, v137
	s_waitcnt lgkmcnt(0)
	v_mul_f32_e32 v162, v148, v151
	v_mad_i64_i32 v[168:169], s[24:25], v134, s15, 0
	v_mov_b32_e32 v151, v25
	v_pk_mul_f32 v[152:153], v[152:153], v[158:159]
	v_mov_b32_e32 v163, v17
	v_pk_mul_f32 v[144:145], v[166:167], v[144:145]
	v_lshl_add_u64 v[170:171], v[168:169], 1, v[138:139]
	v_lshl_add_u64 v[168:169], v[168:169], 2, v[140:141]
	v_pk_fma_f32 v[150:151], v[160:161], v[150:151], v[152:153]
	v_pk_fma_f32 v[152:153], v[130:131], v[162:163], v[144:145]
	v_cvt_pk_bf16_f32 v128, v150, v151
	global_store_dwordx2 v[178:179], v[164:165], off
	global_store_dwordx4 v[172:173], v[154:157], off nt
	v_cvt_pk_bf16_f32 v129, v152, v153
	global_store_dwordx2 v[170:171], v[128:129], off
	global_store_dwordx4 v[168:169], v[150:153], off nt
	v_add_u32_e32 v137, 0x62, v147
	v_lshlrev_b32_e32 v128, 8, v137
	v_and_b32_e32 v134, 0x7fe00, v128
	v_lshl_add_u64 v[154:155], v[142:143], 0, v[134:135]
	global_load_dwordx3 v[158:160], v[154:155], off offset:256
	global_load_dwordx4 v[128:131], v[154:155], off offset:268
	global_load_dword v145, v[154:155], off offset:284
	global_load_dwordx4 v[150:153], v[154:155], off offset:16
	ds_bpermute_b32 v144, v149, v26
	global_load_dwordx4 v[154:157], v[154:155], off
	ds_bpermute_b32 v134, v149, v30
	v_mov_b32_e32 v170, v22
	v_mad_i64_i32 v[172:173], s[24:25], v137, s15, 0
	s_waitcnt lgkmcnt(1)
	v_mul_f32_e32 v169, v148, v144
	ds_bpermute_b32 v144, v149, v27
	ds_bpermute_b32 v137, v149, v31
	v_mov_b32_e32 v168, v30
	s_waitcnt lgkmcnt(2)
	v_mul_f32_e32 v166, v148, v134
	v_mov_b32_e32 v167, v26
	v_add_u32_e32 v134, 0x63, v147
	v_lshl_add_u64 v[178:179], v[172:173], 1, v[138:139]
	v_lshl_add_u64 v[172:173], v[172:173], 2, v[140:141]
	s_waitcnt vmcnt(4)
	v_mov_b32_e32 v161, v160
	s_waitcnt vmcnt(1)
	v_mov_b32_e32 v163, v152
	v_mov_b32_e32 v162, v151
	ds_bpermute_b32 v151, v149, v22
	ds_bpermute_b32 v152, v149, v18
	s_waitcnt vmcnt(0)
	v_mov_b32_e32 v165, v156
	v_mov_b32_e32 v164, v155
	v_mov_b32_e32 v155, v157
	s_waitcnt lgkmcnt(1)
	v_mul_f32_e32 v156, v148, v151
	s_waitcnt lgkmcnt(0)
	v_mul_f32_e32 v171, v148, v152
	v_mov_b32_e32 v151, v153
	v_mov_b32_e32 v157, v18
	v_pk_mul_f32 v[150:151], v[170:171], v[150:151]
	ds_bpermute_b32 v152, v149, v19
	v_pk_fma_f32 v[156:157], v[162:163], v[156:157], v[150:151]
	ds_bpermute_b32 v151, v149, v23
	v_pk_mul_f32 v[154:155], v[168:169], v[154:155]
	v_mov_b32_e32 v160, v159
	v_pk_fma_f32 v[154:155], v[164:165], v[166:167], v[154:155]
	v_mul_f32_e32 v153, v148, v144
	s_waitcnt lgkmcnt(1)
	v_mul_f32_e32 v167, v148, v152
	v_mov_b32_e32 v152, v31
	v_mov_b32_e32 v159, v128
	v_mov_b32_e32 v166, v23
	v_mov_b32_e32 v144, v129
	v_cvt_pk_bf16_f32 v164, v154, v155
	v_cvt_pk_bf16_f32 v165, v156, v157
	v_mul_f32_e32 v150, v148, v137
	s_waitcnt lgkmcnt(0)
	v_mul_f32_e32 v162, v148, v151
	v_mad_i64_i32 v[168:169], s[24:25], v134, s15, 0
	v_mov_b32_e32 v151, v27
	v_pk_mul_f32 v[152:153], v[152:153], v[158:159]
	v_mov_b32_e32 v163, v19
	v_pk_mul_f32 v[144:145], v[166:167], v[144:145]
	v_lshl_add_u64 v[170:171], v[168:169], 1, v[138:139]
	v_lshl_add_u64 v[168:169], v[168:169], 2, v[140:141]
	v_pk_fma_f32 v[150:151], v[160:161], v[150:151], v[152:153]
	v_pk_fma_f32 v[152:153], v[130:131], v[162:163], v[144:145]
	v_cvt_pk_bf16_f32 v128, v150, v151
	global_store_dwordx2 v[178:179], v[164:165], off
	global_store_dwordx4 v[172:173], v[154:157], off nt
	v_cvt_pk_bf16_f32 v129, v152, v153
	global_store_dwordx2 v[170:171], v[128:129], off
	global_store_dwordx4 v[168:169], v[150:153], off nt
	v_add_u32_e32 v137, 0x70, v147
	v_lshlrev_b32_e32 v128, 8, v137
	v_and_b32_e32 v134, 0x7fc00, v128
	v_lshl_add_u64 v[154:155], v[142:143], 0, v[134:135]
	global_load_dwordx3 v[158:160], v[154:155], off offset:256
	global_load_dwordx4 v[128:131], v[154:155], off offset:268
	global_load_dword v145, v[154:155], off offset:284
	global_load_dwordx4 v[150:153], v[154:155], off offset:16
	ds_bpermute_b32 v144, v149, v8
	global_load_dwordx4 v[154:157], v[154:155], off
	ds_bpermute_b32 v134, v149, v12
	v_mov_b32_e32 v170, v4
	v_mad_i64_i32 v[172:173], s[24:25], v137, s15, 0
	s_waitcnt lgkmcnt(1)
	v_mul_f32_e32 v169, v148, v144
	ds_bpermute_b32 v144, v149, v9
	ds_bpermute_b32 v137, v149, v13
	v_mov_b32_e32 v168, v12
	s_waitcnt lgkmcnt(2)
	v_mul_f32_e32 v166, v148, v134
	v_mov_b32_e32 v167, v8
	v_add_u32_e32 v134, 0x71, v147
	v_lshl_add_u64 v[178:179], v[172:173], 1, v[138:139]
	v_lshl_add_u64 v[172:173], v[172:173], 2, v[140:141]
	s_waitcnt vmcnt(4)
	v_mov_b32_e32 v161, v160
	s_waitcnt vmcnt(1)
	v_mov_b32_e32 v163, v152
	v_mov_b32_e32 v162, v151
	ds_bpermute_b32 v151, v149, v4
	ds_bpermute_b32 v152, v149, v0
	s_waitcnt vmcnt(0)
	v_mov_b32_e32 v165, v156
	v_mov_b32_e32 v164, v155
	v_mov_b32_e32 v155, v157
	s_waitcnt lgkmcnt(1)
	v_mul_f32_e32 v156, v148, v151
	s_waitcnt lgkmcnt(0)
	v_mul_f32_e32 v171, v148, v152
	v_mov_b32_e32 v151, v153
	v_mov_b32_e32 v157, v0
	v_pk_mul_f32 v[150:151], v[170:171], v[150:151]
	ds_bpermute_b32 v152, v149, v1
	v_pk_fma_f32 v[156:157], v[162:163], v[156:157], v[150:151]
	ds_bpermute_b32 v151, v149, v5
	v_pk_mul_f32 v[154:155], v[168:169], v[154:155]
	v_mov_b32_e32 v160, v159
	v_pk_fma_f32 v[154:155], v[164:165], v[166:167], v[154:155]
	v_mul_f32_e32 v153, v148, v144
	s_waitcnt lgkmcnt(1)
	v_mul_f32_e32 v167, v148, v152
	v_mov_b32_e32 v152, v13
	v_mov_b32_e32 v159, v128
	v_mov_b32_e32 v166, v5
	v_mov_b32_e32 v144, v129
	v_cvt_pk_bf16_f32 v164, v154, v155
	v_cvt_pk_bf16_f32 v165, v156, v157
	v_mul_f32_e32 v150, v148, v137
	s_waitcnt lgkmcnt(0)
	v_mul_f32_e32 v162, v148, v151
	v_mad_i64_i32 v[168:169], s[24:25], v134, s15, 0
	v_mov_b32_e32 v151, v9
	v_pk_mul_f32 v[152:153], v[152:153], v[158:159]
	v_mov_b32_e32 v163, v1
	v_pk_mul_f32 v[144:145], v[166:167], v[144:145]
	v_lshl_add_u64 v[170:171], v[168:169], 1, v[138:139]
	v_lshl_add_u64 v[168:169], v[168:169], 2, v[140:141]
	v_pk_fma_f32 v[150:151], v[160:161], v[150:151], v[152:153]
	v_pk_fma_f32 v[152:153], v[130:131], v[162:163], v[144:145]
	v_cvt_pk_bf16_f32 v128, v150, v151
	global_store_dwordx2 v[178:179], v[164:165], off
	global_store_dwordx4 v[172:173], v[154:157], off nt
	v_cvt_pk_bf16_f32 v129, v152, v153
	global_store_dwordx2 v[170:171], v[128:129], off
	global_store_dwordx4 v[168:169], v[150:153], off nt
	v_add_u32_e32 v137, 0x72, v147
	v_lshlrev_b32_e32 v128, 8, v137
	v_and_b32_e32 v134, 0x7fe00, v128
	v_lshl_add_u64 v[144:145], v[142:143], 0, v[134:135]
	global_load_dwordx3 v[158:160], v[144:145], off offset:256
	global_load_dwordx4 v[128:131], v[144:145], off offset:268
	global_load_dword v143, v[144:145], off offset:284
	global_load_dwordx4 v[150:153], v[144:145], off offset:16
	global_load_dwordx4 v[154:157], v[144:145], off
	ds_bpermute_b32 v134, v149, v14
	ds_bpermute_b32 v142, v149, v10
	v_mov_b32_e32 v168, v6
	v_mad_i64_i32 v[170:171], s[24:25], v137, s15, 0
	s_waitcnt lgkmcnt(1)
	v_mul_f32_e32 v164, v148, v134
	s_waitcnt lgkmcnt(0)
	v_mul_f32_e32 v167, v148, v142
	v_add_u32_e32 v134, 0x73, v147
	ds_bpermute_b32 v137, v149, v15
	ds_bpermute_b32 v142, v149, v11
	ds_bpermute_b32 v147, v149, v7
	v_mov_b32_e32 v166, v14
	v_mov_b32_e32 v165, v10
	v_lshl_add_u64 v[172:173], v[170:171], 1, v[138:139]
	v_lshl_add_u64 v[170:171], v[170:171], 2, v[140:141]
	s_waitcnt vmcnt(4)
	v_mov_b32_e32 v161, v160
	s_waitcnt vmcnt(1)
	v_mov_b32_e32 v163, v152
	v_mov_b32_e32 v162, v151
	ds_bpermute_b32 v151, v149, v6
	ds_bpermute_b32 v152, v149, v2
	s_waitcnt vmcnt(0)
	v_mov_b32_e32 v145, v156
	v_mov_b32_e32 v144, v155
	v_mov_b32_e32 v155, v157
	s_waitcnt lgkmcnt(1)
	v_mul_f32_e32 v156, v148, v151
	s_waitcnt lgkmcnt(0)
	v_mul_f32_e32 v169, v148, v152
	v_mov_b32_e32 v151, v153
	v_mov_b32_e32 v157, v2
	v_pk_mul_f32 v[150:151], v[168:169], v[150:151]
	v_pk_mul_f32 v[154:155], v[166:167], v[154:155]
	v_pk_fma_f32 v[156:157], v[162:163], v[156:157], v[150:151]
	ds_bpermute_b32 v151, v149, v3
	v_mov_b32_e32 v160, v159
	v_pk_fma_f32 v[154:155], v[144:145], v[164:165], v[154:155]
	v_mul_f32_e32 v150, v148, v137
	v_mul_f32_e32 v149, v148, v142
	v_mul_f32_e32 v152, v148, v147
	s_waitcnt lgkmcnt(0)
	v_mul_f32_e32 v163, v148, v151
	v_mad_i64_i32 v[164:165], s[24:25], v134, s15, 0
	v_mov_b32_e32 v148, v15
	v_mov_b32_e32 v159, v128
	v_mov_b32_e32 v162, v7
	v_mov_b32_e32 v142, v129
	v_cvt_pk_bf16_f32 v144, v154, v155
	v_cvt_pk_bf16_f32 v145, v156, v157
	v_lshl_add_u64 v[166:167], v[164:165], 1, v[138:139]
	v_lshl_add_u64 v[164:165], v[164:165], 2, v[140:141]
	v_mov_b32_e32 v151, v11
	v_pk_mul_f32 v[138:139], v[148:149], v[158:159]
	v_mov_b32_e32 v153, v3
	v_pk_mul_f32 v[140:141], v[162:163], v[142:143]
	v_pk_fma_f32 v[138:139], v[160:161], v[150:151], v[138:139]
	v_pk_fma_f32 v[140:141], v[130:131], v[152:153], v[140:141]
	v_cvt_pk_bf16_f32 v128, v138, v139
	global_store_dwordx2 v[172:173], v[144:145], off
	global_store_dwordx4 v[170:171], v[154:157], off nt
	v_cvt_pk_bf16_f32 v129, v140, v141
	global_store_dwordx2 v[166:167], v[128:129], off
	global_store_dwordx4 v[164:165], v[138:141], off nt

.LBB0_512:
	s_or_b64 exec, exec, s[66:67]
	s_movk_i32 s23, 0x7fd
	v_bitop3_b32 v131, v128, s23, 1 bitop3:0xc8
	v_mad_i64_i32 v[178:179], s[24:25], v166, s13, v[170:171]
	v_cmp_lt_u32_e32 vcc, s19, v131
	v_cvt_pk_bf16_f32 v180, v125, v121
	v_cvt_pk_bf16_f32 v181, v117, v113
	global_store_dwordx2 v[178:179], v[180:181], off
	s_and_saveexec_b64 s[66:67], vcc
	s_cbranch_execz .LBB0_514
	v_lshlrev_b64 v[178:179], 9, v[172:173]
	v_add_u32_e32 v134, 0xfffffa00, v131
	v_lshl_add_u64 v[178:179], v[178:179], 0, v[134:135]
	v_mad_u64_u32 v[182:183], s[24:25], v178, s14, v[168:169]
	v_mad_i32_i24 v183, v179, s14, v183
	v_mov_b32_e32 v178, v125
	v_mov_b32_e32 v179, v121
	v_mov_b32_e32 v180, v117
	v_mov_b32_e32 v181, v113
	global_store_dwordx4 v[182:183], v[178:181], off nt
.LBB0_514:
	s_or_b64 exec, exec, s[66:67]
	s_movk_i32 s23, 0x7fe
	v_bitop3_b32 v131, v128, s23, 2 bitop3:0xc8
	v_mad_i64_i32 v[178:179], s[24:25], v164, s13, v[170:171]
	v_cmp_lt_u32_e32 vcc, s19, v131
	v_cvt_pk_bf16_f32 v180, v126, v122
	v_cvt_pk_bf16_f32 v181, v118, v114
	global_store_dwordx2 v[178:179], v[180:181], off
	s_and_saveexec_b64 s[66:67], vcc
	s_cbranch_execz .LBB0_516
	v_lshlrev_b64 v[178:179], 9, v[172:173]
	v_add_u32_e32 v134, 0xfffffa00, v131
	v_lshl_add_u64 v[178:179], v[178:179], 0, v[134:135]
	v_mad_u64_u32 v[182:183], s[24:25], v178, s14, v[168:169]
	v_mad_i32_i24 v183, v179, s14, v183
	v_mov_b32_e32 v178, v126
	v_mov_b32_e32 v179, v122
	v_mov_b32_e32 v180, v118
	v_mov_b32_e32 v181, v114
	global_store_dwordx4 v[182:183], v[178:181], off nt
.LBB0_516:
	s_or_b64 exec, exec, s[66:67]
	s_movk_i32 s23, 0x7ff
	v_bitop3_b32 v131, v128, s23, 3 bitop3:0xc8
	v_mad_i64_i32 v[178:179], s[24:25], v162, s13, v[170:171]
	v_cmp_lt_u32_e32 vcc, s19, v131
	v_cvt_pk_bf16_f32 v180, v127, v123
	v_cvt_pk_bf16_f32 v181, v119, v115
	global_store_dwordx2 v[178:179], v[180:181], off
	s_and_saveexec_b64 s[66:67], vcc
	s_cbranch_execz .LBB0_518
	v_lshlrev_b64 v[172:173], 9, v[172:173]
	v_add_u32_e32 v134, 0xfffffa00, v131
	v_lshl_add_u64 v[172:173], v[172:173], 0, v[134:135]
	v_mad_u64_u32 v[182:183], s[24:25], v172, s14, v[168:169]
	v_mad_i32_i24 v183, v173, s14, v183
	v_mov_b32_e32 v178, v127
	v_mov_b32_e32 v179, v123
	v_mov_b32_e32 v180, v119
	v_mov_b32_e32 v181, v115
	global_store_dwordx4 v[182:183], v[178:181], off nt
.LBB0_518:
	s_or_b64 exec, exec, s[66:67]
	v_and_b32_e32 v131, 0x7fc, v160
	v_mad_i64_i32 v[172:173], s[24:25], v160, s13, v[170:171]
	v_cmp_lt_u32_e32 vcc, s19, v131
	v_cvt_pk_bf16_f32 v178, v108, v104
	v_cvt_pk_bf16_f32 v179, v100, v96
	global_store_dwordx2 v[172:173], v[178:179], off
	s_and_saveexec_b64 s[66:67], vcc
	s_cbranch_execz .LBB0_520
	v_ashrrev_i32_e32 v172, 11, v160
	v_ashrrev_i32_e32 v173, 31, v172
	v_lshlrev_b64 v[172:173], 9, v[172:173]
	v_add_u32_e32 v134, 0xfffffa00, v131
	v_lshl_add_u64 v[172:173], v[172:173], 0, v[134:135]
	v_mad_u64_u32 v[182:183], s[24:25], v172, s14, v[168:169]
	v_mad_i32_i24 v183, v173, s14, v183
	v_mov_b32_e32 v178, v108
	v_mov_b32_e32 v179, v104
	v_mov_b32_e32 v180, v100
	v_mov_b32_e32 v181, v96
	global_store_dwordx4 v[182:183], v[178:181], off nt
.LBB0_520:
	s_or_b64 exec, exec, s[66:67]
	v_and_b32_e32 v131, 0x7fd, v158
	v_mad_i64_i32 v[172:173], s[24:25], v158, s13, v[170:171]
	v_cmp_lt_u32_e32 vcc, s19, v131
	v_cvt_pk_bf16_f32 v178, v109, v105
	v_cvt_pk_bf16_f32 v179, v101, v97
	global_store_dwordx2 v[172:173], v[178:179], off
	s_and_saveexec_b64 s[66:67], vcc
	s_cbranch_execz .LBB0_522
	v_ashrrev_i32_e32 v172, 11, v158
	v_ashrrev_i32_e32 v173, 31, v172
	v_lshlrev_b64 v[172:173], 9, v[172:173]
	v_add_u32_e32 v134, 0xfffffa00, v131
	v_lshl_add_u64 v[172:173], v[172:173], 0, v[134:135]
	v_mad_u64_u32 v[182:183], s[24:25], v172, s14, v[168:169]
	v_mad_i32_i24 v183, v173, s14, v183
	v_mov_b32_e32 v178, v109
	v_mov_b32_e32 v179, v105
	v_mov_b32_e32 v180, v101
	v_mov_b32_e32 v181, v97
	global_store_dwordx4 v[182:183], v[178:181], off nt
.LBB0_522:
	s_or_b64 exec, exec, s[66:67]
	v_and_b32_e32 v131, 0x7fe, v156
	v_mad_i64_i32 v[172:173], s[24:25], v156, s13, v[170:171]
	v_cmp_lt_u32_e32 vcc, s19, v131
	v_cvt_pk_bf16_f32 v178, v110, v106
	v_cvt_pk_bf16_f32 v179, v102, v98
	global_store_dwordx2 v[172:173], v[178:179], off
	s_and_saveexec_b64 s[66:67], vcc
	s_cbranch_execz .LBB0_524
	v_ashrrev_i32_e32 v172, 11, v156
	v_ashrrev_i32_e32 v173, 31, v172
	v_lshlrev_b64 v[172:173], 9, v[172:173]
	v_add_u32_e32 v134, 0xfffffa00, v131
	v_lshl_add_u64 v[172:173], v[172:173], 0, v[134:135]
	v_mad_u64_u32 v[182:183], s[24:25], v172, s14, v[168:169]
	v_mad_i32_i24 v183, v173, s14, v183
	v_mov_b32_e32 v178, v110
	v_mov_b32_e32 v179, v106
	v_mov_b32_e32 v180, v102
	v_mov_b32_e32 v181, v98
	global_store_dwordx4 v[182:183], v[178:181], off nt
.LBB0_524:
	s_or_b64 exec, exec, s[66:67]
	v_and_b32_e32 v131, 0x7ff, v154
	v_mad_i64_i32 v[172:173], s[24:25], v154, s13, v[170:171]
	v_cmp_lt_u32_e32 vcc, s19, v131
	v_cvt_pk_bf16_f32 v178, v111, v107
	v_cvt_pk_bf16_f32 v179, v103, v99
	global_store_dwordx2 v[172:173], v[178:179], off
	s_and_saveexec_b64 s[66:67], vcc
	s_cbranch_execz .LBB0_526
	v_ashrrev_i32_e32 v172, 11, v154
	v_ashrrev_i32_e32 v173, 31, v172
	v_lshlrev_b64 v[172:173], 9, v[172:173]
	v_add_u32_e32 v134, 0xfffffa00, v131
	v_lshl_add_u64 v[172:173], v[172:173], 0, v[134:135]
	v_mad_u64_u32 v[182:183], s[24:25], v172, s14, v[168:169]
	v_mad_i32_i24 v183, v173, s14, v183
	v_mov_b32_e32 v178, v111
	v_mov_b32_e32 v179, v107
	v_mov_b32_e32 v180, v103
	v_mov_b32_e32 v181, v99
	global_store_dwordx4 v[182:183], v[178:181], off nt
.LBB0_526:
	s_or_b64 exec, exec, s[66:67]
	v_and_b32_e32 v131, 0x7fc, v152
	v_mad_i64_i32 v[172:173], s[24:25], v152, s13, v[170:171]
	v_cmp_lt_u32_e32 vcc, s19, v131
	v_cvt_pk_bf16_f32 v178, v92, v88
	v_cvt_pk_bf16_f32 v179, v84, v80
	global_store_dwordx2 v[172:173], v[178:179], off
	s_and_saveexec_b64 s[66:67], vcc
	s_cbranch_execz .LBB0_528
	v_ashrrev_i32_e32 v172, 11, v152
	v_ashrrev_i32_e32 v173, 31, v172
	v_lshlrev_b64 v[172:173], 9, v[172:173]
	v_add_u32_e32 v134, 0xfffffa00, v131
	v_lshl_add_u64 v[172:173], v[172:173], 0, v[134:135]
	v_mad_u64_u32 v[182:183], s[24:25], v172, s14, v[168:169]
	v_mad_i32_i24 v183, v173, s14, v183
	v_mov_b32_e32 v178, v92
	v_mov_b32_e32 v179, v88
	v_mov_b32_e32 v180, v84
	v_mov_b32_e32 v181, v80
	global_store_dwordx4 v[182:183], v[178:181], off nt
.LBB0_528:
	s_or_b64 exec, exec, s[66:67]
	v_and_b32_e32 v131, 0x7fd, v150
	v_mad_i64_i32 v[172:173], s[24:25], v150, s13, v[170:171]
	v_cmp_lt_u32_e32 vcc, s19, v131
	v_cvt_pk_bf16_f32 v178, v93, v89
	v_cvt_pk_bf16_f32 v179, v85, v81
	global_store_dwordx2 v[172:173], v[178:179], off
	s_and_saveexec_b64 s[66:67], vcc
	s_cbranch_execz .LBB0_530
	v_ashrrev_i32_e32 v172, 11, v150
	v_ashrrev_i32_e32 v173, 31, v172
	v_lshlrev_b64 v[172:173], 9, v[172:173]
	v_add_u32_e32 v134, 0xfffffa00, v131
	v_lshl_add_u64 v[172:173], v[172:173], 0, v[134:135]
	v_mad_u64_u32 v[182:183], s[24:25], v172, s14, v[168:169]
	v_mad_i32_i24 v183, v173, s14, v183
	v_mov_b32_e32 v178, v93
	v_mov_b32_e32 v179, v89
	v_mov_b32_e32 v180, v85
	v_mov_b32_e32 v181, v81
	global_store_dwordx4 v[182:183], v[178:181], off nt
.LBB0_530:
	s_or_b64 exec, exec, s[66:67]
	v_and_b32_e32 v131, 0x7fe, v148
	v_mad_i64_i32 v[172:173], s[24:25], v148, s13, v[170:171]
	v_cmp_lt_u32_e32 vcc, s19, v131
	v_cvt_pk_bf16_f32 v178, v94, v90
	v_cvt_pk_bf16_f32 v179, v86, v82
	global_store_dwordx2 v[172:173], v[178:179], off
	s_and_saveexec_b64 s[66:67], vcc
	s_cbranch_execz .LBB0_532
	v_ashrrev_i32_e32 v172, 11, v148
	v_ashrrev_i32_e32 v173, 31, v172
	v_lshlrev_b64 v[172:173], 9, v[172:173]
	v_add_u32_e32 v134, 0xfffffa00, v131
	v_lshl_add_u64 v[172:173], v[172:173], 0, v[134:135]
	v_mad_u64_u32 v[182:183], s[24:25], v172, s14, v[168:169]
	v_mad_i32_i24 v183, v173, s14, v183
	v_mov_b32_e32 v178, v94
	v_mov_b32_e32 v179, v90
	v_mov_b32_e32 v180, v86
	v_mov_b32_e32 v181, v82
	global_store_dwordx4 v[182:183], v[178:181], off nt
.LBB0_532:
	s_or_b64 exec, exec, s[66:67]
	v_and_b32_e32 v131, 0x7ff, v146
	v_mad_i64_i32 v[172:173], s[24:25], v146, s13, v[170:171]
	v_cmp_lt_u32_e32 vcc, s19, v131
	v_cvt_pk_bf16_f32 v178, v95, v91
	v_cvt_pk_bf16_f32 v179, v87, v83
	global_store_dwordx2 v[172:173], v[178:179], off
	s_and_saveexec_b64 s[66:67], vcc
	s_cbranch_execz .LBB0_534
	v_ashrrev_i32_e32 v172, 11, v146
	v_ashrrev_i32_e32 v173, 31, v172
	v_lshlrev_b64 v[172:173], 9, v[172:173]
	v_add_u32_e32 v134, 0xfffffa00, v131
	v_lshl_add_u64 v[172:173], v[172:173], 0, v[134:135]
	v_mad_u64_u32 v[182:183], s[24:25], v172, s14, v[168:169]
	v_mad_i32_i24 v183, v173, s14, v183
	v_mov_b32_e32 v178, v95
	v_mov_b32_e32 v179, v91
	v_mov_b32_e32 v180, v87
	v_mov_b32_e32 v181, v83
	global_store_dwordx4 v[182:183], v[178:181], off nt
.LBB0_534:
	s_or_b64 exec, exec, s[66:67]
	v_and_b32_e32 v131, 0x7fc, v144
	v_mad_i64_i32 v[172:173], s[24:25], v144, s13, v[170:171]
	v_cmp_lt_u32_e32 vcc, s19, v131
	v_cvt_pk_bf16_f32 v178, v76, v72
	v_cvt_pk_bf16_f32 v179, v68, v64
	global_store_dwordx2 v[172:173], v[178:179], off
	s_and_saveexec_b64 s[66:67], vcc
	s_cbranch_execz .LBB0_536
	v_ashrrev_i32_e32 v172, 11, v144
	v_ashrrev_i32_e32 v173, 31, v172
	v_lshlrev_b64 v[172:173], 9, v[172:173]
	v_add_u32_e32 v134, 0xfffffa00, v131
	v_lshl_add_u64 v[172:173], v[172:173], 0, v[134:135]
	v_mad_u64_u32 v[182:183], s[24:25], v172, s14, v[168:169]
	v_mad_i32_i24 v183, v173, s14, v183
	v_mov_b32_e32 v178, v76
	v_mov_b32_e32 v179, v72
	v_mov_b32_e32 v180, v68
	v_mov_b32_e32 v181, v64
	global_store_dwordx4 v[182:183], v[178:181], off nt
.LBB0_536:
	s_or_b64 exec, exec, s[66:67]
	v_and_b32_e32 v131, 0x7fd, v142
	v_mad_i64_i32 v[172:173], s[24:25], v142, s13, v[170:171]
	v_cmp_lt_u32_e32 vcc, s19, v131
	v_cvt_pk_bf16_f32 v178, v77, v73
	v_cvt_pk_bf16_f32 v179, v69, v65
	global_store_dwordx2 v[172:173], v[178:179], off
	s_and_saveexec_b64 s[66:67], vcc
	s_cbranch_execz .LBB0_538
	v_ashrrev_i32_e32 v172, 11, v142
	v_ashrrev_i32_e32 v173, 31, v172
	v_lshlrev_b64 v[172:173], 9, v[172:173]
	v_add_u32_e32 v134, 0xfffffa00, v131
	v_lshl_add_u64 v[172:173], v[172:173], 0, v[134:135]
	v_mad_u64_u32 v[182:183], s[24:25], v172, s14, v[168:169]
	v_mad_i32_i24 v183, v173, s14, v183
	v_mov_b32_e32 v178, v77
	v_mov_b32_e32 v179, v73
	v_mov_b32_e32 v180, v69
	v_mov_b32_e32 v181, v65
	global_store_dwordx4 v[182:183], v[178:181], off nt
.LBB0_538:
	s_or_b64 exec, exec, s[66:67]
	v_and_b32_e32 v131, 0x7fe, v140
	v_mad_i64_i32 v[172:173], s[24:25], v140, s13, v[170:171]
	v_cmp_lt_u32_e32 vcc, s19, v131
	v_cvt_pk_bf16_f32 v178, v78, v74
	v_cvt_pk_bf16_f32 v179, v70, v66
	global_store_dwordx2 v[172:173], v[178:179], off
	s_and_saveexec_b64 s[66:67], vcc
	s_cbranch_execz .LBB0_540
	v_ashrrev_i32_e32 v172, 11, v140
	v_ashrrev_i32_e32 v173, 31, v172
	v_lshlrev_b64 v[172:173], 9, v[172:173]
	v_add_u32_e32 v134, 0xfffffa00, v131
	v_lshl_add_u64 v[172:173], v[172:173], 0, v[134:135]
	v_mad_u64_u32 v[182:183], s[24:25], v172, s14, v[168:169]
	v_mad_i32_i24 v183, v173, s14, v183
	v_mov_b32_e32 v178, v78
	v_mov_b32_e32 v179, v74
	v_mov_b32_e32 v180, v70
	v_mov_b32_e32 v181, v66
	global_store_dwordx4 v[182:183], v[178:181], off nt
.LBB0_540:
	s_or_b64 exec, exec, s[66:67]
	v_and_b32_e32 v131, 0x7ff, v138
	v_mad_i64_i32 v[172:173], s[24:25], v138, s13, v[170:171]
	v_cmp_lt_u32_e32 vcc, s19, v131
	v_cvt_pk_bf16_f32 v178, v79, v75
	v_cvt_pk_bf16_f32 v179, v71, v67
	global_store_dwordx2 v[172:173], v[178:179], off
	s_and_saveexec_b64 s[66:67], vcc
	s_cbranch_execz .LBB0_542
	v_ashrrev_i32_e32 v172, 11, v138
	v_ashrrev_i32_e32 v173, 31, v172
	v_lshlrev_b64 v[172:173], 9, v[172:173]
	v_add_u32_e32 v134, 0xfffffa00, v131
	v_lshl_add_u64 v[172:173], v[172:173], 0, v[134:135]
	v_mad_u64_u32 v[182:183], s[24:25], v172, s14, v[168:169]
	v_mad_i32_i24 v183, v173, s14, v183
	v_mov_b32_e32 v178, v79
	v_mov_b32_e32 v179, v75
	v_mov_b32_e32 v180, v71
	v_mov_b32_e32 v181, v67
	global_store_dwordx4 v[182:183], v[178:181], off nt
.LBB0_542:
	s_or_b64 exec, exec, s[66:67]
	v_and_b32_e32 v131, 0x7fc, v130
	v_mad_i64_i32 v[172:173], s[24:25], v130, s13, v[170:171]
	v_cmp_lt_u32_e32 vcc, s19, v131
	v_cvt_pk_bf16_f32 v178, v60, v56
	v_cvt_pk_bf16_f32 v179, v52, v48
	global_store_dwordx2 v[172:173], v[178:179], off
	s_and_saveexec_b64 s[66:67], vcc
	s_cbranch_execz .LBB0_544
	v_ashrrev_i32_e32 v172, 11, v130
	v_ashrrev_i32_e32 v173, 31, v172
	v_lshlrev_b64 v[172:173], 9, v[172:173]
	v_add_u32_e32 v134, 0xfffffa00, v131
	v_lshl_add_u64 v[172:173], v[172:173], 0, v[134:135]
	v_mad_u64_u32 v[182:183], s[24:25], v172, s14, v[168:169]
	v_mad_i32_i24 v183, v173, s14, v183
	v_mov_b32_e32 v178, v60
	v_mov_b32_e32 v179, v56
	v_mov_b32_e32 v180, v52
	v_mov_b32_e32 v181, v48
	global_store_dwordx4 v[182:183], v[178:181], off nt
.LBB0_544:
	s_or_b64 exec, exec, s[66:67]
	v_add_u32_e32 v134, 0x41, v128
	v_and_b32_e32 v131, 0x7fd, v134
	v_mad_i64_i32 v[172:173], s[24:25], v134, s13, v[170:171]
	v_cmp_lt_u32_e32 vcc, s19, v131
	v_cvt_pk_bf16_f32 v178, v61, v57
	v_cvt_pk_bf16_f32 v179, v53, v49
	global_store_dwordx2 v[172:173], v[178:179], off
	s_and_saveexec_b64 s[66:67], vcc
	s_cbranch_execz .LBB0_546
	v_ashrrev_i32_e32 v172, 11, v134
	v_ashrrev_i32_e32 v173, 31, v172
	v_lshlrev_b64 v[172:173], 9, v[172:173]
	v_add_u32_e32 v134, 0xfffffa00, v131
	v_lshl_add_u64 v[172:173], v[172:173], 0, v[134:135]
	v_mad_u64_u32 v[182:183], s[24:25], v172, s14, v[168:169]
	v_mad_i32_i24 v183, v173, s14, v183
	v_mov_b32_e32 v178, v61
	v_mov_b32_e32 v179, v57
	v_mov_b32_e32 v180, v53
	v_mov_b32_e32 v181, v49
	global_store_dwordx4 v[182:183], v[178:181], off nt
.LBB0_546:
	s_or_b64 exec, exec, s[66:67]
	v_add_u32_e32 v134, 0x42, v128
	v_and_b32_e32 v131, 0x7fe, v134
	v_mad_i64_i32 v[172:173], s[24:25], v134, s13, v[170:171]
	v_cmp_lt_u32_e32 vcc, s19, v131
	v_cvt_pk_bf16_f32 v178, v62, v58
	v_cvt_pk_bf16_f32 v179, v54, v50
	global_store_dwordx2 v[172:173], v[178:179], off
	s_and_saveexec_b64 s[66:67], vcc
	s_cbranch_execz .LBB0_548
	v_ashrrev_i32_e32 v172, 11, v134
	v_ashrrev_i32_e32 v173, 31, v172
	v_lshlrev_b64 v[172:173], 9, v[172:173]
	v_add_u32_e32 v134, 0xfffffa00, v131
	v_lshl_add_u64 v[172:173], v[172:173], 0, v[134:135]
	v_mad_u64_u32 v[182:183], s[24:25], v172, s14, v[168:169]
	v_mad_i32_i24 v183, v173, s14, v183
	v_mov_b32_e32 v178, v62
	v_mov_b32_e32 v179, v58
	v_mov_b32_e32 v180, v54
	v_mov_b32_e32 v181, v50
	global_store_dwordx4 v[182:183], v[178:181], off nt
.LBB0_548:
	s_or_b64 exec, exec, s[66:67]
	v_add_u32_e32 v134, 0x43, v128
	v_and_b32_e32 v131, 0x7ff, v134
	v_mad_i64_i32 v[172:173], s[24:25], v134, s13, v[170:171]
	v_cmp_lt_u32_e32 vcc, s19, v131
	v_cvt_pk_bf16_f32 v178, v63, v59
	v_cvt_pk_bf16_f32 v179, v55, v51
	global_store_dwordx2 v[172:173], v[178:179], off
	s_and_saveexec_b64 s[66:67], vcc
	s_cbranch_execz .LBB0_550
	v_ashrrev_i32_e32 v172, 11, v134
	v_ashrrev_i32_e32 v173, 31, v172
	v_lshlrev_b64 v[172:173], 9, v[172:173]
	v_add_u32_e32 v134, 0xfffffa00, v131
	v_lshl_add_u64 v[172:173], v[172:173], 0, v[134:135]
	v_mad_u64_u32 v[182:183], s[24:25], v172, s14, v[168:169]
	v_mad_i32_i24 v183, v173, s14, v183
	v_mov_b32_e32 v178, v63
	v_mov_b32_e32 v179, v59
	v_mov_b32_e32 v180, v55
	v_mov_b32_e32 v181, v51
	global_store_dwordx4 v[182:183], v[178:181], off nt
.LBB0_550:
	s_or_b64 exec, exec, s[66:67]
	v_add_u32_e32 v134, 0x50, v128
	v_and_b32_e32 v131, 0x7fc, v134
	v_mad_i64_i32 v[172:173], s[24:25], v134, s13, v[170:171]
	v_cmp_lt_u32_e32 vcc, s19, v131
	v_cvt_pk_bf16_f32 v178, v44, v40
	v_cvt_pk_bf16_f32 v179, v36, v32
	global_store_dwordx2 v[172:173], v[178:179], off
	s_and_saveexec_b64 s[66:67], vcc
	s_cbranch_execz .LBB0_552
	v_ashrrev_i32_e32 v172, 11, v134
	v_ashrrev_i32_e32 v173, 31, v172
	v_lshlrev_b64 v[172:173], 9, v[172:173]
	v_add_u32_e32 v134, 0xfffffa00, v131
	v_lshl_add_u64 v[172:173], v[172:173], 0, v[134:135]
	v_mad_u64_u32 v[182:183], s[24:25], v172, s14, v[168:169]
	v_mad_i32_i24 v183, v173, s14, v183
	v_mov_b32_e32 v178, v44
	v_mov_b32_e32 v179, v40
	v_mov_b32_e32 v180, v36
	v_mov_b32_e32 v181, v32
	global_store_dwordx4 v[182:183], v[178:181], off nt
.LBB0_552:
	s_or_b64 exec, exec, s[66:67]
	v_add_u32_e32 v134, 0x51, v128
	v_and_b32_e32 v131, 0x7fd, v134
	v_mad_i64_i32 v[172:173], s[24:25], v134, s13, v[170:171]
	v_cmp_lt_u32_e32 vcc, s19, v131
	v_cvt_pk_bf16_f32 v178, v45, v41
	v_cvt_pk_bf16_f32 v179, v37, v33
	global_store_dwordx2 v[172:173], v[178:179], off
	s_and_saveexec_b64 s[66:67], vcc
	s_cbranch_execz .LBB0_554
	v_ashrrev_i32_e32 v172, 11, v134
	v_ashrrev_i32_e32 v173, 31, v172
	v_lshlrev_b64 v[172:173], 9, v[172:173]
	v_add_u32_e32 v134, 0xfffffa00, v131
	v_lshl_add_u64 v[172:173], v[172:173], 0, v[134:135]
	v_mad_u64_u32 v[182:183], s[24:25], v172, s14, v[168:169]
	v_mad_i32_i24 v183, v173, s14, v183
	v_mov_b32_e32 v178, v45
	v_mov_b32_e32 v179, v41
	v_mov_b32_e32 v180, v37
	v_mov_b32_e32 v181, v33
	global_store_dwordx4 v[182:183], v[178:181], off nt
.LBB0_554:
	s_or_b64 exec, exec, s[66:67]
	v_add_u32_e32 v134, 0x52, v128
	v_and_b32_e32 v131, 0x7fe, v134
	v_mad_i64_i32 v[172:173], s[24:25], v134, s13, v[170:171]
	v_cmp_lt_u32_e32 vcc, s19, v131
	v_cvt_pk_bf16_f32 v178, v46, v42
	v_cvt_pk_bf16_f32 v179, v38, v34
	global_store_dwordx2 v[172:173], v[178:179], off
	s_and_saveexec_b64 s[66:67], vcc
	s_cbranch_execz .LBB0_556
	v_ashrrev_i32_e32 v172, 11, v134
	v_ashrrev_i32_e32 v173, 31, v172
	v_lshlrev_b64 v[172:173], 9, v[172:173]
	v_add_u32_e32 v134, 0xfffffa00, v131
	v_lshl_add_u64 v[172:173], v[172:173], 0, v[134:135]
	v_mad_u64_u32 v[182:183], s[24:25], v172, s14, v[168:169]
	v_mad_i32_i24 v183, v173, s14, v183
	v_mov_b32_e32 v178, v46
	v_mov_b32_e32 v179, v42
	v_mov_b32_e32 v180, v38
	v_mov_b32_e32 v181, v34
	global_store_dwordx4 v[182:183], v[178:181], off nt
.LBB0_556:
	s_or_b64 exec, exec, s[66:67]
	v_add_u32_e32 v134, 0x53, v128
	v_and_b32_e32 v131, 0x7ff, v134
	v_mad_i64_i32 v[172:173], s[24:25], v134, s13, v[170:171]
	v_cmp_lt_u32_e32 vcc, s19, v131
	v_cvt_pk_bf16_f32 v178, v47, v43
	v_cvt_pk_bf16_f32 v179, v39, v35
	global_store_dwordx2 v[172:173], v[178:179], off
	s_and_saveexec_b64 s[66:67], vcc
	s_cbranch_execz .LBB0_558
	v_ashrrev_i32_e32 v172, 11, v134
	v_ashrrev_i32_e32 v173, 31, v172
	v_lshlrev_b64 v[172:173], 9, v[172:173]
	v_add_u32_e32 v134, 0xfffffa00, v131
	v_lshl_add_u64 v[172:173], v[172:173], 0, v[134:135]
	v_mad_u64_u32 v[182:183], s[24:25], v172, s14, v[168:169]
	v_mad_i32_i24 v183, v173, s14, v183
	v_mov_b32_e32 v178, v47
	v_mov_b32_e32 v179, v43
	v_mov_b32_e32 v180, v39
	v_mov_b32_e32 v181, v35
	global_store_dwordx4 v[182:183], v[178:181], off nt
.LBB0_558:
	s_or_b64 exec, exec, s[66:67]
	v_add_u32_e32 v134, 0x60, v128
	v_and_b32_e32 v131, 0x7fc, v134
	v_mad_i64_i32 v[172:173], s[24:25], v134, s13, v[170:171]
	v_cmp_lt_u32_e32 vcc, s19, v131
	v_cvt_pk_bf16_f32 v178, v28, v24
	v_cvt_pk_bf16_f32 v179, v20, v16
	global_store_dwordx2 v[172:173], v[178:179], off
	s_and_saveexec_b64 s[66:67], vcc
	s_cbranch_execz .LBB0_560
	v_ashrrev_i32_e32 v172, 11, v134
	v_ashrrev_i32_e32 v173, 31, v172
	v_lshlrev_b64 v[172:173], 9, v[172:173]
	v_add_u32_e32 v134, 0xfffffa00, v131
	v_lshl_add_u64 v[172:173], v[172:173], 0, v[134:135]
	v_mad_u64_u32 v[182:183], s[24:25], v172, s14, v[168:169]
	v_mad_i32_i24 v183, v173, s14, v183
	v_mov_b32_e32 v178, v28
	v_mov_b32_e32 v179, v24
	v_mov_b32_e32 v180, v20
	v_mov_b32_e32 v181, v16
	global_store_dwordx4 v[182:183], v[178:181], off nt
.LBB0_560:
	s_or_b64 exec, exec, s[66:67]
	v_add_u32_e32 v134, 0x61, v128
	v_and_b32_e32 v131, 0x7fd, v134
	v_mad_i64_i32 v[172:173], s[24:25], v134, s13, v[170:171]
	v_cmp_lt_u32_e32 vcc, s19, v131
	v_cvt_pk_bf16_f32 v178, v29, v25
	v_cvt_pk_bf16_f32 v179, v21, v17
	global_store_dwordx2 v[172:173], v[178:179], off
	s_and_saveexec_b64 s[66:67], vcc
	s_cbranch_execz .LBB0_562
	v_ashrrev_i32_e32 v172, 11, v134
	v_ashrrev_i32_e32 v173, 31, v172
	v_lshlrev_b64 v[172:173], 9, v[172:173]
	v_add_u32_e32 v134, 0xfffffa00, v131
	v_lshl_add_u64 v[172:173], v[172:173], 0, v[134:135]
	v_mad_u64_u32 v[182:183], s[24:25], v172, s14, v[168:169]
	v_mad_i32_i24 v183, v173, s14, v183
	v_mov_b32_e32 v178, v29
	v_mov_b32_e32 v179, v25
	v_mov_b32_e32 v180, v21
	v_mov_b32_e32 v181, v17
	global_store_dwordx4 v[182:183], v[178:181], off nt
.LBB0_562:
	s_or_b64 exec, exec, s[66:67]
	v_add_u32_e32 v134, 0x62, v128
	v_and_b32_e32 v131, 0x7fe, v134
	v_mad_i64_i32 v[172:173], s[24:25], v134, s13, v[170:171]
	v_cmp_lt_u32_e32 vcc, s19, v131
	v_cvt_pk_bf16_f32 v178, v30, v26
	v_cvt_pk_bf16_f32 v179, v22, v18
	global_store_dwordx2 v[172:173], v[178:179], off
	s_and_saveexec_b64 s[66:67], vcc
	s_cbranch_execz .LBB0_564
	v_ashrrev_i32_e32 v172, 11, v134
	v_ashrrev_i32_e32 v173, 31, v172
	v_lshlrev_b64 v[172:173], 9, v[172:173]
	v_add_u32_e32 v134, 0xfffffa00, v131
	v_lshl_add_u64 v[172:173], v[172:173], 0, v[134:135]
	v_mad_u64_u32 v[182:183], s[24:25], v172, s14, v[168:169]
	v_mad_i32_i24 v183, v173, s14, v183
	v_mov_b32_e32 v178, v30
	v_mov_b32_e32 v179, v26
	v_mov_b32_e32 v180, v22
	v_mov_b32_e32 v181, v18
	global_store_dwordx4 v[182:183], v[178:181], off nt
.LBB0_564:
	s_or_b64 exec, exec, s[66:67]
	v_add_u32_e32 v134, 0x63, v128
	v_and_b32_e32 v131, 0x7ff, v134
	v_mad_i64_i32 v[172:173], s[24:25], v134, s13, v[170:171]
	v_cmp_lt_u32_e32 vcc, s19, v131
	v_cvt_pk_bf16_f32 v178, v31, v27
	v_cvt_pk_bf16_f32 v179, v23, v19
	global_store_dwordx2 v[172:173], v[178:179], off
	s_and_saveexec_b64 s[66:67], vcc
	s_cbranch_execz .LBB0_566
	v_ashrrev_i32_e32 v172, 11, v134
	v_ashrrev_i32_e32 v173, 31, v172
	v_lshlrev_b64 v[172:173], 9, v[172:173]
	v_add_u32_e32 v134, 0xfffffa00, v131
	v_lshl_add_u64 v[172:173], v[172:173], 0, v[134:135]
	v_mad_u64_u32 v[182:183], s[24:25], v172, s14, v[168:169]
	v_mad_i32_i24 v183, v173, s14, v183
	v_mov_b32_e32 v178, v31
	v_mov_b32_e32 v179, v27
	v_mov_b32_e32 v180, v23
	v_mov_b32_e32 v181, v19
	global_store_dwordx4 v[182:183], v[178:181], off nt
.LBB0_566:
	s_or_b64 exec, exec, s[66:67]
	v_add_u32_e32 v134, 0x70, v128
	v_and_b32_e32 v131, 0x7fc, v134
	v_mad_i64_i32 v[172:173], s[24:25], v134, s13, v[170:171]
	v_cmp_lt_u32_e32 vcc, s19, v131
	v_cvt_pk_bf16_f32 v178, v12, v8
	v_cvt_pk_bf16_f32 v179, v4, v0
	global_store_dwordx2 v[172:173], v[178:179], off
	s_and_saveexec_b64 s[66:67], vcc
	s_cbranch_execz .LBB0_568
	v_ashrrev_i32_e32 v172, 11, v134
	v_ashrrev_i32_e32 v173, 31, v172
	v_lshlrev_b64 v[172:173], 9, v[172:173]
	v_add_u32_e32 v134, 0xfffffa00, v131
	v_lshl_add_u64 v[172:173], v[172:173], 0, v[134:135]
	v_mad_u64_u32 v[182:183], s[24:25], v172, s14, v[168:169]
	v_mad_i32_i24 v183, v173, s14, v183
	v_mov_b32_e32 v178, v12
	v_mov_b32_e32 v179, v8
	v_mov_b32_e32 v180, v4
	v_mov_b32_e32 v181, v0
	global_store_dwordx4 v[182:183], v[178:181], off nt
.LBB0_568:
	s_or_b64 exec, exec, s[66:67]
	v_add_u32_e32 v134, 0x71, v128
	v_and_b32_e32 v131, 0x7fd, v134
	v_mad_i64_i32 v[172:173], s[24:25], v134, s13, v[170:171]
	v_cmp_lt_u32_e32 vcc, s19, v131
	v_cvt_pk_bf16_f32 v178, v13, v9
	v_cvt_pk_bf16_f32 v179, v5, v1
	global_store_dwordx2 v[172:173], v[178:179], off
	s_and_saveexec_b64 s[66:67], vcc
	s_cbranch_execz .LBB0_570
	v_ashrrev_i32_e32 v172, 11, v134
	v_ashrrev_i32_e32 v173, 31, v172
	v_lshlrev_b64 v[172:173], 9, v[172:173]
	v_add_u32_e32 v134, 0xfffffa00, v131
	v_lshl_add_u64 v[172:173], v[172:173], 0, v[134:135]
	v_mad_u64_u32 v[182:183], s[24:25], v172, s14, v[168:169]
	v_mad_i32_i24 v183, v173, s14, v183
	v_mov_b32_e32 v178, v13
	v_mov_b32_e32 v179, v9
	v_mov_b32_e32 v180, v5
	v_mov_b32_e32 v181, v1
	global_store_dwordx4 v[182:183], v[178:181], off nt
.LBB0_570:
	s_or_b64 exec, exec, s[66:67]
	v_add_u32_e32 v134, 0x72, v128
	v_and_b32_e32 v131, 0x7fe, v134
	v_mad_i64_i32 v[172:173], s[24:25], v134, s13, v[170:171]
	v_cmp_lt_u32_e32 vcc, s19, v131
	v_cvt_pk_bf16_f32 v178, v14, v10
	v_cvt_pk_bf16_f32 v179, v6, v2
	global_store_dwordx2 v[172:173], v[178:179], off
	s_and_saveexec_b64 s[66:67], vcc
	s_cbranch_execz .LBB0_572
	v_ashrrev_i32_e32 v172, 11, v134
	v_ashrrev_i32_e32 v173, 31, v172
	v_lshlrev_b64 v[172:173], 9, v[172:173]
	v_add_u32_e32 v134, 0xfffffa00, v131
	v_lshl_add_u64 v[172:173], v[172:173], 0, v[134:135]
	v_mad_u64_u32 v[182:183], s[24:25], v172, s14, v[168:169]
	v_mad_i32_i24 v183, v173, s14, v183
	v_mov_b32_e32 v178, v14
	v_mov_b32_e32 v179, v10
	v_mov_b32_e32 v180, v6
	v_mov_b32_e32 v181, v2
	global_store_dwordx4 v[182:183], v[178:181], off nt
.LBB0_572:
	s_or_b64 exec, exec, s[66:67]
	v_add_u32_e32 v134, 0x73, v128
	v_and_b32_e32 v131, 0x7ff, v134
	v_mad_i64_i32 v[170:171], s[24:25], v134, s13, v[170:171]
	v_cmp_lt_u32_e32 vcc, s19, v131
	v_cvt_pk_bf16_f32 v172, v15, v11
	v_cvt_pk_bf16_f32 v173, v7, v3
	global_store_dwordx2 v[170:171], v[172:173], off
	s_and_saveexec_b64 s[66:67], vcc
	s_cbranch_execz .LBB0_574
	v_ashrrev_i32_e32 v170, 11, v134
	v_ashrrev_i32_e32 v171, 31, v170
	v_lshlrev_b64 v[170:171], 9, v[170:171]
	v_add_u32_e32 v134, 0xfffffa00, v131
	v_lshl_add_u64 v[170:171], v[170:171], 0, v[134:135]
	v_mad_u64_u32 v[172:173], s[24:25], v170, s14, v[168:169]
	v_mad_i32_i24 v173, v171, s14, v173
	v_mov_b32_e32 v168, v15
	v_mov_b32_e32 v169, v11
	v_mov_b32_e32 v170, v7
	v_mov_b32_e32 v171, v3
	global_store_dwordx4 v[172:173], v[168:171], off nt

.LBB0_580:
	s_or_saveexec_b64 s[72:73], s[72:73]
	v_readlane_b32 s36, v253, 44
	v_lshlrev_b32_e32 v172, 1, v174
	v_mov_b32_e32 v173, v135
	v_readlane_b32 s48, v253, 56
	v_readlane_b32 s49, v253, 57
	v_cndmask_b32_e64 v170, 1.0, -1.0, s[0:1]
	v_lshl_add_u64 v[174:175], s[76:77], 0, v[134:135]
	v_lshl_add_u64 v[172:173], s[48:49], 0, v[172:173]
	v_readlane_b32 s37, v253, 45
	v_readlane_b32 s38, v253, 46
	v_readlane_b32 s39, v253, 47
	v_readlane_b32 s40, v253, 48
	v_readlane_b32 s41, v253, 49
	v_readlane_b32 s42, v253, 50
	v_readlane_b32 s43, v253, 51
	v_readlane_b32 s44, v253, 52
	v_readlane_b32 s45, v253, 53
	v_readlane_b32 s46, v253, 54
	v_readlane_b32 s47, v253, 55
	v_readlane_b32 s50, v253, 58
	v_readlane_b32 s51, v253, 59
	s_xor_b64 exec, exec, s[72:73]
	s_cbranch_execz .LBB0_582
	v_mov_b32_e32 v189, v135
	v_lshl_add_u64 v[188:189], s[58:59], 0, v[188:189]
	global_load_dwordx2 v[194:195], v[188:189], off offset:16
	global_load_dwordx2 v[196:197], v[188:189], off
	v_mov_b32_e32 v198, v124
	v_mov_b32_e32 v199, v120
	s_waitcnt lgkmcnt(2)
	v_pk_mul_f32 v[186:187], v[170:171], v[186:187] op_sel_hi:[0,1]
	v_lshlrev_b64 v[190:191], 6, v[128:129]
	s_waitcnt lgkmcnt(0)
	v_pk_mul_f32 v[184:185], v[170:171], v[184:185] op_sel_hi:[0,1]
	v_lshl_add_u64 v[190:191], v[172:173], 0, v[190:191]
	v_lshlrev_b64 v[192:193], 7, v[128:129]
	v_lshl_add_u64 v[192:193], v[174:175], 0, v[192:193]
	s_waitcnt vmcnt(1)
	v_mov_b32_e32 v201, v194
	s_waitcnt vmcnt(0)
	v_mov_b32_e32 v200, v196
	v_mov_b32_e32 v194, v197
	global_load_dwordx2 v[196:197], v[188:189], off offset:48
	s_nop 0
	global_load_dwordx2 v[188:189], v[188:189], off offset:32
	v_pk_mul_f32 v[198:199], v[198:199], v[200:201]
	s_waitcnt vmcnt(1)
	v_mov_b32_e32 v201, v196
	v_pk_fma_f32 v[186:187], v[186:187], v[194:195], v[198:199]
	v_mov_b32_e32 v198, v116
	v_mov_b32_e32 v199, v112
	s_waitcnt vmcnt(0)
	v_mov_b32_e32 v200, v188
	v_pk_mul_f32 v[198:199], v[198:199], v[200:201]
	v_mov_b32_e32 v196, v189
	v_cvt_pk_bf16_f32 v194, v186, v187
	v_pk_fma_f32 v[188:189], v[184:185], v[196:197], v[198:199]
	s_nop 0
	v_cvt_pk_bf16_f32 v195, v188, v189
	global_store_dwordx2 v[190:191], v[194:195], off
	global_store_dwordx4 v[192:193], v[186:189], off nt

.LBB0_586:
	s_andn2_saveexec_b64 s[0:1], s[0:1]
	s_cbranch_execz .LBB0_588
	s_waitcnt vmcnt(0)
	v_mov_b32_e32 v193, v176
	v_mov_b32_e32 v196, v182
	v_mov_b32_e32 v197, v180
	s_waitcnt lgkmcnt(2)
	v_pk_mul_f32 v[186:187], v[170:171], v[186:187] op_sel_hi:[0,1]
	v_mov_b32_e32 v180, v183
	s_waitcnt lgkmcnt(0)
	v_pk_mul_f32 v[182:183], v[170:171], v[184:185] op_sel_hi:[0,1]
	v_mov_b32_e32 v176, v179
	v_mov_b32_e32 v190, v117
	v_mov_b32_e32 v191, v113
	v_mov_b32_e32 v192, v178
	v_mov_b32_e32 v194, v125
	v_mov_b32_e32 v195, v121
	v_lshlrev_b64 v[198:199], 6, v[188:189]
	v_pk_mul_f32 v[180:181], v[180:181], v[186:187]
	v_pk_mul_f32 v[176:177], v[176:177], v[182:183]
	v_lshl_add_u64 v[198:199], v[172:173], 0, v[198:199]
	v_lshlrev_b64 v[188:189], 7, v[188:189]
	v_pk_fma_f32 v[180:181], v[194:195], v[196:197], v[180:181]
	v_pk_fma_f32 v[182:183], v[190:191], v[192:193], v[176:177]
	v_cvt_pk_bf16_f32 v178, v180, v181
	v_lshl_add_u64 v[188:189], v[174:175], 0, v[188:189]
	v_cvt_pk_bf16_f32 v179, v182, v183
	global_store_dwordx2 v[198:199], v[178:179], off
	global_store_dwordx4 v[188:189], v[180:183], off nt

.LBB0_592:
	s_andn2_saveexec_b64 s[0:1], s[0:1]
	s_cbranch_execz .LBB0_594
	v_lshl_add_u64 v[190:191], s[58:59], 0, v[134:135]
	v_lshlrev_b64 v[192:193], 6, v[186:187]
	v_lshlrev_b64 v[186:187], 7, v[186:187]
	v_lshl_add_u64 v[194:195], v[174:175], 0, v[186:187]
	global_load_dwordx2 v[186:187], v[190:191], off offset:16
	global_load_dwordx2 v[196:197], v[190:191], off
	v_mov_b32_e32 v198, v126
	v_mov_b32_e32 v199, v122
	s_waitcnt lgkmcnt(2)
	v_pk_mul_f32 v[188:189], v[170:171], v[188:189] op_sel_hi:[0,1]
	s_waitcnt lgkmcnt(0)
	v_pk_mul_f32 v[184:185], v[170:171], v[184:185] op_sel_hi:[0,1]
	v_lshl_add_u64 v[192:193], v[172:173], 0, v[192:193]
	s_waitcnt vmcnt(1)
	v_mov_b32_e32 v201, v186
	s_waitcnt vmcnt(0)
	v_mov_b32_e32 v200, v196
	v_pk_mul_f32 v[198:199], v[198:199], v[200:201]
	v_mov_b32_e32 v186, v197
	v_pk_fma_f32 v[186:187], v[188:189], v[186:187], v[198:199]
	global_load_dwordx2 v[188:189], v[190:191], off offset:48
	s_nop 0
	global_load_dwordx2 v[190:191], v[190:191], off offset:32
	v_mov_b32_e32 v198, v118
	v_mov_b32_e32 v199, v114
	v_cvt_pk_bf16_f32 v196, v186, v187
	s_waitcnt vmcnt(1)
	v_mov_b32_e32 v201, v188
	s_waitcnt vmcnt(0)
	v_mov_b32_e32 v200, v190
	v_pk_mul_f32 v[198:199], v[198:199], v[200:201]
	v_mov_b32_e32 v188, v191
	v_pk_fma_f32 v[188:189], v[184:185], v[188:189], v[198:199]
	s_nop 0
	v_cvt_pk_bf16_f32 v197, v188, v189
	global_store_dwordx2 v[192:193], v[196:197], off
	global_store_dwordx4 v[194:195], v[186:189], off nt

.LBB0_598:
	s_andn2_saveexec_b64 s[0:1], s[0:1]
	s_cbranch_execz .LBB0_600
	s_waitcnt vmcnt(0)
	v_mov_b32_e32 v193, v176
	v_mov_b32_e32 v196, v182
	v_mov_b32_e32 v197, v180
	s_waitcnt lgkmcnt(2)
	v_pk_mul_f32 v[186:187], v[170:171], v[186:187] op_sel_hi:[0,1]
	v_mov_b32_e32 v180, v183
	s_waitcnt lgkmcnt(0)
	v_pk_mul_f32 v[182:183], v[170:171], v[184:185] op_sel_hi:[0,1]
	v_mov_b32_e32 v176, v179
	v_mov_b32_e32 v190, v119
	v_mov_b32_e32 v191, v115
	v_mov_b32_e32 v192, v178
	v_mov_b32_e32 v194, v127
	v_mov_b32_e32 v195, v123
	v_lshlrev_b64 v[198:199], 6, v[188:189]
	v_pk_mul_f32 v[180:181], v[180:181], v[186:187]
	v_pk_mul_f32 v[176:177], v[176:177], v[182:183]
	v_lshl_add_u64 v[198:199], v[172:173], 0, v[198:199]
	v_lshlrev_b64 v[188:189], 7, v[188:189]
	v_pk_fma_f32 v[180:181], v[194:195], v[196:197], v[180:181]
	v_pk_fma_f32 v[182:183], v[190:191], v[192:193], v[176:177]
	v_cvt_pk_bf16_f32 v178, v180, v181
	v_lshl_add_u64 v[188:189], v[174:175], 0, v[188:189]
	v_cvt_pk_bf16_f32 v179, v182, v183
	global_store_dwordx2 v[198:199], v[178:179], off
	global_store_dwordx4 v[188:189], v[180:183], off nt

.LBB0_604:
	s_andn2_saveexec_b64 s[0:1], s[0:1]
	s_cbranch_execz .LBB0_606
	v_lshl_add_u64 v[190:191], s[58:59], 0, v[134:135]
	v_lshlrev_b64 v[192:193], 6, v[186:187]
	v_lshlrev_b64 v[186:187], 7, v[186:187]
	v_lshl_add_u64 v[194:195], v[174:175], 0, v[186:187]
	global_load_dwordx2 v[186:187], v[190:191], off offset:16
	global_load_dwordx2 v[196:197], v[190:191], off
	v_mov_b32_e32 v198, v108
	v_mov_b32_e32 v199, v104
	s_waitcnt lgkmcnt(2)
	v_pk_mul_f32 v[188:189], v[170:171], v[188:189] op_sel_hi:[0,1]
	s_waitcnt lgkmcnt(0)
	v_pk_mul_f32 v[184:185], v[170:171], v[184:185] op_sel_hi:[0,1]
	v_lshl_add_u64 v[192:193], v[172:173], 0, v[192:193]
	s_waitcnt vmcnt(1)
	v_mov_b32_e32 v201, v186
	s_waitcnt vmcnt(0)
	v_mov_b32_e32 v200, v196
	v_pk_mul_f32 v[198:199], v[198:199], v[200:201]
	v_mov_b32_e32 v186, v197
	v_pk_fma_f32 v[186:187], v[188:189], v[186:187], v[198:199]
	global_load_dwordx2 v[188:189], v[190:191], off offset:48
	s_nop 0
	global_load_dwordx2 v[190:191], v[190:191], off offset:32
	v_mov_b32_e32 v198, v100
	v_mov_b32_e32 v199, v96
	v_cvt_pk_bf16_f32 v196, v186, v187
	s_waitcnt vmcnt(1)
	v_mov_b32_e32 v201, v188
	s_waitcnt vmcnt(0)
	v_mov_b32_e32 v200, v190
	v_pk_mul_f32 v[198:199], v[198:199], v[200:201]
	v_mov_b32_e32 v188, v191
	v_pk_fma_f32 v[188:189], v[184:185], v[188:189], v[198:199]
	s_nop 0
	v_cvt_pk_bf16_f32 v197, v188, v189
	global_store_dwordx2 v[192:193], v[196:197], off
	global_store_dwordx4 v[194:195], v[186:189], off nt

.LBB0_610:
	s_andn2_saveexec_b64 s[0:1], s[0:1]
	s_cbranch_execz .LBB0_612
	s_waitcnt vmcnt(0)
	v_mov_b32_e32 v193, v176
	v_mov_b32_e32 v196, v182
	v_mov_b32_e32 v197, v180
	s_waitcnt lgkmcnt(2)
	v_pk_mul_f32 v[186:187], v[170:171], v[186:187] op_sel_hi:[0,1]
	v_mov_b32_e32 v180, v183
	s_waitcnt lgkmcnt(0)
	v_pk_mul_f32 v[182:183], v[170:171], v[184:185] op_sel_hi:[0,1]
	v_mov_b32_e32 v176, v179
	v_mov_b32_e32 v190, v101
	v_mov_b32_e32 v191, v97
	v_mov_b32_e32 v192, v178
	v_mov_b32_e32 v194, v109
	v_mov_b32_e32 v195, v105
	v_lshlrev_b64 v[198:199], 6, v[188:189]
	v_pk_mul_f32 v[180:181], v[180:181], v[186:187]
	v_pk_mul_f32 v[176:177], v[176:177], v[182:183]
	v_lshl_add_u64 v[198:199], v[172:173], 0, v[198:199]
	v_lshlrev_b64 v[188:189], 7, v[188:189]
	v_pk_fma_f32 v[180:181], v[194:195], v[196:197], v[180:181]
	v_pk_fma_f32 v[182:183], v[190:191], v[192:193], v[176:177]
	v_cvt_pk_bf16_f32 v178, v180, v181
	v_lshl_add_u64 v[188:189], v[174:175], 0, v[188:189]
	v_cvt_pk_bf16_f32 v179, v182, v183
	global_store_dwordx2 v[198:199], v[178:179], off
	global_store_dwordx4 v[188:189], v[180:183], off nt

.LBB0_616:
	s_andn2_saveexec_b64 s[0:1], s[0:1]
	s_cbranch_execz .LBB0_618
	v_lshl_add_u64 v[190:191], s[58:59], 0, v[134:135]
	v_lshlrev_b64 v[192:193], 6, v[186:187]
	v_lshlrev_b64 v[186:187], 7, v[186:187]
	v_lshl_add_u64 v[194:195], v[174:175], 0, v[186:187]
	global_load_dwordx2 v[186:187], v[190:191], off offset:16
	global_load_dwordx2 v[196:197], v[190:191], off
	v_mov_b32_e32 v198, v110
	v_mov_b32_e32 v199, v106
	s_waitcnt lgkmcnt(2)
	v_pk_mul_f32 v[188:189], v[170:171], v[188:189] op_sel_hi:[0,1]
	s_waitcnt lgkmcnt(0)
	v_pk_mul_f32 v[184:185], v[170:171], v[184:185] op_sel_hi:[0,1]
	v_lshl_add_u64 v[192:193], v[172:173], 0, v[192:193]
	s_waitcnt vmcnt(1)
	v_mov_b32_e32 v201, v186
	s_waitcnt vmcnt(0)
	v_mov_b32_e32 v200, v196
	v_pk_mul_f32 v[198:199], v[198:199], v[200:201]
	v_mov_b32_e32 v186, v197
	v_pk_fma_f32 v[186:187], v[188:189], v[186:187], v[198:199]
	global_load_dwordx2 v[188:189], v[190:191], off offset:48
	s_nop 0
	global_load_dwordx2 v[190:191], v[190:191], off offset:32
	v_mov_b32_e32 v198, v102
	v_mov_b32_e32 v199, v98
	v_cvt_pk_bf16_f32 v196, v186, v187
	s_waitcnt vmcnt(1)
	v_mov_b32_e32 v201, v188
	s_waitcnt vmcnt(0)
	v_mov_b32_e32 v200, v190
	v_pk_mul_f32 v[198:199], v[198:199], v[200:201]
	v_mov_b32_e32 v188, v191
	v_pk_fma_f32 v[188:189], v[184:185], v[188:189], v[198:199]
	s_nop 0
	v_cvt_pk_bf16_f32 v197, v188, v189
	global_store_dwordx2 v[192:193], v[196:197], off
	global_store_dwordx4 v[194:195], v[186:189], off nt

.LBB0_622:
	s_andn2_saveexec_b64 s[0:1], s[0:1]
	s_cbranch_execz .LBB0_624
	s_waitcnt vmcnt(0)
	v_mov_b32_e32 v193, v176
	v_mov_b32_e32 v196, v182
	v_mov_b32_e32 v197, v180
	s_waitcnt lgkmcnt(2)
	v_pk_mul_f32 v[186:187], v[170:171], v[186:187] op_sel_hi:[0,1]
	v_mov_b32_e32 v180, v183
	s_waitcnt lgkmcnt(0)
	v_pk_mul_f32 v[182:183], v[170:171], v[184:185] op_sel_hi:[0,1]
	v_mov_b32_e32 v176, v179
	v_mov_b32_e32 v190, v103
	v_mov_b32_e32 v191, v99
	v_mov_b32_e32 v192, v178
	v_mov_b32_e32 v194, v111
	v_mov_b32_e32 v195, v107
	v_lshlrev_b64 v[198:199], 6, v[188:189]
	v_pk_mul_f32 v[180:181], v[180:181], v[186:187]
	v_pk_mul_f32 v[176:177], v[176:177], v[182:183]
	v_lshl_add_u64 v[198:199], v[172:173], 0, v[198:199]
	v_lshlrev_b64 v[188:189], 7, v[188:189]
	v_pk_fma_f32 v[180:181], v[194:195], v[196:197], v[180:181]
	v_pk_fma_f32 v[182:183], v[190:191], v[192:193], v[176:177]
	v_cvt_pk_bf16_f32 v178, v180, v181
	v_lshl_add_u64 v[188:189], v[174:175], 0, v[188:189]
	v_cvt_pk_bf16_f32 v179, v182, v183
	global_store_dwordx2 v[198:199], v[178:179], off
	global_store_dwordx4 v[188:189], v[180:183], off nt

.LBB0_628:
	s_andn2_saveexec_b64 s[0:1], s[0:1]
	s_cbranch_execz .LBB0_630
	v_lshl_add_u64 v[190:191], s[58:59], 0, v[134:135]
	v_lshlrev_b64 v[192:193], 6, v[186:187]
	v_lshlrev_b64 v[186:187], 7, v[186:187]
	v_lshl_add_u64 v[194:195], v[174:175], 0, v[186:187]
	global_load_dwordx2 v[186:187], v[190:191], off offset:16
	global_load_dwordx2 v[196:197], v[190:191], off
	v_mov_b32_e32 v198, v92
	v_mov_b32_e32 v199, v88
	s_waitcnt lgkmcnt(2)
	v_pk_mul_f32 v[188:189], v[170:171], v[188:189] op_sel_hi:[0,1]
	s_waitcnt lgkmcnt(0)
	v_pk_mul_f32 v[184:185], v[170:171], v[184:185] op_sel_hi:[0,1]
	v_lshl_add_u64 v[192:193], v[172:173], 0, v[192:193]
	s_waitcnt vmcnt(1)
	v_mov_b32_e32 v201, v186
	s_waitcnt vmcnt(0)
	v_mov_b32_e32 v200, v196
	v_pk_mul_f32 v[198:199], v[198:199], v[200:201]
	v_mov_b32_e32 v186, v197
	v_pk_fma_f32 v[186:187], v[188:189], v[186:187], v[198:199]
	global_load_dwordx2 v[188:189], v[190:191], off offset:48
	s_nop 0
	global_load_dwordx2 v[190:191], v[190:191], off offset:32
	v_mov_b32_e32 v198, v84
	v_mov_b32_e32 v199, v80
	v_cvt_pk_bf16_f32 v196, v186, v187
	s_waitcnt vmcnt(1)
	v_mov_b32_e32 v201, v188
	s_waitcnt vmcnt(0)
	v_mov_b32_e32 v200, v190
	v_pk_mul_f32 v[198:199], v[198:199], v[200:201]
	v_mov_b32_e32 v188, v191
	v_pk_fma_f32 v[188:189], v[184:185], v[188:189], v[198:199]
	s_nop 0
	v_cvt_pk_bf16_f32 v197, v188, v189
	global_store_dwordx2 v[192:193], v[196:197], off
	global_store_dwordx4 v[194:195], v[186:189], off nt

.LBB0_634:
	s_andn2_saveexec_b64 s[0:1], s[0:1]
	s_cbranch_execz .LBB0_636
	s_waitcnt vmcnt(0)
	v_mov_b32_e32 v193, v176
	v_mov_b32_e32 v196, v182
	v_mov_b32_e32 v197, v180
	s_waitcnt lgkmcnt(2)
	v_pk_mul_f32 v[186:187], v[170:171], v[186:187] op_sel_hi:[0,1]
	v_mov_b32_e32 v180, v183
	s_waitcnt lgkmcnt(0)
	v_pk_mul_f32 v[182:183], v[170:171], v[184:185] op_sel_hi:[0,1]
	v_mov_b32_e32 v176, v179
	v_mov_b32_e32 v190, v85
	v_mov_b32_e32 v191, v81
	v_mov_b32_e32 v192, v178
	v_mov_b32_e32 v194, v93
	v_mov_b32_e32 v195, v89
	v_lshlrev_b64 v[198:199], 6, v[188:189]
	v_pk_mul_f32 v[180:181], v[180:181], v[186:187]
	v_pk_mul_f32 v[176:177], v[176:177], v[182:183]
	v_lshl_add_u64 v[198:199], v[172:173], 0, v[198:199]
	v_lshlrev_b64 v[188:189], 7, v[188:189]
	v_pk_fma_f32 v[180:181], v[194:195], v[196:197], v[180:181]
	v_pk_fma_f32 v[182:183], v[190:191], v[192:193], v[176:177]
	v_cvt_pk_bf16_f32 v178, v180, v181
	v_lshl_add_u64 v[188:189], v[174:175], 0, v[188:189]
	v_cvt_pk_bf16_f32 v179, v182, v183
	global_store_dwordx2 v[198:199], v[178:179], off
	global_store_dwordx4 v[188:189], v[180:183], off nt

.LBB0_640:
	s_andn2_saveexec_b64 s[0:1], s[0:1]
	s_cbranch_execz .LBB0_642
	v_lshl_add_u64 v[190:191], s[58:59], 0, v[134:135]
	v_lshlrev_b64 v[192:193], 6, v[186:187]
	v_lshlrev_b64 v[186:187], 7, v[186:187]
	v_lshl_add_u64 v[194:195], v[174:175], 0, v[186:187]
	global_load_dwordx2 v[186:187], v[190:191], off offset:16
	global_load_dwordx2 v[196:197], v[190:191], off
	v_mov_b32_e32 v198, v94
	v_mov_b32_e32 v199, v90
	s_waitcnt lgkmcnt(2)
	v_pk_mul_f32 v[188:189], v[170:171], v[188:189] op_sel_hi:[0,1]
	s_waitcnt lgkmcnt(0)
	v_pk_mul_f32 v[184:185], v[170:171], v[184:185] op_sel_hi:[0,1]
	v_lshl_add_u64 v[192:193], v[172:173], 0, v[192:193]
	s_waitcnt vmcnt(1)
	v_mov_b32_e32 v201, v186
	s_waitcnt vmcnt(0)
	v_mov_b32_e32 v200, v196
	v_pk_mul_f32 v[198:199], v[198:199], v[200:201]
	v_mov_b32_e32 v186, v197
	v_pk_fma_f32 v[186:187], v[188:189], v[186:187], v[198:199]
	global_load_dwordx2 v[188:189], v[190:191], off offset:48
	s_nop 0
	global_load_dwordx2 v[190:191], v[190:191], off offset:32
	v_mov_b32_e32 v198, v86
	v_mov_b32_e32 v199, v82
	v_cvt_pk_bf16_f32 v196, v186, v187
	s_waitcnt vmcnt(1)
	v_mov_b32_e32 v201, v188
	s_waitcnt vmcnt(0)
	v_mov_b32_e32 v200, v190
	v_pk_mul_f32 v[198:199], v[198:199], v[200:201]
	v_mov_b32_e32 v188, v191
	v_pk_fma_f32 v[188:189], v[184:185], v[188:189], v[198:199]
	s_nop 0
	v_cvt_pk_bf16_f32 v197, v188, v189
	global_store_dwordx2 v[192:193], v[196:197], off
	global_store_dwordx4 v[194:195], v[186:189], off nt

.LBB0_646:
	s_andn2_saveexec_b64 s[0:1], s[0:1]
	s_cbranch_execz .LBB0_648
	s_waitcnt vmcnt(0)
	v_mov_b32_e32 v193, v176
	v_mov_b32_e32 v196, v182
	v_mov_b32_e32 v197, v180
	s_waitcnt lgkmcnt(2)
	v_pk_mul_f32 v[186:187], v[170:171], v[186:187] op_sel_hi:[0,1]
	v_mov_b32_e32 v180, v183
	s_waitcnt lgkmcnt(0)
	v_pk_mul_f32 v[182:183], v[170:171], v[184:185] op_sel_hi:[0,1]
	v_mov_b32_e32 v176, v179
	v_mov_b32_e32 v190, v87
	v_mov_b32_e32 v191, v83
	v_mov_b32_e32 v192, v178
	v_mov_b32_e32 v194, v95
	v_mov_b32_e32 v195, v91
	v_lshlrev_b64 v[198:199], 6, v[188:189]
	v_pk_mul_f32 v[180:181], v[180:181], v[186:187]
	v_pk_mul_f32 v[176:177], v[176:177], v[182:183]
	v_lshl_add_u64 v[198:199], v[172:173], 0, v[198:199]
	v_lshlrev_b64 v[188:189], 7, v[188:189]
	v_pk_fma_f32 v[180:181], v[194:195], v[196:197], v[180:181]
	v_pk_fma_f32 v[182:183], v[190:191], v[192:193], v[176:177]
	v_cvt_pk_bf16_f32 v178, v180, v181
	v_lshl_add_u64 v[188:189], v[174:175], 0, v[188:189]
	v_cvt_pk_bf16_f32 v179, v182, v183
	global_store_dwordx2 v[198:199], v[178:179], off
	global_store_dwordx4 v[188:189], v[180:183], off nt

.LBB0_652:
	s_andn2_saveexec_b64 s[0:1], s[0:1]
	s_cbranch_execz .LBB0_654
	v_lshl_add_u64 v[190:191], s[58:59], 0, v[134:135]
	v_lshlrev_b64 v[192:193], 6, v[186:187]
	v_lshlrev_b64 v[186:187], 7, v[186:187]
	v_lshl_add_u64 v[194:195], v[174:175], 0, v[186:187]
	global_load_dwordx2 v[186:187], v[190:191], off offset:16
	global_load_dwordx2 v[196:197], v[190:191], off
	v_mov_b32_e32 v198, v76
	v_mov_b32_e32 v199, v72
	s_waitcnt lgkmcnt(2)
	v_pk_mul_f32 v[188:189], v[170:171], v[188:189] op_sel_hi:[0,1]
	s_waitcnt lgkmcnt(0)
	v_pk_mul_f32 v[184:185], v[170:171], v[184:185] op_sel_hi:[0,1]
	v_lshl_add_u64 v[192:193], v[172:173], 0, v[192:193]
	s_waitcnt vmcnt(1)
	v_mov_b32_e32 v201, v186
	s_waitcnt vmcnt(0)
	v_mov_b32_e32 v200, v196
	v_pk_mul_f32 v[198:199], v[198:199], v[200:201]
	v_mov_b32_e32 v186, v197
	v_pk_fma_f32 v[186:187], v[188:189], v[186:187], v[198:199]
	global_load_dwordx2 v[188:189], v[190:191], off offset:48
	s_nop 0
	global_load_dwordx2 v[190:191], v[190:191], off offset:32
	v_mov_b32_e32 v198, v68
	v_mov_b32_e32 v199, v64
	v_cvt_pk_bf16_f32 v196, v186, v187
	s_waitcnt vmcnt(1)
	v_mov_b32_e32 v201, v188
	s_waitcnt vmcnt(0)
	v_mov_b32_e32 v200, v190
	v_pk_mul_f32 v[198:199], v[198:199], v[200:201]
	v_mov_b32_e32 v188, v191
	v_pk_fma_f32 v[188:189], v[184:185], v[188:189], v[198:199]
	s_nop 0
	v_cvt_pk_bf16_f32 v197, v188, v189
	global_store_dwordx2 v[192:193], v[196:197], off
	global_store_dwordx4 v[194:195], v[186:189], off nt

.LBB0_658:
	s_andn2_saveexec_b64 s[0:1], s[0:1]
	s_cbranch_execz .LBB0_660
	s_waitcnt vmcnt(0)
	v_mov_b32_e32 v193, v176
	v_mov_b32_e32 v196, v182
	v_mov_b32_e32 v197, v180
	s_waitcnt lgkmcnt(2)
	v_pk_mul_f32 v[186:187], v[170:171], v[186:187] op_sel_hi:[0,1]
	v_mov_b32_e32 v180, v183
	s_waitcnt lgkmcnt(0)
	v_pk_mul_f32 v[182:183], v[170:171], v[184:185] op_sel_hi:[0,1]
	v_mov_b32_e32 v176, v179
	v_mov_b32_e32 v190, v69
	v_mov_b32_e32 v191, v65
	v_mov_b32_e32 v192, v178
	v_mov_b32_e32 v194, v77
	v_mov_b32_e32 v195, v73
	v_lshlrev_b64 v[198:199], 6, v[188:189]
	v_pk_mul_f32 v[180:181], v[180:181], v[186:187]
	v_pk_mul_f32 v[176:177], v[176:177], v[182:183]
	v_lshl_add_u64 v[198:199], v[172:173], 0, v[198:199]
	v_lshlrev_b64 v[188:189], 7, v[188:189]
	v_pk_fma_f32 v[180:181], v[194:195], v[196:197], v[180:181]
	v_pk_fma_f32 v[182:183], v[190:191], v[192:193], v[176:177]
	v_cvt_pk_bf16_f32 v178, v180, v181
	v_lshl_add_u64 v[188:189], v[174:175], 0, v[188:189]
	v_cvt_pk_bf16_f32 v179, v182, v183
	global_store_dwordx2 v[198:199], v[178:179], off
	global_store_dwordx4 v[188:189], v[180:183], off nt

.LBB0_664:
	s_andn2_saveexec_b64 s[0:1], s[0:1]
	s_cbranch_execz .LBB0_666
	v_lshl_add_u64 v[190:191], s[58:59], 0, v[134:135]
	v_lshlrev_b64 v[192:193], 6, v[186:187]
	v_lshlrev_b64 v[186:187], 7, v[186:187]
	v_lshl_add_u64 v[194:195], v[174:175], 0, v[186:187]
	global_load_dwordx2 v[186:187], v[190:191], off offset:16
	global_load_dwordx2 v[196:197], v[190:191], off
	v_mov_b32_e32 v198, v78
	v_mov_b32_e32 v199, v74
	s_waitcnt lgkmcnt(2)
	v_pk_mul_f32 v[188:189], v[170:171], v[188:189] op_sel_hi:[0,1]
	s_waitcnt lgkmcnt(0)
	v_pk_mul_f32 v[184:185], v[170:171], v[184:185] op_sel_hi:[0,1]
	v_lshl_add_u64 v[192:193], v[172:173], 0, v[192:193]
	s_waitcnt vmcnt(1)
	v_mov_b32_e32 v201, v186
	s_waitcnt vmcnt(0)
	v_mov_b32_e32 v200, v196
	v_pk_mul_f32 v[198:199], v[198:199], v[200:201]
	v_mov_b32_e32 v186, v197
	v_pk_fma_f32 v[186:187], v[188:189], v[186:187], v[198:199]
	global_load_dwordx2 v[188:189], v[190:191], off offset:48
	s_nop 0
	global_load_dwordx2 v[190:191], v[190:191], off offset:32
	v_mov_b32_e32 v198, v70
	v_mov_b32_e32 v199, v66
	v_cvt_pk_bf16_f32 v196, v186, v187
	s_waitcnt vmcnt(1)
	v_mov_b32_e32 v201, v188
	s_waitcnt vmcnt(0)
	v_mov_b32_e32 v200, v190
	v_pk_mul_f32 v[198:199], v[198:199], v[200:201]
	v_mov_b32_e32 v188, v191
	v_pk_fma_f32 v[188:189], v[184:185], v[188:189], v[198:199]
	s_nop 0
	v_cvt_pk_bf16_f32 v197, v188, v189
	global_store_dwordx2 v[192:193], v[196:197], off
	global_store_dwordx4 v[194:195], v[186:189], off nt

.LBB0_670:
	s_andn2_saveexec_b64 s[0:1], s[0:1]
	s_cbranch_execz .LBB0_672
	s_waitcnt vmcnt(0)
	v_mov_b32_e32 v193, v176
	v_mov_b32_e32 v196, v182
	v_mov_b32_e32 v197, v180
	s_waitcnt lgkmcnt(2)
	v_pk_mul_f32 v[186:187], v[170:171], v[186:187] op_sel_hi:[0,1]
	v_mov_b32_e32 v180, v183
	s_waitcnt lgkmcnt(0)
	v_pk_mul_f32 v[182:183], v[170:171], v[184:185] op_sel_hi:[0,1]
	v_mov_b32_e32 v176, v179
	v_mov_b32_e32 v190, v71
	v_mov_b32_e32 v191, v67
	v_mov_b32_e32 v192, v178
	v_mov_b32_e32 v194, v79
	v_mov_b32_e32 v195, v75
	v_lshlrev_b64 v[198:199], 6, v[188:189]
	v_pk_mul_f32 v[180:181], v[180:181], v[186:187]
	v_pk_mul_f32 v[176:177], v[176:177], v[182:183]
	v_lshl_add_u64 v[198:199], v[172:173], 0, v[198:199]
	v_lshlrev_b64 v[188:189], 7, v[188:189]
	v_pk_fma_f32 v[180:181], v[194:195], v[196:197], v[180:181]
	v_pk_fma_f32 v[182:183], v[190:191], v[192:193], v[176:177]
	v_cvt_pk_bf16_f32 v178, v180, v181
	v_lshl_add_u64 v[188:189], v[174:175], 0, v[188:189]
	v_cvt_pk_bf16_f32 v179, v182, v183
	global_store_dwordx2 v[198:199], v[178:179], off
	global_store_dwordx4 v[188:189], v[180:183], off nt

.LBB0_676:
	s_andn2_saveexec_b64 s[0:1], s[0:1]
	s_cbranch_execz .LBB0_678
	v_lshl_add_u64 v[190:191], s[58:59], 0, v[134:135]
	v_lshlrev_b64 v[192:193], 6, v[186:187]
	v_lshlrev_b64 v[186:187], 7, v[186:187]
	v_lshl_add_u64 v[194:195], v[174:175], 0, v[186:187]
	global_load_dwordx2 v[186:187], v[190:191], off offset:16
	global_load_dwordx2 v[196:197], v[190:191], off
	v_mov_b32_e32 v198, v60
	v_mov_b32_e32 v199, v56
	s_waitcnt lgkmcnt(2)
	v_pk_mul_f32 v[188:189], v[170:171], v[188:189] op_sel_hi:[0,1]
	s_waitcnt lgkmcnt(0)
	v_pk_mul_f32 v[184:185], v[170:171], v[184:185] op_sel_hi:[0,1]
	v_lshl_add_u64 v[192:193], v[172:173], 0, v[192:193]
	s_waitcnt vmcnt(1)
	v_mov_b32_e32 v201, v186
	s_waitcnt vmcnt(0)
	v_mov_b32_e32 v200, v196
	v_pk_mul_f32 v[198:199], v[198:199], v[200:201]
	v_mov_b32_e32 v186, v197
	v_pk_fma_f32 v[186:187], v[188:189], v[186:187], v[198:199]
	global_load_dwordx2 v[188:189], v[190:191], off offset:48
	s_nop 0
	global_load_dwordx2 v[190:191], v[190:191], off offset:32
	v_mov_b32_e32 v198, v52
	v_mov_b32_e32 v199, v48
	v_cvt_pk_bf16_f32 v196, v186, v187
	s_waitcnt vmcnt(1)
	v_mov_b32_e32 v201, v188
	s_waitcnt vmcnt(0)
	v_mov_b32_e32 v200, v190
	v_pk_mul_f32 v[198:199], v[198:199], v[200:201]
	v_mov_b32_e32 v188, v191
	v_pk_fma_f32 v[188:189], v[184:185], v[188:189], v[198:199]
	s_nop 0
	v_cvt_pk_bf16_f32 v197, v188, v189
	global_store_dwordx2 v[192:193], v[196:197], off
	global_store_dwordx4 v[194:195], v[186:189], off nt

.LBB0_682:
	s_andn2_saveexec_b64 s[0:1], s[0:1]
	s_cbranch_execz .LBB0_684
	s_waitcnt vmcnt(0)
	v_mov_b32_e32 v193, v176
	v_mov_b32_e32 v196, v182
	v_mov_b32_e32 v197, v180
	s_waitcnt lgkmcnt(2)
	v_pk_mul_f32 v[186:187], v[170:171], v[186:187] op_sel_hi:[0,1]
	v_mov_b32_e32 v180, v183
	s_waitcnt lgkmcnt(0)
	v_pk_mul_f32 v[182:183], v[170:171], v[184:185] op_sel_hi:[0,1]
	v_mov_b32_e32 v176, v179
	v_mov_b32_e32 v190, v53
	v_mov_b32_e32 v191, v49
	v_mov_b32_e32 v192, v178
	v_mov_b32_e32 v194, v61
	v_mov_b32_e32 v195, v57
	v_lshlrev_b64 v[198:199], 6, v[188:189]
	v_pk_mul_f32 v[180:181], v[180:181], v[186:187]
	v_pk_mul_f32 v[176:177], v[176:177], v[182:183]
	v_lshl_add_u64 v[198:199], v[172:173], 0, v[198:199]
	v_lshlrev_b64 v[188:189], 7, v[188:189]
	v_pk_fma_f32 v[180:181], v[194:195], v[196:197], v[180:181]
	v_pk_fma_f32 v[182:183], v[190:191], v[192:193], v[176:177]
	v_cvt_pk_bf16_f32 v178, v180, v181
	v_lshl_add_u64 v[188:189], v[174:175], 0, v[188:189]
	v_cvt_pk_bf16_f32 v179, v182, v183
	global_store_dwordx2 v[198:199], v[178:179], off
	global_store_dwordx4 v[188:189], v[180:183], off nt

.LBB0_688:
	s_andn2_saveexec_b64 s[0:1], s[0:1]
	s_cbranch_execz .LBB0_690
	v_lshl_add_u64 v[190:191], s[58:59], 0, v[134:135]
	v_lshlrev_b64 v[192:193], 6, v[186:187]
	v_lshlrev_b64 v[186:187], 7, v[186:187]
	v_lshl_add_u64 v[194:195], v[174:175], 0, v[186:187]
	global_load_dwordx2 v[186:187], v[190:191], off offset:16
	global_load_dwordx2 v[196:197], v[190:191], off
	v_mov_b32_e32 v198, v62
	v_mov_b32_e32 v199, v58
	s_waitcnt lgkmcnt(2)
	v_pk_mul_f32 v[188:189], v[170:171], v[188:189] op_sel_hi:[0,1]
	s_waitcnt lgkmcnt(0)
	v_pk_mul_f32 v[184:185], v[170:171], v[184:185] op_sel_hi:[0,1]
	v_lshl_add_u64 v[192:193], v[172:173], 0, v[192:193]
	s_waitcnt vmcnt(1)
	v_mov_b32_e32 v201, v186
	s_waitcnt vmcnt(0)
	v_mov_b32_e32 v200, v196
	v_pk_mul_f32 v[198:199], v[198:199], v[200:201]
	v_mov_b32_e32 v186, v197
	v_pk_fma_f32 v[186:187], v[188:189], v[186:187], v[198:199]
	global_load_dwordx2 v[188:189], v[190:191], off offset:48
	s_nop 0
	global_load_dwordx2 v[190:191], v[190:191], off offset:32
	v_mov_b32_e32 v198, v54
	v_mov_b32_e32 v199, v50
	v_cvt_pk_bf16_f32 v196, v186, v187
	s_waitcnt vmcnt(1)
	v_mov_b32_e32 v201, v188
	s_waitcnt vmcnt(0)
	v_mov_b32_e32 v200, v190
	v_pk_mul_f32 v[198:199], v[198:199], v[200:201]
	v_mov_b32_e32 v188, v191
	v_pk_fma_f32 v[188:189], v[184:185], v[188:189], v[198:199]
	s_nop 0
	v_cvt_pk_bf16_f32 v197, v188, v189
	global_store_dwordx2 v[192:193], v[196:197], off
	global_store_dwordx4 v[194:195], v[186:189], off nt

.LBB0_694:
	s_andn2_saveexec_b64 s[0:1], s[0:1]
	s_cbranch_execz .LBB0_696
	s_waitcnt vmcnt(0)
	v_mov_b32_e32 v193, v176
	v_mov_b32_e32 v196, v182
	v_mov_b32_e32 v197, v180
	s_waitcnt lgkmcnt(2)
	v_pk_mul_f32 v[186:187], v[170:171], v[186:187] op_sel_hi:[0,1]
	v_mov_b32_e32 v180, v183
	s_waitcnt lgkmcnt(0)
	v_pk_mul_f32 v[182:183], v[170:171], v[184:185] op_sel_hi:[0,1]
	v_mov_b32_e32 v176, v179
	v_mov_b32_e32 v190, v55
	v_mov_b32_e32 v191, v51
	v_mov_b32_e32 v192, v178
	v_mov_b32_e32 v194, v63
	v_mov_b32_e32 v195, v59
	v_lshlrev_b64 v[198:199], 6, v[188:189]
	v_pk_mul_f32 v[180:181], v[180:181], v[186:187]
	v_pk_mul_f32 v[176:177], v[176:177], v[182:183]
	v_lshl_add_u64 v[198:199], v[172:173], 0, v[198:199]
	v_lshlrev_b64 v[188:189], 7, v[188:189]
	v_pk_fma_f32 v[180:181], v[194:195], v[196:197], v[180:181]
	v_pk_fma_f32 v[182:183], v[190:191], v[192:193], v[176:177]
	v_cvt_pk_bf16_f32 v178, v180, v181
	v_lshl_add_u64 v[188:189], v[174:175], 0, v[188:189]
	v_cvt_pk_bf16_f32 v179, v182, v183
	global_store_dwordx2 v[198:199], v[178:179], off
	global_store_dwordx4 v[188:189], v[180:183], off nt

.LBB0_700:
	s_andn2_saveexec_b64 s[0:1], s[0:1]
	s_cbranch_execz .LBB0_702
	v_lshl_add_u64 v[190:191], s[58:59], 0, v[134:135]
	v_lshlrev_b64 v[192:193], 6, v[186:187]
	v_lshlrev_b64 v[186:187], 7, v[186:187]
	v_lshl_add_u64 v[194:195], v[174:175], 0, v[186:187]
	global_load_dwordx2 v[186:187], v[190:191], off offset:16
	global_load_dwordx2 v[196:197], v[190:191], off
	v_mov_b32_e32 v198, v44
	v_mov_b32_e32 v199, v40
	s_waitcnt lgkmcnt(2)
	v_pk_mul_f32 v[188:189], v[170:171], v[188:189] op_sel_hi:[0,1]
	s_waitcnt lgkmcnt(0)
	v_pk_mul_f32 v[184:185], v[170:171], v[184:185] op_sel_hi:[0,1]
	v_lshl_add_u64 v[192:193], v[172:173], 0, v[192:193]
	s_waitcnt vmcnt(1)
	v_mov_b32_e32 v201, v186
	s_waitcnt vmcnt(0)
	v_mov_b32_e32 v200, v196
	v_pk_mul_f32 v[198:199], v[198:199], v[200:201]
	v_mov_b32_e32 v186, v197
	v_pk_fma_f32 v[186:187], v[188:189], v[186:187], v[198:199]
	global_load_dwordx2 v[188:189], v[190:191], off offset:48
	s_nop 0
	global_load_dwordx2 v[190:191], v[190:191], off offset:32
	v_mov_b32_e32 v198, v36
	v_mov_b32_e32 v199, v32
	v_cvt_pk_bf16_f32 v196, v186, v187
	s_waitcnt vmcnt(1)
	v_mov_b32_e32 v201, v188
	s_waitcnt vmcnt(0)
	v_mov_b32_e32 v200, v190
	v_pk_mul_f32 v[198:199], v[198:199], v[200:201]
	v_mov_b32_e32 v188, v191
	v_pk_fma_f32 v[188:189], v[184:185], v[188:189], v[198:199]
	s_nop 0
	v_cvt_pk_bf16_f32 v197, v188, v189
	global_store_dwordx2 v[192:193], v[196:197], off
	global_store_dwordx4 v[194:195], v[186:189], off nt

.LBB0_706:
	s_andn2_saveexec_b64 s[0:1], s[0:1]
	s_cbranch_execz .LBB0_708
	s_waitcnt vmcnt(0)
	v_mov_b32_e32 v193, v176
	v_mov_b32_e32 v196, v182
	v_mov_b32_e32 v197, v180
	s_waitcnt lgkmcnt(2)
	v_pk_mul_f32 v[186:187], v[170:171], v[186:187] op_sel_hi:[0,1]
	v_mov_b32_e32 v180, v183
	s_waitcnt lgkmcnt(0)
	v_pk_mul_f32 v[182:183], v[170:171], v[184:185] op_sel_hi:[0,1]
	v_mov_b32_e32 v176, v179
	v_mov_b32_e32 v190, v37
	v_mov_b32_e32 v191, v33
	v_mov_b32_e32 v192, v178
	v_mov_b32_e32 v194, v45
	v_mov_b32_e32 v195, v41
	v_lshlrev_b64 v[198:199], 6, v[188:189]
	v_pk_mul_f32 v[180:181], v[180:181], v[186:187]
	v_pk_mul_f32 v[176:177], v[176:177], v[182:183]
	v_lshl_add_u64 v[198:199], v[172:173], 0, v[198:199]
	v_lshlrev_b64 v[188:189], 7, v[188:189]
	v_pk_fma_f32 v[180:181], v[194:195], v[196:197], v[180:181]
	v_pk_fma_f32 v[182:183], v[190:191], v[192:193], v[176:177]
	v_cvt_pk_bf16_f32 v178, v180, v181
	v_lshl_add_u64 v[188:189], v[174:175], 0, v[188:189]
	v_cvt_pk_bf16_f32 v179, v182, v183
	global_store_dwordx2 v[198:199], v[178:179], off
	global_store_dwordx4 v[188:189], v[180:183], off nt

.LBB0_712:
	s_andn2_saveexec_b64 s[0:1], s[0:1]
	s_cbranch_execz .LBB0_714
	v_lshl_add_u64 v[190:191], s[58:59], 0, v[134:135]
	v_lshlrev_b64 v[192:193], 6, v[186:187]
	v_lshlrev_b64 v[186:187], 7, v[186:187]
	v_lshl_add_u64 v[194:195], v[174:175], 0, v[186:187]
	global_load_dwordx2 v[186:187], v[190:191], off offset:16
	global_load_dwordx2 v[196:197], v[190:191], off
	v_mov_b32_e32 v198, v46
	v_mov_b32_e32 v199, v42
	s_waitcnt lgkmcnt(2)
	v_pk_mul_f32 v[188:189], v[170:171], v[188:189] op_sel_hi:[0,1]
	s_waitcnt lgkmcnt(0)
	v_pk_mul_f32 v[184:185], v[170:171], v[184:185] op_sel_hi:[0,1]
	v_lshl_add_u64 v[192:193], v[172:173], 0, v[192:193]
	s_waitcnt vmcnt(1)
	v_mov_b32_e32 v201, v186
	s_waitcnt vmcnt(0)
	v_mov_b32_e32 v200, v196
	v_pk_mul_f32 v[198:199], v[198:199], v[200:201]
	v_mov_b32_e32 v186, v197
	v_pk_fma_f32 v[186:187], v[188:189], v[186:187], v[198:199]
	global_load_dwordx2 v[188:189], v[190:191], off offset:48
	s_nop 0
	global_load_dwordx2 v[190:191], v[190:191], off offset:32
	v_mov_b32_e32 v198, v38
	v_mov_b32_e32 v199, v34
	v_cvt_pk_bf16_f32 v196, v186, v187
	s_waitcnt vmcnt(1)
	v_mov_b32_e32 v201, v188
	s_waitcnt vmcnt(0)
	v_mov_b32_e32 v200, v190
	v_pk_mul_f32 v[198:199], v[198:199], v[200:201]
	v_mov_b32_e32 v188, v191
	v_pk_fma_f32 v[188:189], v[184:185], v[188:189], v[198:199]
	s_nop 0
	v_cvt_pk_bf16_f32 v197, v188, v189
	global_store_dwordx2 v[192:193], v[196:197], off
	global_store_dwordx4 v[194:195], v[186:189], off nt

.LBB0_718:
	s_andn2_saveexec_b64 s[0:1], s[0:1]
	s_cbranch_execz .LBB0_720
	s_waitcnt vmcnt(0)
	v_mov_b32_e32 v193, v176
	v_mov_b32_e32 v196, v182
	v_mov_b32_e32 v197, v180
	s_waitcnt lgkmcnt(2)
	v_pk_mul_f32 v[186:187], v[170:171], v[186:187] op_sel_hi:[0,1]
	v_mov_b32_e32 v180, v183
	s_waitcnt lgkmcnt(0)
	v_pk_mul_f32 v[182:183], v[170:171], v[184:185] op_sel_hi:[0,1]
	v_mov_b32_e32 v176, v179
	v_mov_b32_e32 v190, v39
	v_mov_b32_e32 v191, v35
	v_mov_b32_e32 v192, v178
	v_mov_b32_e32 v194, v47
	v_mov_b32_e32 v195, v43
	v_lshlrev_b64 v[198:199], 6, v[188:189]
	v_pk_mul_f32 v[180:181], v[180:181], v[186:187]
	v_pk_mul_f32 v[176:177], v[176:177], v[182:183]
	v_lshl_add_u64 v[198:199], v[172:173], 0, v[198:199]
	v_lshlrev_b64 v[188:189], 7, v[188:189]
	v_pk_fma_f32 v[180:181], v[194:195], v[196:197], v[180:181]
	v_pk_fma_f32 v[182:183], v[190:191], v[192:193], v[176:177]
	v_cvt_pk_bf16_f32 v178, v180, v181
	v_lshl_add_u64 v[188:189], v[174:175], 0, v[188:189]
	v_cvt_pk_bf16_f32 v179, v182, v183
	global_store_dwordx2 v[198:199], v[178:179], off
	global_store_dwordx4 v[188:189], v[180:183], off nt

.LBB0_724:
	s_andn2_saveexec_b64 s[0:1], s[0:1]
	s_cbranch_execz .LBB0_726
	v_lshl_add_u64 v[190:191], s[58:59], 0, v[134:135]
	v_lshlrev_b64 v[192:193], 6, v[186:187]
	v_lshlrev_b64 v[186:187], 7, v[186:187]
	v_lshl_add_u64 v[194:195], v[174:175], 0, v[186:187]
	global_load_dwordx2 v[186:187], v[190:191], off offset:16
	global_load_dwordx2 v[196:197], v[190:191], off
	v_mov_b32_e32 v198, v28
	v_mov_b32_e32 v199, v24
	s_waitcnt lgkmcnt(2)
	v_pk_mul_f32 v[188:189], v[170:171], v[188:189] op_sel_hi:[0,1]
	s_waitcnt lgkmcnt(0)
	v_pk_mul_f32 v[184:185], v[170:171], v[184:185] op_sel_hi:[0,1]
	v_lshl_add_u64 v[192:193], v[172:173], 0, v[192:193]
	s_waitcnt vmcnt(1)
	v_mov_b32_e32 v201, v186
	s_waitcnt vmcnt(0)
	v_mov_b32_e32 v200, v196
	v_pk_mul_f32 v[198:199], v[198:199], v[200:201]
	v_mov_b32_e32 v186, v197
	v_pk_fma_f32 v[186:187], v[188:189], v[186:187], v[198:199]
	global_load_dwordx2 v[188:189], v[190:191], off offset:48
	s_nop 0
	global_load_dwordx2 v[190:191], v[190:191], off offset:32
	v_mov_b32_e32 v198, v20
	v_mov_b32_e32 v199, v16
	v_cvt_pk_bf16_f32 v196, v186, v187
	s_waitcnt vmcnt(1)
	v_mov_b32_e32 v201, v188
	s_waitcnt vmcnt(0)
	v_mov_b32_e32 v200, v190
	v_pk_mul_f32 v[198:199], v[198:199], v[200:201]
	v_mov_b32_e32 v188, v191
	v_pk_fma_f32 v[188:189], v[184:185], v[188:189], v[198:199]
	s_nop 0
	v_cvt_pk_bf16_f32 v197, v188, v189
	global_store_dwordx2 v[192:193], v[196:197], off
	global_store_dwordx4 v[194:195], v[186:189], off nt

.LBB0_730:
	s_andn2_saveexec_b64 s[0:1], s[0:1]
	s_cbranch_execz .LBB0_732
	s_waitcnt vmcnt(0)
	v_mov_b32_e32 v193, v176
	v_mov_b32_e32 v196, v182
	v_mov_b32_e32 v197, v180
	s_waitcnt lgkmcnt(2)
	v_pk_mul_f32 v[186:187], v[170:171], v[186:187] op_sel_hi:[0,1]
	v_mov_b32_e32 v180, v183
	s_waitcnt lgkmcnt(0)
	v_pk_mul_f32 v[182:183], v[170:171], v[184:185] op_sel_hi:[0,1]
	v_mov_b32_e32 v176, v179
	v_mov_b32_e32 v190, v21
	v_mov_b32_e32 v191, v17
	v_mov_b32_e32 v192, v178
	v_mov_b32_e32 v194, v29
	v_mov_b32_e32 v195, v25
	v_lshlrev_b64 v[198:199], 6, v[188:189]
	v_pk_mul_f32 v[180:181], v[180:181], v[186:187]
	v_pk_mul_f32 v[176:177], v[176:177], v[182:183]
	v_lshl_add_u64 v[198:199], v[172:173], 0, v[198:199]
	v_lshlrev_b64 v[188:189], 7, v[188:189]
	v_pk_fma_f32 v[180:181], v[194:195], v[196:197], v[180:181]
	v_pk_fma_f32 v[182:183], v[190:191], v[192:193], v[176:177]
	v_cvt_pk_bf16_f32 v178, v180, v181
	v_lshl_add_u64 v[188:189], v[174:175], 0, v[188:189]
	v_cvt_pk_bf16_f32 v179, v182, v183
	global_store_dwordx2 v[198:199], v[178:179], off
	global_store_dwordx4 v[188:189], v[180:183], off nt

.LBB0_736:
	s_andn2_saveexec_b64 s[0:1], s[0:1]
	s_cbranch_execz .LBB0_738
	v_lshl_add_u64 v[190:191], s[58:59], 0, v[134:135]
	v_lshlrev_b64 v[192:193], 6, v[186:187]
	v_lshlrev_b64 v[186:187], 7, v[186:187]
	v_lshl_add_u64 v[194:195], v[174:175], 0, v[186:187]
	global_load_dwordx2 v[186:187], v[190:191], off offset:16
	global_load_dwordx2 v[196:197], v[190:191], off
	v_mov_b32_e32 v198, v30
	v_mov_b32_e32 v199, v26
	s_waitcnt lgkmcnt(2)
	v_pk_mul_f32 v[188:189], v[170:171], v[188:189] op_sel_hi:[0,1]
	s_waitcnt lgkmcnt(0)
	v_pk_mul_f32 v[184:185], v[170:171], v[184:185] op_sel_hi:[0,1]
	v_lshl_add_u64 v[192:193], v[172:173], 0, v[192:193]
	s_waitcnt vmcnt(1)
	v_mov_b32_e32 v201, v186
	s_waitcnt vmcnt(0)
	v_mov_b32_e32 v200, v196
	v_pk_mul_f32 v[198:199], v[198:199], v[200:201]
	v_mov_b32_e32 v186, v197
	v_pk_fma_f32 v[186:187], v[188:189], v[186:187], v[198:199]
	global_load_dwordx2 v[188:189], v[190:191], off offset:48
	s_nop 0
	global_load_dwordx2 v[190:191], v[190:191], off offset:32
	v_mov_b32_e32 v198, v22
	v_mov_b32_e32 v199, v18
	v_cvt_pk_bf16_f32 v196, v186, v187
	s_waitcnt vmcnt(1)
	v_mov_b32_e32 v201, v188
	s_waitcnt vmcnt(0)
	v_mov_b32_e32 v200, v190
	v_pk_mul_f32 v[198:199], v[198:199], v[200:201]
	v_mov_b32_e32 v188, v191
	v_pk_fma_f32 v[188:189], v[184:185], v[188:189], v[198:199]
	s_nop 0
	v_cvt_pk_bf16_f32 v197, v188, v189
	global_store_dwordx2 v[192:193], v[196:197], off
	global_store_dwordx4 v[194:195], v[186:189], off nt

.LBB0_742:
	s_andn2_saveexec_b64 s[0:1], s[0:1]
	s_cbranch_execz .LBB0_744
	s_waitcnt vmcnt(0)
	v_mov_b32_e32 v193, v176
	v_mov_b32_e32 v196, v182
	v_mov_b32_e32 v197, v180
	s_waitcnt lgkmcnt(2)
	v_pk_mul_f32 v[186:187], v[170:171], v[186:187] op_sel_hi:[0,1]
	v_mov_b32_e32 v180, v183
	s_waitcnt lgkmcnt(0)
	v_pk_mul_f32 v[182:183], v[170:171], v[184:185] op_sel_hi:[0,1]
	v_mov_b32_e32 v176, v179
	v_mov_b32_e32 v190, v23
	v_mov_b32_e32 v191, v19
	v_mov_b32_e32 v192, v178
	v_mov_b32_e32 v194, v31
	v_mov_b32_e32 v195, v27
	v_lshlrev_b64 v[198:199], 6, v[188:189]
	v_pk_mul_f32 v[180:181], v[180:181], v[186:187]
	v_pk_mul_f32 v[176:177], v[176:177], v[182:183]
	v_lshl_add_u64 v[198:199], v[172:173], 0, v[198:199]
	v_lshlrev_b64 v[188:189], 7, v[188:189]
	v_pk_fma_f32 v[180:181], v[194:195], v[196:197], v[180:181]
	v_pk_fma_f32 v[182:183], v[190:191], v[192:193], v[176:177]
	v_cvt_pk_bf16_f32 v178, v180, v181
	v_lshl_add_u64 v[188:189], v[174:175], 0, v[188:189]
	v_cvt_pk_bf16_f32 v179, v182, v183
	global_store_dwordx2 v[198:199], v[178:179], off
	global_store_dwordx4 v[188:189], v[180:183], off nt

.LBB0_748:
	s_andn2_saveexec_b64 s[0:1], s[0:1]
	s_cbranch_execz .LBB0_750
	v_lshl_add_u64 v[190:191], s[58:59], 0, v[134:135]
	v_lshlrev_b64 v[192:193], 6, v[186:187]
	v_lshlrev_b64 v[186:187], 7, v[186:187]
	v_lshl_add_u64 v[194:195], v[174:175], 0, v[186:187]
	global_load_dwordx2 v[186:187], v[190:191], off offset:16
	global_load_dwordx2 v[196:197], v[190:191], off
	v_mov_b32_e32 v198, v12
	v_mov_b32_e32 v199, v8
	s_waitcnt lgkmcnt(2)
	v_pk_mul_f32 v[188:189], v[170:171], v[188:189] op_sel_hi:[0,1]
	s_waitcnt lgkmcnt(0)
	v_pk_mul_f32 v[184:185], v[170:171], v[184:185] op_sel_hi:[0,1]
	v_lshl_add_u64 v[192:193], v[172:173], 0, v[192:193]
	s_waitcnt vmcnt(1)
	v_mov_b32_e32 v201, v186
	s_waitcnt vmcnt(0)
	v_mov_b32_e32 v200, v196
	v_pk_mul_f32 v[198:199], v[198:199], v[200:201]
	v_mov_b32_e32 v186, v197
	v_pk_fma_f32 v[186:187], v[188:189], v[186:187], v[198:199]
	global_load_dwordx2 v[188:189], v[190:191], off offset:48
	s_nop 0
	global_load_dwordx2 v[190:191], v[190:191], off offset:32
	v_mov_b32_e32 v198, v4
	v_mov_b32_e32 v199, v0
	v_cvt_pk_bf16_f32 v196, v186, v187
	s_waitcnt vmcnt(1)
	v_mov_b32_e32 v201, v188
	s_waitcnt vmcnt(0)
	v_mov_b32_e32 v200, v190
	v_pk_mul_f32 v[198:199], v[198:199], v[200:201]
	v_mov_b32_e32 v188, v191
	v_pk_fma_f32 v[188:189], v[184:185], v[188:189], v[198:199]
	s_nop 0
	v_cvt_pk_bf16_f32 v197, v188, v189
	global_store_dwordx2 v[192:193], v[196:197], off
	global_store_dwordx4 v[194:195], v[186:189], off nt

.LBB0_754:
	s_andn2_saveexec_b64 s[0:1], s[0:1]
	s_cbranch_execz .LBB0_756
	s_waitcnt vmcnt(0)
	v_mov_b32_e32 v193, v176
	v_mov_b32_e32 v196, v182
	v_mov_b32_e32 v197, v180
	s_waitcnt lgkmcnt(2)
	v_pk_mul_f32 v[186:187], v[170:171], v[186:187] op_sel_hi:[0,1]
	v_mov_b32_e32 v180, v183
	s_waitcnt lgkmcnt(0)
	v_pk_mul_f32 v[182:183], v[170:171], v[184:185] op_sel_hi:[0,1]
	v_mov_b32_e32 v176, v179
	v_mov_b32_e32 v190, v5
	v_mov_b32_e32 v191, v1
	v_mov_b32_e32 v192, v178
	v_mov_b32_e32 v194, v13
	v_mov_b32_e32 v195, v9
	v_lshlrev_b64 v[198:199], 6, v[188:189]
	v_pk_mul_f32 v[180:181], v[180:181], v[186:187]
	v_pk_mul_f32 v[176:177], v[176:177], v[182:183]
	v_lshl_add_u64 v[198:199], v[172:173], 0, v[198:199]
	v_lshlrev_b64 v[188:189], 7, v[188:189]
	v_pk_fma_f32 v[180:181], v[194:195], v[196:197], v[180:181]
	v_pk_fma_f32 v[182:183], v[190:191], v[192:193], v[176:177]
	v_cvt_pk_bf16_f32 v178, v180, v181
	v_lshl_add_u64 v[188:189], v[174:175], 0, v[188:189]
	v_cvt_pk_bf16_f32 v179, v182, v183
	global_store_dwordx2 v[198:199], v[178:179], off
	global_store_dwordx4 v[188:189], v[180:183], off nt

.LBB0_760:
	s_andn2_saveexec_b64 s[0:1], s[0:1]
	s_cbranch_execz .LBB0_762
	v_lshl_add_u64 v[190:191], s[58:59], 0, v[134:135]
	v_lshlrev_b64 v[192:193], 6, v[186:187]
	v_lshlrev_b64 v[186:187], 7, v[186:187]
	v_lshl_add_u64 v[194:195], v[174:175], 0, v[186:187]
	global_load_dwordx2 v[186:187], v[190:191], off offset:16
	global_load_dwordx2 v[196:197], v[190:191], off
	v_mov_b32_e32 v198, v14
	v_mov_b32_e32 v199, v10
	s_waitcnt lgkmcnt(2)
	v_pk_mul_f32 v[188:189], v[170:171], v[188:189] op_sel_hi:[0,1]
	s_waitcnt lgkmcnt(0)
	v_pk_mul_f32 v[184:185], v[170:171], v[184:185] op_sel_hi:[0,1]
	v_lshl_add_u64 v[192:193], v[172:173], 0, v[192:193]
	s_waitcnt vmcnt(1)
	v_mov_b32_e32 v201, v186
	s_waitcnt vmcnt(0)
	v_mov_b32_e32 v200, v196
	v_pk_mul_f32 v[198:199], v[198:199], v[200:201]
	v_mov_b32_e32 v186, v197
	v_pk_fma_f32 v[186:187], v[188:189], v[186:187], v[198:199]
	global_load_dwordx2 v[188:189], v[190:191], off offset:48
	s_nop 0
	global_load_dwordx2 v[190:191], v[190:191], off offset:32
	v_mov_b32_e32 v198, v6
	v_mov_b32_e32 v199, v2
	v_cvt_pk_bf16_f32 v196, v186, v187
	s_waitcnt vmcnt(1)
	v_mov_b32_e32 v201, v188
	s_waitcnt vmcnt(0)
	v_mov_b32_e32 v200, v190
	v_pk_mul_f32 v[198:199], v[198:199], v[200:201]
	v_mov_b32_e32 v188, v191
	v_pk_fma_f32 v[188:189], v[184:185], v[188:189], v[198:199]
	s_nop 0
	v_cvt_pk_bf16_f32 v197, v188, v189
	global_store_dwordx2 v[192:193], v[196:197], off
	global_store_dwordx4 v[194:195], v[186:189], off nt

.LBB0_766:
	s_andn2_saveexec_b64 s[0:1], s[0:1]
	s_cbranch_execz .LBB0_768
	s_waitcnt vmcnt(0)
	v_mov_b32_e32 v193, v176
	v_mov_b32_e32 v195, v180
	s_waitcnt lgkmcnt(2)
	v_pk_mul_f32 v[186:187], v[170:171], v[186:187] op_sel_hi:[0,1]
	v_mov_b32_e32 v180, v183
	s_waitcnt lgkmcnt(0)
	v_pk_mul_f32 v[170:171], v[170:171], v[184:185] op_sel_hi:[0,1]
	v_mov_b32_e32 v176, v179
	v_mov_b32_e32 v190, v7
	v_mov_b32_e32 v191, v3
	v_mov_b32_e32 v192, v178
	v_mov_b32_e32 v168, v15
	v_mov_b32_e32 v169, v11
	v_mov_b32_e32 v194, v182
	v_lshlrev_b64 v[196:197], 6, v[188:189]
	v_pk_mul_f32 v[180:181], v[180:181], v[186:187]
	v_pk_mul_f32 v[170:171], v[176:177], v[170:171]
	v_lshl_add_u64 v[172:173], v[172:173], 0, v[196:197]
	v_lshlrev_b64 v[188:189], 7, v[188:189]
	v_pk_fma_f32 v[168:169], v[168:169], v[194:195], v[180:181]
	v_pk_fma_f32 v[170:171], v[190:191], v[192:193], v[170:171]
	v_cvt_pk_bf16_f32 v178, v168, v169
	v_lshl_add_u64 v[174:175], v[174:175], 0, v[188:189]
	v_cvt_pk_bf16_f32 v179, v170, v171
	global_store_dwordx2 v[172:173], v[178:179], off
	global_store_dwordx4 v[174:175], v[168:171], off nt
